# GEMM: skip the first two counted waits after a draining epilogue; epilogue flat_* accesses as global_*
# speedup vs baseline: 1.0074x; 1.0006x over previous
; #define PG8_STAGE(bufoff, gbase, voff) do { _Pragma("unroll") for (int _i = 0; _i < 2; ++_i) \
;         __builtin_amdgcn_global_load_lds((const unsigned*)((const char*)(gbase) + (voff)[_i]), (PG8_LAS unsigned*)(lds + (bufoff) + ldsw + _i * 8192), 16, 0, 0); } while (0)
; #define PG8_WAIT_V(n) asm volatile("s_waitcnt vmcnt(" #n ")" ::: "memory")
; #define PG8_BAR __builtin_amdgcn_s_barrier()
; template <class Epi, class Sched, bool ALIGN_EPI = false, bool SP2 = false>
; __device__ __forceinline__ void gemm_phase(PG8_LAS unsigned char* lds, const Gemm g, const Sched& S, const Epi& E) {
;     ...
;     for (int i = 0; i < 2; ++i) { int R, C; stage_rc(tid * 16 + i * 8192, R, C); const int Rb = Epi::PERM ? ((R & ~31) + perm32(R & 31)) : R;
;         voffA[i] = (unsigned)(R * K + C) * 2u; voffB[i] = (unsigned)(Rb * K + C) * 2u; }
;     const size_t kstep = (size_t)(BK * 2);
;     const size_t hstep = (size_t)HALF * K * 2;
;     const size_t tstep = 2 * hstep;
;     const unsigned ldsw = (unsigned)wid * 1024u;
;     const int aoff = lds_byte(wr * 64 + fr, fq * 8), boff = lds_byte(wc * 32 + fr, fq * 8);
;     ...
;     const char* cA = (const char*)g.A + (size_t)cur.pm * tstep; const char* cB = (const char*)g.Bt + (size_t)cur.pn * tstep;
;     S.a_ready(cur);
;     if constexpr (SP2) {
;         PG8_STAGE(PG8_SB(0, 0), cB, voffB); PG8_STAGE(PG8_SB(0, 1), cB + hstep, voffB); PG8_STAGE(PG8_SA(0, 0), cA, voffA); PG8_STAGE(PG8_SA(0, 1), cA + hstep, voffA);
;         if (wr == 1) PG8_BAR;
;         PG8_WAIT_V(2); PG8_BAR;
;         PG8_STAGE(PG8_SB(1, 0), cB + kstep, voffB); PG8_STAGE(PG8_SA(1, 0), cA + kstep, voffA); PG8_STAGE(PG8_SB(1, 1), cB + hstep + kstep, voffB);
;         PG8_WAIT_V(6); PG8_BAR;
.LBB0_259:
	v_bfe_u32 v18, v12, 4, 2
	v_readlane_b32 s14, v254, 42
	v_and_b32_e32 v13, 15, v12
	v_lshlrev_b32_e32 v0, 4, v18
	v_lshlrev_b32_e32 v12, 2, v12
	s_lshl_b32 s1, s1, 5
	v_mov_b32_e32 v165, v1
	v_readlane_b32 s15, v254, 43
	v_lshl_or_b32 v176, s4, 6, v13
	v_lshl_or_b32 v13, v13, 6, v0
	s_lshl_b32 s4, s4, 13
	v_and_b32_e32 v12, 32, v12
	s_and_b32 s1, s1, 0x60
	s_add_i32 m0, s62, 0x18000
	v_lshl_add_u64 v[2:3], v[2:3], 0, s[60:61]
	v_lshl_add_u64 v[14:15], s[14:15], 0, v[164:165]
	v_mov_b32_e32 v161, v1
	v_bitop3_b32 v19, v13, s4, v12 bitop3:0xde
	s_lshl_b32 s4, s1, 7
	s_waitcnt vmcnt(2)
	s_barrier
	global_load_lds_dwordx4 v[2:3], off
	v_lshl_add_u64 v[2:3], v[4:5], 0, s[60:61]
	s_add_i32 m0, s62, 0x1a000
	s_add_i32 s81, s62, 0x8000
	s_add_i32 s82, s62, 0xa000
	v_lshl_add_u64 v[16:17], s[14:15], 0, v[160:161]
	v_bitop3_b32 v177, v13, s4, v12 bitop3:0xde
	global_load_lds_dwordx4 v[2:3], off
	v_lshl_add_u64 v[2:3], v[14:15], 0, s[60:61]
	s_mov_b32 m0, s81
	s_add_u32 s4, s6, 0x40080
	global_load_lds_dwordx4 v[2:3], off
	v_lshl_add_u64 v[2:3], v[16:17], 0, s[60:61]
	s_mov_b32 m0, s82
	s_addc_u32 s5, s7, 0
	global_load_lds_dwordx4 v[2:3], off
	s_add_i32 m0, s62, 0x1c000
	v_lshl_add_u64 v[2:3], s[4:5], 0, v[162:163]
	global_load_lds_dwordx4 v[2:3], off
	v_lshl_add_u64 v[2:3], s[4:5], 0, v[158:159]
	s_add_i32 m0, s62, 0x1e000
	v_readlane_b32 s4, v253, 38
	global_load_lds_dwordx4 v[2:3], off
	v_readlane_b32 s5, v253, 39
	v_and_b32_e32 v2, 1, v10
	s_waitcnt vmcnt(6)
	s_mov_b32 s100, 0
	s_cmpk_lt_u32 s0, 0x100
	v_lshl_add_u64 v[166:167], s[4:5], 0, v[0:1]
	v_lshlrev_b32_e32 v0, 14, v10
	v_and_b32_e32 v0, 0xffff8000, v0
	v_lshl_add_u32 v0, v9, 11, v0
	v_lshl_or_b32 v0, v2, 6, v0
	v_lshl_add_u32 v168, v11, 1, v0
	v_lshlrev_b32_e32 v0, 14, v6
	v_and_b32_e32 v0, 0xffff8000, v0
	v_lshl_or_b32 v178, v18, 3, s1
	v_lshl_add_u32 v0, v7, 11, v0
	v_and_b32_e32 v2, 1, v6
	v_readlane_b32 s0, v254, 40
	v_lshl_or_b32 v0, v2, 6, v0
	v_readlane_b32 s1, v254, 41
	s_cselect_b64 s[10:11], -1, 0
	v_mov_b32_e32 v169, v1
	v_lshl_add_u32 v170, v8, 1, v0
	v_mov_b32_e32 v171, v1
	s_mov_b32 s83, 0
	v_add_u32_e32 v179, 0, v19
	v_readlane_b32 s12, v254, 36
	s_mov_b32 s13, s0
	s_mov_b64 s[0:1], s[14:15]
	s_barrier
	s_branch .LBB0_262

; #define PG8_STAGE(bufoff, gbase, voff) do { _Pragma("unroll") for (int _i = 0; _i < 2; ++_i) \
;         __builtin_amdgcn_global_load_lds((const unsigned*)((const char*)(gbase) + (voff)[_i]), (PG8_LAS unsigned*)(lds + (bufoff) + ldsw + _i * 8192), 16, 0, 0); } while (0)
; #define PG8_LDA(dst, b, h) do { _Pragma("unroll") for (int m = 0; m < 4; ++m) _Pragma("unroll") for (int k = 0; k < 2; ++k) dst[m][k] = *(const PG8_LAS bf16x8*)(lds + PG8_SA(b, h) + aoff + m * 2048 + k * 1024); } while (0)
; #define PG8_LDB(dst, b, h) do { _Pragma("unroll") for (int n = 0; n < 2; ++n) _Pragma("unroll") for (int k = 0; k < 2; ++k) dst[n][k] = *(const PG8_LAS bf16x8*)(lds + PG8_SB(b, h) + boff + n * 2048 + k * 1024); } while (0)
; #define PG8_MMA(ai, bj, At, Bt) do { __builtin_amdgcn_s_setprio(1); _Pragma("unroll") for (int m = 0; m < 4; ++m) _Pragma("unroll") for (int n = 0; n < 2; ++n) _Pragma("unroll") for (int k = 0; k < 2; ++k) \
;         acc[ai][bj][m][n] = __builtin_amdgcn_mfma_f32_16x16x32_bf16(Bt[n][k], At[m][k], acc[ai][bj][m][n], 0, 0, 0); __builtin_amdgcn_s_setprio(0); } while (0)
; #define PG8_WAIT_V(n) asm volatile("s_waitcnt vmcnt(" #n ")" ::: "memory")
; #define PG8_WAIT_L(n) asm volatile("s_waitcnt lgkmcnt(" #n ")" ::: "memory")
; #define PG8_BAR __builtin_amdgcn_s_barrier()
; #define PG8_SCHED __builtin_amdgcn_sched_barrier(0)
; template <class Epi, class Sched, bool ALIGN_EPI = false, bool SP2 = false>
; __device__ __forceinline__ void gemm_phase(PG8_LAS unsigned char* lds, const Gemm g, const Sched& S, const Epi& E) {
;     ...
;             PG8_LDB(B0, 0, 0); PG8_LDB(B1, 0, 1); PG8_SCHED; PG8_LDA(At, 0, 0); PG8_STAGE(PG8_SA(1, 1), a1 + hstep, voffA);
;             PG8_WAIT_V(8); PG8_WAIT_L(0); PG8_BAR; PG8_MMA(0, 0, At, B0); PG8_MMA(0, 1, At, B1); PG8_BAR; PG8_SCHED;
;             PG8_LDA(At, 0, 1); PG8_STAGE(PG8_SB(0, 0), b2, voffB); PG8_STAGE(PG8_SB(0, 1), b2 + hstep, voffB); PG8_STAGE(PG8_SA(0, 0), a2, voffA);
;             PG8_WAIT_V(8); PG8_WAIT_L(0); PG8_BAR; PG8_MMA(1, 0, At, B0); PG8_MMA(1, 1, At, B1); PG8_BAR; PG8_SCHED;
.LBB0_265:
	s_add_u32 s6, s0, 0xfffc0080
	s_addc_u32 s7, s1, -1
	s_add_i32 s50, 0, 0x10000
	s_cmp_eq_u32 s55, 12
	s_cselect_b32 s79, s73, s7
	s_cselect_b32 s78, s84, s6
	v_add_u32_e32 v0, s50, v177
	s_cselect_b32 s7, s52, s54
	s_cselect_b32 s6, s53, s71
	s_add_i32 s51, 0, 0x14000
	ds_read_b128 v[130:133], v0
	ds_read_b128 v[134:137], v0 offset:1024
	ds_read_b128 v[138:141], v0 offset:2048
	ds_read_b128 v[142:145], v0 offset:3072
	v_add_u32_e32 v0, s51, v177
	ds_read_b128 v[146:149], v0
	ds_read_b128 v[150:153], v0 offset:1024
	ds_read_b128 v[154:157], v0 offset:2048
	ds_read_b128 v[172:175], v0 offset:3072
	v_lshl_add_u64 v[184:185], s[0:1], 0, v[168:169]
	s_add_i32 m0, s62, 0xc000
	ds_read_b128 v[180:183], v179
	ds_read_b128 v[192:195], v179 offset:1024
	ds_read_b128 v[196:199], v179 offset:2048
	ds_read_b128 v[200:203], v179 offset:3072
	ds_read_b128 v[204:207], v179 offset:4096
	ds_read_b128 v[208:211], v179 offset:5120
	ds_read_b128 v[212:215], v179 offset:6144
	ds_read_b128 v[216:219], v179 offset:7168
	global_load_lds_dwordx4 v[184:185], off
	v_lshl_add_u64 v[184:185], s[0:1], 0, v[170:171]
	s_add_i32 m0, s62, 0xe000
	s_nop 0
	global_load_lds_dwordx4 v[184:185], off
	s_cmp_lg_u32 s100, 0
	s_cbranch_scc1 .Lpe_skip_inproj_0
	s_waitcnt vmcnt(8)
.Lpe_skip_inproj_0:
	s_waitcnt lgkmcnt(0)
	s_barrier
	s_setprio 1
	s_waitcnt lgkmcnt(0)
	v_mfma_f32_16x16x32_bf16 v[126:129], v[130:133], v[180:183], v[126:129]
	v_mfma_f32_16x16x32_bf16 v[94:97], v[138:141], v[180:183], v[94:97]
	v_mfma_f32_16x16x32_bf16 v[122:125], v[130:133], v[196:199], v[122:125]
	v_mfma_f32_16x16x32_bf16 v[90:93], v[138:141], v[196:199], v[90:93]
	v_mfma_f32_16x16x32_bf16 v[118:121], v[130:133], v[204:207], v[118:121]
	v_mfma_f32_16x16x32_bf16 v[86:89], v[138:141], v[204:207], v[86:89]
	v_mfma_f32_16x16x32_bf16 v[114:117], v[130:133], v[212:215], v[114:117]
	v_mfma_f32_16x16x32_bf16 v[82:85], v[138:141], v[212:215], v[82:85]
	v_mfma_f32_16x16x32_bf16 v[126:129], v[134:137], v[192:195], v[126:129]
	v_mfma_f32_16x16x32_bf16 v[94:97], v[142:145], v[192:195], v[94:97]
	v_mfma_f32_16x16x32_bf16 v[122:125], v[134:137], v[200:203], v[122:125]
	v_mfma_f32_16x16x32_bf16 v[90:93], v[142:145], v[200:203], v[90:93]
	v_mfma_f32_16x16x32_bf16 v[118:121], v[134:137], v[208:211], v[118:121]
	v_mfma_f32_16x16x32_bf16 v[86:89], v[142:145], v[208:211], v[86:89]
	v_mfma_f32_16x16x32_bf16 v[114:117], v[134:137], v[216:219], v[114:117]
	v_mfma_f32_16x16x32_bf16 v[82:85], v[142:145], v[216:219], v[82:85]
	s_setprio 0
	s_setprio 1
	v_mfma_f32_16x16x32_bf16 v[62:65], v[146:149], v[180:183], v[62:65]
	v_mfma_f32_16x16x32_bf16 v[30:33], v[154:157], v[180:183], v[30:33]
	v_mfma_f32_16x16x32_bf16 v[58:61], v[146:149], v[196:199], v[58:61]
	v_mfma_f32_16x16x32_bf16 v[26:29], v[154:157], v[196:199], v[26:29]
	v_mfma_f32_16x16x32_bf16 v[54:57], v[146:149], v[204:207], v[54:57]
	v_mfma_f32_16x16x32_bf16 v[22:25], v[154:157], v[204:207], v[22:25]
	v_mfma_f32_16x16x32_bf16 v[50:53], v[146:149], v[212:215], v[50:53]
	v_mfma_f32_16x16x32_bf16 v[18:21], v[154:157], v[212:215], v[18:21]
	v_mfma_f32_16x16x32_bf16 v[62:65], v[150:153], v[192:195], v[62:65]
	v_mfma_f32_16x16x32_bf16 v[30:33], v[172:175], v[192:195], v[30:33]
	v_mfma_f32_16x16x32_bf16 v[58:61], v[150:153], v[200:203], v[58:61]
	v_mfma_f32_16x16x32_bf16 v[26:29], v[172:175], v[200:203], v[26:29]
	v_mfma_f32_16x16x32_bf16 v[54:57], v[150:153], v[208:211], v[54:57]
	v_mfma_f32_16x16x32_bf16 v[22:25], v[172:175], v[208:211], v[22:25]
	v_mfma_f32_16x16x32_bf16 v[50:53], v[150:153], v[216:219], v[50:53]
	v_mfma_f32_16x16x32_bf16 v[18:21], v[172:175], v[216:219], v[18:21]
	s_setprio 0
	s_barrier
	s_add_i32 s50, s50, s35
	v_lshl_add_u64 v[184:185], s[6:7], 0, v[162:163]
	s_mov_b32 m0, s50
	ds_read_b128 v[180:183], v179 offset:16384
	ds_read_b128 v[192:195], v179 offset:17408
	ds_read_b128 v[196:199], v179 offset:18432
	ds_read_b128 v[200:203], v179 offset:19456
	ds_read_b128 v[204:207], v179 offset:20480
	ds_read_b128 v[208:211], v179 offset:21504
	ds_read_b128 v[212:215], v179 offset:22528
	ds_read_b128 v[216:219], v179 offset:23552
	global_load_lds_dwordx4 v[184:185], off
	s_add_i32 m0, s50, 0x2000
	s_add_u32 s56, s6, 0x40000
	v_lshl_add_u64 v[188:189], s[6:7], 0, v[158:159]
	s_addc_u32 s57, s7, 0
	s_add_i32 s50, s51, s35
	global_load_lds_dwordx4 v[188:189], off
	v_lshl_add_u64 v[190:191], s[56:57], 0, v[162:163]
	s_mov_b32 m0, s50
	v_lshl_add_u64 v[220:221], s[78:79], 0, v[160:161]
	global_load_lds_dwordx4 v[190:191], off
	v_lshl_add_u64 v[190:191], s[56:57], 0, v[158:159]
	s_add_i32 m0, s50, 0x2000
	s_nop 0
	global_load_lds_dwordx4 v[190:191], off
	v_lshl_add_u64 v[190:191], s[78:79], 0, v[164:165]
	s_mov_b32 m0, s62
	s_nop 0
	global_load_lds_dwordx4 v[190:191], off
	s_mov_b32 m0, s63
	s_nop 0
	global_load_lds_dwordx4 v[220:221], off
	s_cmp_lg_u32 s100, 0
	s_cbranch_scc1 .Lpe_skip_inproj_1
	s_waitcnt vmcnt(8)
; #define PG8_STAGE(bufoff, gbase, voff) do { _Pragma("unroll") for (int _i = 0; _i < 2; ++_i) \
;         __builtin_amdgcn_global_load_lds((const unsigned*)((const char*)(gbase) + (voff)[_i]), (PG8_LAS unsigned*)(lds + (bufoff) + ldsw + _i * 8192), 16, 0, 0); } while (0)
; #define PG8_LDA(dst, b, h) do { _Pragma("unroll") for (int m = 0; m < 4; ++m) _Pragma("unroll") for (int k = 0; k < 2; ++k) dst[m][k] = *(const PG8_LAS bf16x8*)(lds + PG8_SA(b, h) + aoff + m * 2048 + k * 1024); } while (0)
; #define PG8_LDB(dst, b, h) do { _Pragma("unroll") for (int n = 0; n < 2; ++n) _Pragma("unroll") for (int k = 0; k < 2; ++k) dst[n][k] = *(const PG8_LAS bf16x8*)(lds + PG8_SB(b, h) + boff + n * 2048 + k * 1024); } while (0)
; #define PG8_MMA(ai, bj, At, Bt) do { __builtin_amdgcn_s_setprio(1); _Pragma("unroll") for (int m = 0; m < 4; ++m) _Pragma("unroll") for (int n = 0; n < 2; ++n) _Pragma("unroll") for (int k = 0; k < 2; ++k) \
;         acc[ai][bj][m][n] = __builtin_amdgcn_mfma_f32_16x16x32_bf16(Bt[n][k], At[m][k], acc[ai][bj][m][n], 0, 0, 0); __builtin_amdgcn_s_setprio(0); } while (0)
; #define PG8_WAIT_V(n) asm volatile("s_waitcnt vmcnt(" #n ")" ::: "memory")
; #define PG8_WAIT_L(n) asm volatile("s_waitcnt lgkmcnt(" #n ")" ::: "memory")
; #define PG8_BAR __builtin_amdgcn_s_barrier()
; #define PG8_SCHED __builtin_amdgcn_sched_barrier(0)
; template <class Epi, class Sched, bool ALIGN_EPI = false, bool SP2 = false>
; __device__ __forceinline__ void gemm_phase(PG8_LAS unsigned char* lds, const Gemm g, const Sched& S, const Epi& E) {
;     ...
;             PG8_WAIT_V(8); PG8_WAIT_L(0); PG8_BAR; PG8_MMA(1, 0, At, B0); PG8_MMA(1, 1, At, B1); PG8_BAR; PG8_SCHED;
;             PG8_LDB(B0, 1, 0); PG8_LDB(B1, 1, 1); PG8_SCHED; PG8_LDA(At, 1, 0); PG8_STAGE(PG8_SA(0, 1), a2 + hstep, voffA);
;             PG8_WAIT_V(8); PG8_WAIT_L(0); PG8_BAR; PG8_MMA(0, 0, At, B0); PG8_MMA(0, 1, At, B1); PG8_BAR; PG8_SCHED;
.Lpe_skip_inproj_1:
	s_mov_b32 s100, 0
	s_waitcnt lgkmcnt(0)
	s_barrier
	s_setprio 1
	s_waitcnt lgkmcnt(0)
	v_mfma_f32_16x16x32_bf16 v[110:113], v[130:133], v[180:183], v[110:113]
	v_mfma_f32_16x16x32_bf16 v[78:81], v[138:141], v[180:183], v[78:81]
	v_mfma_f32_16x16x32_bf16 v[106:109], v[130:133], v[196:199], v[106:109]
	v_mfma_f32_16x16x32_bf16 v[74:77], v[138:141], v[196:199], v[74:77]
	v_mfma_f32_16x16x32_bf16 v[102:105], v[130:133], v[204:207], v[102:105]
	v_mfma_f32_16x16x32_bf16 v[70:73], v[138:141], v[204:207], v[70:73]
	v_mfma_f32_16x16x32_bf16 v[98:101], v[130:133], v[212:215], v[98:101]
	v_mfma_f32_16x16x32_bf16 v[66:69], v[138:141], v[212:215], v[66:69]
	v_mfma_f32_16x16x32_bf16 v[110:113], v[134:137], v[192:195], v[110:113]
	v_mfma_f32_16x16x32_bf16 v[78:81], v[142:145], v[192:195], v[78:81]
	v_mfma_f32_16x16x32_bf16 v[106:109], v[134:137], v[200:203], v[106:109]
	v_mfma_f32_16x16x32_bf16 v[74:77], v[142:145], v[200:203], v[74:77]
	v_mfma_f32_16x16x32_bf16 v[102:105], v[134:137], v[208:211], v[102:105]
	v_mfma_f32_16x16x32_bf16 v[70:73], v[142:145], v[208:211], v[70:73]
	v_mfma_f32_16x16x32_bf16 v[98:101], v[134:137], v[216:219], v[98:101]
	v_mfma_f32_16x16x32_bf16 v[66:69], v[142:145], v[216:219], v[66:69]
	s_setprio 0
	s_setprio 1
	v_mfma_f32_16x16x32_bf16 v[46:49], v[146:149], v[180:183], v[46:49]
	v_mfma_f32_16x16x32_bf16 v[14:17], v[154:157], v[180:183], v[14:17]
	v_mfma_f32_16x16x32_bf16 v[42:45], v[146:149], v[196:199], v[42:45]
	v_mfma_f32_16x16x32_bf16 v[10:13], v[154:157], v[196:199], v[10:13]
	v_mfma_f32_16x16x32_bf16 v[38:41], v[146:149], v[204:207], v[38:41]
	v_mfma_f32_16x16x32_bf16 v[6:9], v[154:157], v[204:207], v[6:9]
	v_mfma_f32_16x16x32_bf16 v[34:37], v[146:149], v[212:215], v[34:37]
	v_mfma_f32_16x16x32_bf16 v[2:5], v[154:157], v[212:215], v[2:5]
	v_mfma_f32_16x16x32_bf16 v[46:49], v[150:153], v[192:195], v[46:49]
	v_mfma_f32_16x16x32_bf16 v[14:17], v[172:175], v[192:195], v[14:17]
	v_mfma_f32_16x16x32_bf16 v[42:45], v[150:153], v[200:203], v[42:45]
	v_mfma_f32_16x16x32_bf16 v[10:13], v[172:175], v[200:203], v[10:13]
	v_mfma_f32_16x16x32_bf16 v[38:41], v[150:153], v[208:211], v[38:41]
	v_mfma_f32_16x16x32_bf16 v[6:9], v[172:175], v[208:211], v[6:9]
	v_mfma_f32_16x16x32_bf16 v[34:37], v[150:153], v[216:219], v[34:37]
	v_mfma_f32_16x16x32_bf16 v[2:5], v[172:175], v[216:219], v[2:5]
	s_setprio 0
	s_barrier
	s_add_i32 s50, 0, 0x18000
	v_add_u32_e32 v0, s50, v177
	s_add_i32 s51, 0, 0x1c000
	ds_read_b128 v[130:133], v0
	ds_read_b128 v[134:137], v0 offset:1024
	ds_read_b128 v[138:141], v0 offset:2048
	ds_read_b128 v[142:145], v0 offset:3072
	v_add_u32_e32 v0, s51, v177
	ds_read_b128 v[146:149], v0
	ds_read_b128 v[150:153], v0 offset:1024
	ds_read_b128 v[154:157], v0 offset:2048
	ds_read_b128 v[172:175], v0 offset:3072
	s_add_u32 s56, s78, 0x40000
	s_addc_u32 s57, s79, 0
	s_mov_b32 m0, s64
	v_lshl_add_u64 v[222:223], s[56:57], 0, v[164:165]
	ds_read_b128 v[180:183], v179 offset:32768
	ds_read_b128 v[192:195], v179 offset:33792
	ds_read_b128 v[196:199], v179 offset:34816
	ds_read_b128 v[200:203], v179 offset:35840
	ds_read_b128 v[204:207], v179 offset:36864
	ds_read_b128 v[208:211], v179 offset:37888
	ds_read_b128 v[212:215], v179 offset:38912
	ds_read_b128 v[216:219], v179 offset:39936
	global_load_lds_dwordx4 v[222:223], off
	v_lshl_add_u64 v[222:223], s[56:57], 0, v[160:161]
	s_mov_b32 m0, s80
	s_nop 0
	global_load_lds_dwordx4 v[222:223], off
	s_waitcnt vmcnt(8)
	s_waitcnt lgkmcnt(0)
	s_barrier
	s_setprio 1
	s_waitcnt lgkmcnt(0)
	v_mfma_f32_16x16x32_bf16 v[126:129], v[130:133], v[180:183], v[126:129]
	v_mfma_f32_16x16x32_bf16 v[94:97], v[138:141], v[180:183], v[94:97]
	v_mfma_f32_16x16x32_bf16 v[122:125], v[130:133], v[196:199], v[122:125]
	v_mfma_f32_16x16x32_bf16 v[90:93], v[138:141], v[196:199], v[90:93]
	v_mfma_f32_16x16x32_bf16 v[118:121], v[130:133], v[204:207], v[118:121]
	v_mfma_f32_16x16x32_bf16 v[86:89], v[138:141], v[204:207], v[86:89]
	v_mfma_f32_16x16x32_bf16 v[114:117], v[130:133], v[212:215], v[114:117]
	v_mfma_f32_16x16x32_bf16 v[82:85], v[138:141], v[212:215], v[82:85]
	v_mfma_f32_16x16x32_bf16 v[126:129], v[134:137], v[192:195], v[126:129]
	v_mfma_f32_16x16x32_bf16 v[94:97], v[142:145], v[192:195], v[94:97]
	v_mfma_f32_16x16x32_bf16 v[122:125], v[134:137], v[200:203], v[122:125]
	v_mfma_f32_16x16x32_bf16 v[90:93], v[142:145], v[200:203], v[90:93]
	v_mfma_f32_16x16x32_bf16 v[118:121], v[134:137], v[208:211], v[118:121]
	v_mfma_f32_16x16x32_bf16 v[86:89], v[142:145], v[208:211], v[86:89]
	v_mfma_f32_16x16x32_bf16 v[114:117], v[134:137], v[216:219], v[114:117]
	v_mfma_f32_16x16x32_bf16 v[82:85], v[142:145], v[216:219], v[82:85]
	s_setprio 0
	s_setprio 1
	v_mfma_f32_16x16x32_bf16 v[62:65], v[146:149], v[180:183], v[62:65]
	v_mfma_f32_16x16x32_bf16 v[30:33], v[154:157], v[180:183], v[30:33]
	v_mfma_f32_16x16x32_bf16 v[58:61], v[146:149], v[196:199], v[58:61]
	v_mfma_f32_16x16x32_bf16 v[26:29], v[154:157], v[196:199], v[26:29]
	v_mfma_f32_16x16x32_bf16 v[54:57], v[146:149], v[204:207], v[54:57]
	v_mfma_f32_16x16x32_bf16 v[22:25], v[154:157], v[204:207], v[22:25]
	v_mfma_f32_16x16x32_bf16 v[50:53], v[146:149], v[212:215], v[50:53]
	v_mfma_f32_16x16x32_bf16 v[18:21], v[154:157], v[212:215], v[18:21]
	v_mfma_f32_16x16x32_bf16 v[62:65], v[150:153], v[192:195], v[62:65]
	v_mfma_f32_16x16x32_bf16 v[30:33], v[172:175], v[192:195], v[30:33]
	v_mfma_f32_16x16x32_bf16 v[58:61], v[150:153], v[200:203], v[58:61]
	v_mfma_f32_16x16x32_bf16 v[26:29], v[172:175], v[200:203], v[26:29]
	v_mfma_f32_16x16x32_bf16 v[54:57], v[150:153], v[208:211], v[54:57]
	v_mfma_f32_16x16x32_bf16 v[22:25], v[172:175], v[208:211], v[22:25]
	v_mfma_f32_16x16x32_bf16 v[50:53], v[150:153], v[216:219], v[50:53]
	v_mfma_f32_16x16x32_bf16 v[18:21], v[172:175], v[216:219], v[18:21]
	s_setprio 0
	s_barrier
; #define PG8_STAGE(bufoff, gbase, voff) do { _Pragma("unroll") for (int _i = 0; _i < 2; ++_i) \
;         __builtin_amdgcn_global_load_lds((const unsigned*)((const char*)(gbase) + (voff)[_i]), (PG8_LAS unsigned*)(lds + (bufoff) + ldsw + _i * 8192), 16, 0, 0); } while (0)
; #define PG8_LDA(dst, b, h) do { _Pragma("unroll") for (int m = 0; m < 4; ++m) _Pragma("unroll") for (int k = 0; k < 2; ++k) dst[m][k] = *(const PG8_LAS bf16x8*)(lds + PG8_SA(b, h) + aoff + m * 2048 + k * 1024); } while (0)
; #define PG8_MMA(ai, bj, At, Bt) do { __builtin_amdgcn_s_setprio(1); _Pragma("unroll") for (int m = 0; m < 4; ++m) _Pragma("unroll") for (int n = 0; n < 2; ++n) _Pragma("unroll") for (int k = 0; k < 2; ++k) \
;         acc[ai][bj][m][n] = __builtin_amdgcn_mfma_f32_16x16x32_bf16(Bt[n][k], At[m][k], acc[ai][bj][m][n], 0, 0, 0); __builtin_amdgcn_s_setprio(0); } while (0)
; #define PG8_WAIT_V(n) asm volatile("s_waitcnt vmcnt(" #n ")" ::: "memory")
; #define PG8_WAIT_L(n) asm volatile("s_waitcnt lgkmcnt(" #n ")" ::: "memory")
; #define PG8_BAR __builtin_amdgcn_s_barrier()
; #define PG8_SCHED __builtin_amdgcn_sched_barrier(0)
; template <class Epi, class Sched, bool ALIGN_EPI = false, bool SP2 = false>
; __device__ __forceinline__ void gemm_phase(PG8_LAS unsigned char* lds, const Gemm g, const Sched& S, const Epi& E) {
;     ...
;             PG8_LDA(At, 1, 1); PG8_STAGE(PG8_SB(1, 0), b3, voffB); PG8_STAGE(PG8_SB(1, 1), b3 + hstep, voffB); PG8_STAGE(PG8_SA(1, 0), a3, voffA);
;             PG8_WAIT_V(8); PG8_WAIT_L(0); PG8_BAR; PG8_MMA(1, 0, At, B0); PG8_MMA(1, 1, At, B1); PG8_BAR; PG8_SCHED;
;     ...
;         if constexpr (ALIGN_EPI) { if (wr == 0) PG8_BAR; }
	s_add_i32 s50, s50, s35
	v_lshl_add_u64 v[184:185], v[184:185], 0, s[60:61]
	s_mov_b32 m0, s50
	ds_read_b128 v[180:183], v179 offset:49152
	ds_read_b128 v[192:195], v179 offset:50176
	ds_read_b128 v[196:199], v179 offset:51200
	ds_read_b128 v[200:203], v179 offset:52224
	ds_read_b128 v[204:207], v179 offset:53248
	ds_read_b128 v[208:211], v179 offset:54272
	ds_read_b128 v[212:215], v179 offset:55296
	ds_read_b128 v[216:219], v179 offset:56320
	global_load_lds_dwordx4 v[184:185], off
	s_add_i32 m0, s50, 0x2000
	s_add_u32 s6, s6, 0x40080
	v_lshl_add_u64 v[184:185], v[188:189], 0, s[60:61]
	s_addc_u32 s7, s7, 0
	s_add_i32 s50, s51, s35
	global_load_lds_dwordx4 v[184:185], off
	v_lshl_add_u64 v[184:185], s[6:7], 0, v[162:163]
	s_mov_b32 m0, s50
	s_nop 0
	global_load_lds_dwordx4 v[184:185], off
	v_lshl_add_u64 v[184:185], s[6:7], 0, v[158:159]
	s_add_i32 m0, s50, 0x2000
	s_nop 0
	global_load_lds_dwordx4 v[184:185], off
	v_lshl_add_u64 v[184:185], v[190:191], 0, s[60:61]
	s_mov_b32 m0, s81
	s_nop 0
	global_load_lds_dwordx4 v[184:185], off
	v_lshl_add_u64 v[184:185], v[220:221], 0, s[60:61]
	s_mov_b32 m0, s82
	s_nop 0
	global_load_lds_dwordx4 v[184:185], off
	s_waitcnt vmcnt(8)
	s_waitcnt lgkmcnt(0)
	s_barrier
	s_setprio 1
	s_waitcnt lgkmcnt(0)
	v_mfma_f32_16x16x32_bf16 v[110:113], v[130:133], v[180:183], v[110:113]
	v_mfma_f32_16x16x32_bf16 v[78:81], v[138:141], v[180:183], v[78:81]
	v_mfma_f32_16x16x32_bf16 v[106:109], v[130:133], v[196:199], v[106:109]
	v_mfma_f32_16x16x32_bf16 v[74:77], v[138:141], v[196:199], v[74:77]
	v_mfma_f32_16x16x32_bf16 v[102:105], v[130:133], v[204:207], v[102:105]
	v_mfma_f32_16x16x32_bf16 v[70:73], v[138:141], v[204:207], v[70:73]
	v_mfma_f32_16x16x32_bf16 v[98:101], v[130:133], v[212:215], v[98:101]
	v_mfma_f32_16x16x32_bf16 v[66:69], v[138:141], v[212:215], v[66:69]
	v_mfma_f32_16x16x32_bf16 v[110:113], v[134:137], v[192:195], v[110:113]
	v_mfma_f32_16x16x32_bf16 v[78:81], v[142:145], v[192:195], v[78:81]
	v_mfma_f32_16x16x32_bf16 v[106:109], v[134:137], v[200:203], v[106:109]
	v_mfma_f32_16x16x32_bf16 v[74:77], v[142:145], v[200:203], v[74:77]
	v_mfma_f32_16x16x32_bf16 v[102:105], v[134:137], v[208:211], v[102:105]
	v_mfma_f32_16x16x32_bf16 v[70:73], v[142:145], v[208:211], v[70:73]
	v_mfma_f32_16x16x32_bf16 v[98:101], v[134:137], v[216:219], v[98:101]
	v_mfma_f32_16x16x32_bf16 v[66:69], v[142:145], v[216:219], v[66:69]
	s_setprio 0
	s_setprio 1
	v_mfma_f32_16x16x32_bf16 v[46:49], v[146:149], v[180:183], v[46:49]
	v_mfma_f32_16x16x32_bf16 v[14:17], v[154:157], v[180:183], v[14:17]
	v_mfma_f32_16x16x32_bf16 v[42:45], v[146:149], v[196:199], v[42:45]
	v_mfma_f32_16x16x32_bf16 v[10:13], v[154:157], v[196:199], v[10:13]
	v_mfma_f32_16x16x32_bf16 v[38:41], v[146:149], v[204:207], v[38:41]
	v_mfma_f32_16x16x32_bf16 v[6:9], v[154:157], v[204:207], v[6:9]
	v_mfma_f32_16x16x32_bf16 v[34:37], v[146:149], v[212:215], v[34:37]
	v_mfma_f32_16x16x32_bf16 v[2:5], v[154:157], v[212:215], v[2:5]
	v_mfma_f32_16x16x32_bf16 v[46:49], v[150:153], v[192:195], v[46:49]
	v_mfma_f32_16x16x32_bf16 v[14:17], v[172:175], v[192:195], v[14:17]
	v_mfma_f32_16x16x32_bf16 v[42:45], v[150:153], v[200:203], v[42:45]
	v_mfma_f32_16x16x32_bf16 v[10:13], v[172:175], v[200:203], v[10:13]
	v_mfma_f32_16x16x32_bf16 v[38:41], v[150:153], v[208:211], v[38:41]
	v_mfma_f32_16x16x32_bf16 v[6:9], v[172:175], v[208:211], v[6:9]
	v_mfma_f32_16x16x32_bf16 v[34:37], v[150:153], v[216:219], v[34:37]
	v_mfma_f32_16x16x32_bf16 v[2:5], v[172:175], v[216:219], v[2:5]
	s_setprio 0
	s_barrier
	s_add_i32 s55, s55, 2
	s_add_u32 s0, s0, 0x100
	s_addc_u32 s1, s1, 0
	s_add_u32 s71, s71, 0x100
	s_addc_u32 s54, s54, 0
	s_cmp_gt_u32 s55, 13
	s_cbranch_scc0 .LBB0_265
	s_and_b64 vcc, exec, s[10:11]
	s_cbranch_vccz .LBB0_268
	s_barrier

; __device__ __forceinline__ void load_row_scales(const float* ssp, int row0, int fq, float (&rs)[2][4]) {
;     ...
;     const float* sp = ssp + (size_t)row0 * 16 + 4 * fq;
; #pragma unroll
;     for (int ai = 0; ai < 2; ++ai)
; #pragma unroll
;         for (int m = 0; m < 4; ++m) part[ai][m] = *(const f32x4*)(sp + (size_t)(ai * HALF + m * 16) * 16);
; #pragma unroll
;     for (int ai = 0; ai < 2; ++ai)
; #pragma unroll
;         for (int m = 0; m < 4; ++m) { float t = (part[ai][m][0] + part[ai][m][1]) + (part[ai][m][2] + part[ai][m][3]);
;             t += __shfl_xor(t, 16); t += __shfl_xor(t, 32);
;             rs[ai][m] = 1.0f / sqrtf(t * (1.0f / 1024.0f) + 1e-6f); }
.LBB0_271:
	s_and_b64 vcc, exec, s[6:7]
	s_cbranch_vccnz .LBB0_273
	v_lshlrev_b64 v[130:131], 6, v[172:173]
	v_lshl_add_u64 v[130:131], v[166:167], 0, v[130:131]
	global_load_dwordx4 v[182:185], v[130:131], off
	global_load_dwordx4 v[154:157], v[130:131], off offset:1024
	global_load_dwordx4 v[150:153], v[130:131], off offset:2048
	global_load_dwordx4 v[146:149], v[130:131], off offset:3072
	v_add_co_u32_e32 v130, vcc, 0x2000, v130
	v_and_b32_e32 v175, 64, v229
	s_nop 0
	v_addc_co_u32_e32 v131, vcc, 0, v131, vcc
	v_xor_b32_e32 v0, 16, v229
	v_add_u32_e32 v180, 64, v175
	v_cmp_lt_i32_e32 vcc, v0, v180
	global_load_dwordx4 v[142:145], v[130:131], off
	global_load_dwordx4 v[138:141], v[130:131], off offset:1024
	global_load_dwordx4 v[134:137], v[130:131], off offset:2048
	s_nop 0
	global_load_dwordx4 v[130:133], v[130:131], off offset:3072
	v_cndmask_b32_e32 v0, v229, v0, vcc
	v_lshlrev_b32_e32 v175, 2, v0
	v_xor_b32_e32 v0, 32, v229
	v_cmp_lt_i32_e32 vcc, v0, v180
	s_waitcnt vmcnt(0)
	s_mov_b32 s100, 1
	v_mov_b32_e32 v188, v183
	v_mov_b32_e32 v189, v184
	v_mov_b32_e32 v183, v185
	v_cndmask_b32_e32 v0, v229, v0, vcc
	v_pk_add_f32 v[182:183], v[188:189], v[182:183]
	v_lshlrev_b32_e32 v180, 2, v0
	v_add_f32_e32 v0, v182, v183
	v_mov_b32_e32 v181, v0
	s_nop 1
	v_permlane16_swap_b32_e32 v181, v0
	s_waitcnt lgkmcnt(0)
	v_add_f32_e32 v0, v0, v181
	v_mov_b32_e32 v181, v0
	s_nop 1
	v_permlane32_swap_b32_e32 v181, v0
	s_waitcnt lgkmcnt(0)
	v_add_f32_e32 v0, v0, v181
	v_fmamk_f32 v0, v0, 0x3a800000, v230
	v_mov_b32_e32 v182, v155
	v_mov_b32_e32 v183, v156
	v_mov_b32_e32 v155, v157
	v_pk_add_f32 v[154:155], v[182:183], v[154:155]
	v_rsq_f32_e32 v0, v0
	s_nop 0
	v_add_f32_e32 v154, v154, v155
	v_mov_b32_e32 v155, v154
	s_nop 1
	v_permlane16_swap_b32_e32 v155, v154
	s_waitcnt lgkmcnt(0)
	v_add_f32_e32 v154, v154, v155
	v_mov_b32_e32 v155, v154
	s_nop 1
	v_permlane32_swap_b32_e32 v155, v154
	s_waitcnt lgkmcnt(0)
	v_add_f32_e32 v154, v154, v155
	v_fmamk_f32 v154, v154, 0x3a800000, v230
	v_mov_b32_e32 v156, v151
	v_mov_b32_e32 v157, v152
	v_mov_b32_e32 v151, v153
	v_pk_add_f32 v[150:151], v[156:157], v[150:151]
	v_rsq_f32_e32 v154, v154
	s_nop 0
	v_add_f32_e32 v150, v150, v151
	v_mov_b32_e32 v151, v150
	s_nop 1
	v_permlane16_swap_b32_e32 v151, v150
	s_waitcnt lgkmcnt(0)
	v_add_f32_e32 v150, v150, v151
	v_mov_b32_e32 v151, v150
	s_nop 1
	v_permlane32_swap_b32_e32 v151, v150
	s_waitcnt lgkmcnt(0)
	v_add_f32_e32 v150, v150, v151
	v_fmamk_f32 v150, v150, 0x3a800000, v230
	v_mov_b32_e32 v152, v147
	v_mov_b32_e32 v153, v148
	v_mov_b32_e32 v147, v149
	v_pk_add_f32 v[146:147], v[152:153], v[146:147]
	v_rsq_f32_e32 v150, v150
	s_nop 0
	v_add_f32_e32 v146, v146, v147
	v_mov_b32_e32 v147, v146
	s_nop 1
	v_permlane16_swap_b32_e32 v147, v146
	s_waitcnt lgkmcnt(0)
	v_add_f32_e32 v146, v146, v147
	v_mov_b32_e32 v147, v146
	s_nop 1
	v_permlane32_swap_b32_e32 v147, v146
	s_waitcnt lgkmcnt(0)
	v_add_f32_e32 v146, v146, v147
	v_fmamk_f32 v146, v146, 0x3a800000, v230
	v_mov_b32_e32 v148, v143
	v_mov_b32_e32 v149, v144
	v_mov_b32_e32 v143, v145
	v_pk_add_f32 v[142:143], v[148:149], v[142:143]
	v_rsq_f32_e32 v146, v146
	s_nop 0
	v_add_f32_e32 v142, v142, v143
	v_mov_b32_e32 v143, v142
	s_nop 1
	v_permlane16_swap_b32_e32 v143, v142
	s_waitcnt lgkmcnt(0)
	v_add_f32_e32 v142, v142, v143
	v_mov_b32_e32 v143, v142
	s_nop 1
	v_permlane32_swap_b32_e32 v143, v142
	s_waitcnt lgkmcnt(0)
	v_add_f32_e32 v142, v142, v143
	v_fmamk_f32 v142, v142, 0x3a800000, v230
	v_mov_b32_e32 v144, v139
	v_mov_b32_e32 v145, v140
	v_mov_b32_e32 v139, v141
	v_pk_add_f32 v[138:139], v[144:145], v[138:139]
	v_rsq_f32_e32 v142, v142
	s_nop 0
	v_add_f32_e32 v138, v138, v139
	v_mov_b32_e32 v139, v138
	s_nop 1
	v_permlane16_swap_b32_e32 v139, v138
	s_waitcnt lgkmcnt(0)
	v_add_f32_e32 v138, v138, v139
	v_mov_b32_e32 v139, v138
	s_nop 1
	v_permlane32_swap_b32_e32 v139, v138
	s_waitcnt lgkmcnt(0)
	v_add_f32_e32 v138, v138, v139
	v_fmamk_f32 v138, v138, 0x3a800000, v230
	v_mov_b32_e32 v140, v135
	v_mov_b32_e32 v141, v136
	v_mov_b32_e32 v135, v137
	v_pk_add_f32 v[134:135], v[140:141], v[134:135]
	v_rsq_f32_e32 v138, v138
	s_nop 0
	v_add_f32_e32 v134, v134, v135
	v_mov_b32_e32 v135, v134
	s_nop 1
	v_permlane16_swap_b32_e32 v135, v134
	s_waitcnt lgkmcnt(0)
	v_add_f32_e32 v134, v134, v135
	v_mov_b32_e32 v135, v134
	s_nop 1
	v_permlane32_swap_b32_e32 v135, v134
	s_waitcnt lgkmcnt(0)
	v_add_f32_e32 v134, v134, v135
	v_fmamk_f32 v134, v134, 0x3a800000, v230
	v_mov_b32_e32 v136, v131
	v_mov_b32_e32 v137, v132
	v_mov_b32_e32 v131, v133
	v_pk_add_f32 v[130:131], v[136:137], v[130:131]
	v_rsq_f32_e32 v134, v134
	s_nop 0
	v_add_f32_e32 v130, v130, v131
	v_mov_b32_e32 v131, v130
	s_nop 1
	v_permlane16_swap_b32_e32 v131, v130
	s_waitcnt lgkmcnt(0)
	v_add_f32_e32 v130, v130, v131
	v_mov_b32_e32 v131, v130
	s_nop 1
	v_permlane32_swap_b32_e32 v131, v130
	s_waitcnt lgkmcnt(0)
	v_add_f32_e32 v130, v130, v131
	v_fmamk_f32 v130, v130, 0x3a800000, v230
	v_rsq_f32_e32 v130, v130
	s_nop 0
	s_branch .LBB0_274

; __device__ __forceinline__ unsigned cvt_pk_bf16(float lo, float hi) { unsigned r; asm volatile("v_cvt_pk_bf16_f32 %0, %1, %2" : "=v"(r) : "v"(lo), "v"(hi)); return r; }
;     __device__ __forceinline__ void operator()(f32x4 (&acc)[2][2][4][2], const Unit& u, int wr, int wc, int fr, int fq) const {
;     ...
;                 for (int m = 0; m < 4; ++m) { const float rs = rsa[ai][m];
; #pragma unroll
;                     for (int bj = 0; bj < 2; ++bj) { const f32x4 v0 = acc[ai][bj][m][0] * rs, v1 = acc[ai][bj][m][1] * rs;
;                         u32x4 w; w.x = cvt_pk_bf16(v0[0], v0[1]); w.y = cvt_pk_bf16(v0[2], v0[3]); w.z = cvt_pk_bf16(v1[0], v1[1]); w.w = cvt_pk_bf16(v1[2], v1[3]);
;                         *(u32x4*)(rowp + bj * HALF) = w; }
;                     rowp += (size_t)16 * ldr; asm volatile("" : "+v"(rowp) :: "memory"); }
;                 rowp += (size_t)64 * ldr; asm volatile("" : "+v"(rowp)); }
.LBB0_274:
	v_mov_b64_e32 v[132:133], s[46:47]
	v_mad_i64_i32 v[132:133], s[0:1], v172, s37, v[132:133]
	v_ashrrev_i32_e32 v175, 31, v174
	v_pk_mul_f32 v[136:137], v[128:129], v[0:1] op_sel_hi:[1,0]
	v_pk_mul_f32 v[140:141], v[126:127], v[0:1] op_sel_hi:[1,0]
	v_pk_mul_f32 v[144:145], v[96:97], v[0:1] op_sel_hi:[1,0]
	v_lshl_add_u64 v[132:133], v[174:175], 1, v[132:133]
	v_pk_mul_f32 v[148:149], v[94:95], v[0:1] op_sel_hi:[1,0]
	v_cvt_pk_bf16_f32 v180, v140, v141
	v_cvt_pk_bf16_f32 v181, v136, v137
	v_pk_mul_f32 v[136:137], v[64:65], v[0:1] op_sel_hi:[1,0]
	v_cvt_pk_bf16_f32 v182, v148, v149
	v_cvt_pk_bf16_f32 v183, v144, v145
	v_pk_mul_f32 v[140:141], v[62:63], v[0:1] op_sel_hi:[1,0]
	v_pk_mul_f32 v[144:145], v[32:33], v[0:1] op_sel_hi:[1,0]
	s_mov_b64 s[0:1], 0x15800
	global_store_dwordx4 v[132:133], v[180:183], off offset:-2048
	v_pk_mul_f32 v[148:149], v[30:31], v[0:1] op_sel_hi:[1,0]
	s_mov_b64 s[12:13], 0x58000
	v_cvt_pk_bf16_f32 v180, v140, v141
	v_cvt_pk_bf16_f32 v181, v136, v137
	v_cvt_pk_bf16_f32 v182, v148, v149
	v_cvt_pk_bf16_f32 v183, v144, v145
	global_store_dwordx4 v[132:133], v[180:183], off offset:-1792
	v_lshl_add_u64 v[132:133], v[132:133], 0, s[0:1]
	v_pk_mul_f32 v[136:137], v[124:125], v[154:155] op_sel_hi:[1,0]
	v_pk_mul_f32 v[140:141], v[122:123], v[154:155] op_sel_hi:[1,0]
	v_pk_mul_f32 v[144:145], v[92:93], v[154:155] op_sel_hi:[1,0]
	v_pk_mul_f32 v[148:149], v[90:91], v[154:155] op_sel_hi:[1,0]
	v_cvt_pk_bf16_f32 v180, v140, v141
	v_cvt_pk_bf16_f32 v181, v136, v137
	v_pk_mul_f32 v[136:137], v[60:61], v[154:155] op_sel_hi:[1,0]
	v_cvt_pk_bf16_f32 v182, v148, v149
	v_cvt_pk_bf16_f32 v183, v144, v145
	v_pk_mul_f32 v[140:141], v[58:59], v[154:155] op_sel_hi:[1,0]
	v_pk_mul_f32 v[144:145], v[28:29], v[154:155] op_sel_hi:[1,0]
	s_mov_b64 s[0:1], 0x16000
	global_store_dwordx4 v[132:133], v[180:183], off
	v_pk_mul_f32 v[148:149], v[26:27], v[154:155] op_sel_hi:[1,0]
	v_cvt_pk_bf16_f32 v152, v140, v141
	v_cvt_pk_bf16_f32 v153, v136, v137
	v_pk_mul_f32 v[136:137], v[120:121], v[150:151] op_sel_hi:[1,0]
	v_cvt_pk_bf16_f32 v154, v148, v149
	v_cvt_pk_bf16_f32 v155, v144, v145
	global_store_dwordx4 v[132:133], v[152:155], off offset:256
	v_lshl_add_u64 v[132:133], v[132:133], 0, s[0:1]
	v_pk_mul_f32 v[140:141], v[118:119], v[150:151] op_sel_hi:[1,0]
	v_pk_mul_f32 v[144:145], v[88:89], v[150:151] op_sel_hi:[1,0]
	v_pk_mul_f32 v[148:149], v[86:87], v[150:151] op_sel_hi:[1,0]
	v_cvt_pk_bf16_f32 v152, v140, v141
	v_cvt_pk_bf16_f32 v153, v136, v137
	v_pk_mul_f32 v[136:137], v[56:57], v[150:151] op_sel_hi:[1,0]
	v_cvt_pk_bf16_f32 v154, v148, v149
	v_cvt_pk_bf16_f32 v155, v144, v145
	v_pk_mul_f32 v[140:141], v[54:55], v[150:151] op_sel_hi:[1,0]
	v_pk_mul_f32 v[144:145], v[24:25], v[150:151] op_sel_hi:[1,0]
	v_pk_mul_f32 v[150:151], v[22:23], v[150:151] op_sel_hi:[1,0]
	global_store_dwordx4 v[132:133], v[152:155], off
	v_cvt_pk_bf16_f32 v148, v140, v141
	v_cvt_pk_bf16_f32 v149, v136, v137
	v_cvt_pk_bf16_f32 v150, v150, v151
	v_cvt_pk_bf16_f32 v151, v144, v145
	global_store_dwordx4 v[132:133], v[148:151], off offset:256
	v_lshl_add_u64 v[132:133], v[132:133], 0, s[0:1]
	v_pk_mul_f32 v[136:137], v[116:117], v[146:147] op_sel_hi:[1,0]
	v_pk_mul_f32 v[140:141], v[114:115], v[146:147] op_sel_hi:[1,0]
	v_pk_mul_f32 v[150:151], v[82:83], v[146:147] op_sel_hi:[1,0]
	v_cvt_pk_bf16_f32 v148, v140, v141
	v_cvt_pk_bf16_f32 v149, v136, v137
	v_pk_mul_f32 v[144:145], v[84:85], v[146:147] op_sel_hi:[1,0]
	v_cvt_pk_bf16_f32 v150, v150, v151
	v_pk_mul_f32 v[136:137], v[52:53], v[146:147] op_sel_hi:[1,0]
	v_cvt_pk_bf16_f32 v151, v144, v145
	global_store_dwordx4 v[132:133], v[148:151], off
	v_pk_mul_f32 v[140:141], v[50:51], v[146:147] op_sel_hi:[1,0]
	s_nop 0
	v_pk_mul_f32 v[148:149], v[20:21], v[146:147] op_sel_hi:[1,0]
	v_pk_mul_f32 v[146:147], v[18:19], v[146:147] op_sel_hi:[1,0]
	v_cvt_pk_bf16_f32 v144, v140, v141
	v_cvt_pk_bf16_f32 v145, v136, v137
	v_pk_mul_f32 v[136:137], v[112:113], v[142:143] op_sel_hi:[1,0]
	v_cvt_pk_bf16_f32 v146, v146, v147
	v_cvt_pk_bf16_f32 v147, v148, v149
	global_store_dwordx4 v[132:133], v[144:147], off offset:256
	v_lshl_add_u64 v[132:133], v[132:133], 0, s[0:1]
	v_pk_mul_f32 v[140:141], v[110:111], v[142:143] op_sel_hi:[1,0]
	v_lshl_add_u64 v[132:133], v[132:133], 0, s[12:13]
	v_pk_mul_f32 v[146:147], v[78:79], v[142:143] op_sel_hi:[1,0]
	v_cvt_pk_bf16_f32 v144, v140, v141
	v_cvt_pk_bf16_f32 v145, v136, v137
	v_pk_mul_f32 v[148:149], v[80:81], v[142:143] op_sel_hi:[1,0]
	v_cvt_pk_bf16_f32 v146, v146, v147
	v_pk_mul_f32 v[136:137], v[48:49], v[142:143] op_sel_hi:[1,0]
	v_cvt_pk_bf16_f32 v147, v148, v149
	global_store_dwordx4 v[132:133], v[144:147], off
	v_pk_mul_f32 v[140:141], v[46:47], v[142:143] op_sel_hi:[1,0]
	s_nop 0
	v_pk_mul_f32 v[144:145], v[16:17], v[142:143] op_sel_hi:[1,0]
	v_pk_mul_f32 v[142:143], v[14:15], v[142:143] op_sel_hi:[1,0]
	v_cvt_pk_bf16_f32 v140, v140, v141
	v_cvt_pk_bf16_f32 v141, v136, v137
	v_pk_mul_f32 v[136:137], v[108:109], v[138:139] op_sel_hi:[1,0]
	v_cvt_pk_bf16_f32 v142, v142, v143
	v_cvt_pk_bf16_f32 v143, v144, v145
	global_store_dwordx4 v[132:133], v[140:143], off offset:256
	v_lshl_add_u64 v[132:133], v[132:133], 0, s[0:1]
	v_pk_mul_f32 v[144:145], v[76:77], v[138:139] op_sel_hi:[1,0]
	v_pk_mul_f32 v[140:141], v[106:107], v[138:139] op_sel_hi:[1,0]
	v_pk_mul_f32 v[142:143], v[74:75], v[138:139] op_sel_hi:[1,0]
	v_cvt_pk_bf16_f32 v140, v140, v141
	v_cvt_pk_bf16_f32 v141, v136, v137
	v_pk_mul_f32 v[136:137], v[42:43], v[138:139] op_sel_hi:[1,0]
	v_cvt_pk_bf16_f32 v142, v142, v143
	v_cvt_pk_bf16_f32 v143, v144, v145
	global_store_dwordx4 v[132:133], v[140:143], off
; __device__ __forceinline__ void load_row_scales(const float* ssp, int row0, int fq, float (&rs)[2][4]) {
;     ...
;     const float* sp = ssp + (size_t)row0 * 16 + 4 * fq;
; #pragma unroll
;     for (int ai = 0; ai < 2; ++ai)
; #pragma unroll
;         for (int m = 0; m < 4; ++m) part[ai][m] = *(const f32x4*)(sp + (size_t)(ai * HALF + m * 16) * 16);
; #pragma unroll
;     for (int ai = 0; ai < 2; ++ai)
; #pragma unroll
;         for (int m = 0; m < 4; ++m) { float t = (part[ai][m][0] + part[ai][m][1]) + (part[ai][m][2] + part[ai][m][3]);
;             t += __shfl_xor(t, 16); t += __shfl_xor(t, 32);
;             rs[ai][m] = 1.0f / sqrtf(t * (1.0f / 1024.0f) + 1e-6f); }
; }
;     __device__ __forceinline__ float row_rs(const float* sp) const {
;         const f32x4 a = *(const f32x4*)sp, b = *(const f32x4*)(sp + 4), c = *(const f32x4*)(sp + 8), d = *(const f32x4*)(sp + 12);
;         const float tot = ((a[0] + a[1]) + (a[2] + a[3])) + ((b[0] + b[1]) + (b[2] + b[3])) + ((c[0] + c[1]) + (c[2] + c[3])) + ((d[0] + d[1]) + (d[2] + d[3]));
;         return 1.0f / sqrtf(tot * (1.0f / 1024.0f) + 1e-6f);
;     }
;     __device__ __forceinline__ void operator()(f32x4 (&acc)[2][2][4][2], const Unit& u, int wr, int wc, int fr, int fq) const {
;         const int row0 = u.pm * BM + wr * 64 + fr;
;         const int colt = u.pn * BM + wc * 32 + 8 * fq;
;         if (u.pn >= t_lo && u.pn < t_hi) {
;             if (ssp) { float rs[2][4]; load_row_scales(ssp, row0, fq, rs);
; #pragma unroll
;                 for (int ai = 0; ai < 2; ++ai)
; #pragma unroll
;                     for (int m = 0; m < 4; ++m)
; #pragma unroll
;                         for (int bj = 0; bj < 2; ++bj)
; #pragma unroll
;                             for (int n = 0; n < 2; ++n) acc[ai][bj][m][n] = acc[ai][bj][m][n] * rs[ai][m];
;     ...
;                     for (int bj = 0; bj < 2; ++bj) { const f32x4 v0 = acc[ai][bj][m][0] * rs, v1 = acc[ai][bj][m][1] * rs;
;                         u32x4 w; w.x = cvt_pk_bf16(v0[0], v0[1]); w.y = cvt_pk_bf16(v0[2], v0[3]); w.z = cvt_pk_bf16(v1[0], v1[1]); w.w = cvt_pk_bf16(v1[2], v1[3]);
;                         *(u32x4*)(rowp + bj * HALF) = w; }
;                     rowp += (size_t)16 * ldr; asm volatile("" : "+v"(rowp) :: "memory"); }
;                 rowp += (size_t)64 * ldr; asm volatile("" : "+v"(rowp)); }
	v_cvt_pk_bf16_f32 v136, v136, v137
	s_nop 1
	v_pk_mul_f32 v[140:141], v[44:45], v[138:139] op_sel_hi:[1,0]
	v_pk_mul_f32 v[142:143], v[12:13], v[138:139] op_sel_hi:[1,0]
	v_pk_mul_f32 v[138:139], v[10:11], v[138:139] op_sel_hi:[1,0]
	v_cvt_pk_bf16_f32 v137, v140, v141
	v_lshl_add_u64 v[140:141], v[132:133], 0, s[0:1]
	v_cvt_pk_bf16_f32 v138, v138, v139
	v_cvt_pk_bf16_f32 v139, v142, v143
	global_store_dwordx4 v[132:133], v[136:139], off offset:256
	v_pk_mul_f32 v[132:133], v[104:105], v[134:135] op_sel_hi:[1,0]
	v_pk_mul_f32 v[142:143], v[72:73], v[134:135] op_sel_hi:[1,0]
	v_pk_mul_f32 v[136:137], v[102:103], v[134:135] op_sel_hi:[1,0]
	v_pk_mul_f32 v[138:139], v[70:71], v[134:135] op_sel_hi:[1,0]
	v_cvt_pk_bf16_f32 v136, v136, v137
	v_cvt_pk_bf16_f32 v137, v132, v133
	v_pk_mul_f32 v[132:133], v[38:39], v[134:135] op_sel_hi:[1,0]
	v_cvt_pk_bf16_f32 v138, v138, v139
	v_cvt_pk_bf16_f32 v139, v142, v143
	global_store_dwordx4 v[140:141], v[136:139], off
	v_cvt_pk_bf16_f32 v132, v132, v133
	s_nop 1
	v_pk_mul_f32 v[136:137], v[40:41], v[134:135] op_sel_hi:[1,0]
	v_pk_mul_f32 v[138:139], v[8:9], v[134:135] op_sel_hi:[1,0]
	v_pk_mul_f32 v[134:135], v[6:7], v[134:135] op_sel_hi:[1,0]
	v_cvt_pk_bf16_f32 v133, v136, v137
	v_lshl_add_u64 v[136:137], v[140:141], 0, s[0:1]
	v_cvt_pk_bf16_f32 v134, v134, v135
	v_cvt_pk_bf16_f32 v135, v138, v139
	global_store_dwordx4 v[140:141], v[132:135], off offset:256
	v_pk_mul_f32 v[138:139], v[68:69], v[130:131] op_sel_hi:[1,0]
	v_pk_mul_f32 v[140:141], v[66:67], v[130:131] op_sel_hi:[1,0]
	v_pk_mul_f32 v[134:135], v[100:101], v[130:131] op_sel_hi:[1,0]
	v_pk_mul_f32 v[132:133], v[98:99], v[130:131] op_sel_hi:[1,0]
	s_nop 0
	v_cvt_pk_bf16_f32 v132, v132, v133
	v_cvt_pk_bf16_f32 v133, v134, v135
	v_cvt_pk_bf16_f32 v134, v140, v141
	v_cvt_pk_bf16_f32 v135, v138, v139
	global_store_dwordx4 v[136:137], v[132:135], off
	v_pk_mul_f32 v[138:139], v[4:5], v[130:131] op_sel_hi:[1,0]
	v_pk_mul_f32 v[140:141], v[2:3], v[130:131] op_sel_hi:[1,0]
	v_pk_mul_f32 v[132:133], v[36:37], v[130:131] op_sel_hi:[1,0]
	v_pk_mul_f32 v[134:135], v[34:35], v[130:131] op_sel_hi:[1,0]
	s_nop 0
	v_cvt_pk_bf16_f32 v130, v134, v135
	v_cvt_pk_bf16_f32 v131, v132, v133
	v_cvt_pk_bf16_f32 v132, v140, v141
	v_cvt_pk_bf16_f32 v133, v138, v139
	global_store_dwordx4 v[136:137], v[130:133], off offset:256
	s_nop 1
	v_lshl_add_u64 v[130:131], v[136:137], 0, s[0:1]
	s_nop 0
	v_lshl_add_u64 v[130:131], v[130:131], 0, s[12:13]
	s_branch .LBB0_270
.LBB0_275:
	s_and_b64 vcc, exec, s[6:7]
	s_cbranch_vccnz .LBB0_277
	v_lshlrev_b64 v[130:131], 6, v[172:173]
	v_lshl_add_u64 v[130:131], v[166:167], 0, v[130:131]
	global_load_dwordx4 v[182:185], v[130:131], off
	global_load_dwordx4 v[154:157], v[130:131], off offset:1024
	global_load_dwordx4 v[150:153], v[130:131], off offset:2048
	global_load_dwordx4 v[146:149], v[130:131], off offset:3072
	v_add_co_u32_e32 v130, vcc, 0x2000, v130
	v_and_b32_e32 v175, 64, v229
	s_nop 0
	v_addc_co_u32_e32 v131, vcc, 0, v131, vcc
	v_xor_b32_e32 v0, 16, v229
	v_add_u32_e32 v180, 64, v175
	v_cmp_lt_i32_e32 vcc, v0, v180
	global_load_dwordx4 v[142:145], v[130:131], off
	global_load_dwordx4 v[138:141], v[130:131], off offset:1024
	global_load_dwordx4 v[134:137], v[130:131], off offset:2048
	s_nop 0
	global_load_dwordx4 v[130:133], v[130:131], off offset:3072
	v_cndmask_b32_e32 v0, v229, v0, vcc
	v_lshlrev_b32_e32 v175, 2, v0
	v_xor_b32_e32 v0, 32, v229
	v_cmp_lt_i32_e32 vcc, v0, v180
	s_waitcnt vmcnt(0)
	s_mov_b32 s100, 1
	v_mov_b32_e32 v188, v183
	v_mov_b32_e32 v189, v184
	v_mov_b32_e32 v183, v185
	v_cndmask_b32_e32 v0, v229, v0, vcc
	v_pk_add_f32 v[182:183], v[188:189], v[182:183]
	v_lshlrev_b32_e32 v180, 2, v0
	v_add_f32_e32 v0, v182, v183
	v_mov_b32_e32 v181, v0
	s_nop 1
	v_permlane16_swap_b32_e32 v181, v0
	s_waitcnt lgkmcnt(0)
	v_add_f32_e32 v0, v0, v181
	v_mov_b32_e32 v181, v0
	s_nop 1
	v_permlane32_swap_b32_e32 v181, v0
	s_waitcnt lgkmcnt(0)
	v_add_f32_e32 v0, v0, v181
	v_fmamk_f32 v0, v0, 0x3a800000, v230
	v_mov_b32_e32 v182, v155
	v_mov_b32_e32 v183, v156
	v_mov_b32_e32 v155, v157
	v_pk_add_f32 v[154:155], v[182:183], v[154:155]
	v_rsq_f32_e32 v0, v0
	s_nop 0
	v_add_f32_e32 v154, v154, v155
	v_mov_b32_e32 v155, v154
	s_nop 1
	v_permlane16_swap_b32_e32 v155, v154
	v_pk_mul_f32 v[128:129], v[128:129], v[0:1] op_sel_hi:[1,0]
	v_pk_mul_f32 v[126:127], v[126:127], v[0:1] op_sel_hi:[1,0]
	v_pk_mul_f32 v[96:97], v[96:97], v[0:1] op_sel_hi:[1,0]
	v_pk_mul_f32 v[94:95], v[94:95], v[0:1] op_sel_hi:[1,0]
	s_waitcnt lgkmcnt(0)
	v_add_f32_e32 v154, v154, v155
	v_mov_b32_e32 v155, v154
	s_nop 1
	v_permlane32_swap_b32_e32 v155, v154
	v_pk_mul_f32 v[64:65], v[64:65], v[0:1] op_sel_hi:[1,0]
	v_pk_mul_f32 v[62:63], v[62:63], v[0:1] op_sel_hi:[1,0]
	v_pk_mul_f32 v[32:33], v[32:33], v[0:1] op_sel_hi:[1,0]
	v_pk_mul_f32 v[30:31], v[30:31], v[0:1] op_sel_hi:[1,0]
	s_waitcnt lgkmcnt(0)
	v_add_f32_e32 v154, v154, v155
	v_fmamk_f32 v154, v154, 0x3a800000, v230
	v_mov_b32_e32 v156, v151
	v_mov_b32_e32 v157, v152
	v_mov_b32_e32 v151, v153
	v_pk_add_f32 v[150:151], v[156:157], v[150:151]
	v_rsq_f32_e32 v154, v154
	s_nop 0
	v_add_f32_e32 v150, v150, v151
	v_mov_b32_e32 v151, v150
	s_nop 1
	v_permlane16_swap_b32_e32 v151, v150
	s_waitcnt lgkmcnt(0)
	v_add_f32_e32 v150, v150, v151
	v_mov_b32_e32 v151, v150
	s_nop 1
	v_permlane32_swap_b32_e32 v151, v150
	s_waitcnt lgkmcnt(0)
; __device__ __forceinline__ void load_row_scales(const float* ssp, int row0, int fq, float (&rs)[2][4]) {
;     ...
;         for (int m = 0; m < 4; ++m) { float t = (part[ai][m][0] + part[ai][m][1]) + (part[ai][m][2] + part[ai][m][3]);
;             t += __shfl_xor(t, 16); t += __shfl_xor(t, 32);
;             rs[ai][m] = 1.0f / sqrtf(t * (1.0f / 1024.0f) + 1e-6f); }
;     __device__ __forceinline__ void operator()(f32x4 (&acc)[2][2][4][2], const Unit& u, int wr, int wc, int fr, int fq) const {
;     ...
;                 for (int ai = 0; ai < 2; ++ai)
; #pragma unroll
;                     for (int m = 0; m < 4; ++m)
; #pragma unroll
;                         for (int bj = 0; bj < 2; ++bj)
; #pragma unroll
;                             for (int n = 0; n < 2; ++n) acc[ai][bj][m][n] = acc[ai][bj][m][n] * rs[ai][m];
	v_add_f32_e32 v150, v150, v151
	v_fmamk_f32 v150, v150, 0x3a800000, v230
	v_mov_b32_e32 v152, v147
	v_mov_b32_e32 v153, v148
	v_mov_b32_e32 v147, v149
	v_pk_add_f32 v[146:147], v[152:153], v[146:147]
	v_rsq_f32_e32 v150, v150
	s_nop 0
	v_add_f32_e32 v146, v146, v147
	v_mov_b32_e32 v147, v146
	s_nop 1
	v_permlane16_swap_b32_e32 v147, v146
	v_pk_mul_f32 v[124:125], v[124:125], v[154:155] op_sel_hi:[1,0]
	v_pk_mul_f32 v[122:123], v[122:123], v[154:155] op_sel_hi:[1,0]
	v_pk_mul_f32 v[92:93], v[92:93], v[154:155] op_sel_hi:[1,0]
	v_pk_mul_f32 v[90:91], v[90:91], v[154:155] op_sel_hi:[1,0]
	s_waitcnt lgkmcnt(0)
	v_add_f32_e32 v146, v146, v147
	v_mov_b32_e32 v147, v146
	s_nop 1
	v_permlane32_swap_b32_e32 v147, v146
	v_pk_mul_f32 v[60:61], v[60:61], v[154:155] op_sel_hi:[1,0]
	v_pk_mul_f32 v[58:59], v[58:59], v[154:155] op_sel_hi:[1,0]
	v_pk_mul_f32 v[28:29], v[28:29], v[154:155] op_sel_hi:[1,0]
	v_pk_mul_f32 v[26:27], v[26:27], v[154:155] op_sel_hi:[1,0]
	s_waitcnt lgkmcnt(0)
	v_add_f32_e32 v146, v146, v147
	v_fmamk_f32 v146, v146, 0x3a800000, v230
	v_mov_b32_e32 v148, v143
	v_mov_b32_e32 v149, v144
	v_mov_b32_e32 v143, v145
	v_pk_add_f32 v[142:143], v[148:149], v[142:143]
	v_rsq_f32_e32 v146, v146
	s_nop 0
	v_add_f32_e32 v142, v142, v143
	v_mov_b32_e32 v143, v142
	s_nop 1
	v_permlane16_swap_b32_e32 v143, v142
	v_pk_mul_f32 v[120:121], v[120:121], v[150:151] op_sel_hi:[1,0]
	v_pk_mul_f32 v[118:119], v[118:119], v[150:151] op_sel_hi:[1,0]
	v_pk_mul_f32 v[88:89], v[88:89], v[150:151] op_sel_hi:[1,0]
	v_pk_mul_f32 v[86:87], v[86:87], v[150:151] op_sel_hi:[1,0]
	s_waitcnt lgkmcnt(0)
	v_add_f32_e32 v142, v142, v143
	v_mov_b32_e32 v143, v142
	s_nop 1
	v_permlane32_swap_b32_e32 v143, v142
	v_pk_mul_f32 v[56:57], v[56:57], v[150:151] op_sel_hi:[1,0]
	v_pk_mul_f32 v[54:55], v[54:55], v[150:151] op_sel_hi:[1,0]
	v_pk_mul_f32 v[24:25], v[24:25], v[150:151] op_sel_hi:[1,0]
	v_pk_mul_f32 v[22:23], v[22:23], v[150:151] op_sel_hi:[1,0]
	s_waitcnt lgkmcnt(0)
	v_add_f32_e32 v142, v142, v143
	v_fmamk_f32 v142, v142, 0x3a800000, v230
	v_mov_b32_e32 v144, v139
	v_mov_b32_e32 v145, v140
	v_mov_b32_e32 v139, v141
	v_pk_add_f32 v[138:139], v[144:145], v[138:139]
	v_rsq_f32_e32 v142, v142
	s_nop 0
	v_add_f32_e32 v138, v138, v139
	v_mov_b32_e32 v139, v138
	s_nop 1
	v_permlane16_swap_b32_e32 v139, v138
	v_pk_mul_f32 v[116:117], v[116:117], v[146:147] op_sel_hi:[1,0]
	v_pk_mul_f32 v[114:115], v[114:115], v[146:147] op_sel_hi:[1,0]
	v_pk_mul_f32 v[84:85], v[84:85], v[146:147] op_sel_hi:[1,0]
	v_pk_mul_f32 v[82:83], v[82:83], v[146:147] op_sel_hi:[1,0]
	s_waitcnt lgkmcnt(0)
	v_add_f32_e32 v138, v138, v139
	v_mov_b32_e32 v139, v138
	s_nop 1
	v_permlane32_swap_b32_e32 v139, v138
	v_pk_mul_f32 v[52:53], v[52:53], v[146:147] op_sel_hi:[1,0]
	v_pk_mul_f32 v[50:51], v[50:51], v[146:147] op_sel_hi:[1,0]
	v_pk_mul_f32 v[20:21], v[20:21], v[146:147] op_sel_hi:[1,0]
	v_pk_mul_f32 v[18:19], v[18:19], v[146:147] op_sel_hi:[1,0]
	s_waitcnt lgkmcnt(0)
	v_add_f32_e32 v138, v138, v139
	v_fmamk_f32 v138, v138, 0x3a800000, v230
	v_mov_b32_e32 v140, v135
	v_mov_b32_e32 v141, v136
	v_mov_b32_e32 v135, v137
	v_pk_add_f32 v[134:135], v[140:141], v[134:135]
	v_rsq_f32_e32 v138, v138
	s_nop 0
	v_add_f32_e32 v134, v134, v135
	v_mov_b32_e32 v135, v134
	s_nop 1
	v_permlane16_swap_b32_e32 v135, v134
	v_pk_mul_f32 v[112:113], v[112:113], v[142:143] op_sel_hi:[1,0]
	v_pk_mul_f32 v[110:111], v[110:111], v[142:143] op_sel_hi:[1,0]
	v_pk_mul_f32 v[80:81], v[80:81], v[142:143] op_sel_hi:[1,0]
	v_pk_mul_f32 v[78:79], v[78:79], v[142:143] op_sel_hi:[1,0]
	s_waitcnt lgkmcnt(0)
	v_add_f32_e32 v134, v134, v135
	v_mov_b32_e32 v135, v134
	s_nop 1
	v_permlane32_swap_b32_e32 v135, v134
	v_pk_mul_f32 v[48:49], v[48:49], v[142:143] op_sel_hi:[1,0]
	v_pk_mul_f32 v[46:47], v[46:47], v[142:143] op_sel_hi:[1,0]
	v_pk_mul_f32 v[16:17], v[16:17], v[142:143] op_sel_hi:[1,0]
	v_pk_mul_f32 v[14:15], v[14:15], v[142:143] op_sel_hi:[1,0]
	s_waitcnt lgkmcnt(0)
	v_add_f32_e32 v134, v134, v135
	v_fmamk_f32 v134, v134, 0x3a800000, v230
	v_mov_b32_e32 v136, v131
	v_mov_b32_e32 v137, v132
	v_mov_b32_e32 v131, v133
	v_pk_add_f32 v[130:131], v[136:137], v[130:131]
	v_rsq_f32_e32 v134, v134
	s_nop 0
	v_add_f32_e32 v130, v130, v131
	v_mov_b32_e32 v131, v130
	s_nop 1
	v_permlane16_swap_b32_e32 v131, v130
	v_pk_mul_f32 v[108:109], v[108:109], v[138:139] op_sel_hi:[1,0]
	v_pk_mul_f32 v[106:107], v[106:107], v[138:139] op_sel_hi:[1,0]
	v_pk_mul_f32 v[76:77], v[76:77], v[138:139] op_sel_hi:[1,0]
	v_pk_mul_f32 v[74:75], v[74:75], v[138:139] op_sel_hi:[1,0]
	s_waitcnt lgkmcnt(0)
	v_add_f32_e32 v130, v130, v131
	v_mov_b32_e32 v131, v130
	s_nop 1
	v_permlane32_swap_b32_e32 v131, v130
	v_pk_mul_f32 v[44:45], v[44:45], v[138:139] op_sel_hi:[1,0]
	v_pk_mul_f32 v[42:43], v[42:43], v[138:139] op_sel_hi:[1,0]
	v_pk_mul_f32 v[12:13], v[12:13], v[138:139] op_sel_hi:[1,0]
	v_pk_mul_f32 v[10:11], v[10:11], v[138:139] op_sel_hi:[1,0]
	s_waitcnt lgkmcnt(0)
	v_add_f32_e32 v130, v130, v131
	v_fmamk_f32 v130, v130, 0x3a800000, v230
	v_rsq_f32_e32 v130, v130
	s_nop 0
	v_pk_mul_f32 v[104:105], v[104:105], v[134:135] op_sel_hi:[1,0]
	v_pk_mul_f32 v[102:103], v[102:103], v[134:135] op_sel_hi:[1,0]
	v_pk_mul_f32 v[72:73], v[72:73], v[134:135] op_sel_hi:[1,0]
	v_pk_mul_f32 v[70:71], v[70:71], v[134:135] op_sel_hi:[1,0]
	v_pk_mul_f32 v[40:41], v[40:41], v[134:135] op_sel_hi:[1,0]
	v_pk_mul_f32 v[38:39], v[38:39], v[134:135] op_sel_hi:[1,0]
	v_pk_mul_f32 v[8:9], v[8:9], v[134:135] op_sel_hi:[1,0]
	v_pk_mul_f32 v[6:7], v[6:7], v[134:135] op_sel_hi:[1,0]
	v_pk_mul_f32 v[100:101], v[100:101], v[130:131] op_sel_hi:[1,0]
	v_pk_mul_f32 v[98:99], v[98:99], v[130:131] op_sel_hi:[1,0]
	v_pk_mul_f32 v[68:69], v[68:69], v[130:131] op_sel_hi:[1,0]
	v_pk_mul_f32 v[66:67], v[66:67], v[130:131] op_sel_hi:[1,0]
	v_pk_mul_f32 v[36:37], v[36:37], v[130:131] op_sel_hi:[1,0]
	v_pk_mul_f32 v[34:35], v[34:35], v[130:131] op_sel_hi:[1,0]
	v_pk_mul_f32 v[4:5], v[4:5], v[130:131] op_sel_hi:[1,0]
	v_pk_mul_f32 v[2:3], v[2:3], v[130:131] op_sel_hi:[1,0]
; __device__ __forceinline__ unsigned cvt_pk_bf16(float lo, float hi) { unsigned r; asm volatile("v_cvt_pk_bf16_f32 %0, %1, %2" : "=v"(r) : "v"(lo), "v"(hi)); return r; }
;     __device__ __forceinline__ void operator()(f32x4 (&acc)[2][2][4][2], const Unit& u, int wr, int wc, int fr, int fq) const {
;     ...
;             bf16_t* tp = T + (size_t)(colt - t_col0) * ldt + row0;
; #pragma unroll
;             for (int bj = 0; bj < 2; ++bj) {
; #pragma unroll
;                 for (int n = 0; n < 2; ++n)
; #pragma unroll
;                     for (int j = 0; j < 4; ++j) {
; #pragma unroll
;                         for (int ai = 0; ai < 2; ++ai)
; #pragma unroll
;                             for (int m = 0; m < 4; ++m) tp[ai * HALF + m * 16] = (bf16_t)(cvt_pk_bf16(acc[ai][bj][m][n][j], 0.f) & 0xffffu);
;                         tp += ldt; asm volatile("" : "+v"(tp)); }
;                 tp += (size_t)120 * ldt; asm volatile("" : "+v"(tp)); }
.LBB0_277:
	v_lshlrev_b32_e32 v0, 17, v174
	v_lshl_add_u64 v[130:131], s[18:19], 0, v[0:1]
	v_lshl_add_u64 v[130:131], v[172:173], 1, v[130:131]
	v_cvt_pk_bf16_f32 v0, v126, v1
	global_store_short v[130:131], v0, off
	v_cvt_pk_bf16_f32 v0, v122, v1
	global_store_short v[130:131], v0, off offset:32
	v_cvt_pk_bf16_f32 v0, v118, v1
	global_store_short v[130:131], v0, off offset:64
	v_cvt_pk_bf16_f32 v0, v114, v1
	global_store_short v[130:131], v0, off offset:96
	v_cvt_pk_bf16_f32 v0, v110, v1
	global_store_short v[130:131], v0, off offset:256
	v_cvt_pk_bf16_f32 v0, v106, v1
	global_store_short v[130:131], v0, off offset:288
	v_cvt_pk_bf16_f32 v0, v102, v1
	s_mov_b64 s[0:1], 0x20000
	global_store_short v[130:131], v0, off offset:320
	v_cvt_pk_bf16_f32 v0, v98, v1
	global_store_short v[130:131], v0, off offset:352
	v_lshl_add_u64 v[130:131], v[130:131], 0, s[0:1]
	v_cvt_pk_bf16_f32 v0, v127, v1
	global_store_short v[130:131], v0, off
	v_cvt_pk_bf16_f32 v0, v123, v1
	global_store_short v[130:131], v0, off offset:32
	v_cvt_pk_bf16_f32 v0, v119, v1
	global_store_short v[130:131], v0, off offset:64
	v_cvt_pk_bf16_f32 v0, v115, v1
	global_store_short v[130:131], v0, off offset:96
	v_cvt_pk_bf16_f32 v0, v111, v1
	global_store_short v[130:131], v0, off offset:256
	v_cvt_pk_bf16_f32 v0, v107, v1
	global_store_short v[130:131], v0, off offset:288
	v_cvt_pk_bf16_f32 v0, v103, v1
	global_store_short v[130:131], v0, off offset:320
	v_cvt_pk_bf16_f32 v0, v99, v1
	v_lshl_add_u64 v[98:99], v[130:131], 0, s[0:1]
	global_store_short v[130:131], v0, off offset:352
	v_cvt_pk_bf16_f32 v0, v128, v1
	global_store_short v[98:99], v0, off
	v_cvt_pk_bf16_f32 v0, v124, v1
	global_store_short v[98:99], v0, off offset:32
	v_cvt_pk_bf16_f32 v0, v120, v1
	global_store_short v[98:99], v0, off offset:64
	v_cvt_pk_bf16_f32 v0, v116, v1
	global_store_short v[98:99], v0, off offset:96
	v_cvt_pk_bf16_f32 v0, v112, v1
	global_store_short v[98:99], v0, off offset:256
	v_cvt_pk_bf16_f32 v0, v108, v1
	global_store_short v[98:99], v0, off offset:288
	v_cvt_pk_bf16_f32 v0, v104, v1
	global_store_short v[98:99], v0, off offset:320
	v_cvt_pk_bf16_f32 v0, v100, v1
	global_store_short v[98:99], v0, off offset:352
	v_lshl_add_u64 v[98:99], v[98:99], 0, s[0:1]
	v_cvt_pk_bf16_f32 v0, v129, v1
	global_store_short v[98:99], v0, off
	v_cvt_pk_bf16_f32 v0, v125, v1
	global_store_short v[98:99], v0, off offset:32
	v_cvt_pk_bf16_f32 v0, v121, v1
	global_store_short v[98:99], v0, off offset:64
	v_cvt_pk_bf16_f32 v0, v117, v1
	global_store_short v[98:99], v0, off offset:96
	v_cvt_pk_bf16_f32 v0, v113, v1
	global_store_short v[98:99], v0, off offset:256
	v_cvt_pk_bf16_f32 v0, v109, v1
	global_store_short v[98:99], v0, off offset:288
	v_cvt_pk_bf16_f32 v0, v105, v1
	global_store_short v[98:99], v0, off offset:320
	v_cvt_pk_bf16_f32 v0, v101, v1
	global_store_short v[98:99], v0, off offset:352
	v_lshl_add_u64 v[98:99], v[98:99], 0, s[0:1]
	v_cvt_pk_bf16_f32 v0, v94, v1
	global_store_short v[98:99], v0, off
	v_cvt_pk_bf16_f32 v0, v90, v1
	global_store_short v[98:99], v0, off offset:32
	v_cvt_pk_bf16_f32 v0, v86, v1
	global_store_short v[98:99], v0, off offset:64
	v_cvt_pk_bf16_f32 v0, v82, v1
	global_store_short v[98:99], v0, off offset:96
	v_cvt_pk_bf16_f32 v0, v78, v1
	global_store_short v[98:99], v0, off offset:256
	v_cvt_pk_bf16_f32 v0, v74, v1
	global_store_short v[98:99], v0, off offset:288
	v_cvt_pk_bf16_f32 v0, v70, v1
	global_store_short v[98:99], v0, off offset:320
	v_cvt_pk_bf16_f32 v0, v66, v1
	global_store_short v[98:99], v0, off offset:352
	v_lshl_add_u64 v[98:99], v[98:99], 0, s[0:1]
	v_cvt_pk_bf16_f32 v0, v95, v1
	global_store_short v[98:99], v0, off
	v_cvt_pk_bf16_f32 v0, v91, v1
	global_store_short v[98:99], v0, off offset:32
	v_cvt_pk_bf16_f32 v0, v87, v1
	global_store_short v[98:99], v0, off offset:64
	v_cvt_pk_bf16_f32 v0, v83, v1
	global_store_short v[98:99], v0, off offset:96
	v_cvt_pk_bf16_f32 v0, v79, v1
	global_store_short v[98:99], v0, off offset:256
	v_cvt_pk_bf16_f32 v0, v75, v1
	global_store_short v[98:99], v0, off offset:288
	v_cvt_pk_bf16_f32 v0, v71, v1
	global_store_short v[98:99], v0, off offset:320
	v_cvt_pk_bf16_f32 v0, v67, v1
	v_lshl_add_u64 v[66:67], v[98:99], 0, s[0:1]
	global_store_short v[98:99], v0, off offset:352
	v_cvt_pk_bf16_f32 v0, v96, v1
	global_store_short v[66:67], v0, off
	v_cvt_pk_bf16_f32 v0, v92, v1
	global_store_short v[66:67], v0, off offset:32
	v_cvt_pk_bf16_f32 v0, v88, v1
	global_store_short v[66:67], v0, off offset:64
	v_cvt_pk_bf16_f32 v0, v84, v1
	global_store_short v[66:67], v0, off offset:96
	v_cvt_pk_bf16_f32 v0, v80, v1
	global_store_short v[66:67], v0, off offset:256
	v_cvt_pk_bf16_f32 v0, v76, v1
	global_store_short v[66:67], v0, off offset:288
	v_cvt_pk_bf16_f32 v0, v72, v1
	global_store_short v[66:67], v0, off offset:320
	v_cvt_pk_bf16_f32 v0, v68, v1
	global_store_short v[66:67], v0, off offset:352
	v_lshl_add_u64 v[66:67], v[66:67], 0, s[0:1]
	v_cvt_pk_bf16_f32 v0, v97, v1
	global_store_short v[66:67], v0, off
	v_cvt_pk_bf16_f32 v0, v93, v1
	global_store_short v[66:67], v0, off offset:32
	v_cvt_pk_bf16_f32 v0, v89, v1
	global_store_short v[66:67], v0, off offset:64
	v_cvt_pk_bf16_f32 v0, v85, v1
	global_store_short v[66:67], v0, off offset:96
	v_cvt_pk_bf16_f32 v0, v81, v1
	global_store_short v[66:67], v0, off offset:256
	v_cvt_pk_bf16_f32 v0, v77, v1
	global_store_short v[66:67], v0, off offset:288
	v_cvt_pk_bf16_f32 v0, v73, v1
	global_store_short v[66:67], v0, off offset:320
	v_cvt_pk_bf16_f32 v0, v69, v1
	global_store_short v[66:67], v0, off offset:352
; __device__ __forceinline__ unsigned cvt_pk_bf16(float lo, float hi) { unsigned r; asm volatile("v_cvt_pk_bf16_f32 %0, %1, %2" : "=v"(r) : "v"(lo), "v"(hi)); return r; }
;     __device__ __forceinline__ void operator()(f32x4 (&acc)[2][2][4][2], const Unit& u, int wr, int wc, int fr, int fq) const {
;     ...
;             bf16_t* tp = T + (size_t)(colt - t_col0) * ldt + row0;
; #pragma unroll
;             for (int bj = 0; bj < 2; ++bj) {
; #pragma unroll
;                 for (int n = 0; n < 2; ++n)
; #pragma unroll
;                     for (int j = 0; j < 4; ++j) {
; #pragma unroll
;                         for (int ai = 0; ai < 2; ++ai)
; #pragma unroll
;                             for (int m = 0; m < 4; ++m) tp[ai * HALF + m * 16] = (bf16_t)(cvt_pk_bf16(acc[ai][bj][m][n][j], 0.f) & 0xffffu);
;                         tp += ldt; asm volatile("" : "+v"(tp)); }
;                 tp += (size_t)120 * ldt; asm volatile("" : "+v"(tp)); }
	v_lshl_add_u64 v[66:67], v[66:67], 0, s[0:1]
	s_mov_b64 s[6:7], 0xf00000
	v_lshl_add_u64 v[66:67], v[66:67], 0, s[6:7]
	v_cvt_pk_bf16_f32 v0, v62, v1
	global_store_short v[66:67], v0, off
	v_cvt_pk_bf16_f32 v0, v58, v1
	global_store_short v[66:67], v0, off offset:32
	v_cvt_pk_bf16_f32 v0, v54, v1
	global_store_short v[66:67], v0, off offset:64
	v_cvt_pk_bf16_f32 v0, v50, v1
	global_store_short v[66:67], v0, off offset:96
	v_cvt_pk_bf16_f32 v0, v46, v1
	global_store_short v[66:67], v0, off offset:256
	v_cvt_pk_bf16_f32 v0, v42, v1
	global_store_short v[66:67], v0, off offset:288
	v_cvt_pk_bf16_f32 v0, v38, v1
	global_store_short v[66:67], v0, off offset:320
	v_cvt_pk_bf16_f32 v0, v34, v1
	global_store_short v[66:67], v0, off offset:352
	v_lshl_add_u64 v[66:67], v[66:67], 0, s[0:1]
	v_cvt_pk_bf16_f32 v0, v63, v1
	global_store_short v[66:67], v0, off
	v_cvt_pk_bf16_f32 v0, v59, v1
	global_store_short v[66:67], v0, off offset:32
	v_cvt_pk_bf16_f32 v0, v55, v1
	global_store_short v[66:67], v0, off offset:64
	v_cvt_pk_bf16_f32 v0, v51, v1
	global_store_short v[66:67], v0, off offset:96
	v_cvt_pk_bf16_f32 v0, v47, v1
	global_store_short v[66:67], v0, off offset:256
	v_cvt_pk_bf16_f32 v0, v43, v1
	global_store_short v[66:67], v0, off offset:288
	v_cvt_pk_bf16_f32 v0, v39, v1
	global_store_short v[66:67], v0, off offset:320
	v_cvt_pk_bf16_f32 v0, v35, v1
	v_lshl_add_u64 v[34:35], v[66:67], 0, s[0:1]
	global_store_short v[66:67], v0, off offset:352
	v_cvt_pk_bf16_f32 v0, v64, v1
	global_store_short v[34:35], v0, off
	v_cvt_pk_bf16_f32 v0, v60, v1
	global_store_short v[34:35], v0, off offset:32
	v_cvt_pk_bf16_f32 v0, v56, v1
	global_store_short v[34:35], v0, off offset:64
	v_cvt_pk_bf16_f32 v0, v52, v1
	global_store_short v[34:35], v0, off offset:96
	v_cvt_pk_bf16_f32 v0, v48, v1
	global_store_short v[34:35], v0, off offset:256
	v_cvt_pk_bf16_f32 v0, v44, v1
	global_store_short v[34:35], v0, off offset:288
	v_cvt_pk_bf16_f32 v0, v40, v1
	global_store_short v[34:35], v0, off offset:320
	v_cvt_pk_bf16_f32 v0, v36, v1
	global_store_short v[34:35], v0, off offset:352
	v_lshl_add_u64 v[34:35], v[34:35], 0, s[0:1]
	v_cvt_pk_bf16_f32 v0, v65, v1
	global_store_short v[34:35], v0, off
	v_cvt_pk_bf16_f32 v0, v61, v1
	global_store_short v[34:35], v0, off offset:32
	v_cvt_pk_bf16_f32 v0, v57, v1
	global_store_short v[34:35], v0, off offset:64
	v_cvt_pk_bf16_f32 v0, v53, v1
	global_store_short v[34:35], v0, off offset:96
	v_cvt_pk_bf16_f32 v0, v49, v1
	global_store_short v[34:35], v0, off offset:256
	v_cvt_pk_bf16_f32 v0, v45, v1
	global_store_short v[34:35], v0, off offset:288
	v_cvt_pk_bf16_f32 v0, v41, v1
	global_store_short v[34:35], v0, off offset:320
	v_cvt_pk_bf16_f32 v0, v37, v1
	global_store_short v[34:35], v0, off offset:352
	v_lshl_add_u64 v[34:35], v[34:35], 0, s[0:1]
	v_cvt_pk_bf16_f32 v0, v30, v1
	global_store_short v[34:35], v0, off
	v_cvt_pk_bf16_f32 v0, v26, v1
	global_store_short v[34:35], v0, off offset:32
	v_cvt_pk_bf16_f32 v0, v22, v1
	global_store_short v[34:35], v0, off offset:64
	v_cvt_pk_bf16_f32 v0, v18, v1
	global_store_short v[34:35], v0, off offset:96
	v_cvt_pk_bf16_f32 v0, v14, v1
	global_store_short v[34:35], v0, off offset:256
	v_cvt_pk_bf16_f32 v0, v10, v1
	global_store_short v[34:35], v0, off offset:288
	v_cvt_pk_bf16_f32 v0, v6, v1
	global_store_short v[34:35], v0, off offset:320
	v_cvt_pk_bf16_f32 v0, v2, v1
	global_store_short v[34:35], v0, off offset:352
	v_lshl_add_u64 v[34:35], v[34:35], 0, s[0:1]
	v_cvt_pk_bf16_f32 v0, v31, v1
	global_store_short v[34:35], v0, off
	v_cvt_pk_bf16_f32 v0, v27, v1
	global_store_short v[34:35], v0, off offset:32
	v_cvt_pk_bf16_f32 v0, v23, v1
	global_store_short v[34:35], v0, off offset:64
	v_cvt_pk_bf16_f32 v0, v19, v1
	global_store_short v[34:35], v0, off offset:96
	v_cvt_pk_bf16_f32 v0, v15, v1
	global_store_short v[34:35], v0, off offset:256
	v_cvt_pk_bf16_f32 v0, v11, v1
	global_store_short v[34:35], v0, off offset:288
	v_cvt_pk_bf16_f32 v0, v7, v1
	global_store_short v[34:35], v0, off offset:320
	v_cvt_pk_bf16_f32 v0, v3, v1
	v_lshl_add_u64 v[2:3], v[34:35], 0, s[0:1]
	global_store_short v[34:35], v0, off offset:352
	v_cvt_pk_bf16_f32 v0, v32, v1
	global_store_short v[2:3], v0, off
	v_cvt_pk_bf16_f32 v0, v28, v1
	global_store_short v[2:3], v0, off offset:32
	v_cvt_pk_bf16_f32 v0, v24, v1
	global_store_short v[2:3], v0, off offset:64
	v_cvt_pk_bf16_f32 v0, v20, v1
	global_store_short v[2:3], v0, off offset:96
	v_cvt_pk_bf16_f32 v0, v16, v1
	global_store_short v[2:3], v0, off offset:256
	v_cvt_pk_bf16_f32 v0, v12, v1
	global_store_short v[2:3], v0, off offset:288
	v_cvt_pk_bf16_f32 v0, v8, v1
	global_store_short v[2:3], v0, off offset:320
	v_cvt_pk_bf16_f32 v0, v4, v1
	global_store_short v[2:3], v0, off offset:352
	v_lshl_add_u64 v[2:3], v[2:3], 0, s[0:1]
	v_cvt_pk_bf16_f32 v0, v33, v1
	global_store_short v[2:3], v0, off
	v_cvt_pk_bf16_f32 v0, v29, v1
	global_store_short v[2:3], v0, off offset:32
	v_cvt_pk_bf16_f32 v0, v25, v1
	global_store_short v[2:3], v0, off offset:64
	v_cvt_pk_bf16_f32 v0, v21, v1
	global_store_short v[2:3], v0, off offset:96
	v_cvt_pk_bf16_f32 v0, v17, v1
	global_store_short v[2:3], v0, off offset:256
	v_cvt_pk_bf16_f32 v0, v13, v1
	global_store_short v[2:3], v0, off offset:288
	v_cvt_pk_bf16_f32 v0, v9, v1
	global_store_short v[2:3], v0, off offset:320
	v_cvt_pk_bf16_f32 v0, v5, v1
	global_store_short v[2:3], v0, off offset:352
	v_lshl_add_u64 v[2:3], v[2:3], 0, s[0:1]
	s_nop 0
	v_lshl_add_u64 v[2:3], v[2:3], 0, s[6:7]
	s_andn2_b64 vcc, exec, s[4:5]
	s_mov_b64 s[0:1], -1
	s_cbranch_vccnz .LBB0_261

; #define PG8_STAGE(bufoff, gbase, voff) do { _Pragma("unroll") for (int _i = 0; _i < 2; ++_i) \
;         __builtin_amdgcn_global_load_lds((const unsigned*)((const char*)(gbase) + (voff)[_i]), (PG8_LAS unsigned*)(lds + (bufoff) + ldsw + _i * 8192), 16, 0, 0); } while (0)
; #define PG8_WAIT_V(n) asm volatile("s_waitcnt vmcnt(" #n ")" ::: "memory")
; #define PG8_BAR __builtin_amdgcn_s_barrier()
; template <class Epi, class Sched, bool ALIGN_EPI = false, bool SP2 = false>
; __device__ __forceinline__ void gemm_phase(PG8_LAS unsigned char* lds, const Gemm g, const Sched& S, const Epi& E) {
;     ...
;     for (int i = 0; i < 2; ++i) { int R, C; stage_rc(tid * 16 + i * 8192, R, C); const int Rb = Epi::PERM ? ((R & ~31) + perm32(R & 31)) : R;
;         voffA[i] = (unsigned)(R * K + C) * 2u; voffB[i] = (unsigned)(Rb * K + C) * 2u; }
;     const size_t kstep = (size_t)(BK * 2);
;     const size_t hstep = (size_t)HALF * K * 2;
;     const size_t tstep = 2 * hstep;
;     const unsigned ldsw = (unsigned)wid * 1024u;
;     const int aoff = lds_byte(wr * 64 + fr, fq * 8), boff = lds_byte(wc * 32 + fr, fq * 8);
;     ...
;         PG8_STAGE(PG8_SB(0, 0), cB, voffB); PG8_STAGE(PG8_SB(0, 1), cB + hstep, voffB); PG8_STAGE(PG8_SA(0, 0), cA, voffA); PG8_STAGE(PG8_SA(0, 1), cA + hstep, voffA);
;         if (wr == 1) PG8_BAR;
;         PG8_WAIT_V(2); PG8_BAR;
;         PG8_STAGE(PG8_SB(1, 0), cB + kstep, voffB); PG8_STAGE(PG8_SA(1, 0), cA + kstep, voffA); PG8_STAGE(PG8_SB(1, 1), cB + hstep + kstep, voffB);
;         PG8_WAIT_V(6); PG8_BAR;
.LBB0_1026:
	v_bfe_u32 v20, v10, 4, 2
	v_and_b32_e32 v11, 15, v10
	v_lshlrev_b32_e32 v21, 4, v20
	v_lshlrev_b32_e32 v10, 2, v10
	s_and_b32 s90, s6, 3
	v_lshl_or_b32 v172, s5, 6, v11
	v_lshl_or_b32 v11, v11, 6, v21
	s_lshl_b32 s5, s5, 13
	v_and_b32_e32 v10, 32, v10
	v_lshl_add_u64 v[12:13], s[80:81], 0, v[0:1]
	v_mov_b32_e32 v131, v1
	v_readlane_b32 s78, v254, 61
	v_bitop3_b32 v21, v11, s5, v10 bitop3:0xde
	s_lshl_b32 s5, s90, 12
	v_lshl_add_u64 v[14:15], s[80:81], 0, v[130:131]
	v_readlane_b32 s79, v254, 62
	v_bitop3_b32 v173, v11, s5, v10 bitop3:0xde
	s_add_i32 m0, s62, 0x18000
	v_lshl_add_u64 v[10:11], v[12:13], 0, s[60:61]
	v_lshl_add_u64 v[16:17], s[78:79], 0, v[0:1]
	s_waitcnt vmcnt(2)
	s_barrier
	global_load_lds_dwordx4 v[10:11], off
	v_lshl_add_u64 v[10:11], v[14:15], 0, s[60:61]
	s_add_i32 m0, s62, 0x1a000
	s_add_i32 s94, s62, 0x8000
	s_add_i32 s95, s62, 0xa000
	v_lshl_add_u64 v[18:19], s[78:79], 0, v[130:131]
	global_load_lds_dwordx4 v[10:11], off
	v_lshl_add_u64 v[10:11], v[16:17], 0, s[60:61]
	s_mov_b32 m0, s94
	s_add_u32 s6, s80, 0x40080
	global_load_lds_dwordx4 v[10:11], off
	v_lshl_add_u64 v[10:11], v[18:19], 0, s[60:61]
	s_mov_b32 m0, s95
	s_addc_u32 s7, s81, 0
	global_load_lds_dwordx4 v[10:11], off
	s_add_i32 m0, s62, 0x1c000
	v_lshl_add_u64 v[10:11], s[6:7], 0, v[0:1]
	global_load_lds_dwordx4 v[10:11], off
	v_lshl_add_u64 v[10:11], s[6:7], 0, v[130:131]
	s_add_i32 m0, s62, 0x1e000
	v_lshlrev_b32_e32 v7, 13, v7
	global_load_lds_dwordx4 v[10:11], off
	v_lshlrev_b32_e32 v2, 13, v2
	v_and_b32_e32 v7, 0x7fffc000, v7
	v_and_b32_e32 v2, 0x7fffc000, v2
	v_lshl_add_u32 v6, v6, 10, v7
	v_lshl_add_u32 v2, v3, 10, v2
	v_or_b32_e32 v6, v6, v8
	v_or_b32_e32 v2, v2, v4
	s_waitcnt vmcnt(6)
	s_mov_b32 s100, 0
	v_add_lshl_u32 v6, v6, v9, 1
	v_mov_b32_e32 v7, v1
	s_mov_b64 s[8:9], 0x40080
	v_add_lshl_u32 v2, v2, v5, 1
	v_mov_b32_e32 v3, v1
	s_cmpk_lt_u32 s4, 0x100
	v_lshlrev_b32_e32 v10, 2, v20
	v_lshl_add_u64 v[132:133], v[6:7], 0, s[8:9]
	v_lshl_add_u64 v[134:135], v[2:3], 0, s[8:9]
	v_readlane_b32 s8, v255, 1
	s_cselect_b64 s[4:5], -1, 0
	v_lshl_or_b32 v174, s90, 5, v10
	s_mov_b32 s96, 0
	v_cmp_eq_u32_e64 s[6:7], 0, v20
	v_add_u32_e32 v175, 0, v21
	v_readlane_b32 s12, v254, 46
	s_mov_b32 s13, s8
	s_barrier
	v_readlane_b32 s9, v255, 2
	s_branch .LBB0_1029

; #define PG8_STAGE(bufoff, gbase, voff) do { _Pragma("unroll") for (int _i = 0; _i < 2; ++_i) \
;         __builtin_amdgcn_global_load_lds((const unsigned*)((const char*)(gbase) + (voff)[_i]), (PG8_LAS unsigned*)(lds + (bufoff) + ldsw + _i * 8192), 16, 0, 0); } while (0)
; #define PG8_LDA(dst, b, h) do { _Pragma("unroll") for (int m = 0; m < 4; ++m) _Pragma("unroll") for (int k = 0; k < 2; ++k) dst[m][k] = *(const PG8_LAS bf16x8*)(lds + PG8_SA(b, h) + aoff + m * 2048 + k * 1024); } while (0)
; #define PG8_LDB(dst, b, h) do { _Pragma("unroll") for (int n = 0; n < 2; ++n) _Pragma("unroll") for (int k = 0; k < 2; ++k) dst[n][k] = *(const PG8_LAS bf16x8*)(lds + PG8_SB(b, h) + boff + n * 2048 + k * 1024); } while (0)
; #define PG8_MMA(ai, bj, At, Bt) do { __builtin_amdgcn_s_setprio(1); _Pragma("unroll") for (int m = 0; m < 4; ++m) _Pragma("unroll") for (int n = 0; n < 2; ++n) _Pragma("unroll") for (int k = 0; k < 2; ++k) \
;         acc[ai][bj][m][n] = __builtin_amdgcn_mfma_f32_16x16x32_bf16(Bt[n][k], At[m][k], acc[ai][bj][m][n], 0, 0, 0); __builtin_amdgcn_s_setprio(0); } while (0)
; #define PG8_WAIT_V(n) asm volatile("s_waitcnt vmcnt(" #n ")" ::: "memory")
; #define PG8_WAIT_L(n) asm volatile("s_waitcnt lgkmcnt(" #n ")" ::: "memory")
; #define PG8_BAR __builtin_amdgcn_s_barrier()
; #define PG8_SCHED __builtin_amdgcn_sched_barrier(0)
; template <class Epi, class Sched, bool ALIGN_EPI = false, bool SP2 = false>
; __device__ __forceinline__ void gemm_phase(PG8_LAS unsigned char* lds, const Gemm g, const Sched& S, const Epi& E) {
;     ...
;             const bool last = (t == nt - 2);
;             const char* a1 = cA + (size_t)(t + 1) * kstep;
;             const char* a2 = last ? nA : cA + (size_t)(t + 2) * kstep; const char* b2 = last ? nB : cB + (size_t)(t + 2) * kstep;
;             const char* a3 = a2 + kstep; const char* b3 = b2 + kstep;
;             if (last && has_next) S.a_ready(nxt);
;             if constexpr (SP2) {
;             PG8_LDB(B0, 0, 0); PG8_LDB(B1, 0, 1); PG8_SCHED; PG8_LDA(At, 0, 0); PG8_STAGE(PG8_SA(1, 1), a1 + hstep, voffA);
;             PG8_WAIT_V(8); PG8_WAIT_L(0); PG8_BAR; PG8_MMA(0, 0, At, B0); PG8_MMA(0, 1, At, B1); PG8_BAR; PG8_SCHED;
;             PG8_LDA(At, 0, 1); PG8_STAGE(PG8_SB(0, 0), b2, voffB); PG8_STAGE(PG8_SB(0, 1), b2 + hstep, voffB); PG8_STAGE(PG8_SA(0, 0), a2, voffA);
.LBB0_1036:
	s_add_u32 s80, s78, 0x100
	s_addc_u32 s81, s79, 0
	s_add_i32 s50, 0, 0x10000
	s_cmp_eq_u32 s56, 12
	s_cselect_b32 s85, s52, s81
	s_cselect_b32 s84, s53, s80
	s_cselect_b32 s83, s64, s55
	s_cselect_b32 s82, s71, s54
	s_add_i32 s51, 0, 0x14000
	v_add_u32_e32 v148, s50, v173
	v_add_u32_e32 v164, s51, v173
	ds_read_b128 v[136:139], v148
	ds_read_b128 v[140:143], v148 offset:1024
	ds_read_b128 v[144:147], v148 offset:2048
	ds_read_b128 v[148:151], v148 offset:3072
	ds_read_b128 v[152:155], v164
	ds_read_b128 v[156:159], v164 offset:1024
	ds_read_b128 v[160:163], v164 offset:2048
	ds_read_b128 v[164:167], v164 offset:3072
	v_lshl_add_u64 v[184:185], s[78:79], 0, v[132:133]
	s_add_i32 m0, s62, 0xc000
	ds_read_b128 v[168:171], v175
	ds_read_b128 v[176:179], v175 offset:1024
	ds_read_b128 v[180:183], v175 offset:2048
	ds_read_b128 v[192:195], v175 offset:3072
	ds_read_b128 v[196:199], v175 offset:4096
	ds_read_b128 v[200:203], v175 offset:5120
	ds_read_b128 v[204:207], v175 offset:6144
	ds_read_b128 v[208:211], v175 offset:7168
	global_load_lds_dwordx4 v[184:185], off
	v_lshl_add_u64 v[184:185], s[78:79], 0, v[134:135]
	s_add_i32 m0, s62, 0xe000
	s_nop 0
	global_load_lds_dwordx4 v[184:185], off
	s_cmp_lg_u32 s100, 0
	s_cbranch_scc1 .Lpe_skip_out_0
	s_waitcnt vmcnt(8)
.Lpe_skip_out_0:
	s_waitcnt lgkmcnt(0)
	s_barrier
	s_setprio 1
	s_waitcnt lgkmcnt(0)
	v_mfma_f32_16x16x32_bf16 v[126:129], v[136:139], v[168:171], v[126:129]
	v_mfma_f32_16x16x32_bf16 v[122:125], v[144:147], v[168:171], v[122:125]
	v_mfma_f32_16x16x32_bf16 v[110:113], v[136:139], v[180:183], v[110:113]
	v_mfma_f32_16x16x32_bf16 v[106:109], v[144:147], v[180:183], v[106:109]
	v_mfma_f32_16x16x32_bf16 v[94:97], v[136:139], v[196:199], v[94:97]
	v_mfma_f32_16x16x32_bf16 v[90:93], v[144:147], v[196:199], v[90:93]
	v_mfma_f32_16x16x32_bf16 v[78:81], v[136:139], v[204:207], v[78:81]
	v_mfma_f32_16x16x32_bf16 v[74:77], v[144:147], v[204:207], v[74:77]
	v_mfma_f32_16x16x32_bf16 v[126:129], v[140:143], v[176:179], v[126:129]
	v_mfma_f32_16x16x32_bf16 v[122:125], v[148:151], v[176:179], v[122:125]
	v_mfma_f32_16x16x32_bf16 v[110:113], v[140:143], v[192:195], v[110:113]
	v_mfma_f32_16x16x32_bf16 v[106:109], v[148:151], v[192:195], v[106:109]
	v_mfma_f32_16x16x32_bf16 v[94:97], v[140:143], v[200:203], v[94:97]
	v_mfma_f32_16x16x32_bf16 v[90:93], v[148:151], v[200:203], v[90:93]
	v_mfma_f32_16x16x32_bf16 v[78:81], v[140:143], v[208:211], v[78:81]
	v_mfma_f32_16x16x32_bf16 v[74:77], v[148:151], v[208:211], v[74:77]
	s_setprio 0
	s_setprio 1
	v_mfma_f32_16x16x32_bf16 v[118:121], v[152:155], v[168:171], v[118:121]
	v_mfma_f32_16x16x32_bf16 v[114:117], v[160:163], v[168:171], v[114:117]
	v_mfma_f32_16x16x32_bf16 v[102:105], v[152:155], v[180:183], v[102:105]
	v_mfma_f32_16x16x32_bf16 v[98:101], v[160:163], v[180:183], v[98:101]
	v_mfma_f32_16x16x32_bf16 v[86:89], v[152:155], v[196:199], v[86:89]
	v_mfma_f32_16x16x32_bf16 v[82:85], v[160:163], v[196:199], v[82:85]
	v_mfma_f32_16x16x32_bf16 v[70:73], v[152:155], v[204:207], v[70:73]
	v_mfma_f32_16x16x32_bf16 v[66:69], v[160:163], v[204:207], v[66:69]
	v_mfma_f32_16x16x32_bf16 v[118:121], v[156:159], v[176:179], v[118:121]
	v_mfma_f32_16x16x32_bf16 v[114:117], v[164:167], v[176:179], v[114:117]
	v_mfma_f32_16x16x32_bf16 v[102:105], v[156:159], v[192:195], v[102:105]
	v_mfma_f32_16x16x32_bf16 v[98:101], v[164:167], v[192:195], v[98:101]
	v_mfma_f32_16x16x32_bf16 v[86:89], v[156:159], v[200:203], v[86:89]
	v_mfma_f32_16x16x32_bf16 v[82:85], v[164:167], v[200:203], v[82:85]
	v_mfma_f32_16x16x32_bf16 v[70:73], v[156:159], v[208:211], v[70:73]
	v_mfma_f32_16x16x32_bf16 v[66:69], v[164:167], v[208:211], v[66:69]
	s_setprio 0
	s_barrier
	s_add_i32 s50, s50, s35
	v_lshl_add_u64 v[184:185], s[82:83], 0, v[0:1]
	s_mov_b32 m0, s50
	ds_read_b128 v[168:171], v175 offset:16384
	ds_read_b128 v[176:179], v175 offset:17408
	ds_read_b128 v[180:183], v175 offset:18432
	ds_read_b128 v[192:195], v175 offset:19456
	ds_read_b128 v[196:199], v175 offset:20480
	ds_read_b128 v[200:203], v175 offset:21504
	ds_read_b128 v[204:207], v175 offset:22528
	ds_read_b128 v[208:211], v175 offset:23552
	global_load_lds_dwordx4 v[184:185], off
	s_add_i32 m0, s50, 0x2000
	s_add_u32 s78, s82, 0x40000
	v_lshl_add_u64 v[188:189], s[82:83], 0, v[130:131]
	s_addc_u32 s79, s83, 0
	s_add_i32 s50, s51, s35
	global_load_lds_dwordx4 v[188:189], off
	v_lshl_add_u64 v[190:191], s[78:79], 0, v[0:1]
	s_mov_b32 m0, s50
	v_lshl_add_u64 v[212:213], s[84:85], 0, v[130:131]
	global_load_lds_dwordx4 v[190:191], off
	v_lshl_add_u64 v[190:191], s[78:79], 0, v[130:131]
	s_add_i32 m0, s50, 0x2000
	s_nop 0
	global_load_lds_dwordx4 v[190:191], off
	v_lshl_add_u64 v[190:191], s[84:85], 0, v[0:1]
	s_mov_b32 m0, s62
	s_nop 0
	global_load_lds_dwordx4 v[190:191], off
	s_mov_b32 m0, s63
	s_nop 0
	global_load_lds_dwordx4 v[212:213], off
	s_cmp_lg_u32 s100, 0
	s_cbranch_scc1 .Lpe_skip_out_1
	s_waitcnt vmcnt(8)
; #define PG8_STAGE(bufoff, gbase, voff) do { _Pragma("unroll") for (int _i = 0; _i < 2; ++_i) \
;         __builtin_amdgcn_global_load_lds((const unsigned*)((const char*)(gbase) + (voff)[_i]), (PG8_LAS unsigned*)(lds + (bufoff) + ldsw + _i * 8192), 16, 0, 0); } while (0)
; #define PG8_LDA(dst, b, h) do { _Pragma("unroll") for (int m = 0; m < 4; ++m) _Pragma("unroll") for (int k = 0; k < 2; ++k) dst[m][k] = *(const PG8_LAS bf16x8*)(lds + PG8_SA(b, h) + aoff + m * 2048 + k * 1024); } while (0)
; #define PG8_LDB(dst, b, h) do { _Pragma("unroll") for (int n = 0; n < 2; ++n) _Pragma("unroll") for (int k = 0; k < 2; ++k) dst[n][k] = *(const PG8_LAS bf16x8*)(lds + PG8_SB(b, h) + boff + n * 2048 + k * 1024); } while (0)
; #define PG8_MMA(ai, bj, At, Bt) do { __builtin_amdgcn_s_setprio(1); _Pragma("unroll") for (int m = 0; m < 4; ++m) _Pragma("unroll") for (int n = 0; n < 2; ++n) _Pragma("unroll") for (int k = 0; k < 2; ++k) \
;         acc[ai][bj][m][n] = __builtin_amdgcn_mfma_f32_16x16x32_bf16(Bt[n][k], At[m][k], acc[ai][bj][m][n], 0, 0, 0); __builtin_amdgcn_s_setprio(0); } while (0)
; #define PG8_WAIT_V(n) asm volatile("s_waitcnt vmcnt(" #n ")" ::: "memory")
; #define PG8_WAIT_L(n) asm volatile("s_waitcnt lgkmcnt(" #n ")" ::: "memory")
; #define PG8_BAR __builtin_amdgcn_s_barrier()
; #define PG8_SCHED __builtin_amdgcn_sched_barrier(0)
; template <class Epi, class Sched, bool ALIGN_EPI = false, bool SP2 = false>
; __device__ __forceinline__ void gemm_phase(PG8_LAS unsigned char* lds, const Gemm g, const Sched& S, const Epi& E) {
;     ...
;             PG8_WAIT_V(8); PG8_WAIT_L(0); PG8_BAR; PG8_MMA(1, 0, At, B0); PG8_MMA(1, 1, At, B1); PG8_BAR; PG8_SCHED;
;             PG8_LDB(B0, 1, 0); PG8_LDB(B1, 1, 1); PG8_SCHED; PG8_LDA(At, 1, 0); PG8_STAGE(PG8_SA(0, 1), a2 + hstep, voffA);
;             PG8_WAIT_V(8); PG8_WAIT_L(0); PG8_BAR; PG8_MMA(0, 0, At, B0); PG8_MMA(0, 1, At, B1); PG8_BAR; PG8_SCHED;
.Lpe_skip_out_1:
	s_mov_b32 s100, 0
	s_waitcnt lgkmcnt(0)
	s_barrier
	s_setprio 1
	s_waitcnt lgkmcnt(0)
	v_mfma_f32_16x16x32_bf16 v[62:65], v[136:139], v[168:171], v[62:65]
	v_mfma_f32_16x16x32_bf16 v[58:61], v[144:147], v[168:171], v[58:61]
	v_mfma_f32_16x16x32_bf16 v[46:49], v[136:139], v[180:183], v[46:49]
	v_mfma_f32_16x16x32_bf16 v[42:45], v[144:147], v[180:183], v[42:45]
	v_mfma_f32_16x16x32_bf16 v[30:33], v[136:139], v[196:199], v[30:33]
	v_mfma_f32_16x16x32_bf16 v[26:29], v[144:147], v[196:199], v[26:29]
	v_mfma_f32_16x16x32_bf16 v[14:17], v[136:139], v[204:207], v[14:17]
	v_mfma_f32_16x16x32_bf16 v[10:13], v[144:147], v[204:207], v[10:13]
	v_mfma_f32_16x16x32_bf16 v[62:65], v[140:143], v[176:179], v[62:65]
	v_mfma_f32_16x16x32_bf16 v[58:61], v[148:151], v[176:179], v[58:61]
	v_mfma_f32_16x16x32_bf16 v[46:49], v[140:143], v[192:195], v[46:49]
	v_mfma_f32_16x16x32_bf16 v[42:45], v[148:151], v[192:195], v[42:45]
	v_mfma_f32_16x16x32_bf16 v[30:33], v[140:143], v[200:203], v[30:33]
	v_mfma_f32_16x16x32_bf16 v[26:29], v[148:151], v[200:203], v[26:29]
	v_mfma_f32_16x16x32_bf16 v[14:17], v[140:143], v[208:211], v[14:17]
	v_mfma_f32_16x16x32_bf16 v[10:13], v[148:151], v[208:211], v[10:13]
	s_setprio 0
	s_setprio 1
	v_mfma_f32_16x16x32_bf16 v[54:57], v[152:155], v[168:171], v[54:57]
	v_mfma_f32_16x16x32_bf16 v[50:53], v[160:163], v[168:171], v[50:53]
	v_mfma_f32_16x16x32_bf16 v[38:41], v[152:155], v[180:183], v[38:41]
	v_mfma_f32_16x16x32_bf16 v[34:37], v[160:163], v[180:183], v[34:37]
	v_mfma_f32_16x16x32_bf16 v[22:25], v[152:155], v[196:199], v[22:25]
	v_mfma_f32_16x16x32_bf16 v[18:21], v[160:163], v[196:199], v[18:21]
	v_mfma_f32_16x16x32_bf16 v[6:9], v[152:155], v[204:207], v[6:9]
	v_mfma_f32_16x16x32_bf16 v[2:5], v[160:163], v[204:207], v[2:5]
	v_mfma_f32_16x16x32_bf16 v[54:57], v[156:159], v[176:179], v[54:57]
	v_mfma_f32_16x16x32_bf16 v[50:53], v[164:167], v[176:179], v[50:53]
	v_mfma_f32_16x16x32_bf16 v[38:41], v[156:159], v[192:195], v[38:41]
	v_mfma_f32_16x16x32_bf16 v[34:37], v[164:167], v[192:195], v[34:37]
	v_mfma_f32_16x16x32_bf16 v[22:25], v[156:159], v[200:203], v[22:25]
	v_mfma_f32_16x16x32_bf16 v[18:21], v[164:167], v[200:203], v[18:21]
	v_mfma_f32_16x16x32_bf16 v[6:9], v[156:159], v[208:211], v[6:9]
	v_mfma_f32_16x16x32_bf16 v[2:5], v[164:167], v[208:211], v[2:5]
	s_setprio 0
	s_barrier
	s_add_i32 s50, 0, 0x18000
	s_add_i32 s51, 0, 0x1c000
	v_add_u32_e32 v148, s50, v173
	v_add_u32_e32 v164, s51, v173
	ds_read_b128 v[136:139], v148
	ds_read_b128 v[140:143], v148 offset:1024
	ds_read_b128 v[144:147], v148 offset:2048
	ds_read_b128 v[148:151], v148 offset:3072
	ds_read_b128 v[152:155], v164
	ds_read_b128 v[156:159], v164 offset:1024
	ds_read_b128 v[160:163], v164 offset:2048
	ds_read_b128 v[164:167], v164 offset:3072
	s_add_u32 s78, s84, 0x40000
	s_addc_u32 s79, s85, 0
	s_mov_b32 m0, s86
	v_lshl_add_u64 v[214:215], s[78:79], 0, v[0:1]
	ds_read_b128 v[168:171], v175 offset:32768
	ds_read_b128 v[176:179], v175 offset:33792
	ds_read_b128 v[180:183], v175 offset:34816
	ds_read_b128 v[192:195], v175 offset:35840
	ds_read_b128 v[196:199], v175 offset:36864
	ds_read_b128 v[200:203], v175 offset:37888
	ds_read_b128 v[204:207], v175 offset:38912
	ds_read_b128 v[208:211], v175 offset:39936
	global_load_lds_dwordx4 v[214:215], off
	v_lshl_add_u64 v[214:215], s[78:79], 0, v[130:131]
	s_mov_b32 m0, s87
	s_nop 0
	global_load_lds_dwordx4 v[214:215], off
	s_waitcnt vmcnt(8)
	s_waitcnt lgkmcnt(0)
	s_barrier
	s_setprio 1
	s_waitcnt lgkmcnt(0)
	v_mfma_f32_16x16x32_bf16 v[126:129], v[136:139], v[168:171], v[126:129]
	v_mfma_f32_16x16x32_bf16 v[122:125], v[144:147], v[168:171], v[122:125]
	v_mfma_f32_16x16x32_bf16 v[110:113], v[136:139], v[180:183], v[110:113]
	v_mfma_f32_16x16x32_bf16 v[106:109], v[144:147], v[180:183], v[106:109]
	v_mfma_f32_16x16x32_bf16 v[94:97], v[136:139], v[196:199], v[94:97]
	v_mfma_f32_16x16x32_bf16 v[90:93], v[144:147], v[196:199], v[90:93]
	v_mfma_f32_16x16x32_bf16 v[78:81], v[136:139], v[204:207], v[78:81]
	v_mfma_f32_16x16x32_bf16 v[74:77], v[144:147], v[204:207], v[74:77]
	v_mfma_f32_16x16x32_bf16 v[126:129], v[140:143], v[176:179], v[126:129]
	v_mfma_f32_16x16x32_bf16 v[122:125], v[148:151], v[176:179], v[122:125]
	v_mfma_f32_16x16x32_bf16 v[110:113], v[140:143], v[192:195], v[110:113]
	v_mfma_f32_16x16x32_bf16 v[106:109], v[148:151], v[192:195], v[106:109]
	v_mfma_f32_16x16x32_bf16 v[94:97], v[140:143], v[200:203], v[94:97]
	v_mfma_f32_16x16x32_bf16 v[90:93], v[148:151], v[200:203], v[90:93]
	v_mfma_f32_16x16x32_bf16 v[78:81], v[140:143], v[208:211], v[78:81]
	v_mfma_f32_16x16x32_bf16 v[74:77], v[148:151], v[208:211], v[74:77]
	s_setprio 0
	s_setprio 1
	v_mfma_f32_16x16x32_bf16 v[118:121], v[152:155], v[168:171], v[118:121]
	v_mfma_f32_16x16x32_bf16 v[114:117], v[160:163], v[168:171], v[114:117]
	v_mfma_f32_16x16x32_bf16 v[102:105], v[152:155], v[180:183], v[102:105]
	v_mfma_f32_16x16x32_bf16 v[98:101], v[160:163], v[180:183], v[98:101]
	v_mfma_f32_16x16x32_bf16 v[86:89], v[152:155], v[196:199], v[86:89]
	v_mfma_f32_16x16x32_bf16 v[82:85], v[160:163], v[196:199], v[82:85]
	v_mfma_f32_16x16x32_bf16 v[70:73], v[152:155], v[204:207], v[70:73]
	v_mfma_f32_16x16x32_bf16 v[66:69], v[160:163], v[204:207], v[66:69]
	v_mfma_f32_16x16x32_bf16 v[118:121], v[156:159], v[176:179], v[118:121]
	v_mfma_f32_16x16x32_bf16 v[114:117], v[164:167], v[176:179], v[114:117]
	v_mfma_f32_16x16x32_bf16 v[102:105], v[156:159], v[192:195], v[102:105]
	v_mfma_f32_16x16x32_bf16 v[98:101], v[164:167], v[192:195], v[98:101]
	v_mfma_f32_16x16x32_bf16 v[86:89], v[156:159], v[200:203], v[86:89]
	v_mfma_f32_16x16x32_bf16 v[82:85], v[164:167], v[200:203], v[82:85]
	v_mfma_f32_16x16x32_bf16 v[70:73], v[156:159], v[208:211], v[70:73]
	v_mfma_f32_16x16x32_bf16 v[66:69], v[164:167], v[208:211], v[66:69]
	s_setprio 0
	s_barrier
; #define PG8_STAGE(bufoff, gbase, voff) do { _Pragma("unroll") for (int _i = 0; _i < 2; ++_i) \
;         __builtin_amdgcn_global_load_lds((const unsigned*)((const char*)(gbase) + (voff)[_i]), (PG8_LAS unsigned*)(lds + (bufoff) + ldsw + _i * 8192), 16, 0, 0); } while (0)
; #define PG8_LDA(dst, b, h) do { _Pragma("unroll") for (int m = 0; m < 4; ++m) _Pragma("unroll") for (int k = 0; k < 2; ++k) dst[m][k] = *(const PG8_LAS bf16x8*)(lds + PG8_SA(b, h) + aoff + m * 2048 + k * 1024); } while (0)
; #define PG8_MMA(ai, bj, At, Bt) do { __builtin_amdgcn_s_setprio(1); _Pragma("unroll") for (int m = 0; m < 4; ++m) _Pragma("unroll") for (int n = 0; n < 2; ++n) _Pragma("unroll") for (int k = 0; k < 2; ++k) \
;         acc[ai][bj][m][n] = __builtin_amdgcn_mfma_f32_16x16x32_bf16(Bt[n][k], At[m][k], acc[ai][bj][m][n], 0, 0, 0); __builtin_amdgcn_s_setprio(0); } while (0)
; #define PG8_WAIT_V(n) asm volatile("s_waitcnt vmcnt(" #n ")" ::: "memory")
; #define PG8_WAIT_L(n) asm volatile("s_waitcnt lgkmcnt(" #n ")" ::: "memory")
; #define PG8_BAR __builtin_amdgcn_s_barrier()
; #define PG8_SCHED __builtin_amdgcn_sched_barrier(0)
; template <class Epi, class Sched, bool ALIGN_EPI = false, bool SP2 = false>
; __device__ __forceinline__ void gemm_phase(PG8_LAS unsigned char* lds, const Gemm g, const Sched& S, const Epi& E) {
;     ...
;         for (int t = 0; t < nt; t += 2) {
;     ...
;             PG8_LDA(At, 1, 1); PG8_STAGE(PG8_SB(1, 0), b3, voffB); PG8_STAGE(PG8_SB(1, 1), b3 + hstep, voffB); PG8_STAGE(PG8_SA(1, 0), a3, voffA);
;             PG8_WAIT_V(8); PG8_WAIT_L(0); PG8_BAR; PG8_MMA(1, 0, At, B0); PG8_MMA(1, 1, At, B1); PG8_BAR; PG8_SCHED;
;     ...
;         if constexpr (ALIGN_EPI) { if (wr == 0) PG8_BAR; }
	s_add_i32 s50, s50, s35
	v_lshl_add_u64 v[184:185], v[184:185], 0, s[60:61]
	s_mov_b32 m0, s50
	ds_read_b128 v[168:171], v175 offset:49152
	ds_read_b128 v[176:179], v175 offset:50176
	ds_read_b128 v[180:183], v175 offset:51200
	ds_read_b128 v[192:195], v175 offset:52224
	ds_read_b128 v[196:199], v175 offset:53248
	ds_read_b128 v[200:203], v175 offset:54272
	ds_read_b128 v[204:207], v175 offset:55296
	ds_read_b128 v[208:211], v175 offset:56320
	global_load_lds_dwordx4 v[184:185], off
	s_add_i32 m0, s50, 0x2000
	s_add_u32 s78, s82, 0x40080
	v_lshl_add_u64 v[184:185], v[188:189], 0, s[60:61]
	s_addc_u32 s79, s83, 0
	s_add_i32 s50, s51, s35
	global_load_lds_dwordx4 v[184:185], off
	v_lshl_add_u64 v[184:185], s[78:79], 0, v[0:1]
	s_mov_b32 m0, s50
	s_nop 0
	global_load_lds_dwordx4 v[184:185], off
	v_lshl_add_u64 v[184:185], s[78:79], 0, v[130:131]
	s_add_i32 m0, s50, 0x2000
	s_nop 0
	global_load_lds_dwordx4 v[184:185], off
	v_lshl_add_u64 v[184:185], v[190:191], 0, s[60:61]
	s_mov_b32 m0, s94
	s_nop 0
	global_load_lds_dwordx4 v[184:185], off
	v_lshl_add_u64 v[184:185], v[212:213], 0, s[60:61]
	s_mov_b32 m0, s95
	s_nop 0
	global_load_lds_dwordx4 v[184:185], off
	s_waitcnt vmcnt(8)
	s_waitcnt lgkmcnt(0)
	s_barrier
	s_setprio 1
	s_waitcnt lgkmcnt(0)
	v_mfma_f32_16x16x32_bf16 v[62:65], v[136:139], v[168:171], v[62:65]
	v_mfma_f32_16x16x32_bf16 v[58:61], v[144:147], v[168:171], v[58:61]
	v_mfma_f32_16x16x32_bf16 v[46:49], v[136:139], v[180:183], v[46:49]
	v_mfma_f32_16x16x32_bf16 v[42:45], v[144:147], v[180:183], v[42:45]
	v_mfma_f32_16x16x32_bf16 v[30:33], v[136:139], v[196:199], v[30:33]
	v_mfma_f32_16x16x32_bf16 v[26:29], v[144:147], v[196:199], v[26:29]
	v_mfma_f32_16x16x32_bf16 v[14:17], v[136:139], v[204:207], v[14:17]
	v_mfma_f32_16x16x32_bf16 v[10:13], v[144:147], v[204:207], v[10:13]
	v_mfma_f32_16x16x32_bf16 v[62:65], v[140:143], v[176:179], v[62:65]
	v_mfma_f32_16x16x32_bf16 v[58:61], v[148:151], v[176:179], v[58:61]
	v_mfma_f32_16x16x32_bf16 v[46:49], v[140:143], v[192:195], v[46:49]
	v_mfma_f32_16x16x32_bf16 v[42:45], v[148:151], v[192:195], v[42:45]
	v_mfma_f32_16x16x32_bf16 v[30:33], v[140:143], v[200:203], v[30:33]
	v_mfma_f32_16x16x32_bf16 v[26:29], v[148:151], v[200:203], v[26:29]
	v_mfma_f32_16x16x32_bf16 v[14:17], v[140:143], v[208:211], v[14:17]
	v_mfma_f32_16x16x32_bf16 v[10:13], v[148:151], v[208:211], v[10:13]
	s_setprio 0
	s_setprio 1
	v_mfma_f32_16x16x32_bf16 v[54:57], v[152:155], v[168:171], v[54:57]
	v_mfma_f32_16x16x32_bf16 v[50:53], v[160:163], v[168:171], v[50:53]
	v_mfma_f32_16x16x32_bf16 v[38:41], v[152:155], v[180:183], v[38:41]
	v_mfma_f32_16x16x32_bf16 v[34:37], v[160:163], v[180:183], v[34:37]
	v_mfma_f32_16x16x32_bf16 v[22:25], v[152:155], v[196:199], v[22:25]
	v_mfma_f32_16x16x32_bf16 v[18:21], v[160:163], v[196:199], v[18:21]
	v_mfma_f32_16x16x32_bf16 v[6:9], v[152:155], v[204:207], v[6:9]
	v_mfma_f32_16x16x32_bf16 v[2:5], v[160:163], v[204:207], v[2:5]
	v_mfma_f32_16x16x32_bf16 v[54:57], v[156:159], v[176:179], v[54:57]
	v_mfma_f32_16x16x32_bf16 v[50:53], v[164:167], v[176:179], v[50:53]
	v_mfma_f32_16x16x32_bf16 v[38:41], v[156:159], v[192:195], v[38:41]
	v_mfma_f32_16x16x32_bf16 v[34:37], v[164:167], v[192:195], v[34:37]
	v_mfma_f32_16x16x32_bf16 v[22:25], v[156:159], v[200:203], v[22:25]
	v_mfma_f32_16x16x32_bf16 v[18:21], v[164:167], v[200:203], v[18:21]
	v_mfma_f32_16x16x32_bf16 v[6:9], v[156:159], v[208:211], v[6:9]
	v_mfma_f32_16x16x32_bf16 v[2:5], v[164:167], v[208:211], v[2:5]
	s_setprio 0
	s_barrier
	s_add_i32 s56, s56, 2
	s_add_u32 s54, s54, 0x100
	s_addc_u32 s55, s55, 0
	s_cmp_gt_u32 s56, 13
	s_mov_b64 s[78:79], s[80:81]
	s_cbranch_scc0 .LBB0_1036
	s_and_b64 vcc, exec, s[4:5]
	s_cbranch_vccz .LBB0_1039
	s_barrier
; __device__ __forceinline__ unsigned cvt_pk_bf16(float lo, float hi) { unsigned r; asm volatile("v_cvt_pk_bf16_f32 %0, %1, %2" : "=v"(r) : "v"(lo), "v"(hi)); return r; }
;     __device__ __forceinline__ void operator()(f32x4 (&acc)[2][2][4][2], const Unit& u, int wr, int wc, int fr, int fq) const {
;         const int col0 = u.pn * BM + wc * 32 + 4 * fq;
; #pragma unroll
;         for (int ai = 0; ai < 2; ++ai) {
;             unsigned long long old[4][2][2];
; #pragma unroll
;             for (int m = 0; m < 4; ++m) { const size_t off = (size_t)(u.pm * BM + ai * HALF + wr * 64 + m * 16 + fr) * ldc + col0;
; #pragma unroll
;                 for (int bj = 0; bj < 2; ++bj)
; #pragma unroll
;                     for (int n = 0; n < 2; ++n) old[m][bj][n] = *(const unsigned long long*)(xb + off + bj * HALF + n * 16); }
; #pragma unroll
;             for (int m = 0; m < 4; ++m) { const int row = u.pm * BM + ai * HALF + wr * 64 + m * 16 + fr; const size_t off = (size_t)row * ldc + col0; float sq = 0.f;
; #pragma unroll
;                 for (int bj = 0; bj < 2; ++bj)
; #pragma unroll
;                     for (int n = 0; n < 2; ++n) { const unsigned long long b = old[m][bj][n];
;                         const unsigned blo = (unsigned)b, bhi = (unsigned)(b >> 32);
;                         f32x4 v; v[0] = __builtin_bit_cast(float, blo << 16); v[1] = __builtin_bit_cast(float, blo & 0xffff0000u); v[2] = __builtin_bit_cast(float, bhi << 16); v[3] = __builtin_bit_cast(float, bhi & 0xffff0000u);
;                         v = v + acc[ai][bj][m][n];
;                         sq += (v[0] * v[0] + v[1] * v[1]) + (v[2] * v[2] + v[3] * v[3]);
;                         *(unsigned long long*)(xb + off + bj * HALF + n * 16) = (unsigned long long)cvt_pk_bf16(v[0], v[1]) | ((unsigned long long)cvt_pk_bf16(v[2], v[3]) << 32); }
;                 sq += __shfl_xor(sq, 16); sq += __shfl_xor(sq, 32);
;                 if (fq == 0) ssp[(size_t)row * 16 + 4 * u.pn + wc] = sq; }
.LBB0_1039:
	v_lshl_or_b32 v136, s12, 8, v174
	v_lshl_add_u32 v140, s13, 8, v172
	v_ashrrev_i32_e32 v137, 31, v136
	v_lshlrev_b64 v[176:177], 1, v[136:137]
	v_ashrrev_i32_e32 v141, 31, v140
	v_lshl_add_u64 v[138:139], s[42:43], 0, v[176:177]
	v_lshlrev_b64 v[178:179], 11, v[140:141]
	v_lshl_add_u64 v[142:143], v[138:139], 0, v[178:179]
	global_load_dwordx2 v[180:181], v[142:143], off
	global_load_dwordx2 v[182:183], v[142:143], off offset:32
	global_load_dwordx2 v[184:185], v[142:143], off offset:256
	global_load_dwordx2 v[188:189], v[142:143], off offset:288
	v_or_b32_e32 v160, 16, v140
	v_ashrrev_i32_e32 v161, 31, v160
	v_lshlrev_b64 v[142:143], 11, v[160:161]
	v_or_b32_e32 v146, 32, v140
	v_lshl_add_u64 v[142:143], v[138:139], 0, v[142:143]
	v_ashrrev_i32_e32 v147, 31, v146
	global_load_dwordx2 v[170:171], v[142:143], off
	global_load_dwordx2 v[168:169], v[142:143], off offset:32
	global_load_dwordx2 v[166:167], v[142:143], off offset:256
	global_load_dwordx2 v[164:165], v[142:143], off offset:288
	v_lshlrev_b64 v[142:143], 11, v[146:147]
	v_lshl_add_u64 v[142:143], v[138:139], 0, v[142:143]
	global_load_dwordx2 v[162:163], v[142:143], off
	global_load_dwordx2 v[158:159], v[142:143], off offset:32
	global_load_dwordx2 v[154:155], v[142:143], off offset:256
	global_load_dwordx2 v[150:151], v[142:143], off offset:288
	v_or_b32_e32 v142, 48, v140
	v_ashrrev_i32_e32 v143, 31, v142
	v_lshlrev_b64 v[144:145], 11, v[142:143]
	v_lshl_add_u64 v[144:145], v[138:139], 0, v[144:145]
	global_load_dwordx2 v[156:157], v[144:145], off
	global_load_dwordx2 v[152:153], v[144:145], off offset:32
	global_load_dwordx2 v[148:149], v[144:145], off offset:256
	s_nop 0
	global_load_dwordx2 v[144:145], v[144:145], off offset:288
	s_lshl_b32 s78, s12, 2
	s_ashr_i32 s79, s78, 31
	s_waitcnt vmcnt(0)
	s_mov_b32 s100, 1
	v_lshlrev_b32_e32 v190, 16, v180
	v_and_b32_e32 v191, 0xffff0000, v180
	v_lshlrev_b32_e32 v180, 16, v181
	v_and_b32_e32 v181, 0xffff0000, v181
	v_pk_add_f32 v[128:129], v[128:129], v[180:181]
	v_pk_add_f32 v[126:127], v[126:127], v[190:191]
	v_mul_f32_e32 v181, v129, v129
	v_mul_f32_e32 v180, v127, v127
	v_fmac_f32_e32 v180, v126, v126
	v_fmac_f32_e32 v181, v128, v128
	v_cvt_pk_bf16_f32 v126, v126, v127
	v_cvt_pk_bf16_f32 v127, v128, v129
	v_lshl_add_u64 v[128:129], s[42:43], 0, v[178:179]
	v_lshl_add_u64 v[128:129], v[128:129], 0, v[176:177]
	global_store_dwordx2 v[128:129], v[126:127], off
	v_lshlrev_b32_e32 v126, 16, v182
	v_and_b32_e32 v127, 0xffff0000, v182
	v_pk_add_f32 v[122:123], v[122:123], v[126:127]
	v_lshlrev_b32_e32 v176, 16, v183
	v_and_b32_e32 v177, 0xffff0000, v183
	v_mul_f32_e32 v126, v123, v123
	v_pk_add_f32 v[124:125], v[124:125], v[176:177]
	v_fmac_f32_e32 v126, v122, v122
	v_cvt_pk_bf16_f32 v122, v122, v123
	v_cvt_pk_bf16_f32 v123, v124, v125
	v_mul_f32_e32 v127, v125, v125
	global_store_dwordx2 v[128:129], v[122:123], off offset:32
	v_lshlrev_b32_e32 v122, 16, v184
	v_and_b32_e32 v123, 0xffff0000, v184
	v_fmac_f32_e32 v127, v124, v124
	v_lshlrev_b32_e32 v124, 16, v185
	v_and_b32_e32 v125, 0xffff0000, v185
	v_pk_add_f32 v[118:119], v[118:119], v[122:123]
	v_pk_add_f32 v[120:121], v[120:121], v[124:125]
	v_mul_f32_e32 v122, v119, v119
	v_fmac_f32_e32 v122, v118, v118
	v_mul_f32_e32 v123, v121, v121
	v_cvt_pk_bf16_f32 v118, v118, v119
	v_cvt_pk_bf16_f32 v119, v120, v121
	v_fmac_f32_e32 v123, v120, v120
	global_store_dwordx2 v[128:129], v[118:119], off offset:256
	v_lshlrev_b32_e32 v118, 16, v188
	v_and_b32_e32 v119, 0xffff0000, v188
	v_lshlrev_b32_e32 v120, 16, v189
	v_and_b32_e32 v121, 0xffff0000, v189
	v_pk_add_f32 v[116:117], v[116:117], v[120:121]
	v_pk_add_f32 v[118:119], v[114:115], v[118:119]
	v_add_f32_e32 v180, v180, v181
	v_add_f32_e32 v126, v126, v127
	v_mul_f32_e32 v114, v119, v119
	v_mul_f32_e32 v115, v117, v117
	v_add_f32_e32 v126, v180, v126
	v_add_f32_e32 v122, v122, v123
	v_fmac_f32_e32 v114, v118, v118
	v_fmac_f32_e32 v115, v116, v116
	v_add_f32_e32 v122, v126, v122
	v_add_f32_e32 v114, v114, v115
	v_cvt_pk_bf16_f32 v118, v118, v119
	v_cvt_pk_bf16_f32 v119, v116, v117
	v_and_b32_e32 v116, 64, v229
	v_add_f32_e32 v115, v122, v114
	v_xor_b32_e32 v114, 16, v229
	v_add_u32_e32 v117, 64, v116
	v_cmp_lt_i32_e32 vcc, v114, v117
	global_store_dwordx2 v[128:129], v[118:119], off offset:288
	s_nop 0
	v_cndmask_b32_e32 v114, v229, v114, vcc
	v_lshlrev_b32_e32 v114, 2, v114
	v_mov_b32_e32 v116, v115
	s_nop 1
	v_permlane16_swap_b32_e32 v116, v115
	s_waitcnt lgkmcnt(0)
	v_add_f32_e32 v116, v115, v116
	v_xor_b32_e32 v115, 32, v229
	v_cmp_lt_i32_e32 vcc, v115, v117
	s_nop 1
	v_cndmask_b32_e32 v115, v229, v115, vcc
	v_lshlrev_b32_e32 v115, 2, v115
	ds_bpermute_b32 v117, v115, v116
	s_and_saveexec_b64 s[80:81], s[6:7]
	s_cbranch_execz .LBB0_1041
	v_readlane_b32 s12, v253, 40
	v_lshlrev_b64 v[118:119], 6, v[140:141]
	v_readlane_b32 s13, v253, 41
	s_lshl_b32 s64, s90, 2
	s_waitcnt lgkmcnt(0)
	v_add_f32_e32 v116, v116, v117
	v_lshl_add_u64 v[118:119], s[12:13], 0, v[118:119]
	v_lshl_add_u64 v[118:119], s[78:79], 2, v[118:119]
	v_lshl_add_u64 v[118:119], v[118:119], 0, s[64:65]
	global_store_dword v[118:119], v116, off

; #define PG8_STAGE(bufoff, gbase, voff) do { _Pragma("unroll") for (int _i = 0; _i < 2; ++_i) \
;         __builtin_amdgcn_global_load_lds((const unsigned*)((const char*)(gbase) + (voff)[_i]), (PG8_LAS unsigned*)(lds + (bufoff) + ldsw + _i * 8192), 16, 0, 0); } while (0)
; #define PG8_WAIT_V(n) asm volatile("s_waitcnt vmcnt(" #n ")" ::: "memory")
; #define PG8_BAR __builtin_amdgcn_s_barrier()
; template <class Epi, class Sched, bool ALIGN_EPI = false, bool SP2 = false>
; __device__ __forceinline__ void gemm_phase(PG8_LAS unsigned char* lds, const Gemm g, const Sched& S, const Epi& E) {
;     ...
;     for (int i = 0; i < 2; ++i) { int R, C; stage_rc(tid * 16 + i * 8192, R, C); const int Rb = Epi::PERM ? ((R & ~31) + perm32(R & 31)) : R;
;         voffA[i] = (unsigned)(R * K + C) * 2u; voffB[i] = (unsigned)(Rb * K + C) * 2u; }
;     const size_t kstep = (size_t)(BK * 2);
;     const size_t hstep = (size_t)HALF * K * 2;
;     const size_t tstep = 2 * hstep;
;     const unsigned ldsw = (unsigned)wid * 1024u;
;     const int aoff = lds_byte(wr * 64 + fr, fq * 8), boff = lds_byte(wc * 32 + fr, fq * 8);
;     ...
;         PG8_STAGE(PG8_SB(0, 0), cB, voffB); PG8_STAGE(PG8_SB(0, 1), cB + hstep, voffB); PG8_STAGE(PG8_SA(0, 0), cA, voffA); PG8_STAGE(PG8_SA(0, 1), cA + hstep, voffA);
;         if (wr == 1) PG8_BAR;
;         PG8_WAIT_V(2); PG8_BAR;
;         PG8_STAGE(PG8_SB(1, 0), cB + kstep, voffB); PG8_STAGE(PG8_SA(1, 0), cA + kstep, voffA); PG8_STAGE(PG8_SB(1, 1), cB + hstep + kstep, voffB);
;         PG8_WAIT_V(6); PG8_BAR;
.LBB0_1114:
	v_readlane_b32 s14, v254, 49
	s_lshl_b32 s6, s6, 5
	v_mov_b32_e32 v163, v1
	v_readlane_b32 s15, v254, 50
	s_and_b32 s12, s6, 0x60
	s_add_i32 m0, s62, 0x18000
	v_lshl_add_u64 v[2:3], v[2:3], 0, s[60:61]
	v_lshl_add_u64 v[14:15], s[14:15], 0, v[162:163]
	v_mov_b32_e32 v161, v1
	s_lshl_b32 s8, s1, 13
	s_lshl_b32 s9, s12, 7
	s_waitcnt vmcnt(2)
	s_barrier
	global_load_lds_dwordx4 v[2:3], off
	v_lshl_add_u64 v[2:3], v[4:5], 0, s[60:61]
	s_add_i32 m0, s62, 0x1a000
	s_add_i32 s83, s62, 0x8000
	s_add_i32 s84, s62, 0xa000
	v_lshl_add_u64 v[16:17], s[14:15], 0, v[160:161]
	global_load_lds_dwordx4 v[2:3], off
	v_lshl_add_u64 v[2:3], v[14:15], 0, s[60:61]
	s_mov_b32 m0, s83
	s_add_u32 s6, s78, 0x40080
	global_load_lds_dwordx4 v[2:3], off
	v_lshl_add_u64 v[2:3], v[16:17], 0, s[60:61]
	s_mov_b32 m0, s84
	s_addc_u32 s7, s79, 0
	global_load_lds_dwordx4 v[2:3], off
	s_add_i32 m0, s62, 0x1c000
	v_lshl_add_u64 v[2:3], s[6:7], 0, v[0:1]
	global_load_lds_dwordx4 v[2:3], off
	v_lshl_add_u64 v[2:3], s[6:7], 0, v[158:159]
	s_add_i32 m0, s62, 0x1e000
	v_bfe_u32 v4, v7, 4, 2
	global_load_lds_dwordx4 v[2:3], off
	v_and_b32_e32 v3, 15, v7
	v_lshlrev_b32_e32 v2, 4, v4
	v_lshlrev_b32_e32 v5, 2, v7
	v_lshl_or_b32 v173, s1, 6, v3
	v_lshl_or_b32 v3, v3, 6, v2
	v_and_b32_e32 v5, 32, v5
	s_cmpk_lt_u32 s0, 0x100
	v_readlane_b32 s0, v253, 40
	v_bitop3_b32 v7, v3, s8, v5 bitop3:0xde
	v_bitop3_b32 v174, v3, s9, v5 bitop3:0xde
	v_mov_b32_e32 v3, v1
	v_readlane_b32 s1, v253, 41
	s_waitcnt vmcnt(6)
	s_mov_b32 s100, 0
	s_cselect_b64 s[8:9], -1, 0
	v_lshl_or_b32 v175, v4, 3, s12
	v_lshl_add_u64 v[164:165], s[0:1], 0, v[2:3]
	v_lshlrev_b32_e32 v2, 14, v11
	v_and_b32_e32 v2, 0xffff8000, v2
	v_lshl_add_u32 v2, v10, 11, v2
	v_and_b32_e32 v3, 1, v11
	v_lshl_or_b32 v2, v3, 6, v2
	v_lshl_add_u32 v166, v12, 1, v2
	v_lshlrev_b32_e32 v2, 14, v6
	v_and_b32_e32 v2, 0xffff8000, v2
	v_lshl_add_u32 v2, v8, 11, v2
	v_and_b32_e32 v3, 1, v6
	v_readlane_b32 s0, v255, 1
	v_lshl_or_b32 v2, v3, 6, v2
	v_readlane_b32 s1, v255, 2
	v_mov_b32_e32 v167, v1
	v_lshl_add_u32 v168, v9, 1, v2
	v_mov_b32_e32 v169, v1
	s_mov_b32 s85, 0
	v_add_u32_e32 v176, 0, v7
	v_readlane_b32 s12, v254, 46
	s_mov_b32 s13, s0
	s_mov_b64 s[0:1], s[14:15]
	s_barrier
	s_branch .LBB0_1117

; #define PG8_STAGE(bufoff, gbase, voff) do { _Pragma("unroll") for (int _i = 0; _i < 2; ++_i) \
;         __builtin_amdgcn_global_load_lds((const unsigned*)((const char*)(gbase) + (voff)[_i]), (PG8_LAS unsigned*)(lds + (bufoff) + ldsw + _i * 8192), 16, 0, 0); } while (0)
; #define PG8_LDA(dst, b, h) do { _Pragma("unroll") for (int m = 0; m < 4; ++m) _Pragma("unroll") for (int k = 0; k < 2; ++k) dst[m][k] = *(const PG8_LAS bf16x8*)(lds + PG8_SA(b, h) + aoff + m * 2048 + k * 1024); } while (0)
; #define PG8_LDB(dst, b, h) do { _Pragma("unroll") for (int n = 0; n < 2; ++n) _Pragma("unroll") for (int k = 0; k < 2; ++k) dst[n][k] = *(const PG8_LAS bf16x8*)(lds + PG8_SB(b, h) + boff + n * 2048 + k * 1024); } while (0)
; #define PG8_MMA(ai, bj, At, Bt) do { __builtin_amdgcn_s_setprio(1); _Pragma("unroll") for (int m = 0; m < 4; ++m) _Pragma("unroll") for (int n = 0; n < 2; ++n) _Pragma("unroll") for (int k = 0; k < 2; ++k) \
;         acc[ai][bj][m][n] = __builtin_amdgcn_mfma_f32_16x16x32_bf16(Bt[n][k], At[m][k], acc[ai][bj][m][n], 0, 0, 0); __builtin_amdgcn_s_setprio(0); } while (0)
; #define PG8_WAIT_V(n) asm volatile("s_waitcnt vmcnt(" #n ")" ::: "memory")
; #define PG8_WAIT_L(n) asm volatile("s_waitcnt lgkmcnt(" #n ")" ::: "memory")
; #define PG8_BAR __builtin_amdgcn_s_barrier()
; #define PG8_SCHED __builtin_amdgcn_sched_barrier(0)
; template <class Epi, class Sched, bool ALIGN_EPI = false, bool SP2 = false>
; __device__ __forceinline__ void gemm_phase(PG8_LAS unsigned char* lds, const Gemm g, const Sched& S, const Epi& E) {
;     ...
;             const bool last = (t == nt - 2);
;             const char* a1 = cA + (size_t)(t + 1) * kstep;
;             const char* a2 = last ? nA : cA + (size_t)(t + 2) * kstep; const char* b2 = last ? nB : cB + (size_t)(t + 2) * kstep;
;             const char* a3 = a2 + kstep; const char* b3 = b2 + kstep;
;             if (last && has_next) S.a_ready(nxt);
;             if constexpr (SP2) {
;             PG8_LDB(B0, 0, 0); PG8_LDB(B1, 0, 1); PG8_SCHED; PG8_LDA(At, 0, 0); PG8_STAGE(PG8_SA(1, 1), a1 + hstep, voffA);
;             PG8_WAIT_V(8); PG8_WAIT_L(0); PG8_BAR; PG8_MMA(0, 0, At, B0); PG8_MMA(0, 1, At, B1); PG8_BAR; PG8_SCHED;
;             PG8_LDA(At, 0, 1); PG8_STAGE(PG8_SB(0, 0), b2, voffB); PG8_STAGE(PG8_SB(0, 1), b2 + hstep, voffB); PG8_STAGE(PG8_SA(0, 0), a2, voffA);
.LBB0_1124:
	s_add_u32 s50, s0, 0xfffc0080
	s_addc_u32 s51, s1, -1
	s_add_i32 s56, 0, 0x10000
	s_cmp_eq_u32 s55, 12
	s_cselect_b32 s81, s73, s51
	s_cselect_b32 s80, s86, s50
	s_cselect_b32 s79, s52, s54
	s_cselect_b32 s78, s53, s71
	s_add_i32 s50, 0, 0x14000
	v_add_u32_e32 v142, s56, v174
	v_add_u32_e32 v170, s50, v174
	ds_read_b128 v[130:133], v142
	ds_read_b128 v[134:137], v142 offset:1024
	ds_read_b128 v[138:141], v142 offset:2048
	ds_read_b128 v[142:145], v142 offset:3072
	ds_read_b128 v[146:149], v170
	ds_read_b128 v[150:153], v170 offset:1024
	ds_read_b128 v[154:157], v170 offset:2048
	ds_read_b128 v[178:181], v170 offset:3072
	v_lshl_add_u64 v[170:171], s[0:1], 0, v[166:167]
	s_add_i32 m0, s62, 0xc000
	ds_read_b128 v[182:185], v176
	ds_read_b128 v[192:195], v176 offset:1024
	ds_read_b128 v[196:199], v176 offset:2048
	ds_read_b128 v[200:203], v176 offset:3072
	ds_read_b128 v[204:207], v176 offset:4096
	ds_read_b128 v[208:211], v176 offset:5120
	ds_read_b128 v[212:215], v176 offset:6144
	ds_read_b128 v[216:219], v176 offset:7168
	global_load_lds_dwordx4 v[170:171], off
	v_lshl_add_u64 v[170:171], s[0:1], 0, v[168:169]
	s_add_i32 m0, s62, 0xe000
	s_nop 0
	global_load_lds_dwordx4 v[170:171], off
	s_cmp_lg_u32 s100, 0
	s_cbranch_scc1 .Lpe_skip_mq_0
	s_waitcnt vmcnt(8)
.Lpe_skip_mq_0:
	s_waitcnt lgkmcnt(0)
	s_barrier
	s_setprio 1
	s_waitcnt lgkmcnt(0)
	v_mfma_f32_16x16x32_bf16 v[126:129], v[130:133], v[182:185], v[126:129]
	v_mfma_f32_16x16x32_bf16 v[122:125], v[138:141], v[182:185], v[122:125]
	v_mfma_f32_16x16x32_bf16 v[114:117], v[130:133], v[196:199], v[114:117]
	v_mfma_f32_16x16x32_bf16 v[106:109], v[138:141], v[196:199], v[106:109]
	v_mfma_f32_16x16x32_bf16 v[98:101], v[130:133], v[204:207], v[98:101]
	v_mfma_f32_16x16x32_bf16 v[90:93], v[138:141], v[204:207], v[90:93]
	v_mfma_f32_16x16x32_bf16 v[82:85], v[130:133], v[212:215], v[82:85]
	v_mfma_f32_16x16x32_bf16 v[74:77], v[138:141], v[212:215], v[74:77]
	v_mfma_f32_16x16x32_bf16 v[126:129], v[134:137], v[192:195], v[126:129]
	v_mfma_f32_16x16x32_bf16 v[122:125], v[142:145], v[192:195], v[122:125]
	v_mfma_f32_16x16x32_bf16 v[114:117], v[134:137], v[200:203], v[114:117]
	v_mfma_f32_16x16x32_bf16 v[106:109], v[142:145], v[200:203], v[106:109]
	v_mfma_f32_16x16x32_bf16 v[98:101], v[134:137], v[208:211], v[98:101]
	v_mfma_f32_16x16x32_bf16 v[90:93], v[142:145], v[208:211], v[90:93]
	v_mfma_f32_16x16x32_bf16 v[82:85], v[134:137], v[216:219], v[82:85]
	v_mfma_f32_16x16x32_bf16 v[74:77], v[142:145], v[216:219], v[74:77]
	s_setprio 0
	s_setprio 1
	v_mfma_f32_16x16x32_bf16 v[118:121], v[146:149], v[182:185], v[118:121]
	v_mfma_f32_16x16x32_bf16 v[110:113], v[154:157], v[182:185], v[110:113]
	v_mfma_f32_16x16x32_bf16 v[102:105], v[146:149], v[196:199], v[102:105]
	v_mfma_f32_16x16x32_bf16 v[94:97], v[154:157], v[196:199], v[94:97]
	v_mfma_f32_16x16x32_bf16 v[86:89], v[146:149], v[204:207], v[86:89]
	v_mfma_f32_16x16x32_bf16 v[78:81], v[154:157], v[204:207], v[78:81]
	v_mfma_f32_16x16x32_bf16 v[70:73], v[146:149], v[212:215], v[70:73]
	v_mfma_f32_16x16x32_bf16 v[66:69], v[154:157], v[212:215], v[66:69]
	v_mfma_f32_16x16x32_bf16 v[118:121], v[150:153], v[192:195], v[118:121]
	v_mfma_f32_16x16x32_bf16 v[110:113], v[178:181], v[192:195], v[110:113]
	v_mfma_f32_16x16x32_bf16 v[102:105], v[150:153], v[200:203], v[102:105]
	v_mfma_f32_16x16x32_bf16 v[94:97], v[178:181], v[200:203], v[94:97]
	v_mfma_f32_16x16x32_bf16 v[86:89], v[150:153], v[208:211], v[86:89]
	v_mfma_f32_16x16x32_bf16 v[78:81], v[178:181], v[208:211], v[78:81]
	v_mfma_f32_16x16x32_bf16 v[70:73], v[150:153], v[216:219], v[70:73]
	v_mfma_f32_16x16x32_bf16 v[66:69], v[178:181], v[216:219], v[66:69]
	s_setprio 0
	s_barrier
	s_add_i32 s51, s56, s35
	v_lshl_add_u64 v[170:171], s[78:79], 0, v[0:1]
	s_mov_b32 m0, s51
	ds_read_b128 v[182:185], v176 offset:16384
	ds_read_b128 v[192:195], v176 offset:17408
	ds_read_b128 v[196:199], v176 offset:18432
	ds_read_b128 v[200:203], v176 offset:19456
	ds_read_b128 v[204:207], v176 offset:20480
	ds_read_b128 v[208:211], v176 offset:21504
	ds_read_b128 v[212:215], v176 offset:22528
	ds_read_b128 v[216:219], v176 offset:23552
	global_load_lds_dwordx4 v[170:171], off
	s_add_i32 m0, s51, 0x2000
	s_add_u32 s56, s78, 0x40000
	v_lshl_add_u64 v[188:189], s[78:79], 0, v[158:159]
	s_addc_u32 s57, s79, 0
	s_add_i32 s50, s50, s35
	global_load_lds_dwordx4 v[188:189], off
	v_lshl_add_u64 v[190:191], s[56:57], 0, v[0:1]
	s_mov_b32 m0, s50
	v_lshl_add_u64 v[220:221], s[80:81], 0, v[160:161]
	global_load_lds_dwordx4 v[190:191], off
	v_lshl_add_u64 v[190:191], s[56:57], 0, v[158:159]
	s_add_i32 m0, s50, 0x2000
	s_nop 0
	global_load_lds_dwordx4 v[190:191], off
	v_lshl_add_u64 v[190:191], s[80:81], 0, v[162:163]
	s_mov_b32 m0, s62
	s_nop 0
	global_load_lds_dwordx4 v[190:191], off
	s_mov_b32 m0, s63
	s_nop 0
	global_load_lds_dwordx4 v[220:221], off
	s_cmp_lg_u32 s100, 0
	s_cbranch_scc1 .Lpe_skip_mq_1
	s_waitcnt vmcnt(8)
; #define PG8_STAGE(bufoff, gbase, voff) do { _Pragma("unroll") for (int _i = 0; _i < 2; ++_i) \
;         __builtin_amdgcn_global_load_lds((const unsigned*)((const char*)(gbase) + (voff)[_i]), (PG8_LAS unsigned*)(lds + (bufoff) + ldsw + _i * 8192), 16, 0, 0); } while (0)
; #define PG8_LDA(dst, b, h) do { _Pragma("unroll") for (int m = 0; m < 4; ++m) _Pragma("unroll") for (int k = 0; k < 2; ++k) dst[m][k] = *(const PG8_LAS bf16x8*)(lds + PG8_SA(b, h) + aoff + m * 2048 + k * 1024); } while (0)
; #define PG8_LDB(dst, b, h) do { _Pragma("unroll") for (int n = 0; n < 2; ++n) _Pragma("unroll") for (int k = 0; k < 2; ++k) dst[n][k] = *(const PG8_LAS bf16x8*)(lds + PG8_SB(b, h) + boff + n * 2048 + k * 1024); } while (0)
; #define PG8_MMA(ai, bj, At, Bt) do { __builtin_amdgcn_s_setprio(1); _Pragma("unroll") for (int m = 0; m < 4; ++m) _Pragma("unroll") for (int n = 0; n < 2; ++n) _Pragma("unroll") for (int k = 0; k < 2; ++k) \
;         acc[ai][bj][m][n] = __builtin_amdgcn_mfma_f32_16x16x32_bf16(Bt[n][k], At[m][k], acc[ai][bj][m][n], 0, 0, 0); __builtin_amdgcn_s_setprio(0); } while (0)
; #define PG8_WAIT_V(n) asm volatile("s_waitcnt vmcnt(" #n ")" ::: "memory")
; #define PG8_WAIT_L(n) asm volatile("s_waitcnt lgkmcnt(" #n ")" ::: "memory")
; #define PG8_BAR __builtin_amdgcn_s_barrier()
; #define PG8_SCHED __builtin_amdgcn_sched_barrier(0)
; template <class Epi, class Sched, bool ALIGN_EPI = false, bool SP2 = false>
; __device__ __forceinline__ void gemm_phase(PG8_LAS unsigned char* lds, const Gemm g, const Sched& S, const Epi& E) {
;     ...
;             PG8_WAIT_V(8); PG8_WAIT_L(0); PG8_BAR; PG8_MMA(1, 0, At, B0); PG8_MMA(1, 1, At, B1); PG8_BAR; PG8_SCHED;
;             PG8_LDB(B0, 1, 0); PG8_LDB(B1, 1, 1); PG8_SCHED; PG8_LDA(At, 1, 0); PG8_STAGE(PG8_SA(0, 1), a2 + hstep, voffA);
;             PG8_WAIT_V(8); PG8_WAIT_L(0); PG8_BAR; PG8_MMA(0, 0, At, B0); PG8_MMA(0, 1, At, B1); PG8_BAR; PG8_SCHED;
.Lpe_skip_mq_1:
	s_mov_b32 s100, 0
	s_waitcnt lgkmcnt(0)
	s_barrier
	s_setprio 1
	s_waitcnt lgkmcnt(0)
	v_mfma_f32_16x16x32_bf16 v[62:65], v[130:133], v[182:185], v[62:65]
	v_mfma_f32_16x16x32_bf16 v[58:61], v[138:141], v[182:185], v[58:61]
	v_mfma_f32_16x16x32_bf16 v[50:53], v[130:133], v[196:199], v[50:53]
	v_mfma_f32_16x16x32_bf16 v[42:45], v[138:141], v[196:199], v[42:45]
	v_mfma_f32_16x16x32_bf16 v[34:37], v[130:133], v[204:207], v[34:37]
	v_mfma_f32_16x16x32_bf16 v[26:29], v[138:141], v[204:207], v[26:29]
	v_mfma_f32_16x16x32_bf16 v[18:21], v[130:133], v[212:215], v[18:21]
	v_mfma_f32_16x16x32_bf16 v[10:13], v[138:141], v[212:215], v[10:13]
	v_mfma_f32_16x16x32_bf16 v[62:65], v[134:137], v[192:195], v[62:65]
	v_mfma_f32_16x16x32_bf16 v[58:61], v[142:145], v[192:195], v[58:61]
	v_mfma_f32_16x16x32_bf16 v[50:53], v[134:137], v[200:203], v[50:53]
	v_mfma_f32_16x16x32_bf16 v[42:45], v[142:145], v[200:203], v[42:45]
	v_mfma_f32_16x16x32_bf16 v[34:37], v[134:137], v[208:211], v[34:37]
	v_mfma_f32_16x16x32_bf16 v[26:29], v[142:145], v[208:211], v[26:29]
	v_mfma_f32_16x16x32_bf16 v[18:21], v[134:137], v[216:219], v[18:21]
	v_mfma_f32_16x16x32_bf16 v[10:13], v[142:145], v[216:219], v[10:13]
	s_setprio 0
	s_setprio 1
	v_mfma_f32_16x16x32_bf16 v[54:57], v[146:149], v[182:185], v[54:57]
	v_mfma_f32_16x16x32_bf16 v[46:49], v[154:157], v[182:185], v[46:49]
	v_mfma_f32_16x16x32_bf16 v[38:41], v[146:149], v[196:199], v[38:41]
	v_mfma_f32_16x16x32_bf16 v[30:33], v[154:157], v[196:199], v[30:33]
	v_mfma_f32_16x16x32_bf16 v[22:25], v[146:149], v[204:207], v[22:25]
	v_mfma_f32_16x16x32_bf16 v[14:17], v[154:157], v[204:207], v[14:17]
	v_mfma_f32_16x16x32_bf16 v[6:9], v[146:149], v[212:215], v[6:9]
	v_mfma_f32_16x16x32_bf16 v[2:5], v[154:157], v[212:215], v[2:5]
	v_mfma_f32_16x16x32_bf16 v[54:57], v[150:153], v[192:195], v[54:57]
	v_mfma_f32_16x16x32_bf16 v[46:49], v[178:181], v[192:195], v[46:49]
	v_mfma_f32_16x16x32_bf16 v[38:41], v[150:153], v[200:203], v[38:41]
	v_mfma_f32_16x16x32_bf16 v[30:33], v[178:181], v[200:203], v[30:33]
	v_mfma_f32_16x16x32_bf16 v[22:25], v[150:153], v[208:211], v[22:25]
	v_mfma_f32_16x16x32_bf16 v[14:17], v[178:181], v[208:211], v[14:17]
	v_mfma_f32_16x16x32_bf16 v[6:9], v[150:153], v[216:219], v[6:9]
	v_mfma_f32_16x16x32_bf16 v[2:5], v[178:181], v[216:219], v[2:5]
	s_setprio 0
	s_barrier
	s_add_i32 s50, 0, 0x18000
	s_add_i32 s51, 0, 0x1c000
	v_add_u32_e32 v142, s50, v174
	v_add_u32_e32 v172, s51, v174
	ds_read_b128 v[130:133], v142
	ds_read_b128 v[134:137], v142 offset:1024
	ds_read_b128 v[138:141], v142 offset:2048
	ds_read_b128 v[142:145], v142 offset:3072
	ds_read_b128 v[146:149], v172
	ds_read_b128 v[150:153], v172 offset:1024
	ds_read_b128 v[154:157], v172 offset:2048
	ds_read_b128 v[178:181], v172 offset:3072
	s_add_u32 s56, s80, 0x40000
	s_addc_u32 s57, s81, 0
	s_mov_b32 m0, s64
	v_lshl_add_u64 v[222:223], s[56:57], 0, v[162:163]
	ds_read_b128 v[182:185], v176 offset:32768
	ds_read_b128 v[192:195], v176 offset:33792
	ds_read_b128 v[196:199], v176 offset:34816
	ds_read_b128 v[200:203], v176 offset:35840
	ds_read_b128 v[204:207], v176 offset:36864
	ds_read_b128 v[208:211], v176 offset:37888
	ds_read_b128 v[212:215], v176 offset:38912
	ds_read_b128 v[216:219], v176 offset:39936
	global_load_lds_dwordx4 v[222:223], off
	v_lshl_add_u64 v[222:223], s[56:57], 0, v[160:161]
	s_mov_b32 m0, s82
	s_nop 0
	global_load_lds_dwordx4 v[222:223], off
	s_waitcnt vmcnt(8)
	s_waitcnt lgkmcnt(0)
	s_barrier
	s_setprio 1
	s_waitcnt lgkmcnt(0)
	v_mfma_f32_16x16x32_bf16 v[126:129], v[130:133], v[182:185], v[126:129]
	v_mfma_f32_16x16x32_bf16 v[122:125], v[138:141], v[182:185], v[122:125]
	v_mfma_f32_16x16x32_bf16 v[114:117], v[130:133], v[196:199], v[114:117]
	v_mfma_f32_16x16x32_bf16 v[106:109], v[138:141], v[196:199], v[106:109]
	v_mfma_f32_16x16x32_bf16 v[98:101], v[130:133], v[204:207], v[98:101]
	v_mfma_f32_16x16x32_bf16 v[90:93], v[138:141], v[204:207], v[90:93]
	v_mfma_f32_16x16x32_bf16 v[82:85], v[130:133], v[212:215], v[82:85]
	v_mfma_f32_16x16x32_bf16 v[74:77], v[138:141], v[212:215], v[74:77]
	v_mfma_f32_16x16x32_bf16 v[126:129], v[134:137], v[192:195], v[126:129]
	v_mfma_f32_16x16x32_bf16 v[122:125], v[142:145], v[192:195], v[122:125]
	v_mfma_f32_16x16x32_bf16 v[114:117], v[134:137], v[200:203], v[114:117]
	v_mfma_f32_16x16x32_bf16 v[106:109], v[142:145], v[200:203], v[106:109]
	v_mfma_f32_16x16x32_bf16 v[98:101], v[134:137], v[208:211], v[98:101]
	v_mfma_f32_16x16x32_bf16 v[90:93], v[142:145], v[208:211], v[90:93]
	v_mfma_f32_16x16x32_bf16 v[82:85], v[134:137], v[216:219], v[82:85]
	v_mfma_f32_16x16x32_bf16 v[74:77], v[142:145], v[216:219], v[74:77]
	s_setprio 0
	s_setprio 1
	v_mfma_f32_16x16x32_bf16 v[118:121], v[146:149], v[182:185], v[118:121]
	v_mfma_f32_16x16x32_bf16 v[110:113], v[154:157], v[182:185], v[110:113]
	v_mfma_f32_16x16x32_bf16 v[102:105], v[146:149], v[196:199], v[102:105]
	v_mfma_f32_16x16x32_bf16 v[94:97], v[154:157], v[196:199], v[94:97]
	v_mfma_f32_16x16x32_bf16 v[86:89], v[146:149], v[204:207], v[86:89]
	v_mfma_f32_16x16x32_bf16 v[78:81], v[154:157], v[204:207], v[78:81]
	v_mfma_f32_16x16x32_bf16 v[70:73], v[146:149], v[212:215], v[70:73]
	v_mfma_f32_16x16x32_bf16 v[66:69], v[154:157], v[212:215], v[66:69]
	v_mfma_f32_16x16x32_bf16 v[118:121], v[150:153], v[192:195], v[118:121]
	v_mfma_f32_16x16x32_bf16 v[110:113], v[178:181], v[192:195], v[110:113]
	v_mfma_f32_16x16x32_bf16 v[102:105], v[150:153], v[200:203], v[102:105]
	v_mfma_f32_16x16x32_bf16 v[94:97], v[178:181], v[200:203], v[94:97]
	v_mfma_f32_16x16x32_bf16 v[86:89], v[150:153], v[208:211], v[86:89]
	v_mfma_f32_16x16x32_bf16 v[78:81], v[178:181], v[208:211], v[78:81]
	v_mfma_f32_16x16x32_bf16 v[70:73], v[150:153], v[216:219], v[70:73]
	v_mfma_f32_16x16x32_bf16 v[66:69], v[178:181], v[216:219], v[66:69]
	s_setprio 0
	s_barrier
; #define PG8_STAGE(bufoff, gbase, voff) do { _Pragma("unroll") for (int _i = 0; _i < 2; ++_i) \
;         __builtin_amdgcn_global_load_lds((const unsigned*)((const char*)(gbase) + (voff)[_i]), (PG8_LAS unsigned*)(lds + (bufoff) + ldsw + _i * 8192), 16, 0, 0); } while (0)
; #define PG8_LDA(dst, b, h) do { _Pragma("unroll") for (int m = 0; m < 4; ++m) _Pragma("unroll") for (int k = 0; k < 2; ++k) dst[m][k] = *(const PG8_LAS bf16x8*)(lds + PG8_SA(b, h) + aoff + m * 2048 + k * 1024); } while (0)
; #define PG8_MMA(ai, bj, At, Bt) do { __builtin_amdgcn_s_setprio(1); _Pragma("unroll") for (int m = 0; m < 4; ++m) _Pragma("unroll") for (int n = 0; n < 2; ++n) _Pragma("unroll") for (int k = 0; k < 2; ++k) \
;         acc[ai][bj][m][n] = __builtin_amdgcn_mfma_f32_16x16x32_bf16(Bt[n][k], At[m][k], acc[ai][bj][m][n], 0, 0, 0); __builtin_amdgcn_s_setprio(0); } while (0)
; #define PG8_WAIT_V(n) asm volatile("s_waitcnt vmcnt(" #n ")" ::: "memory")
; #define PG8_WAIT_L(n) asm volatile("s_waitcnt lgkmcnt(" #n ")" ::: "memory")
; #define PG8_BAR __builtin_amdgcn_s_barrier()
; #define PG8_SCHED __builtin_amdgcn_sched_barrier(0)
; __device__ __forceinline__ void load_row_scales(const float* ssp, int row0, int fq, float (&rs)[2][4]) {
;     f32x4 part[2][4];
;     const float* sp = ssp + (size_t)row0 * 16 + 4 * fq;
; #pragma unroll
;     for (int ai = 0; ai < 2; ++ai)
; #pragma unroll
;         for (int m = 0; m < 4; ++m) part[ai][m] = *(const f32x4*)(sp + (size_t)(ai * HALF + m * 16) * 16);
; #pragma unroll
;     for (int ai = 0; ai < 2; ++ai)
; #pragma unroll
;         for (int m = 0; m < 4; ++m) { float t = (part[ai][m][0] + part[ai][m][1]) + (part[ai][m][2] + part[ai][m][3]);
;             t += __shfl_xor(t, 16); t += __shfl_xor(t, 32);
;             rs[ai][m] = 1.0f / sqrtf(t * (1.0f / 1024.0f) + 1e-6f); }
; template <class Epi, class Sched, bool ALIGN_EPI = false, bool SP2 = false>
; __device__ __forceinline__ void gemm_phase(PG8_LAS unsigned char* lds, const Gemm g, const Sched& S, const Epi& E) {
;     ...
;             PG8_LDA(At, 1, 1); PG8_STAGE(PG8_SB(1, 0), b3, voffB); PG8_STAGE(PG8_SB(1, 1), b3 + hstep, voffB); PG8_STAGE(PG8_SA(1, 0), a3, voffA);
;             PG8_WAIT_V(8); PG8_WAIT_L(0); PG8_BAR; PG8_MMA(1, 0, At, B0); PG8_MMA(1, 1, At, B1); PG8_BAR; PG8_SCHED;
	s_add_i32 s50, s50, s35
	v_lshl_add_u64 v[170:171], v[170:171], 0, s[60:61]
	s_mov_b32 m0, s50
	ds_read_b128 v[182:185], v176 offset:49152
	ds_read_b128 v[192:195], v176 offset:50176
	ds_read_b128 v[196:199], v176 offset:51200
	ds_read_b128 v[200:203], v176 offset:52224
	ds_read_b128 v[204:207], v176 offset:53248
	ds_read_b128 v[208:211], v176 offset:54272
	ds_read_b128 v[212:215], v176 offset:55296
	ds_read_b128 v[216:219], v176 offset:56320
	global_load_lds_dwordx4 v[170:171], off
	s_add_i32 m0, s50, 0x2000
	s_add_u32 s56, s78, 0x40080
	v_lshl_add_u64 v[170:171], v[188:189], 0, s[60:61]
	s_addc_u32 s57, s79, 0
	s_add_i32 s50, s51, s35
	global_load_lds_dwordx4 v[170:171], off
	v_lshl_add_u64 v[170:171], s[56:57], 0, v[0:1]
	s_mov_b32 m0, s50
	s_nop 0
	global_load_lds_dwordx4 v[170:171], off
	v_lshl_add_u64 v[170:171], s[56:57], 0, v[158:159]
	s_add_i32 m0, s50, 0x2000
	s_nop 0
	global_load_lds_dwordx4 v[170:171], off
	v_lshl_add_u64 v[170:171], v[190:191], 0, s[60:61]
	s_mov_b32 m0, s83
	s_nop 0
	global_load_lds_dwordx4 v[170:171], off
	v_lshl_add_u64 v[170:171], v[220:221], 0, s[60:61]
	s_mov_b32 m0, s84
	s_nop 0
	global_load_lds_dwordx4 v[170:171], off
	s_waitcnt vmcnt(8)
	s_waitcnt lgkmcnt(0)
	s_barrier
	s_setprio 1
	s_waitcnt lgkmcnt(0)
	v_mfma_f32_16x16x32_bf16 v[62:65], v[130:133], v[182:185], v[62:65]
	v_mfma_f32_16x16x32_bf16 v[58:61], v[138:141], v[182:185], v[58:61]
	v_mfma_f32_16x16x32_bf16 v[50:53], v[130:133], v[196:199], v[50:53]
	v_mfma_f32_16x16x32_bf16 v[42:45], v[138:141], v[196:199], v[42:45]
	v_mfma_f32_16x16x32_bf16 v[34:37], v[130:133], v[204:207], v[34:37]
	v_mfma_f32_16x16x32_bf16 v[26:29], v[138:141], v[204:207], v[26:29]
	v_mfma_f32_16x16x32_bf16 v[18:21], v[130:133], v[212:215], v[18:21]
	v_mfma_f32_16x16x32_bf16 v[10:13], v[138:141], v[212:215], v[10:13]
	v_mfma_f32_16x16x32_bf16 v[62:65], v[134:137], v[192:195], v[62:65]
	v_mfma_f32_16x16x32_bf16 v[58:61], v[142:145], v[192:195], v[58:61]
	v_mfma_f32_16x16x32_bf16 v[50:53], v[134:137], v[200:203], v[50:53]
	v_mfma_f32_16x16x32_bf16 v[42:45], v[142:145], v[200:203], v[42:45]
	v_mfma_f32_16x16x32_bf16 v[34:37], v[134:137], v[208:211], v[34:37]
	v_mfma_f32_16x16x32_bf16 v[26:29], v[142:145], v[208:211], v[26:29]
	v_mfma_f32_16x16x32_bf16 v[18:21], v[134:137], v[216:219], v[18:21]
	v_mfma_f32_16x16x32_bf16 v[10:13], v[142:145], v[216:219], v[10:13]
	s_setprio 0
	s_setprio 1
	v_mfma_f32_16x16x32_bf16 v[54:57], v[146:149], v[182:185], v[54:57]
	v_mfma_f32_16x16x32_bf16 v[46:49], v[154:157], v[182:185], v[46:49]
	v_mfma_f32_16x16x32_bf16 v[38:41], v[146:149], v[196:199], v[38:41]
	v_mfma_f32_16x16x32_bf16 v[30:33], v[154:157], v[196:199], v[30:33]
	v_mfma_f32_16x16x32_bf16 v[22:25], v[146:149], v[204:207], v[22:25]
	v_mfma_f32_16x16x32_bf16 v[14:17], v[154:157], v[204:207], v[14:17]
	v_mfma_f32_16x16x32_bf16 v[6:9], v[146:149], v[212:215], v[6:9]
	v_mfma_f32_16x16x32_bf16 v[2:5], v[154:157], v[212:215], v[2:5]
	v_mfma_f32_16x16x32_bf16 v[54:57], v[150:153], v[192:195], v[54:57]
	v_mfma_f32_16x16x32_bf16 v[46:49], v[178:181], v[192:195], v[46:49]
	v_mfma_f32_16x16x32_bf16 v[38:41], v[150:153], v[200:203], v[38:41]
	v_mfma_f32_16x16x32_bf16 v[30:33], v[178:181], v[200:203], v[30:33]
	v_mfma_f32_16x16x32_bf16 v[22:25], v[150:153], v[208:211], v[22:25]
	v_mfma_f32_16x16x32_bf16 v[14:17], v[178:181], v[208:211], v[14:17]
	v_mfma_f32_16x16x32_bf16 v[6:9], v[150:153], v[216:219], v[6:9]
	v_mfma_f32_16x16x32_bf16 v[2:5], v[178:181], v[216:219], v[2:5]
	s_setprio 0
	s_barrier
	s_add_i32 s55, s55, 2
	s_add_u32 s0, s0, 0x100
	s_addc_u32 s1, s1, 0
	s_add_u32 s71, s71, 0x100
	s_addc_u32 s54, s54, 0
	s_cmp_gt_u32 s55, 13
	s_cbranch_scc0 .LBB0_1124
	v_readlane_b32 s86, v255, 25
	s_and_b64 vcc, exec, s[8:9]
	v_readlane_b32 s87, v255, 26
	s_cbranch_vccz .LBB0_1127
	s_barrier
.LBB0_1127:
	v_lshl_add_u32 v130, s13, 8, v173
	v_ashrrev_i32_e32 v131, 31, v130
	v_lshlrev_b64 v[134:135], 11, v[130:131]
	v_lshlrev_b64 v[130:131], 6, v[130:131]
	v_lshl_add_u64 v[130:131], v[164:165], 0, v[130:131]
	global_load_dwordx4 v[180:183], v[130:131], off
	global_load_dwordx4 v[154:157], v[130:131], off offset:1024
	global_load_dwordx4 v[150:153], v[130:131], off offset:2048
	global_load_dwordx4 v[146:149], v[130:131], off offset:3072
	s_movk_i32 s0, 0x2000
	v_add_co_u32_e32 v130, vcc, s0, v130
	v_and_b32_e32 v177, 64, v229
	s_nop 0
	v_addc_co_u32_e32 v131, vcc, 0, v131, vcc
	v_xor_b32_e32 v172, 16, v229
	v_add_u32_e32 v178, 64, v177
	v_cmp_lt_i32_e32 vcc, v172, v178
	v_lshl_or_b32 v132, s12, 8, v175
	v_lshl_add_u64 v[134:135], s[46:47], 0, v[134:135]
	v_cndmask_b32_e32 v172, v229, v172, vcc
	v_lshlrev_b32_e32 v177, 2, v172
	v_xor_b32_e32 v172, 32, v229
	v_cmp_lt_i32_e32 vcc, v172, v178
	v_ashrrev_i32_e32 v133, 31, v132
	v_lshl_add_u64 v[170:171], v[132:133], 1, v[134:135]
	v_cndmask_b32_e32 v172, v229, v172, vcc
	v_lshlrev_b32_e32 v178, 2, v172
	global_load_dwordx4 v[142:145], v[130:131], off
	global_load_dwordx4 v[138:141], v[130:131], off offset:1024
	global_load_dwordx4 v[134:137], v[130:131], off offset:2048
	s_nop 0
	global_load_dwordx4 v[130:133], v[130:131], off offset:3072
	s_mov_b64 s[12:13], 0x8000
	s_waitcnt vmcnt(0)
	s_mov_b32 s100, 1
	v_mov_b32_e32 v184, v181
	v_mov_b32_e32 v185, v182
	v_mov_b32_e32 v181, v183
	v_pk_add_f32 v[180:181], v[184:185], v[180:181]
	s_nop 0
	v_add_f32_e32 v172, v180, v181
	v_mov_b32_e32 v179, v172
	s_nop 1
	v_permlane16_swap_b32_e32 v179, v172
	s_waitcnt lgkmcnt(0)
	v_add_f32_e32 v172, v172, v179
	v_mov_b32_e32 v179, v172
	s_nop 1
	v_permlane32_swap_b32_e32 v179, v172
	s_waitcnt lgkmcnt(0)
; __device__ __forceinline__ void load_row_scales(const float* ssp, int row0, int fq, float (&rs)[2][4]) {
;     ...
;         for (int m = 0; m < 4; ++m) { float t = (part[ai][m][0] + part[ai][m][1]) + (part[ai][m][2] + part[ai][m][3]);
;             t += __shfl_xor(t, 16); t += __shfl_xor(t, 32);
;             rs[ai][m] = 1.0f / sqrtf(t * (1.0f / 1024.0f) + 1e-6f); }
;     __device__ __forceinline__ void operator()(f32x4 (&acc)[2][2][4][2], const Unit& u, int wr, int wc, int fr, int fq) const {
;     ...
;                 for (int m = 0; m < 4; ++m) { const float rs = rsa[ai][m];
; #pragma unroll
;                     for (int bj = 0; bj < 2; ++bj) { const f32x4 v0 = acc[ai][bj][m][0] * rs, v1 = acc[ai][bj][m][1] * rs;
	v_add_f32_e32 v172, v172, v179
	v_fmamk_f32 v172, v172, 0x3a800000, v230
	v_mov_b32_e32 v180, v155
	v_mov_b32_e32 v181, v156
	v_mov_b32_e32 v155, v157
	v_pk_add_f32 v[154:155], v[180:181], v[154:155]
	v_rsq_f32_e32 v172, v172
	s_nop 0
	v_add_f32_e32 v154, v154, v155
	v_mov_b32_e32 v155, v154
	s_nop 1
	v_permlane16_swap_b32_e32 v155, v154
	v_pk_mul_f32 v[128:129], v[128:129], v[172:173] op_sel_hi:[1,0]
	v_pk_mul_f32 v[126:127], v[126:127], v[172:173] op_sel_hi:[1,0]
	v_pk_mul_f32 v[120:121], v[120:121], v[172:173] op_sel_hi:[1,0]
	v_pk_mul_f32 v[118:119], v[118:119], v[172:173] op_sel_hi:[1,0]
	s_waitcnt lgkmcnt(0)
	v_add_f32_e32 v154, v154, v155
	v_mov_b32_e32 v155, v154
	s_nop 1
	v_permlane32_swap_b32_e32 v155, v154
	s_waitcnt lgkmcnt(0)
	v_add_f32_e32 v154, v154, v155
	v_fmamk_f32 v154, v154, 0x3a800000, v230
	v_mov_b32_e32 v156, v151
	v_mov_b32_e32 v157, v152
	v_mov_b32_e32 v151, v153
	v_pk_add_f32 v[150:151], v[156:157], v[150:151]
	v_rsq_f32_e32 v154, v154
	s_nop 0
	v_add_f32_e32 v150, v150, v151
	v_mov_b32_e32 v151, v150
	s_nop 1
	v_permlane16_swap_b32_e32 v151, v150
	s_waitcnt lgkmcnt(0)
	v_add_f32_e32 v150, v150, v151
	v_mov_b32_e32 v151, v150
	s_nop 1
	v_permlane32_swap_b32_e32 v151, v150
	s_waitcnt lgkmcnt(0)
	v_add_f32_e32 v150, v150, v151
	v_fmamk_f32 v150, v150, 0x3a800000, v230
	v_mov_b32_e32 v152, v147
	v_mov_b32_e32 v153, v148
	v_mov_b32_e32 v147, v149
	v_pk_add_f32 v[146:147], v[152:153], v[146:147]
	v_rsq_f32_e32 v150, v150
	s_nop 0
	v_add_f32_e32 v146, v146, v147
	v_mov_b32_e32 v147, v146
	s_nop 1
	v_permlane16_swap_b32_e32 v147, v146
	v_pk_mul_f32 v[114:115], v[114:115], v[154:155] op_sel_hi:[1,0]
	v_pk_mul_f32 v[104:105], v[104:105], v[154:155] op_sel_hi:[1,0]
	v_pk_mul_f32 v[102:103], v[102:103], v[154:155] op_sel_hi:[1,0]
	s_waitcnt lgkmcnt(0)
	v_add_f32_e32 v146, v146, v147
	v_mov_b32_e32 v147, v146
	s_nop 1
	v_permlane32_swap_b32_e32 v147, v146
	s_waitcnt lgkmcnt(0)
	v_add_f32_e32 v146, v146, v147
	v_fmamk_f32 v146, v146, 0x3a800000, v230
	v_mov_b32_e32 v148, v143
	v_mov_b32_e32 v149, v144
	v_mov_b32_e32 v143, v145
	v_pk_add_f32 v[142:143], v[148:149], v[142:143]
	v_rsq_f32_e32 v146, v146
	s_nop 0
	v_add_f32_e32 v142, v142, v143
	v_mov_b32_e32 v143, v142
	s_nop 1
	v_permlane16_swap_b32_e32 v143, v142
	v_pk_mul_f32 v[98:99], v[98:99], v[150:151] op_sel_hi:[1,0]
	v_pk_mul_f32 v[88:89], v[88:89], v[150:151] op_sel_hi:[1,0]
	v_pk_mul_f32 v[86:87], v[86:87], v[150:151] op_sel_hi:[1,0]
	s_waitcnt lgkmcnt(0)
	v_add_f32_e32 v142, v142, v143
	v_mov_b32_e32 v143, v142
	s_nop 1
	v_permlane32_swap_b32_e32 v143, v142
	s_waitcnt lgkmcnt(0)
	v_add_f32_e32 v142, v142, v143
	v_fmamk_f32 v142, v142, 0x3a800000, v230
	v_mov_b32_e32 v144, v139
	v_mov_b32_e32 v145, v140
	v_mov_b32_e32 v139, v141
	v_pk_add_f32 v[138:139], v[144:145], v[138:139]
	v_rsq_f32_e32 v142, v142
	s_nop 0
	v_add_f32_e32 v138, v138, v139
	v_mov_b32_e32 v139, v138
	s_nop 1
	v_permlane16_swap_b32_e32 v139, v138
	v_pk_mul_f32 v[82:83], v[82:83], v[146:147] op_sel_hi:[1,0]
	v_pk_mul_f32 v[72:73], v[72:73], v[146:147] op_sel_hi:[1,0]
	v_pk_mul_f32 v[70:71], v[70:71], v[146:147] op_sel_hi:[1,0]
	s_waitcnt lgkmcnt(0)
	v_add_f32_e32 v138, v138, v139
	v_mov_b32_e32 v139, v138
	s_nop 1
	v_permlane32_swap_b32_e32 v139, v138
	s_waitcnt lgkmcnt(0)
	v_add_f32_e32 v138, v138, v139
	v_fmamk_f32 v138, v138, 0x3a800000, v230
	v_mov_b32_e32 v140, v135
	v_mov_b32_e32 v141, v136
	v_mov_b32_e32 v135, v137
	v_pk_add_f32 v[134:135], v[140:141], v[134:135]
	v_rsq_f32_e32 v138, v138
	s_nop 0
	v_add_f32_e32 v134, v134, v135
	v_mov_b32_e32 v135, v134
	s_nop 1
	v_permlane16_swap_b32_e32 v135, v134
	v_pk_mul_f32 v[64:65], v[64:65], v[142:143] op_sel_hi:[1,0]
	v_pk_mul_f32 v[62:63], v[62:63], v[142:143] op_sel_hi:[1,0]
	v_pk_mul_f32 v[56:57], v[56:57], v[142:143] op_sel_hi:[1,0]
	v_pk_mul_f32 v[54:55], v[54:55], v[142:143] op_sel_hi:[1,0]
	s_waitcnt lgkmcnt(0)
	v_add_f32_e32 v134, v134, v135
	v_mov_b32_e32 v135, v134
	s_nop 1
	v_permlane32_swap_b32_e32 v135, v134
	s_waitcnt lgkmcnt(0)
	v_add_f32_e32 v134, v134, v135
	v_fmamk_f32 v134, v134, 0x3a800000, v230
	v_mov_b32_e32 v136, v131
	v_mov_b32_e32 v137, v132
	v_mov_b32_e32 v131, v133
	v_pk_add_f32 v[130:131], v[136:137], v[130:131]
	v_rsq_f32_e32 v134, v134
	s_nop 0
	v_add_f32_e32 v130, v130, v131
	v_mov_b32_e32 v131, v130
	s_nop 1
	v_permlane16_swap_b32_e32 v131, v130
	v_pk_mul_f32 v[50:51], v[50:51], v[138:139] op_sel_hi:[1,0]
	v_pk_mul_f32 v[40:41], v[40:41], v[138:139] op_sel_hi:[1,0]
	v_pk_mul_f32 v[38:39], v[38:39], v[138:139] op_sel_hi:[1,0]
	s_waitcnt lgkmcnt(0)
	v_add_f32_e32 v130, v130, v131
	v_mov_b32_e32 v131, v130
	s_nop 1
	v_permlane32_swap_b32_e32 v131, v130
	s_waitcnt lgkmcnt(0)
; __device__ __forceinline__ unsigned cvt_pk_bf16(float lo, float hi) { unsigned r; asm volatile("v_cvt_pk_bf16_f32 %0, %1, %2" : "=v"(r) : "v"(lo), "v"(hi)); return r; }
;     __device__ __forceinline__ void operator()(f32x4 (&acc)[2][2][4][2], const Unit& u, int wr, int wc, int fr, int fq) const {
;     ...
; #pragma unroll
;             for (int ai = 0; ai < 2; ++ai) {
; #pragma unroll
;                 for (int m = 0; m < 4; ++m) { const float rs = rsa[ai][m];
; #pragma unroll
;                     for (int bj = 0; bj < 2; ++bj) { const f32x4 v0 = acc[ai][bj][m][0] * rs, v1 = acc[ai][bj][m][1] * rs;
;                         u32x4 w; w.x = cvt_pk_bf16(v0[0], v0[1]); w.y = cvt_pk_bf16(v0[2], v0[3]); w.z = cvt_pk_bf16(v1[0], v1[1]); w.w = cvt_pk_bf16(v1[2], v1[3]);
;                         *(u32x4*)(rowp + bj * HALF) = w; }
;                     rowp += (size_t)16 * ldr; asm volatile("" : "+v"(rowp) :: "memory"); }
;                 rowp += (size_t)64 * ldr; asm volatile("" : "+v"(rowp)); }
	v_add_f32_e32 v130, v130, v131
	v_fmamk_f32 v130, v130, 0x3a800000, v230
	s_mov_b64 s[0:1], 0x20000
	v_pk_mul_f32 v[132:133], v[124:125], v[172:173] op_sel_hi:[1,0]
	v_pk_mul_f32 v[124:125], v[122:123], v[172:173] op_sel_hi:[1,0]
	v_cvt_pk_bf16_f32 v122, v126, v127
	v_cvt_pk_bf16_f32 v123, v128, v129
	v_pk_mul_f32 v[34:35], v[34:35], v[134:135] op_sel_hi:[1,0]
	v_cvt_pk_bf16_f32 v124, v124, v125
	v_cvt_pk_bf16_f32 v125, v132, v133
	global_store_dwordx4 v[170:171], v[122:125], off
	v_pk_mul_f32 v[24:25], v[24:25], v[134:135] op_sel_hi:[1,0]
	v_pk_mul_f32 v[22:23], v[22:23], v[134:135] op_sel_hi:[1,0]
	v_pk_mul_f32 v[122:123], v[112:113], v[172:173] op_sel_hi:[1,0]
	v_pk_mul_f32 v[112:113], v[110:111], v[172:173] op_sel_hi:[1,0]
	v_cvt_pk_bf16_f32 v110, v118, v119
	v_cvt_pk_bf16_f32 v111, v120, v121
	v_rsq_f32_e32 v130, v130
	s_nop 0
	v_cvt_pk_bf16_f32 v112, v112, v113
	v_cvt_pk_bf16_f32 v113, v122, v123
	global_store_dwordx4 v[170:171], v[110:113], off offset:256
	v_pk_mul_f32 v[18:19], v[18:19], v[130:131] op_sel_hi:[1,0]
	v_pk_mul_f32 v[8:9], v[8:9], v[130:131] op_sel_hi:[1,0]
	v_lshl_add_u64 v[110:111], v[170:171], 0, s[12:13]
	v_pk_mul_f32 v[112:113], v[116:117], v[154:155] op_sel_hi:[1,0]
	v_pk_mul_f32 v[116:117], v[108:109], v[154:155] op_sel_hi:[1,0]
	v_pk_mul_f32 v[108:109], v[106:107], v[154:155] op_sel_hi:[1,0]
	v_cvt_pk_bf16_f32 v106, v114, v115
	v_cvt_pk_bf16_f32 v107, v112, v113
	v_pk_mul_f32 v[6:7], v[6:7], v[130:131] op_sel_hi:[1,0]
	v_cvt_pk_bf16_f32 v108, v108, v109
	v_cvt_pk_bf16_f32 v109, v116, v117
	global_store_dwordx4 v[110:111], v[106:109], off
	s_andn2_b64 vcc, exec, s[6:7]
	s_nop 0
	v_pk_mul_f32 v[106:107], v[96:97], v[154:155] op_sel_hi:[1,0]
	v_pk_mul_f32 v[96:97], v[94:95], v[154:155] op_sel_hi:[1,0]
	v_cvt_pk_bf16_f32 v94, v102, v103
	v_cvt_pk_bf16_f32 v95, v104, v105
	s_nop 0
	v_cvt_pk_bf16_f32 v96, v96, v97
	v_cvt_pk_bf16_f32 v97, v106, v107
	global_store_dwordx4 v[110:111], v[94:97], off offset:256
	s_nop 1
	v_lshl_add_u64 v[94:95], v[110:111], 0, s[12:13]
	v_pk_mul_f32 v[96:97], v[100:101], v[150:151] op_sel_hi:[1,0]
	v_pk_mul_f32 v[100:101], v[92:93], v[150:151] op_sel_hi:[1,0]
	v_pk_mul_f32 v[92:93], v[90:91], v[150:151] op_sel_hi:[1,0]
	v_cvt_pk_bf16_f32 v90, v98, v99
	v_cvt_pk_bf16_f32 v91, v96, v97
	s_nop 0
	v_cvt_pk_bf16_f32 v92, v92, v93
	v_cvt_pk_bf16_f32 v93, v100, v101
	global_store_dwordx4 v[94:95], v[90:93], off
	s_nop 1
	v_pk_mul_f32 v[90:91], v[80:81], v[150:151] op_sel_hi:[1,0]
	v_pk_mul_f32 v[80:81], v[78:79], v[150:151] op_sel_hi:[1,0]
	v_cvt_pk_bf16_f32 v78, v86, v87
	v_cvt_pk_bf16_f32 v79, v88, v89
	s_nop 0
	v_cvt_pk_bf16_f32 v80, v80, v81
	v_cvt_pk_bf16_f32 v81, v90, v91
	global_store_dwordx4 v[94:95], v[78:81], off offset:256
	s_nop 1
	v_lshl_add_u64 v[78:79], v[94:95], 0, s[12:13]
	v_pk_mul_f32 v[80:81], v[84:85], v[146:147] op_sel_hi:[1,0]
	v_pk_mul_f32 v[84:85], v[76:77], v[146:147] op_sel_hi:[1,0]
	v_pk_mul_f32 v[76:77], v[74:75], v[146:147] op_sel_hi:[1,0]
	v_cvt_pk_bf16_f32 v74, v82, v83
	v_cvt_pk_bf16_f32 v75, v80, v81
	s_nop 0
	v_cvt_pk_bf16_f32 v76, v76, v77
	v_cvt_pk_bf16_f32 v77, v84, v85
	global_store_dwordx4 v[78:79], v[74:77], off
	s_nop 1
	v_pk_mul_f32 v[74:75], v[68:69], v[146:147] op_sel_hi:[1,0]
	v_pk_mul_f32 v[68:69], v[66:67], v[146:147] op_sel_hi:[1,0]
	v_cvt_pk_bf16_f32 v66, v70, v71
	v_cvt_pk_bf16_f32 v67, v72, v73
	s_nop 0
	v_cvt_pk_bf16_f32 v68, v68, v69
	v_cvt_pk_bf16_f32 v69, v74, v75
	global_store_dwordx4 v[78:79], v[66:69], off offset:256
	s_nop 1
	v_lshl_add_u64 v[66:67], v[78:79], 0, s[12:13]
	v_pk_mul_f32 v[68:69], v[60:61], v[142:143] op_sel_hi:[1,0]
	v_lshl_add_u64 v[66:67], v[66:67], 0, s[0:1]
	v_pk_mul_f32 v[60:61], v[58:59], v[142:143] op_sel_hi:[1,0]
	v_cvt_pk_bf16_f32 v58, v62, v63
	v_cvt_pk_bf16_f32 v59, v64, v65
	s_nop 0
	v_cvt_pk_bf16_f32 v60, v60, v61
	v_cvt_pk_bf16_f32 v61, v68, v69
	global_store_dwordx4 v[66:67], v[58:61], off
	s_nop 1
	v_pk_mul_f32 v[58:59], v[48:49], v[142:143] op_sel_hi:[1,0]
	v_pk_mul_f32 v[48:49], v[46:47], v[142:143] op_sel_hi:[1,0]
	v_cvt_pk_bf16_f32 v46, v54, v55
	v_cvt_pk_bf16_f32 v47, v56, v57
	s_nop 0
	v_cvt_pk_bf16_f32 v48, v48, v49
	v_cvt_pk_bf16_f32 v49, v58, v59
	global_store_dwordx4 v[66:67], v[46:49], off offset:256
	s_nop 1
	v_lshl_add_u64 v[46:47], v[66:67], 0, s[12:13]
	v_pk_mul_f32 v[48:49], v[52:53], v[138:139] op_sel_hi:[1,0]
	v_pk_mul_f32 v[52:53], v[44:45], v[138:139] op_sel_hi:[1,0]
	v_pk_mul_f32 v[44:45], v[42:43], v[138:139] op_sel_hi:[1,0]
	v_cvt_pk_bf16_f32 v42, v50, v51
	v_cvt_pk_bf16_f32 v43, v48, v49
	s_nop 0
	v_cvt_pk_bf16_f32 v44, v44, v45
	v_cvt_pk_bf16_f32 v45, v52, v53
	global_store_dwordx4 v[46:47], v[42:45], off
	s_nop 1
	v_pk_mul_f32 v[42:43], v[32:33], v[138:139] op_sel_hi:[1,0]
	v_pk_mul_f32 v[32:33], v[30:31], v[138:139] op_sel_hi:[1,0]
	v_cvt_pk_bf16_f32 v30, v38, v39
	v_cvt_pk_bf16_f32 v31, v40, v41
	s_nop 0
	v_cvt_pk_bf16_f32 v32, v32, v33
	v_cvt_pk_bf16_f32 v33, v42, v43
	global_store_dwordx4 v[46:47], v[30:33], off offset:256
	s_nop 1
	v_lshl_add_u64 v[30:31], v[46:47], 0, s[12:13]
	v_pk_mul_f32 v[32:33], v[36:37], v[134:135] op_sel_hi:[1,0]
	v_pk_mul_f32 v[36:37], v[28:29], v[134:135] op_sel_hi:[1,0]
	v_pk_mul_f32 v[28:29], v[26:27], v[134:135] op_sel_hi:[1,0]
	v_cvt_pk_bf16_f32 v26, v34, v35
	v_cvt_pk_bf16_f32 v27, v32, v33
	s_nop 0
	v_cvt_pk_bf16_f32 v28, v28, v29
	v_cvt_pk_bf16_f32 v29, v36, v37
	global_store_dwordx4 v[30:31], v[26:29], off
	s_nop 1
	v_pk_mul_f32 v[26:27], v[16:17], v[134:135] op_sel_hi:[1,0]
	v_pk_mul_f32 v[16:17], v[14:15], v[134:135] op_sel_hi:[1,0]
	v_cvt_pk_bf16_f32 v14, v22, v23
	v_cvt_pk_bf16_f32 v15, v24, v25
	s_nop 0
	v_cvt_pk_bf16_f32 v16, v16, v17
	v_cvt_pk_bf16_f32 v17, v26, v27
	global_store_dwordx4 v[30:31], v[14:17], off offset:256
	s_nop 1
	v_lshl_add_u64 v[14:15], v[30:31], 0, s[12:13]
	v_pk_mul_f32 v[16:17], v[20:21], v[130:131] op_sel_hi:[1,0]
	v_pk_mul_f32 v[20:21], v[12:13], v[130:131] op_sel_hi:[1,0]
	v_pk_mul_f32 v[12:13], v[10:11], v[130:131] op_sel_hi:[1,0]
	v_cvt_pk_bf16_f32 v10, v18, v19
	v_cvt_pk_bf16_f32 v11, v16, v17
	s_nop 0
	v_cvt_pk_bf16_f32 v12, v12, v13
	v_cvt_pk_bf16_f32 v13, v20, v21
	global_store_dwordx4 v[14:15], v[10:13], off
	s_nop 1
	v_pk_mul_f32 v[10:11], v[4:5], v[130:131] op_sel_hi:[1,0]
	v_pk_mul_f32 v[4:5], v[2:3], v[130:131] op_sel_hi:[1,0]
	v_cvt_pk_bf16_f32 v2, v6, v7
	v_cvt_pk_bf16_f32 v3, v8, v9
	s_nop 0
	v_cvt_pk_bf16_f32 v4, v4, v5
	v_cvt_pk_bf16_f32 v5, v10, v11
	global_store_dwordx4 v[14:15], v[2:5], off offset:256
	s_nop 1
	v_lshl_add_u64 v[2:3], v[14:15], 0, s[12:13]
	s_nop 0
	v_lshl_add_u64 v[2:3], v[2:3], 0, s[0:1]
	s_mov_b64 s[0:1], -1
	s_cbranch_vccnz .LBB0_1116
	s_andn2_b64 vcc, exec, s[4:5]
	s_cbranch_vccnz .LBB0_1115
	s_barrier
	s_branch .LBB0_1115

; #define PG8_STAGE(bufoff, gbase, voff) do { _Pragma("unroll") for (int _i = 0; _i < 2; ++_i) \
;         __builtin_amdgcn_global_load_lds((const unsigned*)((const char*)(gbase) + (voff)[_i]), (PG8_LAS unsigned*)(lds + (bufoff) + ldsw + _i * 8192), 16, 0, 0); } while (0)
; #define PG8_WAIT_V(n) asm volatile("s_waitcnt vmcnt(" #n ")" ::: "memory")
; #define PG8_BAR __builtin_amdgcn_s_barrier()
; template <class Epi, class Sched, bool ALIGN_EPI = false, bool SP2 = false>
; __device__ __forceinline__ void gemm_phase(PG8_LAS unsigned char* lds, const Gemm g, const Sched& S, const Epi& E) {
;     ...
;     for (int i = 0; i < 2; ++i) { int R, C; stage_rc(tid * 16 + i * 8192, R, C); const int Rb = Epi::PERM ? ((R & ~31) + perm32(R & 31)) : R;
;         voffA[i] = (unsigned)(R * K + C) * 2u; voffB[i] = (unsigned)(Rb * K + C) * 2u; }
;     const size_t kstep = (size_t)(BK * 2);
;     const size_t hstep = (size_t)HALF * K * 2;
;     const size_t tstep = 2 * hstep;
;     const unsigned ldsw = (unsigned)wid * 1024u;
;     const int aoff = lds_byte(wr * 64 + fr, fq * 8), boff = lds_byte(wc * 32 + fr, fq * 8);
;     ...
;         PG8_STAGE(PG8_SB(0, 0), cB, voffB); PG8_STAGE(PG8_SB(0, 1), cB + hstep, voffB); PG8_STAGE(PG8_SA(0, 0), cA, voffA); PG8_STAGE(PG8_SA(0, 1), cA + hstep, voffA);
;         if (wr == 1) PG8_BAR;
;         PG8_WAIT_V(2); PG8_BAR;
;         PG8_STAGE(PG8_SB(1, 0), cB + kstep, voffB); PG8_STAGE(PG8_SA(1, 0), cA + kstep, voffA); PG8_STAGE(PG8_SB(1, 1), cB + hstep + kstep, voffB);
;         PG8_WAIT_V(6); PG8_BAR;
.LBB0_1253:
	v_bfe_u32 v20, v10, 4, 2
	v_and_b32_e32 v11, 15, v10
	v_lshlrev_b32_e32 v21, 4, v20
	v_lshlrev_b32_e32 v10, 2, v10
	s_and_b32 s86, s6, 3
	v_lshl_or_b32 v172, s5, 6, v11
	v_lshl_or_b32 v11, v11, 6, v21
	s_lshl_b32 s5, s5, 13
	v_and_b32_e32 v10, 32, v10
	v_lshl_add_u64 v[12:13], s[78:79], 0, v[0:1]
	v_mov_b32_e32 v131, v1
	v_readlane_b32 s76, v254, 61
	v_bitop3_b32 v21, v11, s5, v10 bitop3:0xde
	s_lshl_b32 s5, s86, 12
	v_lshl_add_u64 v[14:15], s[78:79], 0, v[130:131]
	v_readlane_b32 s77, v254, 62
	v_bitop3_b32 v173, v11, s5, v10 bitop3:0xde
	s_add_i32 m0, s62, 0x18000
	v_lshl_add_u64 v[10:11], v[12:13], 0, s[60:61]
	v_lshl_add_u64 v[16:17], s[76:77], 0, v[0:1]
	s_waitcnt vmcnt(2)
	s_barrier
	global_load_lds_dwordx4 v[10:11], off
	v_lshl_add_u64 v[10:11], v[14:15], 0, s[60:61]
	s_add_i32 m0, s62, 0x1a000
	s_add_i32 s87, s62, 0x8000
	s_add_i32 s90, s62, 0xa000
	v_lshl_add_u64 v[18:19], s[76:77], 0, v[130:131]
	global_load_lds_dwordx4 v[10:11], off
	v_lshl_add_u64 v[10:11], v[16:17], 0, s[60:61]
	s_mov_b32 m0, s87
	s_add_u32 s6, s78, 0x40080
	global_load_lds_dwordx4 v[10:11], off
	v_lshl_add_u64 v[10:11], v[18:19], 0, s[60:61]
	s_mov_b32 m0, s90
	s_addc_u32 s7, s79, 0
	global_load_lds_dwordx4 v[10:11], off
	s_add_i32 m0, s62, 0x1c000
	v_lshl_add_u64 v[10:11], s[6:7], 0, v[0:1]
	global_load_lds_dwordx4 v[10:11], off
	v_lshl_add_u64 v[10:11], s[6:7], 0, v[130:131]
	s_add_i32 m0, s62, 0x1e000
	v_lshlrev_b32_e32 v7, 13, v7
	global_load_lds_dwordx4 v[10:11], off
	v_lshlrev_b32_e32 v2, 13, v2
	v_and_b32_e32 v7, 0x7fffc000, v7
	v_and_b32_e32 v2, 0x7fffc000, v2
	v_lshl_add_u32 v6, v6, 10, v7
	v_lshl_add_u32 v2, v3, 10, v2
	v_or_b32_e32 v6, v6, v8
	v_or_b32_e32 v2, v2, v4
	s_waitcnt vmcnt(6)
	s_mov_b32 s100, 0
	v_add_lshl_u32 v6, v6, v9, 1
	v_mov_b32_e32 v7, v1
	s_mov_b64 s[8:9], 0x40080
	v_add_lshl_u32 v2, v2, v5, 1
	v_mov_b32_e32 v3, v1
	s_cmpk_lt_u32 s4, 0x100
	v_lshlrev_b32_e32 v10, 2, v20
	v_lshl_add_u64 v[132:133], v[6:7], 0, s[8:9]
	v_lshl_add_u64 v[134:135], v[2:3], 0, s[8:9]
	v_readlane_b32 s8, v255, 1
	v_readlane_b32 s14, v253, 42
	s_cselect_b64 s[4:5], -1, 0
	v_lshl_or_b32 v174, s86, 5, v10
	s_mov_b32 s94, 0
	v_cmp_eq_u32_e64 s[6:7], 0, v20
	v_add_u32_e32 v175, 0, v21
	v_readlane_b32 s12, v254, 46
	s_mov_b32 s13, s8
	v_readlane_b32 s15, v253, 43
	s_barrier
	v_readlane_b32 s9, v255, 2
	s_branch .LBB0_1256

; #define PG8_STAGE(bufoff, gbase, voff) do { _Pragma("unroll") for (int _i = 0; _i < 2; ++_i) \
;         __builtin_amdgcn_global_load_lds((const unsigned*)((const char*)(gbase) + (voff)[_i]), (PG8_LAS unsigned*)(lds + (bufoff) + ldsw + _i * 8192), 16, 0, 0); } while (0)
; #define PG8_LDA(dst, b, h) do { _Pragma("unroll") for (int m = 0; m < 4; ++m) _Pragma("unroll") for (int k = 0; k < 2; ++k) dst[m][k] = *(const PG8_LAS bf16x8*)(lds + PG8_SA(b, h) + aoff + m * 2048 + k * 1024); } while (0)
; #define PG8_LDB(dst, b, h) do { _Pragma("unroll") for (int n = 0; n < 2; ++n) _Pragma("unroll") for (int k = 0; k < 2; ++k) dst[n][k] = *(const PG8_LAS bf16x8*)(lds + PG8_SB(b, h) + boff + n * 2048 + k * 1024); } while (0)
; #define PG8_MMA(ai, bj, At, Bt) do { __builtin_amdgcn_s_setprio(1); _Pragma("unroll") for (int m = 0; m < 4; ++m) _Pragma("unroll") for (int n = 0; n < 2; ++n) _Pragma("unroll") for (int k = 0; k < 2; ++k) \
;         acc[ai][bj][m][n] = __builtin_amdgcn_mfma_f32_16x16x32_bf16(Bt[n][k], At[m][k], acc[ai][bj][m][n], 0, 0, 0); __builtin_amdgcn_s_setprio(0); } while (0)
; #define PG8_WAIT_V(n) asm volatile("s_waitcnt vmcnt(" #n ")" ::: "memory")
; #define PG8_WAIT_L(n) asm volatile("s_waitcnt lgkmcnt(" #n ")" ::: "memory")
; #define PG8_BAR __builtin_amdgcn_s_barrier()
; #define PG8_SCHED __builtin_amdgcn_sched_barrier(0)
; template <class Epi, class Sched, bool ALIGN_EPI = false, bool SP2 = false>
; __device__ __forceinline__ void gemm_phase(PG8_LAS unsigned char* lds, const Gemm g, const Sched& S, const Epi& E) {
;     ...
;             const bool last = (t == nt - 2);
;             const char* a1 = cA + (size_t)(t + 1) * kstep;
;             const char* a2 = last ? nA : cA + (size_t)(t + 2) * kstep; const char* b2 = last ? nB : cB + (size_t)(t + 2) * kstep;
;             const char* a3 = a2 + kstep; const char* b3 = b2 + kstep;
;             if (last && has_next) S.a_ready(nxt);
;             if constexpr (SP2) {
;             PG8_LDB(B0, 0, 0); PG8_LDB(B1, 0, 1); PG8_SCHED; PG8_LDA(At, 0, 0); PG8_STAGE(PG8_SA(1, 1), a1 + hstep, voffA);
;             PG8_WAIT_V(8); PG8_WAIT_L(0); PG8_BAR; PG8_MMA(0, 0, At, B0); PG8_MMA(0, 1, At, B1); PG8_BAR; PG8_SCHED;
;             PG8_LDA(At, 0, 1); PG8_STAGE(PG8_SB(0, 0), b2, voffB); PG8_STAGE(PG8_SB(0, 1), b2 + hstep, voffB); PG8_STAGE(PG8_SA(0, 0), a2, voffA);
.LBB0_1263:
	s_add_u32 s78, s76, 0x100
	s_addc_u32 s79, s77, 0
	s_add_i32 s50, 0, 0x10000
	s_cmp_eq_u32 s56, 12
	s_cselect_b32 s83, s52, s79
	s_cselect_b32 s82, s53, s78
	s_cselect_b32 s81, s11, s55
	s_cselect_b32 s80, s64, s54
	s_add_i32 s51, 0, 0x14000
	v_add_u32_e32 v148, s50, v173
	v_add_u32_e32 v164, s51, v173
	ds_read_b128 v[136:139], v148
	ds_read_b128 v[140:143], v148 offset:1024
	ds_read_b128 v[144:147], v148 offset:2048
	ds_read_b128 v[148:151], v148 offset:3072
	ds_read_b128 v[152:155], v164
	ds_read_b128 v[156:159], v164 offset:1024
	ds_read_b128 v[160:163], v164 offset:2048
	ds_read_b128 v[164:167], v164 offset:3072
	v_lshl_add_u64 v[184:185], s[76:77], 0, v[132:133]
	s_add_i32 m0, s62, 0xc000
	ds_read_b128 v[168:171], v175
	ds_read_b128 v[176:179], v175 offset:1024
	ds_read_b128 v[180:183], v175 offset:2048
	ds_read_b128 v[192:195], v175 offset:3072
	ds_read_b128 v[196:199], v175 offset:4096
	ds_read_b128 v[200:203], v175 offset:5120
	ds_read_b128 v[204:207], v175 offset:6144
	ds_read_b128 v[208:211], v175 offset:7168
	global_load_lds_dwordx4 v[184:185], off
	v_lshl_add_u64 v[184:185], s[76:77], 0, v[134:135]
	s_add_i32 m0, s62, 0xe000
	s_nop 0
	global_load_lds_dwordx4 v[184:185], off
	s_cmp_lg_u32 s100, 0
	s_cbranch_scc1 .Lpe_skip_mo_0
	s_waitcnt vmcnt(8)
.Lpe_skip_mo_0:
	s_waitcnt lgkmcnt(0)
	s_barrier
	s_setprio 1
	s_waitcnt lgkmcnt(0)
	v_mfma_f32_16x16x32_bf16 v[126:129], v[136:139], v[168:171], v[126:129]
	v_mfma_f32_16x16x32_bf16 v[122:125], v[144:147], v[168:171], v[122:125]
	v_mfma_f32_16x16x32_bf16 v[110:113], v[136:139], v[180:183], v[110:113]
	v_mfma_f32_16x16x32_bf16 v[106:109], v[144:147], v[180:183], v[106:109]
	v_mfma_f32_16x16x32_bf16 v[94:97], v[136:139], v[196:199], v[94:97]
	v_mfma_f32_16x16x32_bf16 v[90:93], v[144:147], v[196:199], v[90:93]
	v_mfma_f32_16x16x32_bf16 v[78:81], v[136:139], v[204:207], v[78:81]
	v_mfma_f32_16x16x32_bf16 v[74:77], v[144:147], v[204:207], v[74:77]
	v_mfma_f32_16x16x32_bf16 v[126:129], v[140:143], v[176:179], v[126:129]
	v_mfma_f32_16x16x32_bf16 v[122:125], v[148:151], v[176:179], v[122:125]
	v_mfma_f32_16x16x32_bf16 v[110:113], v[140:143], v[192:195], v[110:113]
	v_mfma_f32_16x16x32_bf16 v[106:109], v[148:151], v[192:195], v[106:109]
	v_mfma_f32_16x16x32_bf16 v[94:97], v[140:143], v[200:203], v[94:97]
	v_mfma_f32_16x16x32_bf16 v[90:93], v[148:151], v[200:203], v[90:93]
	v_mfma_f32_16x16x32_bf16 v[78:81], v[140:143], v[208:211], v[78:81]
	v_mfma_f32_16x16x32_bf16 v[74:77], v[148:151], v[208:211], v[74:77]
	s_setprio 0
	s_setprio 1
	v_mfma_f32_16x16x32_bf16 v[118:121], v[152:155], v[168:171], v[118:121]
	v_mfma_f32_16x16x32_bf16 v[114:117], v[160:163], v[168:171], v[114:117]
	v_mfma_f32_16x16x32_bf16 v[102:105], v[152:155], v[180:183], v[102:105]
	v_mfma_f32_16x16x32_bf16 v[98:101], v[160:163], v[180:183], v[98:101]
	v_mfma_f32_16x16x32_bf16 v[86:89], v[152:155], v[196:199], v[86:89]
	v_mfma_f32_16x16x32_bf16 v[82:85], v[160:163], v[196:199], v[82:85]
	v_mfma_f32_16x16x32_bf16 v[70:73], v[152:155], v[204:207], v[70:73]
	v_mfma_f32_16x16x32_bf16 v[66:69], v[160:163], v[204:207], v[66:69]
	v_mfma_f32_16x16x32_bf16 v[118:121], v[156:159], v[176:179], v[118:121]
	v_mfma_f32_16x16x32_bf16 v[114:117], v[164:167], v[176:179], v[114:117]
	v_mfma_f32_16x16x32_bf16 v[102:105], v[156:159], v[192:195], v[102:105]
	v_mfma_f32_16x16x32_bf16 v[98:101], v[164:167], v[192:195], v[98:101]
	v_mfma_f32_16x16x32_bf16 v[86:89], v[156:159], v[200:203], v[86:89]
	v_mfma_f32_16x16x32_bf16 v[82:85], v[164:167], v[200:203], v[82:85]
	v_mfma_f32_16x16x32_bf16 v[70:73], v[156:159], v[208:211], v[70:73]
	v_mfma_f32_16x16x32_bf16 v[66:69], v[164:167], v[208:211], v[66:69]
	s_setprio 0
	s_barrier
	s_add_i32 s50, s50, s35
	v_lshl_add_u64 v[184:185], s[80:81], 0, v[0:1]
	s_mov_b32 m0, s50
	ds_read_b128 v[168:171], v175 offset:16384
	ds_read_b128 v[176:179], v175 offset:17408
	ds_read_b128 v[180:183], v175 offset:18432
	ds_read_b128 v[192:195], v175 offset:19456
	ds_read_b128 v[196:199], v175 offset:20480
	ds_read_b128 v[200:203], v175 offset:21504
	ds_read_b128 v[204:207], v175 offset:22528
	ds_read_b128 v[208:211], v175 offset:23552
	global_load_lds_dwordx4 v[184:185], off
	s_add_i32 m0, s50, 0x2000
	s_add_u32 s76, s80, 0x40000
	v_lshl_add_u64 v[188:189], s[80:81], 0, v[130:131]
	s_addc_u32 s77, s81, 0
	s_add_i32 s50, s51, s35
	global_load_lds_dwordx4 v[188:189], off
	v_lshl_add_u64 v[190:191], s[76:77], 0, v[0:1]
	s_mov_b32 m0, s50
	v_lshl_add_u64 v[212:213], s[82:83], 0, v[130:131]
	global_load_lds_dwordx4 v[190:191], off
	v_lshl_add_u64 v[190:191], s[76:77], 0, v[130:131]
	s_add_i32 m0, s50, 0x2000
	s_nop 0
	global_load_lds_dwordx4 v[190:191], off
	v_lshl_add_u64 v[190:191], s[82:83], 0, v[0:1]
	s_mov_b32 m0, s62
	s_nop 0
	global_load_lds_dwordx4 v[190:191], off
	s_mov_b32 m0, s63
	s_nop 0
	global_load_lds_dwordx4 v[212:213], off
	s_cmp_lg_u32 s100, 0
	s_cbranch_scc1 .Lpe_skip_mo_1
	s_waitcnt vmcnt(8)
; #define PG8_STAGE(bufoff, gbase, voff) do { _Pragma("unroll") for (int _i = 0; _i < 2; ++_i) \
;         __builtin_amdgcn_global_load_lds((const unsigned*)((const char*)(gbase) + (voff)[_i]), (PG8_LAS unsigned*)(lds + (bufoff) + ldsw + _i * 8192), 16, 0, 0); } while (0)
; #define PG8_LDA(dst, b, h) do { _Pragma("unroll") for (int m = 0; m < 4; ++m) _Pragma("unroll") for (int k = 0; k < 2; ++k) dst[m][k] = *(const PG8_LAS bf16x8*)(lds + PG8_SA(b, h) + aoff + m * 2048 + k * 1024); } while (0)
; #define PG8_LDB(dst, b, h) do { _Pragma("unroll") for (int n = 0; n < 2; ++n) _Pragma("unroll") for (int k = 0; k < 2; ++k) dst[n][k] = *(const PG8_LAS bf16x8*)(lds + PG8_SB(b, h) + boff + n * 2048 + k * 1024); } while (0)
; #define PG8_MMA(ai, bj, At, Bt) do { __builtin_amdgcn_s_setprio(1); _Pragma("unroll") for (int m = 0; m < 4; ++m) _Pragma("unroll") for (int n = 0; n < 2; ++n) _Pragma("unroll") for (int k = 0; k < 2; ++k) \
;         acc[ai][bj][m][n] = __builtin_amdgcn_mfma_f32_16x16x32_bf16(Bt[n][k], At[m][k], acc[ai][bj][m][n], 0, 0, 0); __builtin_amdgcn_s_setprio(0); } while (0)
; #define PG8_WAIT_V(n) asm volatile("s_waitcnt vmcnt(" #n ")" ::: "memory")
; #define PG8_WAIT_L(n) asm volatile("s_waitcnt lgkmcnt(" #n ")" ::: "memory")
; #define PG8_BAR __builtin_amdgcn_s_barrier()
; #define PG8_SCHED __builtin_amdgcn_sched_barrier(0)
; template <class Epi, class Sched, bool ALIGN_EPI = false, bool SP2 = false>
; __device__ __forceinline__ void gemm_phase(PG8_LAS unsigned char* lds, const Gemm g, const Sched& S, const Epi& E) {
;     ...
;             PG8_WAIT_V(8); PG8_WAIT_L(0); PG8_BAR; PG8_MMA(1, 0, At, B0); PG8_MMA(1, 1, At, B1); PG8_BAR; PG8_SCHED;
;             PG8_LDB(B0, 1, 0); PG8_LDB(B1, 1, 1); PG8_SCHED; PG8_LDA(At, 1, 0); PG8_STAGE(PG8_SA(0, 1), a2 + hstep, voffA);
;             PG8_WAIT_V(8); PG8_WAIT_L(0); PG8_BAR; PG8_MMA(0, 0, At, B0); PG8_MMA(0, 1, At, B1); PG8_BAR; PG8_SCHED;
.Lpe_skip_mo_1:
	s_mov_b32 s100, 0
	s_waitcnt lgkmcnt(0)
	s_barrier
	s_setprio 1
	s_waitcnt lgkmcnt(0)
	v_mfma_f32_16x16x32_bf16 v[62:65], v[136:139], v[168:171], v[62:65]
	v_mfma_f32_16x16x32_bf16 v[58:61], v[144:147], v[168:171], v[58:61]
	v_mfma_f32_16x16x32_bf16 v[46:49], v[136:139], v[180:183], v[46:49]
	v_mfma_f32_16x16x32_bf16 v[42:45], v[144:147], v[180:183], v[42:45]
	v_mfma_f32_16x16x32_bf16 v[30:33], v[136:139], v[196:199], v[30:33]
	v_mfma_f32_16x16x32_bf16 v[26:29], v[144:147], v[196:199], v[26:29]
	v_mfma_f32_16x16x32_bf16 v[14:17], v[136:139], v[204:207], v[14:17]
	v_mfma_f32_16x16x32_bf16 v[10:13], v[144:147], v[204:207], v[10:13]
	v_mfma_f32_16x16x32_bf16 v[62:65], v[140:143], v[176:179], v[62:65]
	v_mfma_f32_16x16x32_bf16 v[58:61], v[148:151], v[176:179], v[58:61]
	v_mfma_f32_16x16x32_bf16 v[46:49], v[140:143], v[192:195], v[46:49]
	v_mfma_f32_16x16x32_bf16 v[42:45], v[148:151], v[192:195], v[42:45]
	v_mfma_f32_16x16x32_bf16 v[30:33], v[140:143], v[200:203], v[30:33]
	v_mfma_f32_16x16x32_bf16 v[26:29], v[148:151], v[200:203], v[26:29]
	v_mfma_f32_16x16x32_bf16 v[14:17], v[140:143], v[208:211], v[14:17]
	v_mfma_f32_16x16x32_bf16 v[10:13], v[148:151], v[208:211], v[10:13]
	s_setprio 0
	s_setprio 1
	v_mfma_f32_16x16x32_bf16 v[54:57], v[152:155], v[168:171], v[54:57]
	v_mfma_f32_16x16x32_bf16 v[50:53], v[160:163], v[168:171], v[50:53]
	v_mfma_f32_16x16x32_bf16 v[38:41], v[152:155], v[180:183], v[38:41]
	v_mfma_f32_16x16x32_bf16 v[34:37], v[160:163], v[180:183], v[34:37]
	v_mfma_f32_16x16x32_bf16 v[22:25], v[152:155], v[196:199], v[22:25]
	v_mfma_f32_16x16x32_bf16 v[18:21], v[160:163], v[196:199], v[18:21]
	v_mfma_f32_16x16x32_bf16 v[6:9], v[152:155], v[204:207], v[6:9]
	v_mfma_f32_16x16x32_bf16 v[2:5], v[160:163], v[204:207], v[2:5]
	v_mfma_f32_16x16x32_bf16 v[54:57], v[156:159], v[176:179], v[54:57]
	v_mfma_f32_16x16x32_bf16 v[50:53], v[164:167], v[176:179], v[50:53]
	v_mfma_f32_16x16x32_bf16 v[38:41], v[156:159], v[192:195], v[38:41]
	v_mfma_f32_16x16x32_bf16 v[34:37], v[164:167], v[192:195], v[34:37]
	v_mfma_f32_16x16x32_bf16 v[22:25], v[156:159], v[200:203], v[22:25]
	v_mfma_f32_16x16x32_bf16 v[18:21], v[164:167], v[200:203], v[18:21]
	v_mfma_f32_16x16x32_bf16 v[6:9], v[156:159], v[208:211], v[6:9]
	v_mfma_f32_16x16x32_bf16 v[2:5], v[164:167], v[208:211], v[2:5]
	s_setprio 0
	s_barrier
	s_add_i32 s50, 0, 0x18000
	s_add_i32 s51, 0, 0x1c000
	v_add_u32_e32 v148, s50, v173
	v_add_u32_e32 v164, s51, v173
	ds_read_b128 v[136:139], v148
	ds_read_b128 v[140:143], v148 offset:1024
	ds_read_b128 v[144:147], v148 offset:2048
	ds_read_b128 v[148:151], v148 offset:3072
	ds_read_b128 v[152:155], v164
	ds_read_b128 v[156:159], v164 offset:1024
	ds_read_b128 v[160:163], v164 offset:2048
	ds_read_b128 v[164:167], v164 offset:3072
	s_add_u32 s76, s82, 0x40000
	s_addc_u32 s77, s83, 0
	s_mov_b32 m0, s84
	v_lshl_add_u64 v[214:215], s[76:77], 0, v[0:1]
	ds_read_b128 v[168:171], v175 offset:32768
	ds_read_b128 v[176:179], v175 offset:33792
	ds_read_b128 v[180:183], v175 offset:34816
	ds_read_b128 v[192:195], v175 offset:35840
	ds_read_b128 v[196:199], v175 offset:36864
	ds_read_b128 v[200:203], v175 offset:37888
	ds_read_b128 v[204:207], v175 offset:38912
	ds_read_b128 v[208:211], v175 offset:39936
	global_load_lds_dwordx4 v[214:215], off
	v_lshl_add_u64 v[214:215], s[76:77], 0, v[130:131]
	s_mov_b32 m0, s85
	s_nop 0
	global_load_lds_dwordx4 v[214:215], off
	s_waitcnt vmcnt(8)
	s_waitcnt lgkmcnt(0)
	s_barrier
	s_setprio 1
	s_waitcnt lgkmcnt(0)
	v_mfma_f32_16x16x32_bf16 v[126:129], v[136:139], v[168:171], v[126:129]
	v_mfma_f32_16x16x32_bf16 v[122:125], v[144:147], v[168:171], v[122:125]
	v_mfma_f32_16x16x32_bf16 v[110:113], v[136:139], v[180:183], v[110:113]
	v_mfma_f32_16x16x32_bf16 v[106:109], v[144:147], v[180:183], v[106:109]
	v_mfma_f32_16x16x32_bf16 v[94:97], v[136:139], v[196:199], v[94:97]
	v_mfma_f32_16x16x32_bf16 v[90:93], v[144:147], v[196:199], v[90:93]
	v_mfma_f32_16x16x32_bf16 v[78:81], v[136:139], v[204:207], v[78:81]
	v_mfma_f32_16x16x32_bf16 v[74:77], v[144:147], v[204:207], v[74:77]
	v_mfma_f32_16x16x32_bf16 v[126:129], v[140:143], v[176:179], v[126:129]
	v_mfma_f32_16x16x32_bf16 v[122:125], v[148:151], v[176:179], v[122:125]
	v_mfma_f32_16x16x32_bf16 v[110:113], v[140:143], v[192:195], v[110:113]
	v_mfma_f32_16x16x32_bf16 v[106:109], v[148:151], v[192:195], v[106:109]
	v_mfma_f32_16x16x32_bf16 v[94:97], v[140:143], v[200:203], v[94:97]
	v_mfma_f32_16x16x32_bf16 v[90:93], v[148:151], v[200:203], v[90:93]
	v_mfma_f32_16x16x32_bf16 v[78:81], v[140:143], v[208:211], v[78:81]
	v_mfma_f32_16x16x32_bf16 v[74:77], v[148:151], v[208:211], v[74:77]
	s_setprio 0
	s_setprio 1
	v_mfma_f32_16x16x32_bf16 v[118:121], v[152:155], v[168:171], v[118:121]
	v_mfma_f32_16x16x32_bf16 v[114:117], v[160:163], v[168:171], v[114:117]
	v_mfma_f32_16x16x32_bf16 v[102:105], v[152:155], v[180:183], v[102:105]
	v_mfma_f32_16x16x32_bf16 v[98:101], v[160:163], v[180:183], v[98:101]
	v_mfma_f32_16x16x32_bf16 v[86:89], v[152:155], v[196:199], v[86:89]
	v_mfma_f32_16x16x32_bf16 v[82:85], v[160:163], v[196:199], v[82:85]
	v_mfma_f32_16x16x32_bf16 v[70:73], v[152:155], v[204:207], v[70:73]
	v_mfma_f32_16x16x32_bf16 v[66:69], v[160:163], v[204:207], v[66:69]
	v_mfma_f32_16x16x32_bf16 v[118:121], v[156:159], v[176:179], v[118:121]
	v_mfma_f32_16x16x32_bf16 v[114:117], v[164:167], v[176:179], v[114:117]
	v_mfma_f32_16x16x32_bf16 v[102:105], v[156:159], v[192:195], v[102:105]
	v_mfma_f32_16x16x32_bf16 v[98:101], v[164:167], v[192:195], v[98:101]
	v_mfma_f32_16x16x32_bf16 v[86:89], v[156:159], v[200:203], v[86:89]
	v_mfma_f32_16x16x32_bf16 v[82:85], v[164:167], v[200:203], v[82:85]
	v_mfma_f32_16x16x32_bf16 v[70:73], v[156:159], v[208:211], v[70:73]
	v_mfma_f32_16x16x32_bf16 v[66:69], v[164:167], v[208:211], v[66:69]
	s_setprio 0
	s_barrier
; #define PG8_STAGE(bufoff, gbase, voff) do { _Pragma("unroll") for (int _i = 0; _i < 2; ++_i) \
;         __builtin_amdgcn_global_load_lds((const unsigned*)((const char*)(gbase) + (voff)[_i]), (PG8_LAS unsigned*)(lds + (bufoff) + ldsw + _i * 8192), 16, 0, 0); } while (0)
; #define PG8_LDA(dst, b, h) do { _Pragma("unroll") for (int m = 0; m < 4; ++m) _Pragma("unroll") for (int k = 0; k < 2; ++k) dst[m][k] = *(const PG8_LAS bf16x8*)(lds + PG8_SA(b, h) + aoff + m * 2048 + k * 1024); } while (0)
; #define PG8_MMA(ai, bj, At, Bt) do { __builtin_amdgcn_s_setprio(1); _Pragma("unroll") for (int m = 0; m < 4; ++m) _Pragma("unroll") for (int n = 0; n < 2; ++n) _Pragma("unroll") for (int k = 0; k < 2; ++k) \
;         acc[ai][bj][m][n] = __builtin_amdgcn_mfma_f32_16x16x32_bf16(Bt[n][k], At[m][k], acc[ai][bj][m][n], 0, 0, 0); __builtin_amdgcn_s_setprio(0); } while (0)
; #define PG8_WAIT_V(n) asm volatile("s_waitcnt vmcnt(" #n ")" ::: "memory")
; #define PG8_WAIT_L(n) asm volatile("s_waitcnt lgkmcnt(" #n ")" ::: "memory")
; #define PG8_BAR __builtin_amdgcn_s_barrier()
; #define PG8_SCHED __builtin_amdgcn_sched_barrier(0)
; template <class Epi, class Sched, bool ALIGN_EPI = false, bool SP2 = false>
; __device__ __forceinline__ void gemm_phase(PG8_LAS unsigned char* lds, const Gemm g, const Sched& S, const Epi& E) {
;     ...
;         for (int t = 0; t < nt; t += 2) {
;     ...
;             PG8_LDA(At, 1, 1); PG8_STAGE(PG8_SB(1, 0), b3, voffB); PG8_STAGE(PG8_SB(1, 1), b3 + hstep, voffB); PG8_STAGE(PG8_SA(1, 0), a3, voffA);
;             PG8_WAIT_V(8); PG8_WAIT_L(0); PG8_BAR; PG8_MMA(1, 0, At, B0); PG8_MMA(1, 1, At, B1); PG8_BAR; PG8_SCHED;
;     ...
;         if constexpr (ALIGN_EPI) { if (wr == 0) PG8_BAR; }
	s_add_i32 s50, s50, s35
	v_lshl_add_u64 v[184:185], v[184:185], 0, s[60:61]
	s_mov_b32 m0, s50
	ds_read_b128 v[168:171], v175 offset:49152
	ds_read_b128 v[176:179], v175 offset:50176
	ds_read_b128 v[180:183], v175 offset:51200
	ds_read_b128 v[192:195], v175 offset:52224
	ds_read_b128 v[196:199], v175 offset:53248
	ds_read_b128 v[200:203], v175 offset:54272
	ds_read_b128 v[204:207], v175 offset:55296
	ds_read_b128 v[208:211], v175 offset:56320
	global_load_lds_dwordx4 v[184:185], off
	s_add_i32 m0, s50, 0x2000
	s_add_u32 s76, s80, 0x40080
	v_lshl_add_u64 v[184:185], v[188:189], 0, s[60:61]
	s_addc_u32 s77, s81, 0
	s_add_i32 s50, s51, s35
	global_load_lds_dwordx4 v[184:185], off
	v_lshl_add_u64 v[184:185], s[76:77], 0, v[0:1]
	s_mov_b32 m0, s50
	s_nop 0
	global_load_lds_dwordx4 v[184:185], off
	v_lshl_add_u64 v[184:185], s[76:77], 0, v[130:131]
	s_add_i32 m0, s50, 0x2000
	s_nop 0
	global_load_lds_dwordx4 v[184:185], off
	v_lshl_add_u64 v[184:185], v[190:191], 0, s[60:61]
	s_mov_b32 m0, s87
	s_nop 0
	global_load_lds_dwordx4 v[184:185], off
	v_lshl_add_u64 v[184:185], v[212:213], 0, s[60:61]
	s_mov_b32 m0, s90
	s_nop 0
	global_load_lds_dwordx4 v[184:185], off
	s_waitcnt vmcnt(8)
	s_waitcnt lgkmcnt(0)
	s_barrier
	s_setprio 1
	s_waitcnt lgkmcnt(0)
	v_mfma_f32_16x16x32_bf16 v[62:65], v[136:139], v[168:171], v[62:65]
	v_mfma_f32_16x16x32_bf16 v[58:61], v[144:147], v[168:171], v[58:61]
	v_mfma_f32_16x16x32_bf16 v[46:49], v[136:139], v[180:183], v[46:49]
	v_mfma_f32_16x16x32_bf16 v[42:45], v[144:147], v[180:183], v[42:45]
	v_mfma_f32_16x16x32_bf16 v[30:33], v[136:139], v[196:199], v[30:33]
	v_mfma_f32_16x16x32_bf16 v[26:29], v[144:147], v[196:199], v[26:29]
	v_mfma_f32_16x16x32_bf16 v[14:17], v[136:139], v[204:207], v[14:17]
	v_mfma_f32_16x16x32_bf16 v[10:13], v[144:147], v[204:207], v[10:13]
	v_mfma_f32_16x16x32_bf16 v[62:65], v[140:143], v[176:179], v[62:65]
	v_mfma_f32_16x16x32_bf16 v[58:61], v[148:151], v[176:179], v[58:61]
	v_mfma_f32_16x16x32_bf16 v[46:49], v[140:143], v[192:195], v[46:49]
	v_mfma_f32_16x16x32_bf16 v[42:45], v[148:151], v[192:195], v[42:45]
	v_mfma_f32_16x16x32_bf16 v[30:33], v[140:143], v[200:203], v[30:33]
	v_mfma_f32_16x16x32_bf16 v[26:29], v[148:151], v[200:203], v[26:29]
	v_mfma_f32_16x16x32_bf16 v[14:17], v[140:143], v[208:211], v[14:17]
	v_mfma_f32_16x16x32_bf16 v[10:13], v[148:151], v[208:211], v[10:13]
	s_setprio 0
	s_setprio 1
	v_mfma_f32_16x16x32_bf16 v[54:57], v[152:155], v[168:171], v[54:57]
	v_mfma_f32_16x16x32_bf16 v[50:53], v[160:163], v[168:171], v[50:53]
	v_mfma_f32_16x16x32_bf16 v[38:41], v[152:155], v[180:183], v[38:41]
	v_mfma_f32_16x16x32_bf16 v[34:37], v[160:163], v[180:183], v[34:37]
	v_mfma_f32_16x16x32_bf16 v[22:25], v[152:155], v[196:199], v[22:25]
	v_mfma_f32_16x16x32_bf16 v[18:21], v[160:163], v[196:199], v[18:21]
	v_mfma_f32_16x16x32_bf16 v[6:9], v[152:155], v[204:207], v[6:9]
	v_mfma_f32_16x16x32_bf16 v[2:5], v[160:163], v[204:207], v[2:5]
	v_mfma_f32_16x16x32_bf16 v[54:57], v[156:159], v[176:179], v[54:57]
	v_mfma_f32_16x16x32_bf16 v[50:53], v[164:167], v[176:179], v[50:53]
	v_mfma_f32_16x16x32_bf16 v[38:41], v[156:159], v[192:195], v[38:41]
	v_mfma_f32_16x16x32_bf16 v[34:37], v[164:167], v[192:195], v[34:37]
	v_mfma_f32_16x16x32_bf16 v[22:25], v[156:159], v[200:203], v[22:25]
	v_mfma_f32_16x16x32_bf16 v[18:21], v[164:167], v[200:203], v[18:21]
	v_mfma_f32_16x16x32_bf16 v[6:9], v[156:159], v[208:211], v[6:9]
	v_mfma_f32_16x16x32_bf16 v[2:5], v[164:167], v[208:211], v[2:5]
	s_setprio 0
	s_barrier
	s_add_i32 s56, s56, 2
	s_add_u32 s54, s54, 0x100
	s_addc_u32 s55, s55, 0
	s_cmp_gt_u32 s56, 13
	s_mov_b64 s[76:77], s[78:79]
	s_cbranch_scc0 .LBB0_1263
	s_and_b64 vcc, exec, s[4:5]
	s_cbranch_vccz .LBB0_1266
	s_barrier
; __device__ __forceinline__ unsigned cvt_pk_bf16(float lo, float hi) { unsigned r; asm volatile("v_cvt_pk_bf16_f32 %0, %1, %2" : "=v"(r) : "v"(lo), "v"(hi)); return r; }
;     __device__ __forceinline__ void operator()(f32x4 (&acc)[2][2][4][2], const Unit& u, int wr, int wc, int fr, int fq) const {
;         const int col0 = u.pn * BM + wc * 32 + 4 * fq;
; #pragma unroll
;         for (int ai = 0; ai < 2; ++ai) {
;             unsigned long long old[4][2][2];
; #pragma unroll
;             for (int m = 0; m < 4; ++m) { const size_t off = (size_t)(u.pm * BM + ai * HALF + wr * 64 + m * 16 + fr) * ldc + col0;
; #pragma unroll
;                 for (int bj = 0; bj < 2; ++bj)
; #pragma unroll
;                     for (int n = 0; n < 2; ++n) old[m][bj][n] = *(const unsigned long long*)(xb + off + bj * HALF + n * 16); }
; #pragma unroll
;             for (int m = 0; m < 4; ++m) { const int row = u.pm * BM + ai * HALF + wr * 64 + m * 16 + fr; const size_t off = (size_t)row * ldc + col0; float sq = 0.f;
; #pragma unroll
;                 for (int bj = 0; bj < 2; ++bj)
; #pragma unroll
;                     for (int n = 0; n < 2; ++n) { const unsigned long long b = old[m][bj][n];
;                         const unsigned blo = (unsigned)b, bhi = (unsigned)(b >> 32);
;                         f32x4 v; v[0] = __builtin_bit_cast(float, blo << 16); v[1] = __builtin_bit_cast(float, blo & 0xffff0000u); v[2] = __builtin_bit_cast(float, bhi << 16); v[3] = __builtin_bit_cast(float, bhi & 0xffff0000u);
;                         v = v + acc[ai][bj][m][n];
;                         sq += (v[0] * v[0] + v[1] * v[1]) + (v[2] * v[2] + v[3] * v[3]);
;                         *(unsigned long long*)(xb + off + bj * HALF + n * 16) = (unsigned long long)cvt_pk_bf16(v[0], v[1]) | ((unsigned long long)cvt_pk_bf16(v[2], v[3]) << 32); }
;                 sq += __shfl_xor(sq, 16); sq += __shfl_xor(sq, 32);
;                 if (fq == 0) ssp[(size_t)row * 16 + 4 * u.pn + wc] = sq; }
.LBB0_1266:
	v_lshl_or_b32 v136, s12, 8, v174
	v_lshl_add_u32 v140, s13, 8, v172
	v_ashrrev_i32_e32 v137, 31, v136
	v_lshlrev_b64 v[176:177], 1, v[136:137]
	v_ashrrev_i32_e32 v141, 31, v140
	v_lshl_add_u64 v[138:139], s[42:43], 0, v[176:177]
	v_lshlrev_b64 v[178:179], 11, v[140:141]
	v_lshl_add_u64 v[142:143], v[138:139], 0, v[178:179]
	global_load_dwordx2 v[180:181], v[142:143], off
	global_load_dwordx2 v[182:183], v[142:143], off offset:32
	global_load_dwordx2 v[184:185], v[142:143], off offset:256
	global_load_dwordx2 v[188:189], v[142:143], off offset:288
	v_or_b32_e32 v160, 16, v140
	v_ashrrev_i32_e32 v161, 31, v160
	v_lshlrev_b64 v[142:143], 11, v[160:161]
	v_or_b32_e32 v146, 32, v140
	v_lshl_add_u64 v[142:143], v[138:139], 0, v[142:143]
	v_ashrrev_i32_e32 v147, 31, v146
	global_load_dwordx2 v[170:171], v[142:143], off
	global_load_dwordx2 v[168:169], v[142:143], off offset:32
	global_load_dwordx2 v[166:167], v[142:143], off offset:256
	global_load_dwordx2 v[164:165], v[142:143], off offset:288
	v_lshlrev_b64 v[142:143], 11, v[146:147]
	v_lshl_add_u64 v[142:143], v[138:139], 0, v[142:143]
	global_load_dwordx2 v[162:163], v[142:143], off
	global_load_dwordx2 v[158:159], v[142:143], off offset:32
	global_load_dwordx2 v[154:155], v[142:143], off offset:256
	global_load_dwordx2 v[150:151], v[142:143], off offset:288
	v_or_b32_e32 v142, 48, v140
	v_ashrrev_i32_e32 v143, 31, v142
	v_lshlrev_b64 v[144:145], 11, v[142:143]
	v_lshl_add_u64 v[144:145], v[138:139], 0, v[144:145]
	global_load_dwordx2 v[156:157], v[144:145], off
	global_load_dwordx2 v[152:153], v[144:145], off offset:32
	global_load_dwordx2 v[148:149], v[144:145], off offset:256
	s_nop 0
	global_load_dwordx2 v[144:145], v[144:145], off offset:288
	s_lshl_b32 s76, s12, 2
	s_ashr_i32 s77, s76, 31
	s_waitcnt vmcnt(0)
	s_mov_b32 s100, 1
	v_lshlrev_b32_e32 v190, 16, v180
	v_and_b32_e32 v191, 0xffff0000, v180
	v_lshlrev_b32_e32 v180, 16, v181
	v_and_b32_e32 v181, 0xffff0000, v181
	v_pk_add_f32 v[128:129], v[128:129], v[180:181]
	v_pk_add_f32 v[126:127], v[126:127], v[190:191]
	v_mul_f32_e32 v181, v129, v129
	v_mul_f32_e32 v180, v127, v127
	v_fmac_f32_e32 v180, v126, v126
	v_fmac_f32_e32 v181, v128, v128
	v_cvt_pk_bf16_f32 v126, v126, v127
	v_cvt_pk_bf16_f32 v127, v128, v129
	v_lshl_add_u64 v[128:129], s[42:43], 0, v[178:179]
	v_lshl_add_u64 v[128:129], v[128:129], 0, v[176:177]
	global_store_dwordx2 v[128:129], v[126:127], off
	v_lshlrev_b32_e32 v126, 16, v182
	v_and_b32_e32 v127, 0xffff0000, v182
	v_pk_add_f32 v[122:123], v[122:123], v[126:127]
	v_lshlrev_b32_e32 v176, 16, v183
	v_and_b32_e32 v177, 0xffff0000, v183
	v_mul_f32_e32 v126, v123, v123
	v_pk_add_f32 v[124:125], v[124:125], v[176:177]
	v_fmac_f32_e32 v126, v122, v122
	v_cvt_pk_bf16_f32 v122, v122, v123
	v_cvt_pk_bf16_f32 v123, v124, v125
	v_mul_f32_e32 v127, v125, v125
	global_store_dwordx2 v[128:129], v[122:123], off offset:32
	v_lshlrev_b32_e32 v122, 16, v184
	v_and_b32_e32 v123, 0xffff0000, v184
	v_fmac_f32_e32 v127, v124, v124
	v_lshlrev_b32_e32 v124, 16, v185
	v_and_b32_e32 v125, 0xffff0000, v185
	v_pk_add_f32 v[118:119], v[118:119], v[122:123]
	v_pk_add_f32 v[120:121], v[120:121], v[124:125]
	v_mul_f32_e32 v122, v119, v119
	v_fmac_f32_e32 v122, v118, v118
	v_mul_f32_e32 v123, v121, v121
	v_cvt_pk_bf16_f32 v118, v118, v119
	v_cvt_pk_bf16_f32 v119, v120, v121
	v_fmac_f32_e32 v123, v120, v120
	global_store_dwordx2 v[128:129], v[118:119], off offset:256
	v_lshlrev_b32_e32 v118, 16, v188
	v_and_b32_e32 v119, 0xffff0000, v188
	v_lshlrev_b32_e32 v120, 16, v189
	v_and_b32_e32 v121, 0xffff0000, v189
	v_pk_add_f32 v[116:117], v[116:117], v[120:121]
	v_pk_add_f32 v[118:119], v[114:115], v[118:119]
	v_add_f32_e32 v180, v180, v181
	v_add_f32_e32 v126, v126, v127
	v_mul_f32_e32 v114, v119, v119
	v_mul_f32_e32 v115, v117, v117
	v_add_f32_e32 v126, v180, v126
	v_add_f32_e32 v122, v122, v123
	v_fmac_f32_e32 v114, v118, v118
	v_fmac_f32_e32 v115, v116, v116
	v_add_f32_e32 v122, v126, v122
	v_add_f32_e32 v114, v114, v115
	v_cvt_pk_bf16_f32 v118, v118, v119
	v_cvt_pk_bf16_f32 v119, v116, v117
	v_and_b32_e32 v116, 64, v229
	v_add_f32_e32 v115, v122, v114
	v_xor_b32_e32 v114, 16, v229
	v_add_u32_e32 v117, 64, v116
	v_cmp_lt_i32_e32 vcc, v114, v117
	global_store_dwordx2 v[128:129], v[118:119], off offset:288
	s_nop 0
	v_cndmask_b32_e32 v114, v229, v114, vcc
	v_lshlrev_b32_e32 v114, 2, v114
	v_mov_b32_e32 v116, v115
	s_nop 1
	v_permlane16_swap_b32_e32 v116, v115
	s_waitcnt lgkmcnt(0)
	v_add_f32_e32 v116, v115, v116
	v_xor_b32_e32 v115, 32, v229
	v_cmp_lt_i32_e32 vcc, v115, v117
	s_nop 1
	v_cndmask_b32_e32 v115, v229, v115, vcc
	v_lshlrev_b32_e32 v115, 2, v115
	ds_bpermute_b32 v117, v115, v116
	s_and_saveexec_b64 s[78:79], s[6:7]
	s_cbranch_execz .LBB0_1268
	v_lshlrev_b64 v[118:119], 6, v[140:141]
	v_lshl_add_u64 v[118:119], s[14:15], 0, v[118:119]
	v_lshl_add_u64 v[118:119], s[76:77], 2, v[118:119]
	s_lshl_b32 s64, s86, 2
	v_lshl_add_u64 v[118:119], v[118:119], 0, s[64:65]
	s_waitcnt lgkmcnt(0)
	v_add_f32_e32 v116, v116, v117
	global_store_dword v[118:119], v116, off

; #define PG8_STAGE(bufoff, gbase, voff) do { _Pragma("unroll") for (int _i = 0; _i < 2; ++_i) \
;         __builtin_amdgcn_global_load_lds((const unsigned*)((const char*)(gbase) + (voff)[_i]), (PG8_LAS unsigned*)(lds + (bufoff) + ldsw + _i * 8192), 16, 0, 0); } while (0)
; #define PG8_WAIT_V(n) asm volatile("s_waitcnt vmcnt(" #n ")" ::: "memory")
; #define PG8_BAR __builtin_amdgcn_s_barrier()
;     __device__ __forceinline__ void operator()(f32x4 (&acc)[2][2][4][2], const Unit& u, int wr, int wc, int fr, int fq) const {
;     ...
;             const int gc0 = u.pn * 128 + wc * 32 + 8 * fq + 4 * n;
;             const float* cwp = cw + gc0; asm volatile("" : "+v"(cwp));
;             const f32x4 wg0 = *(const f32x4*)(cwp), wg1 = *(const f32x4*)(cwp + FF2c), wg2 = *(const f32x4*)(cwp + 2 * FF2c);
;             const f32x4 wv0 = *(const f32x4*)(cwp + FFc), wv1 = *(const f32x4*)(cwp + FF2c + FFc), wv2 = *(const f32x4*)(cwp + 2 * FF2c + FFc);
;             const f32x4 bg = *(const f32x4*)(cb + gc0), bv = *(const f32x4*)(cb + FFc + gc0);
;             bf16_t* gp = G + (size_t)row0 * FFc + gc0;
;             bf16_t* sb = Fb + ((size_t)(row0 >> 6) * 2 + (fr & 1)) * FF2c + gc0;
;             bf16_t* hb = Hb + ((size_t)(row0 >> 6) * 2 + (fr & 1)) * FF2c + gc0;
; template <class Epi, class Sched, bool ALIGN_EPI = false, bool SP2 = false>
; __device__ __forceinline__ void gemm_phase(PG8_LAS unsigned char* lds, const Gemm g, const Sched& S, const Epi& E) {
;     ...
;     for (int i = 0; i < 2; ++i) { int R, C; stage_rc(tid * 16 + i * 8192, R, C); const int Rb = Epi::PERM ? ((R & ~31) + perm32(R & 31)) : R;
;         voffA[i] = (unsigned)(R * K + C) * 2u; voffB[i] = (unsigned)(Rb * K + C) * 2u; }
;     const size_t kstep = (size_t)(BK * 2);
;     const size_t hstep = (size_t)HALF * K * 2;
;     const size_t tstep = 2 * hstep;
;     const unsigned ldsw = (unsigned)wid * 1024u;
;     const int aoff = lds_byte(wr * 64 + fr, fq * 8), boff = lds_byte(wc * 32 + fr, fq * 8);
;     ...
;         PG8_STAGE(PG8_SB(0, 0), cB, voffB); PG8_STAGE(PG8_SB(0, 1), cB + hstep, voffB); PG8_STAGE(PG8_SA(0, 0), cA, voffA); PG8_STAGE(PG8_SA(0, 1), cA + hstep, voffA);
;         if (wr == 1) PG8_BAR;
;         PG8_WAIT_V(2); PG8_BAR;
;         PG8_STAGE(PG8_SB(1, 0), cB + kstep, voffB); PG8_STAGE(PG8_SA(1, 0), cA + kstep, voffA); PG8_STAGE(PG8_SB(1, 1), cB + hstep + kstep, voffB);
;         PG8_WAIT_V(6); PG8_BAR;
.LBB0_1341:
	v_readlane_b32 s14, v254, 57
	s_lshl_b32 s1, s1, 5
	v_mov_b32_e32 v159, v1
	v_readlane_b32 s15, v254, 58
	s_and_b32 s1, s1, 0x60
	s_add_i32 m0, s96, 0x18000
	v_lshl_add_u64 v[2:3], v[2:3], 0, s[60:61]
	v_lshl_add_u64 v[14:15], s[14:15], 0, v[158:159]
	v_mov_b32_e32 v157, v1
	s_lshl_b32 s24, s4, 6
	s_lshl_b32 s6, s4, 13
	s_lshl_b32 s7, s1, 7
	s_waitcnt vmcnt(2)
	s_barrier
	global_load_lds_dwordx4 v[2:3], off
	v_lshl_add_u64 v[2:3], v[4:5], 0, s[60:61]
	s_add_i32 m0, s96, 0x1a000
	s_add_i32 s25, s96, 0x8000
	s_add_i32 s35, s96, 0xa000
	v_lshl_add_u64 v[16:17], s[14:15], 0, v[156:157]
	global_load_lds_dwordx4 v[2:3], off
	v_lshl_add_u64 v[2:3], v[14:15], 0, s[60:61]
	s_mov_b32 m0, s25
	s_add_u32 s4, s84, 0x40080
	global_load_lds_dwordx4 v[2:3], off
	v_lshl_add_u64 v[2:3], v[16:17], 0, s[60:61]
	s_mov_b32 m0, s35
	s_addc_u32 s5, s85, 0
	global_load_lds_dwordx4 v[2:3], off
	s_add_i32 m0, s96, 0x1c000
	v_lshl_add_u64 v[2:3], s[4:5], 0, v[0:1]
	global_load_lds_dwordx4 v[2:3], off
	v_lshl_add_u64 v[2:3], s[4:5], 0, v[154:155]
	s_add_i32 m0, s96, 0x1e000
	v_bfe_u32 v4, v6, 4, 2
	global_load_lds_dwordx4 v[2:3], off
	v_and_b32_e32 v161, 15, v6
	v_lshlrev_b32_e32 v2, 4, v4
	v_lshlrev_b32_e32 v5, 2, v6
	v_lshl_or_b32 v3, v161, 6, v2
	v_and_b32_e32 v5, 32, v5
	v_readlane_b32 s10, v253, 42
	v_bitop3_b32 v13, v3, s6, v5 bitop3:0xde
	v_bitop3_b32 v187, v3, s7, v5 bitop3:0xde
	v_mov_b32_e32 v3, v1
	v_readlane_b32 s11, v253, 43
	s_waitcnt vmcnt(6)
	s_mov_b32 s100, 0
	s_cmpk_lt_u32 s0, 0x100
	v_lshl_or_b32 v238, v4, 3, s1
	v_lshl_add_u64 v[162:163], s[10:11], 0, v[2:3]
	v_lshlrev_b32_e32 v2, 14, v11
	v_and_b32_e32 v2, 0xffff8000, v2
	v_lshl_add_u32 v2, v10, 11, v2
	v_and_b32_e32 v3, 1, v11
	v_lshl_or_b32 v2, v3, 6, v2
	v_lshl_add_u32 v164, v12, 1, v2
	v_lshlrev_b32_e32 v2, 14, v7
	v_and_b32_e32 v2, 0xffff8000, v2
	v_lshl_add_u32 v2, v8, 11, v2
	v_and_b32_e32 v3, 1, v7
	v_readlane_b32 s0, v254, 55
	s_cselect_b64 s[4:5], -1, 0
	s_add_u32 s76, s72, 0x2c00
	v_lshl_or_b32 v2, v3, 6, v2
	v_readlane_b32 s1, v254, 56
	v_and_b32_e32 v160, 1, v6
	v_cmp_gt_u32_e64 s[6:7], 2, v161
	v_cmp_lt_u32_e64 s[8:9], 13, v161
	s_addc_u32 s77, s73, 0
	v_mov_b32_e32 v165, v1
	v_lshl_add_u32 v166, v9, 1, v2
	v_mov_b32_e32 v167, v1
	s_mov_b32 s90, 0
	v_add_u32_e32 v239, 0, v13
	v_readlane_b32 s12, v254, 39
	s_mov_b32 s13, s0
	s_mov_b64 s[0:1], s[14:15]
	s_barrier
	s_branch .LBB0_1344

; #define PG8_STAGE(bufoff, gbase, voff) do { _Pragma("unroll") for (int _i = 0; _i < 2; ++_i) \
;         __builtin_amdgcn_global_load_lds((const unsigned*)((const char*)(gbase) + (voff)[_i]), (PG8_LAS unsigned*)(lds + (bufoff) + ldsw + _i * 8192), 16, 0, 0); } while (0)
; #define PG8_LDA(dst, b, h) do { _Pragma("unroll") for (int m = 0; m < 4; ++m) _Pragma("unroll") for (int k = 0; k < 2; ++k) dst[m][k] = *(const PG8_LAS bf16x8*)(lds + PG8_SA(b, h) + aoff + m * 2048 + k * 1024); } while (0)
; #define PG8_LDB(dst, b, h) do { _Pragma("unroll") for (int n = 0; n < 2; ++n) _Pragma("unroll") for (int k = 0; k < 2; ++k) dst[n][k] = *(const PG8_LAS bf16x8*)(lds + PG8_SB(b, h) + boff + n * 2048 + k * 1024); } while (0)
; #define PG8_MMA(ai, bj, At, Bt) do { __builtin_amdgcn_s_setprio(1); _Pragma("unroll") for (int m = 0; m < 4; ++m) _Pragma("unroll") for (int n = 0; n < 2; ++n) _Pragma("unroll") for (int k = 0; k < 2; ++k) \
;         acc[ai][bj][m][n] = __builtin_amdgcn_mfma_f32_16x16x32_bf16(Bt[n][k], At[m][k], acc[ai][bj][m][n], 0, 0, 0); __builtin_amdgcn_s_setprio(0); } while (0)
; #define PG8_WAIT_V(n) asm volatile("s_waitcnt vmcnt(" #n ")" ::: "memory")
; #define PG8_WAIT_L(n) asm volatile("s_waitcnt lgkmcnt(" #n ")" ::: "memory")
; #define PG8_BAR __builtin_amdgcn_s_barrier()
; #define PG8_SCHED __builtin_amdgcn_sched_barrier(0)
; template <class Epi, class Sched, bool ALIGN_EPI = false, bool SP2 = false>
; __device__ __forceinline__ void gemm_phase(PG8_LAS unsigned char* lds, const Gemm g, const Sched& S, const Epi& E) {
;     ...
;             const bool last = (t == nt - 2);
;             const char* a1 = cA + (size_t)(t + 1) * kstep;
;             const char* a2 = last ? nA : cA + (size_t)(t + 2) * kstep; const char* b2 = last ? nB : cB + (size_t)(t + 2) * kstep;
;             const char* a3 = a2 + kstep; const char* b3 = b2 + kstep;
;             if (last && has_next) S.a_ready(nxt);
;             if constexpr (SP2) {
;             PG8_LDB(B0, 0, 0); PG8_LDB(B1, 0, 1); PG8_SCHED; PG8_LDA(At, 0, 0); PG8_STAGE(PG8_SA(1, 1), a1 + hstep, voffA);
;             PG8_WAIT_V(8); PG8_WAIT_L(0); PG8_BAR; PG8_MMA(0, 0, At, B0); PG8_MMA(0, 1, At, B1); PG8_BAR; PG8_SCHED;
;             PG8_LDA(At, 0, 1); PG8_STAGE(PG8_SB(0, 0), b2, voffB); PG8_STAGE(PG8_SB(0, 1), b2 + hstep, voffB); PG8_STAGE(PG8_SA(0, 0), a2, voffA);
.LBB0_1347:
	s_add_u32 s50, s0, 0xfffc0080
	s_addc_u32 s51, s1, -1
	s_add_i32 s57, 0, 0x10000
	s_cmp_eq_u32 s56, 12
	s_cselect_b32 vcc_hi, s81, s51
	s_cselect_b32 vcc_lo, s52, s50
	s_cselect_b32 s85, s53, s55
	s_cselect_b32 s84, s79, s54
	s_add_i32 s66, 0, 0x14000
	v_add_u32_e32 v142, s57, v187
	v_add_u32_e32 v172, s66, v187
	ds_read_b128 v[130:133], v142
	ds_read_b128 v[134:137], v142 offset:1024
	ds_read_b128 v[138:141], v142 offset:2048
	ds_read_b128 v[142:145], v142 offset:3072
	ds_read_b128 v[146:149], v172
	ds_read_b128 v[150:153], v172 offset:1024
	ds_read_b128 v[168:171], v172 offset:2048
	ds_read_b128 v[172:175], v172 offset:3072
	v_lshl_add_u64 v[184:185], s[0:1], 0, v[164:165]
	s_add_i32 m0, s96, 0xc000
	ds_read_b128 v[176:179], v239
	ds_read_b128 v[180:183], v239 offset:1024
	ds_read_b128 v[192:195], v239 offset:2048
	ds_read_b128 v[196:199], v239 offset:3072
	ds_read_b128 v[200:203], v239 offset:4096
	ds_read_b128 v[204:207], v239 offset:5120
	ds_read_b128 v[208:211], v239 offset:6144
	ds_read_b128 v[212:215], v239 offset:7168
	global_load_lds_dwordx4 v[184:185], off
	v_lshl_add_u64 v[184:185], s[0:1], 0, v[166:167]
	s_add_i32 m0, s96, 0xe000
	s_nop 0
	global_load_lds_dwordx4 v[184:185], off
	s_cmp_lg_u32 s100, 0
	s_cbranch_scc1 .Lpe_skip_up_0
	s_waitcnt vmcnt(8)
.Lpe_skip_up_0:
	s_waitcnt lgkmcnt(0)
	s_barrier
	s_setprio 1
	s_waitcnt lgkmcnt(0)
	v_mfma_f32_16x16x32_bf16 v[102:105], v[130:133], v[176:179], v[102:105]
	v_mfma_f32_16x16x32_bf16 v[62:65], v[138:141], v[176:179], v[62:65]
	v_mfma_f32_16x16x32_bf16 v[126:129], v[130:133], v[192:195], v[126:129]
	v_mfma_f32_16x16x32_bf16 v[54:57], v[138:141], v[192:195], v[54:57]
	v_mfma_f32_16x16x32_bf16 v[122:125], v[130:133], v[200:203], v[122:125]
	v_mfma_f32_16x16x32_bf16 v[50:53], v[138:141], v[200:203], v[50:53]
	v_mfma_f32_16x16x32_bf16 v[114:117], v[130:133], v[208:211], v[114:117]
	v_mfma_f32_16x16x32_bf16 v[42:45], v[138:141], v[208:211], v[42:45]
	v_mfma_f32_16x16x32_bf16 v[102:105], v[134:137], v[180:183], v[102:105]
	v_mfma_f32_16x16x32_bf16 v[62:65], v[142:145], v[180:183], v[62:65]
	v_mfma_f32_16x16x32_bf16 v[126:129], v[134:137], v[196:199], v[126:129]
	v_mfma_f32_16x16x32_bf16 v[54:57], v[142:145], v[196:199], v[54:57]
	v_mfma_f32_16x16x32_bf16 v[122:125], v[134:137], v[204:207], v[122:125]
	v_mfma_f32_16x16x32_bf16 v[50:53], v[142:145], v[204:207], v[50:53]
	v_mfma_f32_16x16x32_bf16 v[114:117], v[134:137], v[212:215], v[114:117]
	v_mfma_f32_16x16x32_bf16 v[42:45], v[142:145], v[212:215], v[42:45]
	s_setprio 0
	s_setprio 1
	v_mfma_f32_16x16x32_bf16 v[98:101], v[146:149], v[176:179], v[98:101]
	v_mfma_f32_16x16x32_bf16 v[58:61], v[168:171], v[176:179], v[58:61]
	v_mfma_f32_16x16x32_bf16 v[118:121], v[146:149], v[192:195], v[118:121]
	v_mfma_f32_16x16x32_bf16 v[46:49], v[168:171], v[192:195], v[46:49]
	v_mfma_f32_16x16x32_bf16 v[110:113], v[146:149], v[200:203], v[110:113]
	v_mfma_f32_16x16x32_bf16 v[38:41], v[168:171], v[200:203], v[38:41]
	v_mfma_f32_16x16x32_bf16 v[106:109], v[146:149], v[208:211], v[106:109]
	v_mfma_f32_16x16x32_bf16 v[34:37], v[168:171], v[208:211], v[34:37]
	v_mfma_f32_16x16x32_bf16 v[98:101], v[150:153], v[180:183], v[98:101]
	v_mfma_f32_16x16x32_bf16 v[58:61], v[172:175], v[180:183], v[58:61]
	v_mfma_f32_16x16x32_bf16 v[118:121], v[150:153], v[196:199], v[118:121]
	v_mfma_f32_16x16x32_bf16 v[46:49], v[172:175], v[196:199], v[46:49]
	v_mfma_f32_16x16x32_bf16 v[110:113], v[150:153], v[204:207], v[110:113]
	v_mfma_f32_16x16x32_bf16 v[38:41], v[172:175], v[204:207], v[38:41]
	v_mfma_f32_16x16x32_bf16 v[106:109], v[150:153], v[212:215], v[106:109]
	v_mfma_f32_16x16x32_bf16 v[34:37], v[172:175], v[212:215], v[34:37]
	s_setprio 0
	s_barrier
	s_add_i32 s50, s57, s95
	v_lshl_add_u64 v[184:185], s[84:85], 0, v[0:1]
	s_mov_b32 m0, s50
	ds_read_b128 v[176:179], v239 offset:16384
	ds_read_b128 v[180:183], v239 offset:17408
	ds_read_b128 v[192:195], v239 offset:18432
	ds_read_b128 v[196:199], v239 offset:19456
	ds_read_b128 v[200:203], v239 offset:20480
	ds_read_b128 v[204:207], v239 offset:21504
	ds_read_b128 v[208:211], v239 offset:22528
	ds_read_b128 v[212:215], v239 offset:23552
	global_load_lds_dwordx4 v[184:185], off
	s_add_i32 m0, s50, 0x2000
	s_add_u32 s50, s84, 0x40000
	v_lshl_add_u64 v[188:189], s[84:85], 0, v[154:155]
	s_addc_u32 s51, s85, 0
	s_add_i32 s57, s66, s95
	global_load_lds_dwordx4 v[188:189], off
	v_lshl_add_u64 v[190:191], s[50:51], 0, v[0:1]
	s_mov_b32 m0, s57
	v_lshl_add_u64 v[216:217], vcc, 0, v[156:157]
	global_load_lds_dwordx4 v[190:191], off
	v_lshl_add_u64 v[190:191], s[50:51], 0, v[154:155]
	s_add_i32 m0, s57, 0x2000
	s_nop 0
	global_load_lds_dwordx4 v[190:191], off
	v_lshl_add_u64 v[190:191], vcc, 0, v[158:159]
	s_mov_b32 m0, s96
	s_nop 0
	global_load_lds_dwordx4 v[190:191], off
	s_mov_b32 m0, s97
	s_nop 0
	global_load_lds_dwordx4 v[216:217], off
	s_cmp_lg_u32 s100, 0
	s_cbranch_scc1 .Lpe_skip_up_1
	s_waitcnt vmcnt(8)
; #define PG8_STAGE(bufoff, gbase, voff) do { _Pragma("unroll") for (int _i = 0; _i < 2; ++_i) \
;         __builtin_amdgcn_global_load_lds((const unsigned*)((const char*)(gbase) + (voff)[_i]), (PG8_LAS unsigned*)(lds + (bufoff) + ldsw + _i * 8192), 16, 0, 0); } while (0)
; #define PG8_LDA(dst, b, h) do { _Pragma("unroll") for (int m = 0; m < 4; ++m) _Pragma("unroll") for (int k = 0; k < 2; ++k) dst[m][k] = *(const PG8_LAS bf16x8*)(lds + PG8_SA(b, h) + aoff + m * 2048 + k * 1024); } while (0)
; #define PG8_LDB(dst, b, h) do { _Pragma("unroll") for (int n = 0; n < 2; ++n) _Pragma("unroll") for (int k = 0; k < 2; ++k) dst[n][k] = *(const PG8_LAS bf16x8*)(lds + PG8_SB(b, h) + boff + n * 2048 + k * 1024); } while (0)
; #define PG8_MMA(ai, bj, At, Bt) do { __builtin_amdgcn_s_setprio(1); _Pragma("unroll") for (int m = 0; m < 4; ++m) _Pragma("unroll") for (int n = 0; n < 2; ++n) _Pragma("unroll") for (int k = 0; k < 2; ++k) \
;         acc[ai][bj][m][n] = __builtin_amdgcn_mfma_f32_16x16x32_bf16(Bt[n][k], At[m][k], acc[ai][bj][m][n], 0, 0, 0); __builtin_amdgcn_s_setprio(0); } while (0)
; #define PG8_WAIT_V(n) asm volatile("s_waitcnt vmcnt(" #n ")" ::: "memory")
; #define PG8_WAIT_L(n) asm volatile("s_waitcnt lgkmcnt(" #n ")" ::: "memory")
; #define PG8_BAR __builtin_amdgcn_s_barrier()
; #define PG8_SCHED __builtin_amdgcn_sched_barrier(0)
; template <class Epi, class Sched, bool ALIGN_EPI = false, bool SP2 = false>
; __device__ __forceinline__ void gemm_phase(PG8_LAS unsigned char* lds, const Gemm g, const Sched& S, const Epi& E) {
;     ...
;             PG8_WAIT_V(8); PG8_WAIT_L(0); PG8_BAR; PG8_MMA(1, 0, At, B0); PG8_MMA(1, 1, At, B1); PG8_BAR; PG8_SCHED;
;             PG8_LDB(B0, 1, 0); PG8_LDB(B1, 1, 1); PG8_SCHED; PG8_LDA(At, 1, 0); PG8_STAGE(PG8_SA(0, 1), a2 + hstep, voffA);
;             PG8_WAIT_V(8); PG8_WAIT_L(0); PG8_BAR; PG8_MMA(0, 0, At, B0); PG8_MMA(0, 1, At, B1); PG8_BAR; PG8_SCHED;
.Lpe_skip_up_1:
	s_mov_b32 s100, 0
	s_waitcnt lgkmcnt(0)
	s_barrier
	s_setprio 1
	s_waitcnt lgkmcnt(0)
	v_mfma_f32_16x16x32_bf16 v[94:97], v[130:133], v[176:179], v[94:97]
	v_mfma_f32_16x16x32_bf16 v[30:33], v[138:141], v[176:179], v[30:33]
	v_mfma_f32_16x16x32_bf16 v[86:89], v[130:133], v[192:195], v[86:89]
	v_mfma_f32_16x16x32_bf16 v[22:25], v[138:141], v[192:195], v[22:25]
	v_mfma_f32_16x16x32_bf16 v[82:85], v[130:133], v[200:203], v[82:85]
	v_mfma_f32_16x16x32_bf16 v[18:21], v[138:141], v[200:203], v[18:21]
	v_mfma_f32_16x16x32_bf16 v[74:77], v[130:133], v[208:211], v[74:77]
	v_mfma_f32_16x16x32_bf16 v[10:13], v[138:141], v[208:211], v[10:13]
	v_mfma_f32_16x16x32_bf16 v[94:97], v[134:137], v[180:183], v[94:97]
	v_mfma_f32_16x16x32_bf16 v[30:33], v[142:145], v[180:183], v[30:33]
	v_mfma_f32_16x16x32_bf16 v[86:89], v[134:137], v[196:199], v[86:89]
	v_mfma_f32_16x16x32_bf16 v[22:25], v[142:145], v[196:199], v[22:25]
	v_mfma_f32_16x16x32_bf16 v[82:85], v[134:137], v[204:207], v[82:85]
	v_mfma_f32_16x16x32_bf16 v[18:21], v[142:145], v[204:207], v[18:21]
	v_mfma_f32_16x16x32_bf16 v[74:77], v[134:137], v[212:215], v[74:77]
	v_mfma_f32_16x16x32_bf16 v[10:13], v[142:145], v[212:215], v[10:13]
	s_setprio 0
	s_setprio 1
	v_mfma_f32_16x16x32_bf16 v[90:93], v[146:149], v[176:179], v[90:93]
	v_mfma_f32_16x16x32_bf16 v[26:29], v[168:171], v[176:179], v[26:29]
	v_mfma_f32_16x16x32_bf16 v[78:81], v[146:149], v[192:195], v[78:81]
	v_mfma_f32_16x16x32_bf16 v[14:17], v[168:171], v[192:195], v[14:17]
	v_mfma_f32_16x16x32_bf16 v[70:73], v[146:149], v[200:203], v[70:73]
	v_mfma_f32_16x16x32_bf16 v[6:9], v[168:171], v[200:203], v[6:9]
	v_mfma_f32_16x16x32_bf16 v[66:69], v[146:149], v[208:211], v[66:69]
	v_mfma_f32_16x16x32_bf16 v[2:5], v[168:171], v[208:211], v[2:5]
	v_mfma_f32_16x16x32_bf16 v[90:93], v[150:153], v[180:183], v[90:93]
	v_mfma_f32_16x16x32_bf16 v[26:29], v[172:175], v[180:183], v[26:29]
	v_mfma_f32_16x16x32_bf16 v[78:81], v[150:153], v[196:199], v[78:81]
	v_mfma_f32_16x16x32_bf16 v[14:17], v[172:175], v[196:199], v[14:17]
	v_mfma_f32_16x16x32_bf16 v[70:73], v[150:153], v[204:207], v[70:73]
	v_mfma_f32_16x16x32_bf16 v[6:9], v[172:175], v[204:207], v[6:9]
	v_mfma_f32_16x16x32_bf16 v[66:69], v[150:153], v[212:215], v[66:69]
	v_mfma_f32_16x16x32_bf16 v[2:5], v[172:175], v[212:215], v[2:5]
	s_setprio 0
	s_barrier
	s_add_i32 s57, 0, 0x18000
	s_add_i32 s66, 0, 0x1c000
	v_add_u32_e32 v142, s57, v187
	v_add_u32_e32 v172, s66, v187
	ds_read_b128 v[130:133], v142
	ds_read_b128 v[134:137], v142 offset:1024
	ds_read_b128 v[138:141], v142 offset:2048
	ds_read_b128 v[142:145], v142 offset:3072
	ds_read_b128 v[146:149], v172
	ds_read_b128 v[150:153], v172 offset:1024
	ds_read_b128 v[168:171], v172 offset:2048
	ds_read_b128 v[172:175], v172 offset:3072
	s_add_u32 s50, vcc_lo, 0x40000
	s_addc_u32 s51, vcc_hi, 0
	s_mov_b32 m0, s62
	v_lshl_add_u64 v[218:219], s[50:51], 0, v[158:159]
	ds_read_b128 v[176:179], v239 offset:32768
	ds_read_b128 v[180:183], v239 offset:33792
	ds_read_b128 v[192:195], v239 offset:34816
	ds_read_b128 v[196:199], v239 offset:35840
	ds_read_b128 v[200:203], v239 offset:36864
	ds_read_b128 v[204:207], v239 offset:37888
	ds_read_b128 v[208:211], v239 offset:38912
	ds_read_b128 v[212:215], v239 offset:39936
	global_load_lds_dwordx4 v[218:219], off
	v_lshl_add_u64 v[218:219], s[50:51], 0, v[156:157]
	s_mov_b32 m0, s63
	s_nop 0
	global_load_lds_dwordx4 v[218:219], off
	s_waitcnt vmcnt(8)
	s_waitcnt lgkmcnt(0)
	s_barrier
	s_setprio 1
	s_waitcnt lgkmcnt(0)
	v_mfma_f32_16x16x32_bf16 v[102:105], v[130:133], v[176:179], v[102:105]
	v_mfma_f32_16x16x32_bf16 v[62:65], v[138:141], v[176:179], v[62:65]
	v_mfma_f32_16x16x32_bf16 v[126:129], v[130:133], v[192:195], v[126:129]
	v_mfma_f32_16x16x32_bf16 v[54:57], v[138:141], v[192:195], v[54:57]
	v_mfma_f32_16x16x32_bf16 v[122:125], v[130:133], v[200:203], v[122:125]
	v_mfma_f32_16x16x32_bf16 v[50:53], v[138:141], v[200:203], v[50:53]
	v_mfma_f32_16x16x32_bf16 v[114:117], v[130:133], v[208:211], v[114:117]
	v_mfma_f32_16x16x32_bf16 v[42:45], v[138:141], v[208:211], v[42:45]
	v_mfma_f32_16x16x32_bf16 v[102:105], v[134:137], v[180:183], v[102:105]
	v_mfma_f32_16x16x32_bf16 v[62:65], v[142:145], v[180:183], v[62:65]
	v_mfma_f32_16x16x32_bf16 v[126:129], v[134:137], v[196:199], v[126:129]
	v_mfma_f32_16x16x32_bf16 v[54:57], v[142:145], v[196:199], v[54:57]
	v_mfma_f32_16x16x32_bf16 v[122:125], v[134:137], v[204:207], v[122:125]
	v_mfma_f32_16x16x32_bf16 v[50:53], v[142:145], v[204:207], v[50:53]
	v_mfma_f32_16x16x32_bf16 v[114:117], v[134:137], v[212:215], v[114:117]
	v_mfma_f32_16x16x32_bf16 v[42:45], v[142:145], v[212:215], v[42:45]
	s_setprio 0
	s_setprio 1
	v_mfma_f32_16x16x32_bf16 v[98:101], v[146:149], v[176:179], v[98:101]
	v_mfma_f32_16x16x32_bf16 v[58:61], v[168:171], v[176:179], v[58:61]
	v_mfma_f32_16x16x32_bf16 v[118:121], v[146:149], v[192:195], v[118:121]
	v_mfma_f32_16x16x32_bf16 v[46:49], v[168:171], v[192:195], v[46:49]
	v_mfma_f32_16x16x32_bf16 v[110:113], v[146:149], v[200:203], v[110:113]
	v_mfma_f32_16x16x32_bf16 v[38:41], v[168:171], v[200:203], v[38:41]
	v_mfma_f32_16x16x32_bf16 v[106:109], v[146:149], v[208:211], v[106:109]
	v_mfma_f32_16x16x32_bf16 v[34:37], v[168:171], v[208:211], v[34:37]
	v_mfma_f32_16x16x32_bf16 v[98:101], v[150:153], v[180:183], v[98:101]
	v_mfma_f32_16x16x32_bf16 v[58:61], v[172:175], v[180:183], v[58:61]
	v_mfma_f32_16x16x32_bf16 v[118:121], v[150:153], v[196:199], v[118:121]
	v_mfma_f32_16x16x32_bf16 v[46:49], v[172:175], v[196:199], v[46:49]
	v_mfma_f32_16x16x32_bf16 v[110:113], v[150:153], v[204:207], v[110:113]
	v_mfma_f32_16x16x32_bf16 v[38:41], v[172:175], v[204:207], v[38:41]
	v_mfma_f32_16x16x32_bf16 v[106:109], v[150:153], v[212:215], v[106:109]
	v_mfma_f32_16x16x32_bf16 v[34:37], v[172:175], v[212:215], v[34:37]
	s_setprio 0
	s_barrier
; #define PG8_STAGE(bufoff, gbase, voff) do { _Pragma("unroll") for (int _i = 0; _i < 2; ++_i) \
;         __builtin_amdgcn_global_load_lds((const unsigned*)((const char*)(gbase) + (voff)[_i]), (PG8_LAS unsigned*)(lds + (bufoff) + ldsw + _i * 8192), 16, 0, 0); } while (0)
; #define PG8_LDA(dst, b, h) do { _Pragma("unroll") for (int m = 0; m < 4; ++m) _Pragma("unroll") for (int k = 0; k < 2; ++k) dst[m][k] = *(const PG8_LAS bf16x8*)(lds + PG8_SA(b, h) + aoff + m * 2048 + k * 1024); } while (0)
; #define PG8_MMA(ai, bj, At, Bt) do { __builtin_amdgcn_s_setprio(1); _Pragma("unroll") for (int m = 0; m < 4; ++m) _Pragma("unroll") for (int n = 0; n < 2; ++n) _Pragma("unroll") for (int k = 0; k < 2; ++k) \
;         acc[ai][bj][m][n] = __builtin_amdgcn_mfma_f32_16x16x32_bf16(Bt[n][k], At[m][k], acc[ai][bj][m][n], 0, 0, 0); __builtin_amdgcn_s_setprio(0); } while (0)
; #define PG8_WAIT_V(n) asm volatile("s_waitcnt vmcnt(" #n ")" ::: "memory")
; #define PG8_WAIT_L(n) asm volatile("s_waitcnt lgkmcnt(" #n ")" ::: "memory")
; #define PG8_BAR __builtin_amdgcn_s_barrier()
; #define PG8_SCHED __builtin_amdgcn_sched_barrier(0)
; __device__ __forceinline__ void load_row_scales(const float* ssp, int row0, int fq, float (&rs)[2][4]) {
;     f32x4 part[2][4];
;     const float* sp = ssp + (size_t)row0 * 16 + 4 * fq;
; #pragma unroll
;     for (int ai = 0; ai < 2; ++ai)
; #pragma unroll
;         for (int m = 0; m < 4; ++m) part[ai][m] = *(const f32x4*)(sp + (size_t)(ai * HALF + m * 16) * 16);
; #pragma unroll
;     for (int ai = 0; ai < 2; ++ai)
; #pragma unroll
;         for (int m = 0; m < 4; ++m) { float t = (part[ai][m][0] + part[ai][m][1]) + (part[ai][m][2] + part[ai][m][3]);
;             t += __shfl_xor(t, 16); t += __shfl_xor(t, 32);
;             rs[ai][m] = 1.0f / sqrtf(t * (1.0f / 1024.0f) + 1e-6f); }
; template <class Epi, class Sched, bool ALIGN_EPI = false, bool SP2 = false>
; __device__ __forceinline__ void gemm_phase(PG8_LAS unsigned char* lds, const Gemm g, const Sched& S, const Epi& E) {
;     ...
;             PG8_LDA(At, 1, 1); PG8_STAGE(PG8_SB(1, 0), b3, voffB); PG8_STAGE(PG8_SB(1, 1), b3 + hstep, voffB); PG8_STAGE(PG8_SA(1, 0), a3, voffA);
;             PG8_WAIT_V(8); PG8_WAIT_L(0); PG8_BAR; PG8_MMA(1, 0, At, B0); PG8_MMA(1, 1, At, B1); PG8_BAR; PG8_SCHED;
	s_add_i32 s50, s57, s95
	v_lshl_add_u64 v[184:185], v[184:185], 0, s[60:61]
	s_mov_b32 m0, s50
	ds_read_b128 v[176:179], v239 offset:49152
	ds_read_b128 v[180:183], v239 offset:50176
	ds_read_b128 v[192:195], v239 offset:51200
	ds_read_b128 v[196:199], v239 offset:52224
	ds_read_b128 v[200:203], v239 offset:53248
	ds_read_b128 v[204:207], v239 offset:54272
	ds_read_b128 v[208:211], v239 offset:55296
	ds_read_b128 v[212:215], v239 offset:56320
	global_load_lds_dwordx4 v[184:185], off
	s_add_i32 m0, s50, 0x2000
	s_add_u32 s50, s84, 0x40080
	v_lshl_add_u64 v[184:185], v[188:189], 0, s[60:61]
	s_addc_u32 s51, s85, 0
	s_add_i32 s57, s66, s95
	global_load_lds_dwordx4 v[184:185], off
	v_lshl_add_u64 v[184:185], s[50:51], 0, v[0:1]
	s_mov_b32 m0, s57
	s_nop 0
	global_load_lds_dwordx4 v[184:185], off
	v_lshl_add_u64 v[184:185], s[50:51], 0, v[154:155]
	s_add_i32 m0, s57, 0x2000
	s_nop 0
	global_load_lds_dwordx4 v[184:185], off
	v_lshl_add_u64 v[184:185], v[190:191], 0, s[60:61]
	s_mov_b32 m0, s25
	s_nop 0
	global_load_lds_dwordx4 v[184:185], off
	v_lshl_add_u64 v[184:185], v[216:217], 0, s[60:61]
	s_mov_b32 m0, s35
	s_nop 0
	global_load_lds_dwordx4 v[184:185], off
	s_waitcnt vmcnt(8)
	s_waitcnt lgkmcnt(0)
	s_barrier
	s_setprio 1
	s_waitcnt lgkmcnt(0)
	v_mfma_f32_16x16x32_bf16 v[94:97], v[130:133], v[176:179], v[94:97]
	v_mfma_f32_16x16x32_bf16 v[30:33], v[138:141], v[176:179], v[30:33]
	v_mfma_f32_16x16x32_bf16 v[86:89], v[130:133], v[192:195], v[86:89]
	v_mfma_f32_16x16x32_bf16 v[22:25], v[138:141], v[192:195], v[22:25]
	v_mfma_f32_16x16x32_bf16 v[82:85], v[130:133], v[200:203], v[82:85]
	v_mfma_f32_16x16x32_bf16 v[18:21], v[138:141], v[200:203], v[18:21]
	v_mfma_f32_16x16x32_bf16 v[74:77], v[130:133], v[208:211], v[74:77]
	v_mfma_f32_16x16x32_bf16 v[10:13], v[138:141], v[208:211], v[10:13]
	v_mfma_f32_16x16x32_bf16 v[94:97], v[134:137], v[180:183], v[94:97]
	v_mfma_f32_16x16x32_bf16 v[30:33], v[142:145], v[180:183], v[30:33]
	v_mfma_f32_16x16x32_bf16 v[86:89], v[134:137], v[196:199], v[86:89]
	v_mfma_f32_16x16x32_bf16 v[22:25], v[142:145], v[196:199], v[22:25]
	v_mfma_f32_16x16x32_bf16 v[82:85], v[134:137], v[204:207], v[82:85]
	v_mfma_f32_16x16x32_bf16 v[18:21], v[142:145], v[204:207], v[18:21]
	v_mfma_f32_16x16x32_bf16 v[74:77], v[134:137], v[212:215], v[74:77]
	v_mfma_f32_16x16x32_bf16 v[10:13], v[142:145], v[212:215], v[10:13]
	s_setprio 0
	s_setprio 1
	v_mfma_f32_16x16x32_bf16 v[90:93], v[146:149], v[176:179], v[90:93]
	v_mfma_f32_16x16x32_bf16 v[26:29], v[168:171], v[176:179], v[26:29]
	v_mfma_f32_16x16x32_bf16 v[78:81], v[146:149], v[192:195], v[78:81]
	v_mfma_f32_16x16x32_bf16 v[14:17], v[168:171], v[192:195], v[14:17]
	v_mfma_f32_16x16x32_bf16 v[70:73], v[146:149], v[200:203], v[70:73]
	v_mfma_f32_16x16x32_bf16 v[6:9], v[168:171], v[200:203], v[6:9]
	v_mfma_f32_16x16x32_bf16 v[66:69], v[146:149], v[208:211], v[66:69]
	v_mfma_f32_16x16x32_bf16 v[2:5], v[168:171], v[208:211], v[2:5]
	v_mfma_f32_16x16x32_bf16 v[90:93], v[150:153], v[180:183], v[90:93]
	v_mfma_f32_16x16x32_bf16 v[26:29], v[172:175], v[180:183], v[26:29]
	v_mfma_f32_16x16x32_bf16 v[78:81], v[150:153], v[196:199], v[78:81]
	v_mfma_f32_16x16x32_bf16 v[14:17], v[172:175], v[196:199], v[14:17]
	v_mfma_f32_16x16x32_bf16 v[70:73], v[150:153], v[204:207], v[70:73]
	v_mfma_f32_16x16x32_bf16 v[6:9], v[172:175], v[204:207], v[6:9]
	v_mfma_f32_16x16x32_bf16 v[66:69], v[150:153], v[212:215], v[66:69]
	v_mfma_f32_16x16x32_bf16 v[2:5], v[172:175], v[212:215], v[2:5]
	s_setprio 0
	s_barrier
	s_add_i32 s56, s56, 2
	s_add_u32 s0, s0, 0x100
	s_addc_u32 s1, s1, 0
	s_add_u32 s54, s54, 0x100
	s_addc_u32 s55, s55, 0
	s_cmp_gt_u32 s56, 13
	s_cbranch_scc0 .LBB0_1347
	s_and_b64 vcc, exec, s[4:5]
	s_cbranch_vccz .LBB0_1350
	s_barrier
.LBB0_1350:
	s_lshl_b32 s13, s13, 8
	s_add_i32 s13, s13, s24
	v_or_b32_e32 v176, s13, v161
	v_ashrrev_i32_e32 v177, 31, v176
	v_lshlrev_b64 v[130:131], 6, v[176:177]
	v_lshl_add_u64 v[146:147], v[162:163], 0, v[130:131]
	global_load_dwordx4 v[130:133], v[146:147], off
	global_load_dwordx4 v[134:137], v[146:147], off offset:1024
	global_load_dwordx4 v[138:141], v[146:147], off offset:2048
	global_load_dwordx4 v[142:145], v[146:147], off offset:3072
	v_add_co_u32_e32 v168, vcc, 0x2000, v146
	v_mov_b32_e32 v177, v1
	s_nop 0
	v_addc_co_u32_e32 v169, vcc, 0, v147, vcc
	global_load_dwordx4 v[146:149], v[168:169], off
	global_load_dwordx4 v[150:153], v[168:169], off offset:1024
	global_load_dwordx4 v[170:173], v[168:169], off offset:2048
	global_load_dwordx4 v[178:181], v[168:169], off offset:3072
	v_and_b32_e32 v169, 64, v229
	v_xor_b32_e32 v168, 16, v229
	v_add_u32_e32 v169, 64, v169
	v_cmp_lt_i32_e32 vcc, v168, v169
	v_mov_b32_dpp v177, v177 row_ror:1 row_mask:0xf bank_mask:0xf
	v_mov_b32_e32 v189, v177
	v_cndmask_b32_e32 v168, v229, v168, vcc
	v_lshlrev_b32_e32 v174, 2, v168
	v_xor_b32_e32 v168, 32, v229
	v_cmp_lt_i32_e32 vcc, v168, v169
	s_waitcnt vmcnt(0)
	s_mov_b32 s100, 1
	v_mov_b32_e32 v169, v132
	v_cndmask_b32_e32 v168, v229, v168, vcc
	v_lshlrev_b32_e32 v175, 2, v168
	v_mov_b32_e32 v168, v131
	v_mov_b32_e32 v131, v133
	v_pk_add_f32 v[130:131], v[168:169], v[130:131]
	s_nop 0
	v_add_f32_e32 v130, v130, v131
	v_mov_b32_e32 v131, v130
	s_nop 1
	v_permlane16_swap_b32_e32 v131, v130
	s_waitcnt lgkmcnt(0)
	v_add_f32_e32 v130, v130, v131
	v_mov_b32_e32 v131, v130
	s_nop 1
	v_permlane32_swap_b32_e32 v131, v130
	s_waitcnt lgkmcnt(0)
	v_add_f32_e32 v130, v130, v131
	v_fmamk_f32 v130, v130, 0x3a800000, v230
	s_ashr_i32 s0, s13, 5
	v_rsq_f32_e32 v168, v130
	s_nop 0
	v_mov_b32_e32 v130, v135
	v_mov_b32_e32 v131, v136
	v_mov_b32_e32 v135, v137
	v_pk_add_f32 v[130:131], v[130:131], v[134:135]
	s_nop 0
	v_add_f32_e32 v130, v130, v131
	v_mov_b32_e32 v131, v130
	s_nop 1
	v_permlane16_swap_b32_e32 v131, v130
	s_waitcnt lgkmcnt(0)
;     __device__ __forceinline__ void operator()(f32x4 (&acc)[2][2][4][2], const Unit& u, int wr, int wc, int fr, int fq) const {
;     ...
;         { float rs[2][4]; load_row_scales(ssp, row0, fq, rs);
; #pragma unroll
;           for (int ai = 0; ai < 2; ++ai)
; #pragma unroll
;               for (int m = 0; m < 4; ++m)
; #pragma unroll
;                   for (int bj = 0; bj < 2; ++bj)
; #pragma unroll
;                       for (int n = 0; n < 2; ++n) acc[ai][bj][m][n] = acc[ai][bj][m][n] * rs[ai][m]; }
; #pragma unroll
;         for (int n = 0; n < 2; ++n) {
;             const int gc0 = u.pn * 128 + wc * 32 + 8 * fq + 4 * n;
;             const float* cwp = cw + gc0; asm volatile("" : "+v"(cwp));
;             const f32x4 wg0 = *(const f32x4*)(cwp), wg1 = *(const f32x4*)(cwp + FF2c), wg2 = *(const f32x4*)(cwp + 2 * FF2c);
;             const f32x4 wv0 = *(const f32x4*)(cwp + FFc), wv1 = *(const f32x4*)(cwp + FF2c + FFc), wv2 = *(const f32x4*)(cwp + 2 * FF2c + FFc);
;             const f32x4 bg = *(const f32x4*)(cb + gc0), bv = *(const f32x4*)(cb + FFc + gc0);
;             bf16_t* gp = G + (size_t)row0 * FFc + gc0;
;             bf16_t* sb = Fb + ((size_t)(row0 >> 6) * 2 + (fr & 1)) * FF2c + gc0;
;             bf16_t* hb = Hb + ((size_t)(row0 >> 6) * 2 + (fr & 1)) * FF2c + gc0;
	v_add_f32_e32 v205, v130, v131
	v_mov_b32_e32 v130, v139
	v_mov_b32_e32 v131, v140
	v_mov_b32_e32 v139, v141
	v_pk_add_f32 v[130:131], v[130:131], v[138:139]
	ds_bpermute_b32 v206, v175, v205
	v_add_f32_e32 v130, v130, v131
	v_mov_b32_e32 v131, v130
	s_nop 1
	v_permlane16_swap_b32_e32 v131, v130
	s_waitcnt lgkmcnt(0)
	v_add_f32_e32 v203, v130, v131
	v_mov_b32_e32 v130, v143
	v_mov_b32_e32 v131, v144
	v_mov_b32_e32 v143, v145
	v_pk_add_f32 v[130:131], v[130:131], v[142:143]
	ds_bpermute_b32 v204, v175, v203
	v_add_f32_e32 v130, v130, v131
	v_mov_b32_e32 v131, v130
	s_nop 1
	v_permlane16_swap_b32_e32 v131, v130
	s_waitcnt lgkmcnt(0)
	v_add_f32_e32 v182, v130, v131
	v_mov_b32_e32 v130, v147
	v_mov_b32_e32 v131, v148
	v_mov_b32_e32 v147, v149
	v_pk_add_f32 v[130:131], v[130:131], v[146:147]
	ds_bpermute_b32 v202, v175, v182
	v_add_f32_e32 v130, v130, v131
	v_mov_b32_e32 v131, v130
	s_nop 1
	v_permlane16_swap_b32_e32 v131, v130
	s_waitcnt lgkmcnt(0)
	v_add_f32_e32 v244, v130, v131
	v_mov_b32_e32 v130, v151
	v_mov_b32_e32 v131, v152
	v_mov_b32_e32 v151, v153
	v_pk_add_f32 v[130:131], v[130:131], v[150:151]
	ds_bpermute_b32 v245, v175, v244
	v_add_f32_e32 v130, v130, v131
	v_mov_b32_e32 v131, v130
	s_nop 1
	v_permlane16_swap_b32_e32 v131, v130
	s_waitcnt lgkmcnt(0)
	v_add_f32_e32 v242, v130, v131
	v_mov_b32_e32 v130, v171
	v_mov_b32_e32 v131, v172
	v_mov_b32_e32 v171, v173
	v_pk_add_f32 v[130:131], v[130:131], v[170:171]
	v_lshl_or_b32 v170, s12, 7, v238
	v_add_f32_e32 v130, v130, v131
	v_mov_b32_e32 v131, v130
	s_nop 1
	v_permlane16_swap_b32_e32 v131, v130
	v_ashrrev_i32_e32 v171, 31, v170
	v_lshlrev_b64 v[150:151], 2, v[170:171]
	v_lshl_add_u64 v[172:173], s[70:71], 0, v[150:151]
	ds_bpermute_b32 v243, v175, v242
	s_waitcnt lgkmcnt(0)
	v_add_f32_e32 v240, v130, v131
	v_mov_b32_e32 v130, v179
	v_mov_b32_e32 v131, v180
	v_mov_b32_e32 v179, v181
	v_pk_add_f32 v[130:131], v[130:131], v[178:179]
	ds_bpermute_b32 v241, v175, v240
	v_add_f32_e32 v130, v130, v131
	v_mov_b32_e32 v131, v130
	s_nop 1
	v_permlane16_swap_b32_e32 v131, v130
	v_lshlrev_b64 v[178:179], 1, v[170:171]
	s_waitcnt lgkmcnt(0)
	v_add_f32_e32 v169, v130, v131
	v_pk_mul_f32 v[196:197], v[98:99], v[168:169] op_sel_hi:[1,0]
	v_or_b32_e32 v98, s0, v160
	v_mad_i64_i32 v[200:201], s[0:1], v98, s37, 0
	v_pk_mul_f32 v[198:199], v[102:103], v[168:169] op_sel_hi:[1,0]
	v_mov_b64_e32 v[102:103], v[172:173]
	s_movk_i32 s0, 0x5000
	ds_bpermute_b32 v183, v175, v169
	v_add_co_u32_e32 v98, vcc, s0, v102
	s_mov_b32 s0, 0xb000
	s_nop 0
	v_addc_co_u32_e32 v99, vcc, 0, v103, vcc
	global_load_dwordx4 v[142:145], v[98:99], off offset:2048
	v_add_co_u32_e32 v98, vcc, s0, v102
	s_movk_i32 s0, 0x2000
	s_nop 0
	v_addc_co_u32_e32 v99, vcc, 0, v103, vcc
	v_pk_mul_f32 v[194:195], v[104:105], v[168:169] op_sel_hi:[1,0]
	v_add_co_u32_e32 v104, vcc, s0, v102
	v_lshl_add_u64 v[174:175], s[72:73], 0, v[150:151]
	global_load_dwordx4 v[138:141], v[102:103], off
	v_addc_co_u32_e32 v105, vcc, 0, v103, vcc
	s_mov_b32 s0, 0x8000
	global_load_dwordx4 v[146:149], v[174:175], off
	global_load_dwordx4 v[130:133], v[104:105], off offset:3072
	v_add_co_u32_e32 v104, vcc, s0, v102
	v_lshl_add_u64 v[150:151], s[76:77], 0, v[150:151]
	v_pk_mul_f32 v[192:193], v[100:101], v[168:169] op_sel_hi:[1,0]
	global_load_dwordx4 v[98:101], v[98:99], off
	v_addc_co_u32_e32 v105, vcc, 0, v103, vcc
	global_load_dwordx4 v[150:153], v[150:151], off
	s_mov_b32 s0, 0xd000
	global_load_dwordx4 v[134:137], v[104:105], off offset:1024
	v_add_co_u32_e32 v102, vcc, s0, v102
	v_readlane_b32 s0, v253, 44
	s_nop 0
	v_addc_co_u32_e32 v103, vcc, 0, v103, vcc
	global_load_dwordx4 v[102:105], v[102:103], off offset:3072
	v_readlane_b32 s1, v253, 45
	v_mov_b32_dpp v189, v196 row_shr:1 row_mask:0xf bank_mask:0xf
	s_nop 0
	v_lshl_add_u64 v[180:181], v[200:201], 1, s[0:1]
	v_lshl_add_u64 v[184:185], v[180:181], 0, v[178:179]
	v_mov_b32_e32 v181, v1
	v_mov_b32_e32 v180, v177
	s_nop 0
	v_mov_b32_dpp v181, v181 row_ror:2 row_mask:0xf bank_mask:0xf
	v_mov_b32_e32 v188, v181
	v_mov_b32_dpp v180, v198 row_shr:1 row_mask:0xf bank_mask:0xf
	v_mov_b32_e32 v190, v181
	v_mov_b32_dpp v188, v198 row_shr:2 row_mask:0xf bank_mask:0xf
	v_mov_b32_e32 v191, v181
	v_mov_b32_dpp v190, v196 row_shr:2 row_mask:0xf bank_mask:0xf
	v_mov_b32_e32 v207, v181
	v_mov_b32_dpp v191, v197 row_shr:2 row_mask:0xf bank_mask:0xf
	s_waitcnt vmcnt(0) lgkmcnt(0)
; __device__ __forceinline__ unsigned cvt_pk_bf16(float lo, float hi) { unsigned r; asm volatile("v_cvt_pk_bf16_f32 %0, %1, %2" : "=v"(r) : "v"(lo), "v"(hi)); return r; }
;     __device__ __forceinline__ void operator()(f32x4 (&acc)[2][2][4][2], const Unit& u, int wr, int wc, int fr, int fq) const {
;     ...
;                     for (int j = 0; j < 4; ++j) {
;                         const float vg = acc[ai][0][m][n][j], vv = acc[ai][1][m][n][j];
;                         const float pg = (m > 0) ? acc[ai][0][m - 1][n][j] : 0.f, pv = (m > 0) ? acc[ai][1][m - 1][n][j] : 0.f;
;                         const float g1 = dppf(dppf(0.f, pg, 2), vg, 0), g2 = dppf(dppf(0.f, pg, 3), vg, 1);
;                         const float v1 = dppf(dppf(0.f, pv, 2), vv, 0), v2 = dppf(dppf(0.f, pv, 3), vv, 1);
;                         const float cgate = bg[j] + wg0[j] * g2 + wg1[j] * g1 + wg2[j] * vg;
;                         const float cval = bv[j] + wv0[j] * v2 + wv1[j] * v1 + wv2[j] * vv;
;                         og[j] = cgate * __builtin_amdgcn_rcpf(1.0f + __builtin_amdgcn_exp2f(-1.4426950408889634f * cgate)) * cval; }
;                     const unsigned long long w = (unsigned long long)cvt_pk_bf16(og[0], og[1]) | ((unsigned long long)cvt_pk_bf16(og[2], og[3]) << 32);
;                     if (m == 0) {
;                         if (fr >= 2) *(unsigned long long*)gp = w;
;                         else { *(unsigned long long*)sb = (unsigned long long)cvt_pk_bf16(acc[ai][0][0][n][0], acc[ai][0][0][n][1]) | ((unsigned long long)cvt_pk_bf16(acc[ai][0][0][n][2], acc[ai][0][0][n][3]) << 32);
;                                *(unsigned long long*)(sb + FFc) = (unsigned long long)cvt_pk_bf16(acc[ai][1][0][n][0], acc[ai][1][0][n][1]) | ((unsigned long long)cvt_pk_bf16(acc[ai][1][0][n][2], acc[ai][1][0][n][3]) << 32); }
	v_fma_f32 v188, v138, v188, v146
	v_fmac_f32_e32 v188, v142, v180
	v_mov_b32_dpp v207, v192 row_shr:2 row_mask:0xf bank_mask:0xf
	v_fmac_f32_e32 v188, v198, v98
	v_fma_f32 v180, v130, v190, v150
	v_mov_b32_e32 v190, v177
	v_fmac_f32_e32 v180, v134, v189
	v_mul_f32_e32 v189, 0xbfb8aa3b, v188
	v_exp_f32_e32 v189, v189
	v_mov_b32_dpp v190, v197 row_shr:1 row_mask:0xf bank_mask:0xf
	v_add_f32_e32 v189, 1.0, v189
	v_rcp_f32_e32 v189, v189
	v_fmac_f32_e32 v180, v196, v102
	v_mul_f32_e32 v188, v188, v189
	v_mov_b32_e32 v189, v181
	v_mul_f32_e32 v180, v180, v188
	v_mov_b32_e32 v188, v177
	v_mov_b32_dpp v189, v199 row_shr:2 row_mask:0xf bank_mask:0xf
	v_fma_f32 v189, v139, v189, v147
	v_mov_b32_dpp v188, v199 row_shr:1 row_mask:0xf bank_mask:0xf
	v_fmac_f32_e32 v189, v143, v188
	v_fmac_f32_e32 v189, v199, v99
	v_fma_f32 v188, v131, v191, v151
	v_fmac_f32_e32 v188, v135, v190
	v_mul_f32_e32 v190, 0xbfb8aa3b, v189
	v_exp_f32_e32 v190, v190
	v_fmac_f32_e32 v188, v197, v103
	v_mov_b32_e32 v191, v177
	v_add_f32_e32 v190, 1.0, v190
	v_rcp_f32_e32 v190, v190
	v_mov_b32_dpp v191, v192 row_shr:1 row_mask:0xf bank_mask:0xf
	v_mul_f32_e32 v189, v189, v190
	v_mov_b32_e32 v190, v181
	v_mul_f32_e32 v188, v188, v189
	v_mov_b32_e32 v189, v177
	v_mov_b32_dpp v190, v194 row_shr:2 row_mask:0xf bank_mask:0xf
	v_fma_f32 v190, v140, v190, v148
	v_mov_b32_dpp v189, v194 row_shr:1 row_mask:0xf bank_mask:0xf
	v_fmac_f32_e32 v190, v144, v189
	v_fmac_f32_e32 v190, v194, v100
	v_fma_f32 v189, v132, v207, v152
	v_fmac_f32_e32 v189, v136, v191
	v_mul_f32_e32 v191, 0xbfb8aa3b, v190
	v_exp_f32_e32 v191, v191
	v_fmac_f32_e32 v189, v192, v104
	v_cvt_pk_bf16_f32 v180, v180, v188
	v_add_f32_e32 v191, 1.0, v191
	v_rcp_f32_e32 v191, v191
	s_nop 0
	v_mul_f32_e32 v190, v190, v191
	v_mov_b32_e32 v191, v181
	v_mul_f32_e32 v189, v189, v190
	v_mov_b32_e32 v190, v177
	v_mov_b32_dpp v191, v195 row_shr:2 row_mask:0xf bank_mask:0xf
	v_fma_f32 v191, v141, v191, v149
	v_mov_b32_dpp v190, v195 row_shr:1 row_mask:0xf bank_mask:0xf
	v_mov_b32_dpp v181, v193 row_shr:2 row_mask:0xf bank_mask:0xf
	v_fmac_f32_e32 v191, v145, v190
	v_mov_b32_dpp v177, v193 row_shr:1 row_mask:0xf bank_mask:0xf
	v_fmac_f32_e32 v191, v195, v101
	v_fma_f32 v181, v133, v181, v153
	v_fmac_f32_e32 v181, v137, v177
	v_mul_f32_e32 v177, 0xbfb8aa3b, v191
	v_exp_f32_e32 v177, v177
	v_fmac_f32_e32 v181, v193, v105
	v_add_f32_e32 v177, 1.0, v177
	v_rcp_f32_e32 v177, v177
	s_nop 0
	v_mul_f32_e32 v177, v191, v177
	v_mul_f32_e32 v177, v181, v177
	v_cvt_pk_bf16_f32 v181, v189, v177
	s_and_saveexec_b64 s[0:1], s[6:7]
	s_xor_b64 s[0:1], exec, s[0:1]
	s_mov_b64 s[50:51], 0x16000
	s_mov_b64 s[52:53], 0x58000
	s_mov_b64 s[54:55], 0xb000
	s_cbranch_execz .LBB0_1352
	v_cvt_pk_bf16_f32 v180, v198, v199
	v_cvt_pk_bf16_f32 v181, v194, v195
	v_add_co_u32_e32 v188, vcc, 0x1000, v184
	global_store_dwordx2 v[184:185], v[180:181], off
	v_cvt_pk_bf16_f32 v180, v196, v197
	v_cvt_pk_bf16_f32 v181, v192, v193
	s_nop 0
	v_addc_co_u32_e32 v189, vcc, 0, v185, vcc
	global_store_dwordx2 v[188:189], v[180:181], off offset:1536

; __device__ __forceinline__ void load_row_scales(const float* ssp, int row0, int fq, float (&rs)[2][4]) {
;     ...
;             rs[ai][m] = 1.0f / sqrtf(t * (1.0f / 1024.0f) + 1e-6f); }
;     __device__ __forceinline__ void operator()(f32x4 (&acc)[2][2][4][2], const Unit& u, int wr, int wc, int fr, int fq) const {
;     ...
;                 for (int m = 0; m < 4; ++m) {
;                     float og[4];
; #pragma unroll
;                     for (int j = 0; j < 4; ++j) {
;                         const float vg = acc[ai][0][m][n][j], vv = acc[ai][1][m][n][j];
;                         const float pg = (m > 0) ? acc[ai][0][m - 1][n][j] : 0.f, pv = (m > 0) ? acc[ai][1][m - 1][n][j] : 0.f;
;                         const float g1 = dppf(dppf(0.f, pg, 2), vg, 0), g2 = dppf(dppf(0.f, pg, 3), vg, 1);
;                         const float v1 = dppf(dppf(0.f, pv, 2), vv, 0), v2 = dppf(dppf(0.f, pv, 3), vv, 1);
;                         const float cgate = bg[j] + wg0[j] * g2 + wg1[j] * g1 + wg2[j] * vg;
;                         const float cval = bv[j] + wv0[j] * v2 + wv1[j] * v1 + wv2[j] * vv;
;                         og[j] = cgate * __builtin_amdgcn_rcpf(1.0f + __builtin_amdgcn_exp2f(-1.4426950408889634f * cgate)) * cval; }
.LBB0_1354:
	s_or_b64 exec, exec, s[0:1]
	v_add_f32_e32 v178, v205, v206
	v_fmamk_f32 v178, v178, 0x3a800000, v230
	v_mov_b32_e32 v191, v1
	s_nop 1
	v_mov_b32_dpp v191, v194 row_ror:2 row_mask:0xf bank_mask:0xf
	v_lshl_add_u64 v[226:227], v[176:177], 0, s[50:51]
	v_rsq_f32_e32 v178, v178
	s_nop 0
	v_add_f32_e32 v179, v203, v204
	v_fmamk_f32 v179, v179, 0x3a800000, v230
	v_mov_b32_e32 v203, v101
	v_rsq_f32_e32 v180, v179
	s_nop 0
	v_add_f32_e32 v179, v182, v202
	v_fmamk_f32 v179, v179, 0x3a800000, v230
	v_mov_b32_e32 v202, v105
	v_pk_mul_f32 v[224:225], v[126:127], v[178:179] op_sel_hi:[1,0]
	v_pk_mul_f32 v[222:223], v[118:119], v[178:179] op_sel_hi:[1,0]
	v_pk_mul_f32 v[218:219], v[120:121], v[178:179] op_sel_hi:[1,0]
	v_rsq_f32_e32 v182, v179
	s_nop 0
	v_pk_mul_f32 v[208:209], v[114:115], v[182:183] op_sel_hi:[1,0]
	v_mov_b32_e32 v115, v1
	v_mov_b32_e32 v114, v1
	v_pk_mul_f32 v[206:207], v[116:117], v[182:183] op_sel_hi:[1,0]
	v_mov_b32_e32 v117, v1
	v_mov_b32_dpp v115, v198 row_ror:2 row_mask:0xf bank_mask:0xf
	v_mov_b32_e32 v116, v1
	v_mov_b32_dpp v114, v196 row_ror:2 row_mask:0xf bank_mask:0xf
	v_pk_mul_f32 v[210:211], v[112:113], v[180:181] op_sel_hi:[1,0]
	v_pk_mul_f32 v[214:215], v[110:111], v[180:181] op_sel_hi:[1,0]
	v_mov_b32_dpp v117, v198 row_ror:1 row_mask:0xf bank_mask:0xf
	v_mov_b32_dpp v115, v224 row_shr:2 row_mask:0xf bank_mask:0xf
	v_mov_b32_dpp v116, v196 row_ror:1 row_mask:0xf bank_mask:0xf
	v_mov_b32_dpp v114, v222 row_shr:2 row_mask:0xf bank_mask:0xf
	v_mov_b32_e32 v110, v130
	v_mov_b32_e32 v111, v138
	v_mov_b32_e32 v112, v150
	v_mov_b32_e32 v113, v146
	v_mov_b32_dpp v117, v224 row_shr:1 row_mask:0xf bank_mask:0xf
	v_mov_b32_dpp v116, v222 row_shr:1 row_mask:0xf bank_mask:0xf
	v_pk_fma_f32 v[118:119], v[110:111], v[114:115], v[112:113]
	v_mov_b32_e32 v114, v134
	v_mov_b32_e32 v115, v142
	v_pk_fma_f32 v[118:119], v[114:115], v[116:117], v[118:119]
	v_mov_b32_e32 v120, v222
	v_mov_b32_e32 v121, v224
	v_mov_b32_e32 v116, v102
	v_mov_b32_e32 v117, v98
	v_pk_fma_f32 v[118:119], v[120:121], v[116:117], v[118:119]
	v_readlane_b32 s0, v253, 46
	v_mul_f32_e32 v120, 0xbfb8aa3b, v119
	v_exp_f32_e32 v120, v120
	v_pk_mul_f32 v[216:217], v[122:123], v[180:181] op_sel_hi:[1,0]
	v_readlane_b32 s1, v253, 47
	v_mov_b32_e32 v123, v1
	v_add_f32_e32 v120, 1.0, v120
	v_rcp_f32_e32 v120, v120
	v_mov_b32_e32 v122, v1
	v_pk_mul_f32 v[212:213], v[124:125], v[180:181] op_sel_hi:[1,0]
	v_pk_mul_f32 v[204:205], v[108:109], v[182:183] op_sel_hi:[1,0]
	v_lshl_add_u64 v[108:109], v[200:201], 1, s[0:1]
	v_mul_f32_e32 v119, v119, v120
	v_mov_b32_e32 v125, v1
	v_mov_b32_dpp v123, v199 row_ror:2 row_mask:0xf bank_mask:0xf
	v_mov_b32_e32 v124, v1
	v_mov_b32_dpp v122, v197 row_ror:2 row_mask:0xf bank_mask:0xf
	v_lshl_add_u64 v[108:109], v[170:171], 1, v[108:109]
	v_mul_f32_e32 v171, v118, v119
	v_mov_b32_dpp v125, v199 row_ror:1 row_mask:0xf bank_mask:0xf
	v_mov_b32_dpp v123, v225 row_shr:2 row_mask:0xf bank_mask:0xf
	v_mov_b32_dpp v124, v197 row_ror:1 row_mask:0xf bank_mask:0xf
	v_mov_b32_dpp v122, v223 row_shr:2 row_mask:0xf bank_mask:0xf
	v_mov_b32_e32 v118, v131
	v_mov_b32_e32 v119, v139
	v_mov_b32_e32 v120, v151
	v_mov_b32_e32 v121, v147
	v_mov_b32_dpp v125, v225 row_shr:1 row_mask:0xf bank_mask:0xf
	v_mov_b32_dpp v124, v223 row_shr:1 row_mask:0xf bank_mask:0xf
	v_pk_fma_f32 v[126:127], v[118:119], v[122:123], v[120:121]
	v_mov_b32_e32 v122, v135
	v_mov_b32_e32 v123, v143
	v_pk_mul_f32 v[220:221], v[128:129], v[178:179] op_sel_hi:[1,0]
	v_pk_fma_f32 v[126:127], v[122:123], v[124:125], v[126:127]
	v_mov_b32_e32 v128, v223
	v_mov_b32_e32 v129, v225
	v_mov_b32_e32 v124, v103
	v_mov_b32_e32 v125, v99
	v_pk_fma_f32 v[126:127], v[128:129], v[124:125], v[126:127]
	v_mov_b32_e32 v190, v1
	v_mul_f32_e32 v128, 0xbfb8aa3b, v127
	v_exp_f32_e32 v128, v128
	v_mov_b32_e32 v189, v1
	v_mov_b32_e32 v188, v1
	v_mov_b32_dpp v190, v192 row_ror:2 row_mask:0xf bank_mask:0xf
	v_add_f32_e32 v128, 1.0, v128
	v_rcp_f32_e32 v128, v128
	v_mov_b32_dpp v189, v194 row_ror:1 row_mask:0xf bank_mask:0xf
	v_mov_b32_dpp v191, v220 row_shr:2 row_mask:0xf bank_mask:0xf
	v_mov_b32_dpp v188, v192 row_ror:1 row_mask:0xf bank_mask:0xf
	v_mul_f32_e32 v127, v127, v128
	v_mul_f32_e32 v179, v126, v127
	v_mov_b32_dpp v190, v218 row_shr:2 row_mask:0xf bank_mask:0xf
	v_mov_b32_e32 v126, v132
	v_mov_b32_e32 v127, v140
	v_mov_b32_e32 v128, v152
	v_mov_b32_e32 v129, v148
	v_mov_b32_dpp v189, v220 row_shr:1 row_mask:0xf bank_mask:0xf
	v_mov_b32_dpp v188, v218 row_shr:1 row_mask:0xf bank_mask:0xf
	v_pk_fma_f32 v[190:191], v[126:127], v[190:191], v[128:129]
	v_mov_b32_e32 v196, v136
	v_mov_b32_e32 v197, v144
	v_pk_fma_f32 v[188:189], v[196:197], v[188:189], v[190:191]
	v_mov_b32_e32 v190, v218
	v_mov_b32_e32 v191, v220
	v_mov_b32_e32 v198, v104
	v_mov_b32_e32 v199, v100
	v_pk_fma_f32 v[188:189], v[190:191], v[198:199], v[188:189]
	v_mov_b32_e32 v191, v1
	v_mul_f32_e32 v181, 0xbfb8aa3b, v189
	v_exp_f32_e32 v181, v181
	v_mov_b32_e32 v190, v1
	v_mov_b32_dpp v191, v195 row_ror:2 row_mask:0xf bank_mask:0xf
	v_mov_b32_e32 v192, v133
	v_add_f32_e32 v181, 1.0, v181
	v_rcp_f32_e32 v181, v181
	v_mov_b32_dpp v190, v193 row_ror:2 row_mask:0xf bank_mask:0xf
	v_mov_b32_dpp v191, v221 row_shr:2 row_mask:0xf bank_mask:0xf
	v_mov_b32_e32 v194, v153
	v_mul_f32_e32 v181, v189, v181
	v_mul_f32_e32 v181, v188, v181
	v_mov_b32_e32 v189, v1
	v_mov_b32_e32 v188, v1
	v_mov_b32_dpp v190, v219 row_shr:2 row_mask:0xf bank_mask:0xf
	v_mov_b32_dpp v189, v195 row_ror:1 row_mask:0xf bank_mask:0xf
	v_mov_b32_dpp v188, v193 row_ror:1 row_mask:0xf bank_mask:0xf
	v_mov_b32_e32 v193, v141
	v_mov_b32_e32 v195, v149
;     __device__ __forceinline__ void operator()(f32x4 (&acc)[2][2][4][2], const Unit& u, int wr, int wc, int fr, int fq) const {
;     ...
;                     for (int j = 0; j < 4; ++j) {
;                         const float vg = acc[ai][0][m][n][j], vv = acc[ai][1][m][n][j];
;                         const float pg = (m > 0) ? acc[ai][0][m - 1][n][j] : 0.f, pv = (m > 0) ? acc[ai][1][m - 1][n][j] : 0.f;
;                         const float g1 = dppf(dppf(0.f, pg, 2), vg, 0), g2 = dppf(dppf(0.f, pg, 3), vg, 1);
;                         const float v1 = dppf(dppf(0.f, pv, 2), vv, 0), v2 = dppf(dppf(0.f, pv, 3), vv, 1);
;                         const float cgate = bg[j] + wg0[j] * g2 + wg1[j] * g1 + wg2[j] * vg;
;                         const float cval = bv[j] + wv0[j] * v2 + wv1[j] * v1 + wv2[j] * vv;
;                         og[j] = cgate * __builtin_amdgcn_rcpf(1.0f + __builtin_amdgcn_exp2f(-1.4426950408889634f * cgate)) * cval; }
;                     const unsigned long long w = (unsigned long long)cvt_pk_bf16(og[0], og[1]) | ((unsigned long long)cvt_pk_bf16(og[2], og[3]) << 32);
;                     if (m == 0) {
;                         if (fr >= 2) *(unsigned long long*)gp = w;
;                         else { *(unsigned long long*)sb = (unsigned long long)cvt_pk_bf16(acc[ai][0][0][n][0], acc[ai][0][0][n][1]) | ((unsigned long long)cvt_pk_bf16(acc[ai][0][0][n][2], acc[ai][0][0][n][3]) << 32);
;                                *(unsigned long long*)(sb + FFc) = (unsigned long long)cvt_pk_bf16(acc[ai][1][0][n][0], acc[ai][1][0][n][1]) | ((unsigned long long)cvt_pk_bf16(acc[ai][1][0][n][2], acc[ai][1][0][n][3]) << 32); }
;                     } else *(unsigned long long*)gp = w;
;                     if (m == 3 && fr >= 14) {
;                         *(unsigned long long*)hb = (unsigned long long)cvt_pk_bf16(acc[ai][0][3][n][0], acc[ai][0][3][n][1]) | ((unsigned long long)cvt_pk_bf16(acc[ai][0][3][n][2], acc[ai][0][3][n][3]) << 32);
;                         *(unsigned long long*)(hb + FFc) = (unsigned long long)cvt_pk_bf16(acc[ai][1][3][n][0], acc[ai][1][3][n][1]) | ((unsigned long long)cvt_pk_bf16(acc[ai][1][3][n][2], acc[ai][1][3][n][3]) << 32); }
;                     gp += (size_t)16 * FFc; asm volatile("" : "+v"(gp) :: "memory"); }
	v_mov_b32_dpp v189, v221 row_shr:1 row_mask:0xf bank_mask:0xf
	v_mov_b32_dpp v188, v219 row_shr:1 row_mask:0xf bank_mask:0xf
	v_pk_fma_f32 v[190:191], v[192:193], v[190:191], v[194:195]
	v_mov_b32_e32 v200, v137
	v_mov_b32_e32 v201, v145
	v_pk_fma_f32 v[188:189], v[200:201], v[188:189], v[190:191]
	v_mov_b32_e32 v190, v219
	v_mov_b32_e32 v191, v221
	v_pk_fma_f32 v[188:189], v[190:191], v[202:203], v[188:189]
	v_mov_b32_e32 v191, v1
	v_mul_f32_e32 v190, 0xbfb8aa3b, v189
	v_exp_f32_e32 v190, v190
	v_mov_b32_dpp v191, v224 row_ror:1 row_mask:0xf bank_mask:0xf
	v_pk_mul_f32 v[106:107], v[106:107], v[182:183] op_sel_hi:[1,0]
	v_add_f32_e32 v190, 1.0, v190
	v_rcp_f32_e32 v190, v190
	v_mov_b32_dpp v191, v216 row_shr:1 row_mask:0xf bank_mask:0xf
	v_mul_f32_e32 v189, v189, v190
	v_mul_f32_e32 v189, v188, v189
	v_cvt_pk_bf16_f32 v188, v171, v179
	v_cvt_pk_bf16_f32 v189, v181, v189
	global_store_dwordx2 v[226:227], v[188:189], off
	v_lshl_add_u64 v[188:189], v[226:227], 0, s[50:51]
	v_mov_b32_e32 v227, v1
	v_mov_b32_e32 v226, v1
	v_mov_b32_e32 v190, v1
	v_mov_b32_dpp v227, v224 row_ror:2 row_mask:0xf bank_mask:0xf
	v_mov_b32_dpp v226, v222 row_ror:2 row_mask:0xf bank_mask:0xf
	v_mov_b32_dpp v190, v222 row_ror:1 row_mask:0xf bank_mask:0xf
	v_mov_b32_dpp v227, v216 row_shr:2 row_mask:0xf bank_mask:0xf
	v_mov_b32_dpp v226, v214 row_shr:2 row_mask:0xf bank_mask:0xf
	v_mov_b32_dpp v190, v214 row_shr:1 row_mask:0xf bank_mask:0xf
	v_pk_fma_f32 v[226:227], v[110:111], v[226:227], v[112:113]
	s_nop 0
	v_pk_fma_f32 v[190:191], v[114:115], v[190:191], v[226:227]
	v_mov_b32_e32 v226, v214
	v_mov_b32_e32 v227, v216
	v_pk_fma_f32 v[190:191], v[226:227], v[116:117], v[190:191]
	v_mov_b32_e32 v227, v1
	v_mul_f32_e32 v171, 0xbfb8aa3b, v191
	v_exp_f32_e32 v171, v171
	v_mov_b32_e32 v226, v1
	v_mov_b32_dpp v227, v225 row_ror:2 row_mask:0xf bank_mask:0xf
	v_add_f32_e32 v171, 1.0, v171
	v_rcp_f32_e32 v171, v171
	v_mov_b32_dpp v226, v223 row_ror:2 row_mask:0xf bank_mask:0xf
	v_mov_b32_dpp v227, v217 row_shr:2 row_mask:0xf bank_mask:0xf
	v_mul_f32_e32 v171, v191, v171
	v_mul_f32_e32 v171, v190, v171
	v_mov_b32_e32 v191, v1
	v_mov_b32_e32 v190, v1
	v_mov_b32_dpp v226, v215 row_shr:2 row_mask:0xf bank_mask:0xf
	v_mov_b32_dpp v191, v225 row_ror:1 row_mask:0xf bank_mask:0xf
	v_mov_b32_dpp v190, v223 row_ror:1 row_mask:0xf bank_mask:0xf
	v_pk_fma_f32 v[222:223], v[118:119], v[226:227], v[120:121]
	v_mov_b32_dpp v191, v217 row_shr:1 row_mask:0xf bank_mask:0xf
	v_mov_b32_dpp v190, v215 row_shr:1 row_mask:0xf bank_mask:0xf
	v_pk_fma_f32 v[190:191], v[122:123], v[190:191], v[222:223]
	v_mov_b32_e32 v222, v215
	v_mov_b32_e32 v223, v217
	v_pk_fma_f32 v[190:191], v[222:223], v[124:125], v[190:191]
	v_mov_b32_e32 v223, v1
	v_mul_f32_e32 v179, 0xbfb8aa3b, v191
	v_exp_f32_e32 v179, v179
	v_mov_b32_e32 v222, v1
	v_mov_b32_dpp v223, v220 row_ror:2 row_mask:0xf bank_mask:0xf
	v_add_f32_e32 v179, 1.0, v179
	v_rcp_f32_e32 v179, v179
	v_mov_b32_dpp v222, v218 row_ror:2 row_mask:0xf bank_mask:0xf
	v_mov_b32_dpp v223, v212 row_shr:2 row_mask:0xf bank_mask:0xf
	v_mul_f32_e32 v179, v191, v179
	v_mul_f32_e32 v179, v190, v179
	v_mov_b32_e32 v191, v1
	v_mov_b32_e32 v190, v1
	v_mov_b32_dpp v222, v210 row_shr:2 row_mask:0xf bank_mask:0xf
	v_mov_b32_dpp v191, v220 row_ror:1 row_mask:0xf bank_mask:0xf
	v_mov_b32_dpp v190, v218 row_ror:1 row_mask:0xf bank_mask:0xf
	v_pk_fma_f32 v[222:223], v[126:127], v[222:223], v[128:129]
	v_mov_b32_dpp v191, v212 row_shr:1 row_mask:0xf bank_mask:0xf
	v_mov_b32_dpp v190, v210 row_shr:1 row_mask:0xf bank_mask:0xf
	v_pk_fma_f32 v[190:191], v[196:197], v[190:191], v[222:223]
	v_mov_b32_e32 v222, v210
	v_mov_b32_e32 v223, v212
	v_pk_fma_f32 v[190:191], v[222:223], v[198:199], v[190:191]
	v_mov_b32_e32 v223, v1
	v_mul_f32_e32 v181, 0xbfb8aa3b, v191
	v_exp_f32_e32 v181, v181
	v_mov_b32_e32 v222, v1
	v_mov_b32_dpp v223, v221 row_ror:2 row_mask:0xf bank_mask:0xf
	v_add_f32_e32 v181, 1.0, v181
	v_rcp_f32_e32 v181, v181
	v_mov_b32_dpp v222, v219 row_ror:2 row_mask:0xf bank_mask:0xf
	v_mov_b32_dpp v223, v213 row_shr:2 row_mask:0xf bank_mask:0xf
	v_mul_f32_e32 v181, v191, v181
	v_mul_f32_e32 v181, v190, v181
	v_mov_b32_e32 v191, v1
	v_mov_b32_e32 v190, v1
	v_mov_b32_dpp v222, v211 row_shr:2 row_mask:0xf bank_mask:0xf
	v_mov_b32_dpp v191, v221 row_ror:1 row_mask:0xf bank_mask:0xf
	v_mov_b32_dpp v190, v219 row_ror:1 row_mask:0xf bank_mask:0xf
	v_pk_fma_f32 v[218:219], v[192:193], v[222:223], v[194:195]
	v_mov_b32_dpp v191, v213 row_shr:1 row_mask:0xf bank_mask:0xf
	v_mov_b32_dpp v190, v211 row_shr:1 row_mask:0xf bank_mask:0xf
	v_pk_fma_f32 v[190:191], v[200:201], v[190:191], v[218:219]
	v_mov_b32_e32 v218, v211
	v_mov_b32_e32 v219, v213
	v_pk_fma_f32 v[190:191], v[218:219], v[202:203], v[190:191]
	s_nop 0
	v_mul_f32_e32 v218, 0xbfb8aa3b, v191
	v_exp_f32_e32 v218, v218
	s_nop 0
	v_add_f32_e32 v218, 1.0, v218
	v_rcp_f32_e32 v218, v218
	s_nop 0
	v_mul_f32_e32 v191, v191, v218
	v_mul_f32_e32 v191, v190, v191
	v_cvt_pk_bf16_f32 v190, v171, v179
	v_cvt_pk_bf16_f32 v191, v181, v191
	global_store_dwordx2 v[188:189], v[190:191], off
	v_mov_b32_e32 v191, v1
	v_mov_b32_e32 v190, v1
	v_lshl_add_u64 v[218:219], v[188:189], 0, s[50:51]
	v_mov_b32_e32 v189, v1
	v_mov_b32_dpp v191, v216 row_ror:2 row_mask:0xf bank_mask:0xf
	v_mov_b32_e32 v188, v1
	v_mov_b32_dpp v190, v214 row_ror:2 row_mask:0xf bank_mask:0xf
	v_mov_b32_dpp v189, v216 row_ror:1 row_mask:0xf bank_mask:0xf
	v_mov_b32_dpp v191, v208 row_shr:2 row_mask:0xf bank_mask:0xf
	v_mov_b32_dpp v188, v214 row_ror:1 row_mask:0xf bank_mask:0xf
	v_mov_b32_dpp v190, v106 row_shr:2 row_mask:0xf bank_mask:0xf
	v_mov_b32_dpp v189, v208 row_shr:1 row_mask:0xf bank_mask:0xf
;     __device__ __forceinline__ void operator()(f32x4 (&acc)[2][2][4][2], const Unit& u, int wr, int wc, int fr, int fq) const {
;     ...
;             for (int ai = 0; ai < 2; ++ai) {
; #pragma unroll
;                 for (int m = 0; m < 4; ++m) {
;                     float og[4];
; #pragma unroll
;                     for (int j = 0; j < 4; ++j) {
;                         const float vg = acc[ai][0][m][n][j], vv = acc[ai][1][m][n][j];
;                         const float pg = (m > 0) ? acc[ai][0][m - 1][n][j] : 0.f, pv = (m > 0) ? acc[ai][1][m - 1][n][j] : 0.f;
;                         const float g1 = dppf(dppf(0.f, pg, 2), vg, 0), g2 = dppf(dppf(0.f, pg, 3), vg, 1);
;                         const float v1 = dppf(dppf(0.f, pv, 2), vv, 0), v2 = dppf(dppf(0.f, pv, 3), vv, 1);
;                         const float cgate = bg[j] + wg0[j] * g2 + wg1[j] * g1 + wg2[j] * vg;
;                         const float cval = bv[j] + wv0[j] * v2 + wv1[j] * v1 + wv2[j] * vv;
;                         og[j] = cgate * __builtin_amdgcn_rcpf(1.0f + __builtin_amdgcn_exp2f(-1.4426950408889634f * cgate)) * cval; }
;                     const unsigned long long w = (unsigned long long)cvt_pk_bf16(og[0], og[1]) | ((unsigned long long)cvt_pk_bf16(og[2], og[3]) << 32);
;                     if (m == 0) {
;                         if (fr >= 2) *(unsigned long long*)gp = w;
;                         else { *(unsigned long long*)sb = (unsigned long long)cvt_pk_bf16(acc[ai][0][0][n][0], acc[ai][0][0][n][1]) | ((unsigned long long)cvt_pk_bf16(acc[ai][0][0][n][2], acc[ai][0][0][n][3]) << 32);
;                                *(unsigned long long*)(sb + FFc) = (unsigned long long)cvt_pk_bf16(acc[ai][1][0][n][0], acc[ai][1][0][n][1]) | ((unsigned long long)cvt_pk_bf16(acc[ai][1][0][n][2], acc[ai][1][0][n][3]) << 32); }
;                     } else *(unsigned long long*)gp = w;
;                     if (m == 3 && fr >= 14) {
;                         *(unsigned long long*)hb = (unsigned long long)cvt_pk_bf16(acc[ai][0][3][n][0], acc[ai][0][3][n][1]) | ((unsigned long long)cvt_pk_bf16(acc[ai][0][3][n][2], acc[ai][0][3][n][3]) << 32);
;                         *(unsigned long long*)(hb + FFc) = (unsigned long long)cvt_pk_bf16(acc[ai][1][3][n][0], acc[ai][1][3][n][1]) | ((unsigned long long)cvt_pk_bf16(acc[ai][1][3][n][2], acc[ai][1][3][n][3]) << 32); }
	v_mov_b32_dpp v188, v106 row_shr:1 row_mask:0xf bank_mask:0xf
	v_pk_fma_f32 v[190:191], v[110:111], v[190:191], v[112:113]
	s_nop 0
	v_pk_fma_f32 v[188:189], v[114:115], v[188:189], v[190:191]
	v_mov_b32_e32 v190, v106
	v_mov_b32_e32 v191, v208
	v_pk_fma_f32 v[188:189], v[190:191], v[116:117], v[188:189]
	v_mov_b32_e32 v191, v1
	v_mul_f32_e32 v171, 0xbfb8aa3b, v189
	v_exp_f32_e32 v171, v171
	v_mov_b32_e32 v190, v1
	v_mov_b32_dpp v191, v217 row_ror:2 row_mask:0xf bank_mask:0xf
	v_add_f32_e32 v171, 1.0, v171
	v_rcp_f32_e32 v171, v171
	v_mov_b32_dpp v190, v215 row_ror:2 row_mask:0xf bank_mask:0xf
	v_mov_b32_dpp v191, v209 row_shr:2 row_mask:0xf bank_mask:0xf
	v_mul_f32_e32 v171, v189, v171
	v_mul_f32_e32 v171, v188, v171
	v_mov_b32_e32 v189, v1
	v_mov_b32_e32 v188, v1
	v_mov_b32_dpp v190, v107 row_shr:2 row_mask:0xf bank_mask:0xf
	v_mov_b32_dpp v189, v217 row_ror:1 row_mask:0xf bank_mask:0xf
	v_mov_b32_dpp v188, v215 row_ror:1 row_mask:0xf bank_mask:0xf
	v_pk_fma_f32 v[190:191], v[118:119], v[190:191], v[120:121]
	v_mov_b32_dpp v189, v209 row_shr:1 row_mask:0xf bank_mask:0xf
	v_mov_b32_dpp v188, v107 row_shr:1 row_mask:0xf bank_mask:0xf
	v_pk_fma_f32 v[188:189], v[122:123], v[188:189], v[190:191]
	v_mov_b32_e32 v190, v107
	v_mov_b32_e32 v191, v209
	v_pk_fma_f32 v[188:189], v[190:191], v[124:125], v[188:189]
	v_mov_b32_e32 v191, v1
	v_mul_f32_e32 v179, 0xbfb8aa3b, v189
	v_exp_f32_e32 v179, v179
	v_mov_b32_e32 v190, v1
	v_mov_b32_dpp v191, v212 row_ror:2 row_mask:0xf bank_mask:0xf
	v_add_f32_e32 v179, 1.0, v179
	v_rcp_f32_e32 v179, v179
	v_mov_b32_dpp v190, v210 row_ror:2 row_mask:0xf bank_mask:0xf
	v_mov_b32_dpp v191, v206 row_shr:2 row_mask:0xf bank_mask:0xf
	v_mul_f32_e32 v179, v189, v179
	v_mul_f32_e32 v179, v188, v179
	v_mov_b32_e32 v189, v1
	v_mov_b32_e32 v188, v1
	v_mov_b32_dpp v190, v204 row_shr:2 row_mask:0xf bank_mask:0xf
	v_mov_b32_dpp v189, v212 row_ror:1 row_mask:0xf bank_mask:0xf
	v_mov_b32_dpp v188, v210 row_ror:1 row_mask:0xf bank_mask:0xf
	v_pk_fma_f32 v[190:191], v[126:127], v[190:191], v[128:129]
	v_mov_b32_dpp v189, v206 row_shr:1 row_mask:0xf bank_mask:0xf
	v_mov_b32_dpp v188, v204 row_shr:1 row_mask:0xf bank_mask:0xf
	v_pk_fma_f32 v[188:189], v[196:197], v[188:189], v[190:191]
	v_mov_b32_e32 v190, v204
	v_mov_b32_e32 v191, v206
	v_pk_fma_f32 v[188:189], v[190:191], v[198:199], v[188:189]
	v_mov_b32_e32 v191, v1
	v_mul_f32_e32 v181, 0xbfb8aa3b, v189
	v_exp_f32_e32 v181, v181
	v_mov_b32_e32 v190, v1
	v_mov_b32_dpp v191, v213 row_ror:2 row_mask:0xf bank_mask:0xf
	v_add_f32_e32 v181, 1.0, v181
	v_rcp_f32_e32 v181, v181
	v_mov_b32_dpp v190, v211 row_ror:2 row_mask:0xf bank_mask:0xf
	v_mov_b32_dpp v191, v207 row_shr:2 row_mask:0xf bank_mask:0xf
	v_mul_f32_e32 v181, v189, v181
	v_mul_f32_e32 v181, v188, v181
	v_mov_b32_e32 v189, v1
	v_mov_b32_e32 v188, v1
	v_mov_b32_dpp v190, v205 row_shr:2 row_mask:0xf bank_mask:0xf
	v_mov_b32_dpp v189, v213 row_ror:1 row_mask:0xf bank_mask:0xf
	v_mov_b32_dpp v188, v211 row_ror:1 row_mask:0xf bank_mask:0xf
	v_pk_fma_f32 v[190:191], v[192:193], v[190:191], v[194:195]
	v_mov_b32_dpp v189, v207 row_shr:1 row_mask:0xf bank_mask:0xf
	v_mov_b32_dpp v188, v205 row_shr:1 row_mask:0xf bank_mask:0xf
	v_pk_fma_f32 v[188:189], v[200:201], v[188:189], v[190:191]
	v_mov_b32_e32 v190, v205
	v_mov_b32_e32 v191, v207
	v_pk_fma_f32 v[188:189], v[190:191], v[202:203], v[188:189]
	s_nop 0
	v_mul_f32_e32 v190, 0xbfb8aa3b, v189
	v_exp_f32_e32 v190, v190
	s_nop 0
	v_add_f32_e32 v190, 1.0, v190
	v_rcp_f32_e32 v190, v190
	s_nop 0
	v_mul_f32_e32 v189, v189, v190
	v_mul_f32_e32 v189, v188, v189
	v_cvt_pk_bf16_f32 v188, v171, v179
	v_cvt_pk_bf16_f32 v189, v181, v189
	global_store_dwordx2 v[218:219], v[188:189], off
	s_and_saveexec_b64 s[0:1], s[8:9]
	s_mov_b64 s[66:67], s[14:15]
	s_cbranch_execz .LBB0_1356
	v_cvt_pk_bf16_f32 v188, v208, v209
	v_cvt_pk_bf16_f32 v189, v206, v207
	global_store_dwordx2 v[108:109], v[188:189], off
	v_add_co_u32_e32 v188, vcc, 0x1000, v108
	v_cvt_pk_bf16_f32 v106, v106, v107
	v_cvt_pk_bf16_f32 v107, v204, v205
	s_nop 1
	v_addc_co_u32_e32 v189, vcc, 0, v109, vcc
	global_store_dwordx2 v[188:189], v[106:107], off offset:1536
.LBB0_1356:
	s_or_b64 exec, exec, s[0:1]
	v_add_f32_e32 v106, v244, v245
	v_fmamk_f32 v106, v106, 0x3a800000, v230
	v_lshl_add_u64 v[204:205], v[108:109], 0, s[54:55]
	v_rsq_f32_e32 v106, v106
	s_nop 0
	v_pk_mul_f32 v[210:211], v[90:91], v[106:107] op_sel_hi:[1,0]
	v_lshl_add_u64 v[90:91], v[218:219], 0, s[50:51]
	v_pk_mul_f32 v[206:207], v[92:93], v[106:107] op_sel_hi:[1,0]
	v_mov_b32_e32 v92, v1
	v_lshl_add_u64 v[214:215], v[90:91], 0, s[52:53]
	v_mov_b32_e32 v90, v1
	v_mov_b32_dpp v92, v92 row_ror:2 row_mask:0xf bank_mask:0xf
	v_pk_mul_f32 v[212:213], v[94:95], v[106:107] op_sel_hi:[1,0]
	v_mov_b32_dpp v90, v90 row_ror:1 row_mask:0xf bank_mask:0xf
	v_mov_b32_e32 v93, v92
	v_mov_b32_e32 v91, v90
	v_mov_b32_e32 v95, v92
	v_mov_b32_dpp v93, v212 row_shr:2 row_mask:0xf bank_mask:0xf
	v_mov_b32_dpp v91, v212 row_shr:1 row_mask:0xf bank_mask:0xf
	v_fma_f32 v93, v138, v93, v146
	v_fmac_f32_e32 v93, v142, v91
	v_fmac_f32_e32 v93, v212, v98
	v_mul_f32_e32 v91, 0xbfb8aa3b, v93
	v_exp_f32_e32 v91, v91
	v_mov_b32_e32 v94, v90
	v_mov_b32_dpp v95, v210 row_shr:2 row_mask:0xf bank_mask:0xf
	v_fma_f32 v95, v130, v95, v150
	v_add_f32_e32 v91, 1.0, v91
	v_rcp_f32_e32 v91, v91
	v_mov_b32_dpp v94, v210 row_shr:1 row_mask:0xf bank_mask:0xf
	v_fmac_f32_e32 v95, v134, v94
	v_mov_b32_e32 v94, v92
	v_mul_f32_e32 v91, v93, v91
	v_mov_b32_e32 v93, v90
	v_mov_b32_dpp v94, v213 row_shr:2 row_mask:0xf bank_mask:0xf
	v_fma_f32 v94, v139, v94, v147
	v_mov_b32_dpp v93, v213 row_shr:1 row_mask:0xf bank_mask:0xf
;     __device__ __forceinline__ void operator()(f32x4 (&acc)[2][2][4][2], const Unit& u, int wr, int wc, int fr, int fq) const {
;     ...
;                 for (int m = 0; m < 4; ++m) {
;                     float og[4];
; #pragma unroll
;                     for (int j = 0; j < 4; ++j) {
;                         const float vg = acc[ai][0][m][n][j], vv = acc[ai][1][m][n][j];
;                         const float pg = (m > 0) ? acc[ai][0][m - 1][n][j] : 0.f, pv = (m > 0) ? acc[ai][1][m - 1][n][j] : 0.f;
;                         const float g1 = dppf(dppf(0.f, pg, 2), vg, 0), g2 = dppf(dppf(0.f, pg, 3), vg, 1);
;                         const float v1 = dppf(dppf(0.f, pv, 2), vv, 0), v2 = dppf(dppf(0.f, pv, 3), vv, 1);
;                         const float cgate = bg[j] + wg0[j] * g2 + wg1[j] * g1 + wg2[j] * vg;
;                         const float cval = bv[j] + wv0[j] * v2 + wv1[j] * v1 + wv2[j] * vv;
;                         og[j] = cgate * __builtin_amdgcn_rcpf(1.0f + __builtin_amdgcn_exp2f(-1.4426950408889634f * cgate)) * cval; }
;                     const unsigned long long w = (unsigned long long)cvt_pk_bf16(og[0], og[1]) | ((unsigned long long)cvt_pk_bf16(og[2], og[3]) << 32);
;                     if (m == 0) {
;                         if (fr >= 2) *(unsigned long long*)gp = w;
;                         else { *(unsigned long long*)sb = (unsigned long long)cvt_pk_bf16(acc[ai][0][0][n][0], acc[ai][0][0][n][1]) | ((unsigned long long)cvt_pk_bf16(acc[ai][0][0][n][2], acc[ai][0][0][n][3]) << 32);
;                                *(unsigned long long*)(sb + FFc) = (unsigned long long)cvt_pk_bf16(acc[ai][1][0][n][0], acc[ai][1][0][n][1]) | ((unsigned long long)cvt_pk_bf16(acc[ai][1][0][n][2], acc[ai][1][0][n][3]) << 32); }
;                     } else *(unsigned long long*)gp = w;
;                     if (m == 3 && fr >= 14) {
;                         *(unsigned long long*)hb = (unsigned long long)cvt_pk_bf16(acc[ai][0][3][n][0], acc[ai][0][3][n][1]) | ((unsigned long long)cvt_pk_bf16(acc[ai][0][3][n][2], acc[ai][0][3][n][3]) << 32);
;                         *(unsigned long long*)(hb + FFc) = (unsigned long long)cvt_pk_bf16(acc[ai][1][3][n][0], acc[ai][1][3][n][1]) | ((unsigned long long)cvt_pk_bf16(acc[ai][1][3][n][2], acc[ai][1][3][n][3]) << 32); }
;                     gp += (size_t)16 * FFc; asm volatile("" : "+v"(gp) :: "memory"); }
	v_fmac_f32_e32 v94, v143, v93
	v_fmac_f32_e32 v94, v213, v99
	v_mul_f32_e32 v93, 0xbfb8aa3b, v94
	v_exp_f32_e32 v93, v93
	v_pk_mul_f32 v[208:209], v[96:97], v[106:107] op_sel_hi:[1,0]
	v_fmac_f32_e32 v95, v210, v102
	v_mov_b32_e32 v107, v92
	v_add_f32_e32 v93, 1.0, v93
	v_rcp_f32_e32 v93, v93
	v_mul_f32_e32 v91, v95, v91
	v_mov_b32_e32 v95, v90
	v_mov_b32_dpp v107, v211 row_shr:2 row_mask:0xf bank_mask:0xf
	v_fma_f32 v107, v131, v107, v151
	v_mov_b32_dpp v95, v211 row_shr:1 row_mask:0xf bank_mask:0xf
	v_fmac_f32_e32 v107, v135, v95
	v_mov_b32_e32 v95, v92
	v_mul_f32_e32 v93, v94, v93
	v_mov_b32_e32 v94, v90
	v_mov_b32_dpp v95, v208 row_shr:2 row_mask:0xf bank_mask:0xf
	v_fma_f32 v95, v140, v95, v148
	v_mov_b32_dpp v94, v208 row_shr:1 row_mask:0xf bank_mask:0xf
	v_fmac_f32_e32 v95, v144, v94
	v_fmac_f32_e32 v95, v208, v100
	v_mul_f32_e32 v94, 0xbfb8aa3b, v95
	v_exp_f32_e32 v94, v94
	v_fmac_f32_e32 v107, v211, v103
	v_mov_b32_e32 v130, v92
	v_mul_f32_e32 v93, v107, v93
	v_add_f32_e32 v94, 1.0, v94
	v_rcp_f32_e32 v94, v94
	v_mov_b32_e32 v107, v90
	v_mov_b32_dpp v130, v206 row_shr:2 row_mask:0xf bank_mask:0xf
	v_fma_f32 v130, v132, v130, v152
	v_mov_b32_dpp v107, v206 row_shr:1 row_mask:0xf bank_mask:0xf
	v_fmac_f32_e32 v130, v136, v107
	v_mov_b32_e32 v107, v92
	v_mul_f32_e32 v94, v95, v94
	v_mov_b32_e32 v95, v90
	v_mov_b32_dpp v107, v209 row_shr:2 row_mask:0xf bank_mask:0xf
	v_fmac_f32_e32 v149, v141, v107
	v_mov_b32_dpp v95, v209 row_shr:1 row_mask:0xf bank_mask:0xf
	v_fmac_f32_e32 v149, v145, v95
	v_fmac_f32_e32 v149, v209, v101
	v_mul_f32_e32 v95, 0xbfb8aa3b, v149
	v_exp_f32_e32 v95, v95
	v_mov_b32_dpp v92, v207 row_shr:2 row_mask:0xf bank_mask:0xf
	v_mov_b32_dpp v90, v207 row_shr:1 row_mask:0xf bank_mask:0xf
	v_fmac_f32_e32 v153, v133, v92
	v_add_f32_e32 v95, 1.0, v95
	v_rcp_f32_e32 v95, v95
	v_fmac_f32_e32 v153, v137, v90
	v_lshl_add_u64 v[96:97], v[184:185], 0, s[54:55]
	v_fmac_f32_e32 v130, v206, v104
	v_fmac_f32_e32 v153, v207, v105
	v_mul_f32_e32 v90, v149, v95
	v_mul_f32_e32 v94, v130, v94
	v_mul_f32_e32 v92, v153, v90
	v_cvt_pk_bf16_f32 v90, v91, v93
	v_cvt_pk_bf16_f32 v91, v94, v92
	s_and_saveexec_b64 s[0:1], s[6:7]
	s_xor_b64 s[0:1], exec, s[0:1]
	s_cbranch_execz .LBB0_1358
	v_cvt_pk_bf16_f32 v90, v212, v213
	v_cvt_pk_bf16_f32 v91, v208, v209
	v_add_co_u32_e32 v92, vcc, 0x1000, v96
	global_store_dwordx2 v[96:97], v[90:91], off
	v_cvt_pk_bf16_f32 v90, v210, v211
	v_cvt_pk_bf16_f32 v91, v206, v207
	s_nop 0
	v_addc_co_u32_e32 v93, vcc, 0, v97, vcc
	global_store_dwordx2 v[92:93], v[90:91], off offset:1536
.LBB0_1358:
	s_andn2_saveexec_b64 s[0:1], s[0:1]
	s_cbranch_execz .LBB0_1360
	global_store_dwordx2 v[214:215], v[90:91], off
.LBB0_1360:
	s_or_b64 exec, exec, s[0:1]
	v_add_f32_e32 v90, v242, v243
	v_fmamk_f32 v90, v90, 0x3a800000, v230
	v_mov_b32_e32 v135, v1
	v_mov_b32_e32 v134, v1
	s_nop 1
	v_mov_b32_dpp v135, v212 row_ror:2 row_mask:0xf bank_mask:0xf
	v_mov_b32_e32 v136, v102
	s_nop 1
	v_mov_b32_dpp v134, v210 row_ror:2 row_mask:0xf bank_mask:0xf
	v_rsq_f32_e32 v90, v90
	s_nop 0
	v_add_f32_e32 v91, v240, v241
	v_fmamk_f32 v91, v91, 0x3a800000, v230
	v_rsq_f32_e32 v92, v91
	s_nop 0
	v_add_f32_e32 v91, v169, v183
	v_fmamk_f32 v91, v91, 0x3a800000, v230
	v_pk_mul_f32 v[132:133], v[86:87], v[90:91] op_sel_hi:[1,0]
	v_pk_mul_f32 v[86:87], v[80:81], v[90:91] op_sel_hi:[1,0]
	v_mov_b32_e32 v137, v132
	v_rsq_f32_e32 v94, v91
	s_nop 0
	v_pk_mul_f32 v[130:131], v[78:79], v[90:91] op_sel_hi:[1,0]
	v_pk_mul_f32 v[80:81], v[84:85], v[92:93] op_sel_hi:[1,0]
	v_pk_mul_f32 v[84:85], v[82:83], v[92:93] op_sel_hi:[1,0]
	v_pk_mul_f32 v[82:83], v[70:71], v[92:93] op_sel_hi:[1,0]
	v_pk_mul_f32 v[70:71], v[76:77], v[94:95] op_sel_hi:[1,0]
	v_mov_b32_e32 v77, v1
	v_mov_b32_e32 v76, v1
	v_mov_b32_dpp v135, v132 row_shr:2 row_mask:0xf bank_mask:0xf
	v_mov_b32_dpp v77, v212 row_ror:1 row_mask:0xf bank_mask:0xf
	v_mov_b32_dpp v76, v210 row_ror:1 row_mask:0xf bank_mask:0xf
	v_mov_b32_dpp v134, v130 row_shr:2 row_mask:0xf bank_mask:0xf
	v_mov_b32_dpp v77, v132 row_shr:1 row_mask:0xf bank_mask:0xf
	v_mov_b32_dpp v76, v130 row_shr:1 row_mask:0xf bank_mask:0xf
	v_pk_fma_f32 v[134:135], v[110:111], v[134:135], v[112:113]
	v_pk_mul_f32 v[88:89], v[88:89], v[90:91] op_sel_hi:[1,0]
	v_pk_fma_f32 v[76:77], v[114:115], v[76:77], v[134:135]
	v_mov_b32_e32 v134, v130
	v_mov_b32_e32 v135, v98
	v_pk_fma_f32 v[76:77], v[134:135], v[136:137], v[76:77]
	v_mov_b32_e32 v135, v1
	v_mul_f32_e32 v91, 0xbfb8aa3b, v77
	v_exp_f32_e32 v91, v91
	v_mov_b32_e32 v134, v1
	v_mov_b32_dpp v135, v213 row_ror:2 row_mask:0xf bank_mask:0xf
	v_mov_b32_e32 v136, v103
	v_add_f32_e32 v91, 1.0, v91
	v_rcp_f32_e32 v91, v91
	v_mov_b32_dpp v134, v211 row_ror:2 row_mask:0xf bank_mask:0xf
	v_mov_b32_dpp v135, v133 row_shr:2 row_mask:0xf bank_mask:0xf
	v_mov_b32_e32 v137, v133
	v_mul_f32_e32 v77, v77, v91
	v_mul_f32_e32 v91, v76, v77
	v_mov_b32_e32 v77, v1
	v_mov_b32_e32 v76, v1
	v_mov_b32_dpp v134, v131 row_shr:2 row_mask:0xf bank_mask:0xf
	v_mov_b32_dpp v77, v213 row_ror:1 row_mask:0xf bank_mask:0xf
	v_mov_b32_dpp v76, v211 row_ror:1 row_mask:0xf bank_mask:0xf
	v_pk_fma_f32 v[134:135], v[118:119], v[134:135], v[120:121]
	v_mov_b32_dpp v77, v133 row_shr:1 row_mask:0xf bank_mask:0xf
	v_mov_b32_dpp v76, v131 row_shr:1 row_mask:0xf bank_mask:0xf
	v_pk_fma_f32 v[76:77], v[122:123], v[76:77], v[134:135]
	v_mov_b32_e32 v134, v131
	v_mov_b32_e32 v135, v99
	v_pk_fma_f32 v[76:77], v[134:135], v[136:137], v[76:77]
	v_pk_mul_f32 v[78:79], v[72:73], v[92:93] op_sel_hi:[1,0]
	v_mul_f32_e32 v93, 0xbfb8aa3b, v77
	v_exp_f32_e32 v93, v93
	v_mov_b32_e32 v135, v1
	v_mov_b32_e32 v134, v1
	v_mov_b32_e32 v136, v104
;     __device__ __forceinline__ void operator()(f32x4 (&acc)[2][2][4][2], const Unit& u, int wr, int wc, int fr, int fq) const {
;     ...
;                 for (int m = 0; m < 4; ++m) {
;                     float og[4];
; #pragma unroll
;                     for (int j = 0; j < 4; ++j) {
;                         const float vg = acc[ai][0][m][n][j], vv = acc[ai][1][m][n][j];
;                         const float pg = (m > 0) ? acc[ai][0][m - 1][n][j] : 0.f, pv = (m > 0) ? acc[ai][1][m - 1][n][j] : 0.f;
;                         const float g1 = dppf(dppf(0.f, pg, 2), vg, 0), g2 = dppf(dppf(0.f, pg, 3), vg, 1);
;                         const float v1 = dppf(dppf(0.f, pv, 2), vv, 0), v2 = dppf(dppf(0.f, pv, 3), vv, 1);
;                         const float cgate = bg[j] + wg0[j] * g2 + wg1[j] * g1 + wg2[j] * vg;
;                         const float cval = bv[j] + wv0[j] * v2 + wv1[j] * v1 + wv2[j] * vv;
;                         og[j] = cgate * __builtin_amdgcn_rcpf(1.0f + __builtin_amdgcn_exp2f(-1.4426950408889634f * cgate)) * cval; }
;                     const unsigned long long w = (unsigned long long)cvt_pk_bf16(og[0], og[1]) | ((unsigned long long)cvt_pk_bf16(og[2], og[3]) << 32);
;                     if (m == 0) {
;                         if (fr >= 2) *(unsigned long long*)gp = w;
;                         else { *(unsigned long long*)sb = (unsigned long long)cvt_pk_bf16(acc[ai][0][0][n][0], acc[ai][0][0][n][1]) | ((unsigned long long)cvt_pk_bf16(acc[ai][0][0][n][2], acc[ai][0][0][n][3]) << 32);
;                                *(unsigned long long*)(sb + FFc) = (unsigned long long)cvt_pk_bf16(acc[ai][1][0][n][0], acc[ai][1][0][n][1]) | ((unsigned long long)cvt_pk_bf16(acc[ai][1][0][n][2], acc[ai][1][0][n][3]) << 32); }
;                     } else *(unsigned long long*)gp = w;
;                     if (m == 3 && fr >= 14) {
;                         *(unsigned long long*)hb = (unsigned long long)cvt_pk_bf16(acc[ai][0][3][n][0], acc[ai][0][3][n][1]) | ((unsigned long long)cvt_pk_bf16(acc[ai][0][3][n][2], acc[ai][0][3][n][3]) << 32);
;                         *(unsigned long long*)(hb + FFc) = (unsigned long long)cvt_pk_bf16(acc[ai][1][3][n][0], acc[ai][1][3][n][1]) | ((unsigned long long)cvt_pk_bf16(acc[ai][1][3][n][2], acc[ai][1][3][n][3]) << 32); }
;                     gp += (size_t)16 * FFc; asm volatile("" : "+v"(gp) :: "memory"); }
	v_add_f32_e32 v93, 1.0, v93
	v_rcp_f32_e32 v93, v93
	v_mov_b32_dpp v135, v208 row_ror:2 row_mask:0xf bank_mask:0xf
	v_mov_b32_dpp v134, v206 row_ror:2 row_mask:0xf bank_mask:0xf
	v_mov_b32_e32 v137, v88
	v_mul_f32_e32 v77, v77, v93
	v_mul_f32_e32 v93, v76, v77
	v_mov_b32_e32 v77, v1
	v_mov_b32_e32 v76, v1
	v_mov_b32_dpp v135, v88 row_shr:2 row_mask:0xf bank_mask:0xf
	v_mov_b32_dpp v77, v208 row_ror:1 row_mask:0xf bank_mask:0xf
	v_mov_b32_dpp v76, v206 row_ror:1 row_mask:0xf bank_mask:0xf
	v_mov_b32_dpp v134, v86 row_shr:2 row_mask:0xf bank_mask:0xf
	v_mov_b32_dpp v77, v88 row_shr:1 row_mask:0xf bank_mask:0xf
	v_mov_b32_dpp v76, v86 row_shr:1 row_mask:0xf bank_mask:0xf
	v_pk_fma_f32 v[134:135], v[126:127], v[134:135], v[128:129]
	v_pk_mul_f32 v[72:73], v[74:75], v[94:95] op_sel_hi:[1,0]
	v_pk_fma_f32 v[76:77], v[196:197], v[76:77], v[134:135]
	v_mov_b32_e32 v134, v86
	v_mov_b32_e32 v135, v100
	v_pk_fma_f32 v[76:77], v[134:135], v[136:137], v[76:77]
	v_pk_mul_f32 v[68:69], v[68:69], v[94:95] op_sel_hi:[1,0]
	v_pk_mul_f32 v[66:67], v[66:67], v[94:95] op_sel_hi:[1,0]
	v_mul_f32_e32 v95, 0xbfb8aa3b, v77
	v_exp_f32_e32 v95, v95
	v_mov_b32_e32 v135, v1
	v_mov_b32_e32 v134, v1
	v_mov_b32_e32 v136, v105
	v_add_f32_e32 v95, 1.0, v95
	v_rcp_f32_e32 v95, v95
	v_mov_b32_dpp v135, v209 row_ror:2 row_mask:0xf bank_mask:0xf
	v_mov_b32_dpp v134, v207 row_ror:2 row_mask:0xf bank_mask:0xf
	v_mov_b32_e32 v137, v89
	v_mul_f32_e32 v77, v77, v95
	v_mul_f32_e32 v95, v76, v77
	v_mov_b32_e32 v77, v1
	v_mov_b32_e32 v76, v1
	v_mov_b32_dpp v135, v89 row_shr:2 row_mask:0xf bank_mask:0xf
	v_mov_b32_dpp v77, v209 row_ror:1 row_mask:0xf bank_mask:0xf
	v_mov_b32_dpp v76, v207 row_ror:1 row_mask:0xf bank_mask:0xf
	v_mov_b32_dpp v134, v87 row_shr:2 row_mask:0xf bank_mask:0xf
	v_mov_b32_dpp v77, v89 row_shr:1 row_mask:0xf bank_mask:0xf
	v_mov_b32_dpp v76, v87 row_shr:1 row_mask:0xf bank_mask:0xf
	v_pk_fma_f32 v[134:135], v[192:193], v[134:135], v[194:195]
	v_lshl_add_u64 v[74:75], v[214:215], 0, s[50:51]
	v_pk_fma_f32 v[76:77], v[200:201], v[76:77], v[134:135]
	v_mov_b32_e32 v134, v87
	v_mov_b32_e32 v135, v101
	v_pk_fma_f32 v[76:77], v[134:135], v[136:137], v[76:77]
	v_mov_b32_e32 v135, v1
	v_mul_f32_e32 v107, 0xbfb8aa3b, v77
	v_exp_f32_e32 v107, v107
	v_mov_b32_e32 v134, v1
	v_mov_b32_dpp v135, v132 row_ror:2 row_mask:0xf bank_mask:0xf
	v_mov_b32_e32 v136, v102
	v_add_f32_e32 v107, 1.0, v107
	v_rcp_f32_e32 v107, v107
	v_mov_b32_dpp v134, v130 row_ror:2 row_mask:0xf bank_mask:0xf
	v_mov_b32_dpp v135, v84 row_shr:2 row_mask:0xf bank_mask:0xf
	v_mov_b32_e32 v137, v84
	v_mul_f32_e32 v77, v77, v107
	v_mul_f32_e32 v77, v76, v77
	v_cvt_pk_bf16_f32 v76, v91, v93
	v_cvt_pk_bf16_f32 v77, v95, v77
	global_store_dwordx2 v[74:75], v[76:77], off
	v_mov_b32_e32 v77, v1
	v_mov_b32_e32 v76, v1
	v_mov_b32_dpp v134, v82 row_shr:2 row_mask:0xf bank_mask:0xf
	v_mov_b32_dpp v77, v132 row_ror:1 row_mask:0xf bank_mask:0xf
	v_mov_b32_dpp v76, v130 row_ror:1 row_mask:0xf bank_mask:0xf
	v_pk_fma_f32 v[134:135], v[110:111], v[134:135], v[112:113]
	v_mov_b32_dpp v77, v84 row_shr:1 row_mask:0xf bank_mask:0xf
	v_mov_b32_dpp v76, v82 row_shr:1 row_mask:0xf bank_mask:0xf
	v_pk_fma_f32 v[76:77], v[114:115], v[76:77], v[134:135]
	v_mov_b32_e32 v134, v82
	v_mov_b32_e32 v135, v98
	v_pk_fma_f32 v[76:77], v[134:135], v[136:137], v[76:77]
	v_mov_b32_e32 v135, v1
	v_mul_f32_e32 v91, 0xbfb8aa3b, v77
	v_exp_f32_e32 v91, v91
	v_mov_b32_e32 v134, v1
	v_mov_b32_dpp v135, v133 row_ror:2 row_mask:0xf bank_mask:0xf
	v_mov_b32_e32 v98, v83
	v_add_f32_e32 v91, 1.0, v91
	v_rcp_f32_e32 v91, v91
	v_mov_b32_dpp v134, v131 row_ror:2 row_mask:0xf bank_mask:0xf
	v_mov_b32_dpp v135, v85 row_shr:2 row_mask:0xf bank_mask:0xf
	v_mov_b32_e32 v102, v103
	v_mul_f32_e32 v77, v77, v91
	v_mul_f32_e32 v91, v76, v77
	v_mov_b32_e32 v77, v1
	v_mov_b32_e32 v76, v1
	v_mov_b32_dpp v134, v83 row_shr:2 row_mask:0xf bank_mask:0xf
	v_mov_b32_dpp v77, v133 row_ror:1 row_mask:0xf bank_mask:0xf
	v_mov_b32_dpp v76, v131 row_ror:1 row_mask:0xf bank_mask:0xf
	v_pk_fma_f32 v[130:131], v[118:119], v[134:135], v[120:121]
	v_mov_b32_dpp v77, v85 row_shr:1 row_mask:0xf bank_mask:0xf
	v_mov_b32_dpp v76, v83 row_shr:1 row_mask:0xf bank_mask:0xf
	v_pk_fma_f32 v[76:77], v[122:123], v[76:77], v[130:131]
	v_mov_b32_e32 v103, v85
	v_pk_fma_f32 v[76:77], v[98:99], v[102:103], v[76:77]
	v_mov_b32_e32 v99, v1
	v_mul_f32_e32 v93, 0xbfb8aa3b, v77
	v_exp_f32_e32 v93, v93
	v_mov_b32_e32 v98, v1
	v_mov_b32_dpp v99, v88 row_ror:2 row_mask:0xf bank_mask:0xf
	v_mov_b32_e32 v102, v104
	v_add_f32_e32 v93, 1.0, v93
	v_rcp_f32_e32 v93, v93
	v_mov_b32_dpp v98, v86 row_ror:2 row_mask:0xf bank_mask:0xf
	v_mov_b32_dpp v99, v80 row_shr:2 row_mask:0xf bank_mask:0xf
	v_mov_b32_e32 v103, v80
	v_mul_f32_e32 v77, v77, v93
	v_mul_f32_e32 v93, v76, v77
	v_mov_b32_e32 v77, v1
	v_mov_b32_e32 v76, v1
	v_mov_b32_dpp v98, v78 row_shr:2 row_mask:0xf bank_mask:0xf
	v_mov_b32_dpp v77, v88 row_ror:1 row_mask:0xf bank_mask:0xf
	v_mov_b32_dpp v76, v86 row_ror:1 row_mask:0xf bank_mask:0xf
	v_pk_fma_f32 v[98:99], v[126:127], v[98:99], v[128:129]
	v_mov_b32_dpp v77, v80 row_shr:1 row_mask:0xf bank_mask:0xf
	v_mov_b32_dpp v76, v78 row_shr:1 row_mask:0xf bank_mask:0xf
	v_pk_fma_f32 v[76:77], v[196:197], v[76:77], v[98:99]
	v_mov_b32_e32 v98, v78
	v_mov_b32_e32 v99, v100
	v_pk_fma_f32 v[76:77], v[98:99], v[102:103], v[76:77]
	v_mov_b32_e32 v99, v1
	v_mul_f32_e32 v86, 0xbfb8aa3b, v77
	v_exp_f32_e32 v86, v86
	v_mov_b32_e32 v98, v1
	v_mov_b32_dpp v99, v89 row_ror:2 row_mask:0xf bank_mask:0xf
	v_mov_b32_e32 v100, v79
	v_add_f32_e32 v86, 1.0, v86
	v_rcp_f32_e32 v86, v86
	v_mov_b32_dpp v98, v87 row_ror:2 row_mask:0xf bank_mask:0xf
;     __device__ __forceinline__ void operator()(f32x4 (&acc)[2][2][4][2], const Unit& u, int wr, int wc, int fr, int fq) const {
;     ...
;                 for (int m = 0; m < 4; ++m) {
;                     float og[4];
; #pragma unroll
;                     for (int j = 0; j < 4; ++j) {
;                         const float vg = acc[ai][0][m][n][j], vv = acc[ai][1][m][n][j];
;                         const float pg = (m > 0) ? acc[ai][0][m - 1][n][j] : 0.f, pv = (m > 0) ? acc[ai][1][m - 1][n][j] : 0.f;
;                         const float g1 = dppf(dppf(0.f, pg, 2), vg, 0), g2 = dppf(dppf(0.f, pg, 3), vg, 1);
;                         const float v1 = dppf(dppf(0.f, pv, 2), vv, 0), v2 = dppf(dppf(0.f, pv, 3), vv, 1);
;                         const float cgate = bg[j] + wg0[j] * g2 + wg1[j] * g1 + wg2[j] * vg;
;                         const float cval = bv[j] + wv0[j] * v2 + wv1[j] * v1 + wv2[j] * vv;
;                         og[j] = cgate * __builtin_amdgcn_rcpf(1.0f + __builtin_amdgcn_exp2f(-1.4426950408889634f * cgate)) * cval; }
;                     const unsigned long long w = (unsigned long long)cvt_pk_bf16(og[0], og[1]) | ((unsigned long long)cvt_pk_bf16(og[2], og[3]) << 32);
;                     if (m == 0) {
;                         if (fr >= 2) *(unsigned long long*)gp = w;
;                         else { *(unsigned long long*)sb = (unsigned long long)cvt_pk_bf16(acc[ai][0][0][n][0], acc[ai][0][0][n][1]) | ((unsigned long long)cvt_pk_bf16(acc[ai][0][0][n][2], acc[ai][0][0][n][3]) << 32);
;                                *(unsigned long long*)(sb + FFc) = (unsigned long long)cvt_pk_bf16(acc[ai][1][0][n][0], acc[ai][1][0][n][1]) | ((unsigned long long)cvt_pk_bf16(acc[ai][1][0][n][2], acc[ai][1][0][n][3]) << 32); }
;                     } else *(unsigned long long*)gp = w;
;                     if (m == 3 && fr >= 14) {
;                         *(unsigned long long*)hb = (unsigned long long)cvt_pk_bf16(acc[ai][0][3][n][0], acc[ai][0][3][n][1]) | ((unsigned long long)cvt_pk_bf16(acc[ai][0][3][n][2], acc[ai][0][3][n][3]) << 32);
;                         *(unsigned long long*)(hb + FFc) = (unsigned long long)cvt_pk_bf16(acc[ai][1][3][n][0], acc[ai][1][3][n][1]) | ((unsigned long long)cvt_pk_bf16(acc[ai][1][3][n][2], acc[ai][1][3][n][3]) << 32); }
;                     gp += (size_t)16 * FFc; asm volatile("" : "+v"(gp) :: "memory"); }
	v_mov_b32_dpp v99, v81 row_shr:2 row_mask:0xf bank_mask:0xf
	v_lshl_add_u64 v[74:75], v[74:75], 0, s[50:51]
	v_mul_f32_e32 v77, v77, v86
	v_mul_f32_e32 v88, v76, v77
	v_mov_b32_e32 v77, v1
	v_mov_b32_e32 v76, v1
	v_mov_b32_dpp v98, v79 row_shr:2 row_mask:0xf bank_mask:0xf
	v_mov_b32_dpp v77, v89 row_ror:1 row_mask:0xf bank_mask:0xf
	v_mov_b32_dpp v76, v87 row_ror:1 row_mask:0xf bank_mask:0xf
	v_pk_fma_f32 v[86:87], v[192:193], v[98:99], v[194:195]
	v_mov_b32_dpp v77, v81 row_shr:1 row_mask:0xf bank_mask:0xf
	v_mov_b32_dpp v76, v79 row_shr:1 row_mask:0xf bank_mask:0xf
	v_pk_fma_f32 v[76:77], v[200:201], v[76:77], v[86:87]
	v_mov_b32_e32 v86, v105
	v_mov_b32_e32 v87, v81
	v_pk_fma_f32 v[76:77], v[100:101], v[86:87], v[76:77]
	v_mov_b32_e32 v87, v1
	v_mul_f32_e32 v86, 0xbfb8aa3b, v77
	v_exp_f32_e32 v86, v86
	v_mov_b32_dpp v87, v84 row_ror:2 row_mask:0xf bank_mask:0xf
	v_add_f32_e32 v86, 1.0, v86
	v_rcp_f32_e32 v86, v86
	v_mov_b32_dpp v87, v72 row_shr:2 row_mask:0xf bank_mask:0xf
	v_mul_f32_e32 v77, v77, v86
	v_mul_f32_e32 v77, v76, v77
	v_cvt_pk_bf16_f32 v76, v91, v93
	v_cvt_pk_bf16_f32 v77, v88, v77
	v_mov_b32_e32 v86, v1
	global_store_dwordx2 v[74:75], v[76:77], off
	v_mov_b32_e32 v77, v1
	v_mov_b32_e32 v76, v1
	v_mov_b32_dpp v86, v82 row_ror:2 row_mask:0xf bank_mask:0xf
	v_mov_b32_dpp v77, v84 row_ror:1 row_mask:0xf bank_mask:0xf
	v_mov_b32_dpp v76, v82 row_ror:1 row_mask:0xf bank_mask:0xf
	v_mov_b32_dpp v86, v66 row_shr:2 row_mask:0xf bank_mask:0xf
	v_mov_b32_dpp v77, v72 row_shr:1 row_mask:0xf bank_mask:0xf
	v_mov_b32_dpp v76, v66 row_shr:1 row_mask:0xf bank_mask:0xf
	v_pk_fma_f32 v[86:87], v[110:111], v[86:87], v[112:113]
	v_lshl_add_u64 v[74:75], v[74:75], 0, s[50:51]
	v_pk_fma_f32 v[76:77], v[114:115], v[76:77], v[86:87]
	v_mov_b32_e32 v86, v66
	v_mov_b32_e32 v87, v72
	v_pk_fma_f32 v[76:77], v[116:117], v[86:87], v[76:77]
	v_mov_b32_e32 v87, v1
	v_mul_f32_e32 v82, 0xbfb8aa3b, v77
	v_exp_f32_e32 v82, v82
	v_mov_b32_e32 v86, v1
	v_mov_b32_dpp v87, v85 row_ror:2 row_mask:0xf bank_mask:0xf
	v_add_f32_e32 v82, 1.0, v82
	v_rcp_f32_e32 v82, v82
	v_mov_b32_dpp v86, v83 row_ror:2 row_mask:0xf bank_mask:0xf
	v_mov_b32_dpp v87, v73 row_shr:2 row_mask:0xf bank_mask:0xf
	v_mul_f32_e32 v77, v77, v82
	v_mul_f32_e32 v84, v76, v77
	v_mov_b32_e32 v77, v1
	v_mov_b32_e32 v76, v1
	v_mov_b32_dpp v86, v67 row_shr:2 row_mask:0xf bank_mask:0xf
	v_mov_b32_dpp v77, v85 row_ror:1 row_mask:0xf bank_mask:0xf
	v_mov_b32_dpp v76, v83 row_ror:1 row_mask:0xf bank_mask:0xf
	v_pk_fma_f32 v[82:83], v[118:119], v[86:87], v[120:121]
	v_mov_b32_dpp v77, v73 row_shr:1 row_mask:0xf bank_mask:0xf
	v_mov_b32_dpp v76, v67 row_shr:1 row_mask:0xf bank_mask:0xf
	v_pk_fma_f32 v[76:77], v[122:123], v[76:77], v[82:83]
	v_mov_b32_e32 v82, v67
	v_mov_b32_e32 v83, v73
	v_pk_fma_f32 v[76:77], v[124:125], v[82:83], v[76:77]
	v_mov_b32_e32 v83, v1
	v_mul_f32_e32 v82, 0xbfb8aa3b, v77
	v_exp_f32_e32 v82, v82
	v_mov_b32_dpp v83, v80 row_ror:2 row_mask:0xf bank_mask:0xf
	v_add_f32_e32 v82, 1.0, v82
	v_rcp_f32_e32 v82, v82
	v_mov_b32_dpp v83, v70 row_shr:2 row_mask:0xf bank_mask:0xf
	v_mul_f32_e32 v77, v77, v82
	v_mov_b32_e32 v82, v1
	v_mul_f32_e32 v85, v76, v77
	v_mov_b32_e32 v77, v1
	v_mov_b32_e32 v76, v1
	v_mov_b32_dpp v82, v78 row_ror:2 row_mask:0xf bank_mask:0xf
	v_mov_b32_dpp v77, v80 row_ror:1 row_mask:0xf bank_mask:0xf
	v_mov_b32_dpp v76, v78 row_ror:1 row_mask:0xf bank_mask:0xf
	v_mov_b32_dpp v82, v68 row_shr:2 row_mask:0xf bank_mask:0xf
	v_mov_b32_dpp v77, v70 row_shr:1 row_mask:0xf bank_mask:0xf
	v_mov_b32_dpp v76, v68 row_shr:1 row_mask:0xf bank_mask:0xf
	v_pk_fma_f32 v[82:83], v[126:127], v[82:83], v[128:129]
	s_nop 0
	v_pk_fma_f32 v[76:77], v[196:197], v[76:77], v[82:83]
	v_mov_b32_e32 v82, v68
	v_mov_b32_e32 v83, v70
	v_pk_fma_f32 v[76:77], v[198:199], v[82:83], v[76:77]
	v_mov_b32_e32 v83, v1
	v_mul_f32_e32 v78, 0xbfb8aa3b, v77
	v_exp_f32_e32 v78, v78
	v_mov_b32_e32 v82, v1
	v_mov_b32_dpp v83, v81 row_ror:2 row_mask:0xf bank_mask:0xf
	v_add_f32_e32 v78, 1.0, v78
	v_rcp_f32_e32 v78, v78
	v_mov_b32_dpp v82, v79 row_ror:2 row_mask:0xf bank_mask:0xf
	v_mov_b32_dpp v83, v71 row_shr:2 row_mask:0xf bank_mask:0xf
	v_mul_f32_e32 v77, v77, v78
	v_mul_f32_e32 v80, v76, v77
	v_mov_b32_e32 v77, v1
	v_mov_b32_e32 v76, v1
	v_mov_b32_dpp v82, v69 row_shr:2 row_mask:0xf bank_mask:0xf
	v_mov_b32_dpp v77, v81 row_ror:1 row_mask:0xf bank_mask:0xf
	v_mov_b32_dpp v76, v79 row_ror:1 row_mask:0xf bank_mask:0xf
	v_pk_fma_f32 v[78:79], v[192:193], v[82:83], v[194:195]
	v_mov_b32_dpp v77, v71 row_shr:1 row_mask:0xf bank_mask:0xf
	v_mov_b32_dpp v76, v69 row_shr:1 row_mask:0xf bank_mask:0xf
	v_pk_fma_f32 v[76:77], v[200:201], v[76:77], v[78:79]
	v_mov_b32_e32 v78, v69
	v_mov_b32_e32 v79, v71
	v_pk_fma_f32 v[76:77], v[202:203], v[78:79], v[76:77]
	s_nop 0
	v_mul_f32_e32 v78, 0xbfb8aa3b, v77
	v_exp_f32_e32 v78, v78
	s_nop 0
	v_add_f32_e32 v78, 1.0, v78
	v_rcp_f32_e32 v78, v78
	s_nop 0
	v_mul_f32_e32 v77, v77, v78
	v_mul_f32_e32 v77, v76, v77
	v_cvt_pk_bf16_f32 v76, v84, v85
	v_cvt_pk_bf16_f32 v77, v80, v77
	global_store_dwordx2 v[74:75], v[76:77], off
	s_and_saveexec_b64 s[0:1], s[8:9]
	s_cbranch_execz .LBB0_1362
	v_cvt_pk_bf16_f32 v72, v72, v73
	v_cvt_pk_bf16_f32 v73, v70, v71
	global_store_dwordx2 v[204:205], v[72:73], off
	v_cvt_pk_bf16_f32 v66, v66, v67
	v_cvt_pk_bf16_f32 v67, v68, v69
	v_add_co_u32_e32 v68, vcc, 0x1000, v204
	s_nop 1
	v_addc_co_u32_e32 v69, vcc, 0, v205, vcc
	global_store_dwordx2 v[68:69], v[66:67], off offset:1536
;     __device__ __forceinline__ void operator()(f32x4 (&acc)[2][2][4][2], const Unit& u, int wr, int wc, int fr, int fq) const {
;     ...
;         for (int n = 0; n < 2; ++n) {
;             const int gc0 = u.pn * 128 + wc * 32 + 8 * fq + 4 * n;
;             const float* cwp = cw + gc0; asm volatile("" : "+v"(cwp));
;             const f32x4 wg0 = *(const f32x4*)(cwp), wg1 = *(const f32x4*)(cwp + FF2c), wg2 = *(const f32x4*)(cwp + 2 * FF2c);
;             const f32x4 wv0 = *(const f32x4*)(cwp + FFc), wv1 = *(const f32x4*)(cwp + FF2c + FFc), wv2 = *(const f32x4*)(cwp + 2 * FF2c + FFc);
;             const f32x4 bg = *(const f32x4*)(cb + gc0), bv = *(const f32x4*)(cb + FFc + gc0);
;             bf16_t* gp = G + (size_t)row0 * FFc + gc0;
;             bf16_t* sb = Fb + ((size_t)(row0 >> 6) * 2 + (fr & 1)) * FF2c + gc0;
;             bf16_t* hb = Hb + ((size_t)(row0 >> 6) * 2 + (fr & 1)) * FF2c + gc0;
; #pragma unroll
;             for (int ai = 0; ai < 2; ++ai) {
; #pragma unroll
;                 for (int m = 0; m < 4; ++m) {
;                     float og[4];
; #pragma unroll
;                     for (int j = 0; j < 4; ++j) {
;                         const float vg = acc[ai][0][m][n][j], vv = acc[ai][1][m][n][j];
;                         const float pg = (m > 0) ? acc[ai][0][m - 1][n][j] : 0.f, pv = (m > 0) ? acc[ai][1][m - 1][n][j] : 0.f;
;                         const float g1 = dppf(dppf(0.f, pg, 2), vg, 0), g2 = dppf(dppf(0.f, pg, 3), vg, 1);
;                         const float v1 = dppf(dppf(0.f, pv, 2), vv, 0), v2 = dppf(dppf(0.f, pv, 3), vv, 1);
;                         const float cgate = bg[j] + wg0[j] * g2 + wg1[j] * g1 + wg2[j] * vg;
;                         const float cval = bv[j] + wv0[j] * v2 + wv1[j] * v1 + wv2[j] * vv;
;                         og[j] = cgate * __builtin_amdgcn_rcpf(1.0f + __builtin_amdgcn_exp2f(-1.4426950408889634f * cgate)) * cval; }
.LBB0_1362:
	s_or_b64 exec, exec, s[0:1]
	v_mov_b32_e32 v169, v168
	v_pk_mul_f32 v[102:103], v[58:59], v[168:169]
	v_lshl_add_u64 v[58:59], v[74:75], 0, s[50:51]
	v_mov_b32_e32 v66, v168
	v_mov_b32_e32 v67, v168
	v_pk_mul_f32 v[104:105], v[62:63], v[168:169]
	v_pk_mul_f32 v[98:99], v[60:61], v[66:67]
	v_lshl_add_u64 v[58:59], v[58:59], 0, s[52:53]
	v_lshl_add_u64 v[60:61], v[96:97], 0, s[54:55]
	v_lshl_add_u64 v[62:63], v[204:205], 0, s[54:55]
	v_lshl_add_u64 v[78:79], v[172:173], 0, 16
	s_movk_i32 s0, 0x5000
	v_pk_mul_f32 v[100:101], v[64:65], v[66:67]
	v_add_co_u32_e32 v62, vcc, s0, v78
	s_mov_b32 s0, 0xb000
	s_nop 0
	v_addc_co_u32_e32 v63, vcc, 0, v79, vcc
	global_load_dwordx4 v[66:69], v[62:63], off offset:2048
	v_add_co_u32_e32 v62, vcc, s0, v78
	s_movk_i32 s0, 0x2000
	s_nop 0
	v_addc_co_u32_e32 v63, vcc, 0, v79, vcc
	global_load_dwordx4 v[58:61], v[78:79], off
	global_load_dwordx4 v[74:77], v[62:63], off
	v_add_co_u32_e32 v62, vcc, s0, v78
	s_mov_b32 s0, 0x8000
	s_nop 0
	v_addc_co_u32_e32 v63, vcc, 0, v79, vcc
	v_add_co_u32_e32 v70, vcc, s0, v78
	s_mov_b32 s0, 0xd000
	s_nop 0
	v_addc_co_u32_e32 v71, vcc, 0, v79, vcc
	v_add_co_u32_e32 v78, vcc, s0, v78
	v_or_b32_e32 v86, 4, v170
	s_nop 0
	v_addc_co_u32_e32 v79, vcc, 0, v79, vcc
	v_ashrrev_i32_e32 v87, 31, v86
	global_load_dwordx4 v[62:65], v[62:63], off offset:3072
	v_lshl_add_u64 v[86:87], v[86:87], 2, s[76:77]
	global_load_dwordx4 v[70:73], v[70:71], off offset:1024
	s_nop 0
	global_load_dwordx4 v[78:81], v[78:79], off offset:3072
	s_nop 0
	global_load_dwordx4 v[82:85], v[174:175], off offset:16
	v_mov_b32_e32 v95, v1
	global_load_dwordx4 v[86:89], v[86:87], off
	v_mov_b32_e32 v91, v1
	v_mov_b32_dpp v95, v95 row_ror:2 row_mask:0xf bank_mask:0xf
	v_mov_b32_e32 v107, v95
	v_mov_b32_dpp v91, v91 row_ror:1 row_mask:0xf bank_mask:0xf
	v_mov_b32_e32 v93, v91
	v_mov_b32_dpp v107, v104 row_shr:2 row_mask:0xf bank_mask:0xf
	v_mov_b32_e32 v111, v95
	v_mov_b32_dpp v93, v104 row_shr:1 row_mask:0xf bank_mask:0xf
	v_mov_b32_e32 v110, v91
	v_mov_b32_dpp v111, v102 row_shr:2 row_mask:0xf bank_mask:0xf
	v_mov_b32_e32 v112, v95
	v_mov_b32_dpp v110, v102 row_shr:1 row_mask:0xf bank_mask:0xf
	v_mov_b32_e32 v113, v95
	v_mov_b32_dpp v112, v103 row_shr:2 row_mask:0xf bank_mask:0xf
	v_lshl_add_u64 v[96:97], v[184:185], 0, 8
	v_mov_b32_dpp v113, v98 row_shr:2 row_mask:0xf bank_mask:0xf
	s_waitcnt vmcnt(0) lgkmcnt(0)
	v_fma_f32 v107, v58, v107, v82
	v_fmac_f32_e32 v107, v66, v93
	v_fmac_f32_e32 v107, v104, v74
	v_fma_f32 v93, v62, v111, v86
	v_fmac_f32_e32 v93, v70, v110
	v_mul_f32_e32 v110, 0xbfb8aa3b, v107
	v_exp_f32_e32 v110, v110
	v_fmac_f32_e32 v93, v102, v78
	v_mov_b32_e32 v111, v91
	v_add_f32_e32 v110, 1.0, v110
	v_rcp_f32_e32 v110, v110
	v_mov_b32_dpp v111, v103 row_shr:1 row_mask:0xf bank_mask:0xf
	v_mul_f32_e32 v107, v107, v110
	v_mov_b32_e32 v110, v95
	v_mul_f32_e32 v93, v93, v107
	v_mov_b32_e32 v107, v91
	v_mov_b32_dpp v110, v105 row_shr:2 row_mask:0xf bank_mask:0xf
	v_fma_f32 v110, v59, v110, v83
	v_mov_b32_dpp v107, v105 row_shr:1 row_mask:0xf bank_mask:0xf
	v_fmac_f32_e32 v110, v67, v107
	v_fmac_f32_e32 v110, v105, v75
	v_fma_f32 v107, v63, v112, v87
	v_fmac_f32_e32 v107, v71, v111
	v_mul_f32_e32 v111, 0xbfb8aa3b, v110
	v_exp_f32_e32 v111, v111
	v_fmac_f32_e32 v107, v103, v79
	v_mov_b32_e32 v112, v91
	v_add_f32_e32 v111, 1.0, v111
	v_rcp_f32_e32 v111, v111
	v_mov_b32_dpp v112, v98 row_shr:1 row_mask:0xf bank_mask:0xf
	v_mul_f32_e32 v110, v110, v111
	v_mov_b32_e32 v111, v95
	v_mul_f32_e32 v107, v107, v110
	v_mov_b32_e32 v110, v91
	v_mov_b32_dpp v111, v100 row_shr:2 row_mask:0xf bank_mask:0xf
	v_fma_f32 v111, v60, v111, v84
	v_mov_b32_dpp v110, v100 row_shr:1 row_mask:0xf bank_mask:0xf
	v_fmac_f32_e32 v111, v68, v110
	v_fmac_f32_e32 v111, v100, v76
	v_fma_f32 v110, v64, v113, v88
	v_fmac_f32_e32 v110, v72, v112
	v_mul_f32_e32 v112, 0xbfb8aa3b, v111
	v_exp_f32_e32 v112, v112
	v_fmac_f32_e32 v110, v98, v80
	v_add_f32_e32 v112, 1.0, v112
	v_rcp_f32_e32 v112, v112
	s_nop 0
	v_mul_f32_e32 v111, v111, v112
	v_mov_b32_e32 v112, v95
	v_mul_f32_e32 v111, v110, v111
	v_mov_b32_e32 v110, v91
	v_mov_b32_dpp v112, v101 row_shr:2 row_mask:0xf bank_mask:0xf
	v_fma_f32 v112, v61, v112, v85
	v_mov_b32_dpp v110, v101 row_shr:1 row_mask:0xf bank_mask:0xf
	v_mov_b32_dpp v95, v99 row_shr:2 row_mask:0xf bank_mask:0xf
	v_fmac_f32_e32 v112, v69, v110
	v_mov_b32_dpp v91, v99 row_shr:1 row_mask:0xf bank_mask:0xf
	v_fmac_f32_e32 v112, v101, v77
	v_fma_f32 v95, v65, v95, v89
	v_fmac_f32_e32 v95, v73, v91
	v_mul_f32_e32 v91, 0xbfb8aa3b, v112
	v_exp_f32_e32 v91, v91
	v_fmac_f32_e32 v95, v99, v81
	v_cvt_pk_bf16_f32 v110, v93, v107
	v_add_f32_e32 v91, 1.0, v91
	v_rcp_f32_e32 v91, v91
	s_nop 0
	v_mul_f32_e32 v91, v112, v91
	v_mul_f32_e32 v91, v95, v91
	v_cvt_pk_bf16_f32 v111, v111, v91
	s_and_saveexec_b64 s[0:1], s[6:7]
	s_xor_b64 s[0:1], exec, s[0:1]
	s_cbranch_execz .LBB0_1364
	v_cvt_pk_bf16_f32 v110, v104, v105
	v_cvt_pk_bf16_f32 v111, v100, v101
	v_add_co_u32_e32 v112, vcc, 0x1000, v96
	global_store_dwordx2 v[96:97], v[110:111], off
	v_cvt_pk_bf16_f32 v110, v102, v103
	v_cvt_pk_bf16_f32 v111, v98, v99
	s_nop 0
	v_addc_co_u32_e32 v113, vcc, 0, v97, vcc
	global_store_dwordx2 v[112:113], v[110:111], off offset:1536

;     __device__ __forceinline__ void operator()(f32x4 (&acc)[2][2][4][2], const Unit& u, int wr, int wc, int fr, int fq) const {
;     ...
;         { float rs[2][4]; load_row_scales(ssp, row0, fq, rs);
; #pragma unroll
;           for (int ai = 0; ai < 2; ++ai)
; #pragma unroll
;               for (int m = 0; m < 4; ++m)
; #pragma unroll
;                   for (int bj = 0; bj < 2; ++bj)
; #pragma unroll
;                       for (int n = 0; n < 2; ++n) acc[ai][bj][m][n] = acc[ai][bj][m][n] * rs[ai][m]; }
;     ...
; #pragma unroll
;             for (int ai = 0; ai < 2; ++ai) {
; #pragma unroll
;                 for (int m = 0; m < 4; ++m) {
;                     float og[4];
; #pragma unroll
;                     for (int j = 0; j < 4; ++j) {
;                         const float vg = acc[ai][0][m][n][j], vv = acc[ai][1][m][n][j];
;                         const float pg = (m > 0) ? acc[ai][0][m - 1][n][j] : 0.f, pv = (m > 0) ? acc[ai][1][m - 1][n][j] : 0.f;
;                         const float g1 = dppf(dppf(0.f, pg, 2), vg, 0), g2 = dppf(dppf(0.f, pg, 3), vg, 1);
;                         const float v1 = dppf(dppf(0.f, pv, 2), vv, 0), v2 = dppf(dppf(0.f, pv, 3), vv, 1);
;                         const float cgate = bg[j] + wg0[j] * g2 + wg1[j] * g1 + wg2[j] * vg;
;                         const float cval = bv[j] + wv0[j] * v2 + wv1[j] * v1 + wv2[j] * vv;
;                         og[j] = cgate * __builtin_amdgcn_rcpf(1.0f + __builtin_amdgcn_exp2f(-1.4426950408889634f * cgate)) * cval; }
.LBB0_1366:
	s_or_b64 exec, exec, s[0:1]
	v_mov_b32_e32 v181, v180
	v_mov_b32_e32 v179, v178
	v_mov_b32_e32 v110, v178
	v_mov_b32_e32 v111, v178
	v_pk_mul_f32 v[122:123], v[38:39], v[180:181]
	v_mov_b32_e32 v38, v182
	v_mov_b32_e32 v39, v182
	v_pk_mul_f32 v[128:129], v[56:57], v[110:111]
	v_pk_mul_f32 v[126:127], v[48:49], v[110:111]
	v_pk_mul_f32 v[130:131], v[46:47], v[178:179]
	v_mov_b32_e32 v46, v180
	v_mov_b32_e32 v47, v180
	v_pk_mul_f32 v[114:115], v[44:45], v[38:39]
	v_pk_mul_f32 v[110:111], v[36:37], v[38:39]
	v_mov_b32_e32 v39, v1
	v_mov_b32_e32 v38, v1
	v_mov_b32_e32 v183, v182
	v_pk_mul_f32 v[132:133], v[54:55], v[178:179]
	v_pk_mul_f32 v[118:119], v[40:41], v[46:47]
	v_mov_b32_e32 v41, v1
	v_mov_b32_dpp v39, v104 row_ror:2 row_mask:0xf bank_mask:0xf
	v_mov_b32_e32 v40, v1
	v_mov_b32_dpp v38, v102 row_ror:2 row_mask:0xf bank_mask:0xf
	v_pk_mul_f32 v[112:113], v[34:35], v[182:183]
	v_mov_b32_dpp v41, v104 row_ror:1 row_mask:0xf bank_mask:0xf
	v_mov_b32_dpp v39, v132 row_shr:2 row_mask:0xf bank_mask:0xf
	v_mov_b32_dpp v40, v102 row_ror:1 row_mask:0xf bank_mask:0xf
	v_mov_b32_dpp v38, v130 row_shr:2 row_mask:0xf bank_mask:0xf
	v_mov_b32_e32 v34, v62
	v_mov_b32_e32 v35, v58
	v_mov_b32_e32 v36, v86
	v_mov_b32_e32 v37, v82
	v_pk_mul_f32 v[116:117], v[42:43], v[182:183]
	v_mov_b32_dpp v41, v132 row_shr:1 row_mask:0xf bank_mask:0xf
	v_mov_b32_dpp v40, v130 row_shr:1 row_mask:0xf bank_mask:0xf
	v_pk_fma_f32 v[42:43], v[34:35], v[38:39], v[36:37]
	v_mov_b32_e32 v38, v70
	v_mov_b32_e32 v39, v66
	v_pk_fma_f32 v[42:43], v[38:39], v[40:41], v[42:43]
	v_mov_b32_e32 v44, v130
	v_mov_b32_e32 v45, v132
	v_mov_b32_e32 v40, v78
	v_mov_b32_e32 v41, v74
	v_pk_fma_f32 v[42:43], v[44:45], v[40:41], v[42:43]
	v_pk_mul_f32 v[120:121], v[52:53], v[46:47]
	v_mul_f32_e32 v44, 0xbfb8aa3b, v43
	v_exp_f32_e32 v44, v44
	v_mov_b32_e32 v47, v1
	v_mov_b32_e32 v46, v1
	v_mov_b32_e32 v49, v1
	v_add_f32_e32 v44, 1.0, v44
	v_rcp_f32_e32 v44, v44
	v_mov_b32_dpp v47, v105 row_ror:2 row_mask:0xf bank_mask:0xf
	v_mov_b32_e32 v48, v1
	v_mov_b32_dpp v46, v103 row_ror:2 row_mask:0xf bank_mask:0xf
	v_mul_f32_e32 v43, v43, v44
	v_mul_f32_e32 v91, v42, v43
	v_mov_b32_dpp v49, v105 row_ror:1 row_mask:0xf bank_mask:0xf
	v_mov_b32_dpp v47, v133 row_shr:2 row_mask:0xf bank_mask:0xf
	v_mov_b32_dpp v48, v103 row_ror:1 row_mask:0xf bank_mask:0xf
	v_mov_b32_dpp v46, v131 row_shr:2 row_mask:0xf bank_mask:0xf
	v_mov_b32_e32 v42, v63
	v_mov_b32_e32 v43, v59
	v_mov_b32_e32 v44, v87
	v_mov_b32_e32 v45, v83
	v_pk_mul_f32 v[124:125], v[50:51], v[180:181]
	v_mov_b32_dpp v49, v133 row_shr:1 row_mask:0xf bank_mask:0xf
	v_mov_b32_dpp v48, v131 row_shr:1 row_mask:0xf bank_mask:0xf
	v_pk_fma_f32 v[50:51], v[42:43], v[46:47], v[44:45]
	v_mov_b32_e32 v46, v71
	v_mov_b32_e32 v47, v67
	v_pk_fma_f32 v[50:51], v[46:47], v[48:49], v[50:51]
	v_mov_b32_e32 v52, v131
	v_mov_b32_e32 v53, v133
	v_mov_b32_e32 v48, v79
	v_mov_b32_e32 v49, v75
	v_pk_fma_f32 v[50:51], v[52:53], v[48:49], v[50:51]
	v_mov_b32_e32 v55, v1
	v_mul_f32_e32 v52, 0xbfb8aa3b, v51
	v_exp_f32_e32 v52, v52
	v_mov_b32_e32 v54, v1
	v_mov_b32_e32 v57, v1
	v_mov_b32_dpp v55, v100 row_ror:2 row_mask:0xf bank_mask:0xf
	v_add_f32_e32 v52, 1.0, v52
	v_rcp_f32_e32 v52, v52
	v_mov_b32_e32 v56, v1
	v_mov_b32_dpp v54, v98 row_ror:2 row_mask:0xf bank_mask:0xf
	v_mov_b32_dpp v57, v100 row_ror:1 row_mask:0xf bank_mask:0xf
	v_mul_f32_e32 v51, v51, v52
	v_mul_f32_e32 v93, v50, v51
	v_mov_b32_dpp v55, v128 row_shr:2 row_mask:0xf bank_mask:0xf
	v_mov_b32_dpp v56, v98 row_ror:1 row_mask:0xf bank_mask:0xf
	v_mov_b32_dpp v54, v126 row_shr:2 row_mask:0xf bank_mask:0xf
	v_mov_b32_e32 v50, v64
	v_mov_b32_e32 v51, v60
	v_mov_b32_e32 v52, v88
	v_mov_b32_e32 v53, v84
	v_mov_b32_dpp v57, v128 row_shr:1 row_mask:0xf bank_mask:0xf
	v_mov_b32_dpp v56, v126 row_shr:1 row_mask:0xf bank_mask:0xf
	v_pk_fma_f32 v[102:103], v[50:51], v[54:55], v[52:53]
	v_mov_b32_e32 v54, v72
	v_mov_b32_e32 v55, v68
	v_pk_fma_f32 v[102:103], v[54:55], v[56:57], v[102:103]
	v_mov_b32_e32 v104, v126
	v_mov_b32_e32 v105, v128
	v_mov_b32_e32 v56, v80
	v_mov_b32_e32 v57, v76
	v_pk_fma_f32 v[102:103], v[104:105], v[56:57], v[102:103]
	v_mov_b32_e32 v105, v1
	v_mul_f32_e32 v95, 0xbfb8aa3b, v103
	v_exp_f32_e32 v95, v95
	v_mov_b32_e32 v104, v1
	v_mov_b32_dpp v105, v101 row_ror:1 row_mask:0xf bank_mask:0xf
	v_mov_b32_e32 v98, v65
	v_add_f32_e32 v95, 1.0, v95
	v_rcp_f32_e32 v95, v95
	v_mov_b32_dpp v104, v99 row_ror:1 row_mask:0xf bank_mask:0xf
	v_mov_b32_e32 v100, v89
	v_mov_b32_dpp v105, v129 row_shr:1 row_mask:0xf bank_mask:0xf
	v_mul_f32_e32 v95, v103, v95
	v_mul_f32_e32 v95, v102, v95
	v_mov_b32_e32 v103, v1
	v_mov_b32_e32 v102, v1
	v_mov_b32_dpp v104, v127 row_shr:1 row_mask:0xf bank_mask:0xf
	v_mov_b32_dpp v103, v101 row_ror:2 row_mask:0xf bank_mask:0xf
	v_mov_b32_dpp v102, v99 row_ror:2 row_mask:0xf bank_mask:0xf
	v_mov_b32_e32 v99, v61
	v_mov_b32_dpp v103, v129 row_shr:2 row_mask:0xf bank_mask:0xf
	v_mov_b32_dpp v102, v127 row_shr:2 row_mask:0xf bank_mask:0xf
	v_mov_b32_e32 v101, v85
	v_pk_fma_f32 v[136:137], v[98:99], v[102:103], v[100:101]
	v_mov_b32_e32 v102, v73
	v_mov_b32_e32 v103, v69
	v_pk_fma_f32 v[136:137], v[102:103], v[104:105], v[136:137]
	v_mov_b32_e32 v138, v127
	v_mov_b32_e32 v139, v129
	v_mov_b32_e32 v104, v81
	v_mov_b32_e32 v105, v77
	v_pk_fma_f32 v[136:137], v[138:139], v[104:105], v[136:137]
	v_lshl_add_u64 v[134:135], v[134:135], 0, s[50:51]
	v_mul_f32_e32 v107, 0xbfb8aa3b, v137
	v_exp_f32_e32 v107, v107
	v_mov_b32_e32 v139, v1
	v_mov_b32_e32 v138, v1
	v_add_f32_e32 v107, 1.0, v107
	v_rcp_f32_e32 v107, v107
	v_mov_b32_dpp v139, v132 row_ror:2 row_mask:0xf bank_mask:0xf
;     __device__ __forceinline__ void operator()(f32x4 (&acc)[2][2][4][2], const Unit& u, int wr, int wc, int fr, int fq) const {
;     ...
;                 for (int m = 0; m < 4; ++m) {
;                     float og[4];
; #pragma unroll
;                     for (int j = 0; j < 4; ++j) {
;                         const float vg = acc[ai][0][m][n][j], vv = acc[ai][1][m][n][j];
;                         const float pg = (m > 0) ? acc[ai][0][m - 1][n][j] : 0.f, pv = (m > 0) ? acc[ai][1][m - 1][n][j] : 0.f;
;                         const float g1 = dppf(dppf(0.f, pg, 2), vg, 0), g2 = dppf(dppf(0.f, pg, 3), vg, 1);
;                         const float v1 = dppf(dppf(0.f, pv, 2), vv, 0), v2 = dppf(dppf(0.f, pv, 3), vv, 1);
;                         const float cgate = bg[j] + wg0[j] * g2 + wg1[j] * g1 + wg2[j] * vg;
;                         const float cval = bv[j] + wv0[j] * v2 + wv1[j] * v1 + wv2[j] * vv;
;                         og[j] = cgate * __builtin_amdgcn_rcpf(1.0f + __builtin_amdgcn_exp2f(-1.4426950408889634f * cgate)) * cval; }
;                     const unsigned long long w = (unsigned long long)cvt_pk_bf16(og[0], og[1]) | ((unsigned long long)cvt_pk_bf16(og[2], og[3]) << 32);
;                     if (m == 0) {
;                         if (fr >= 2) *(unsigned long long*)gp = w;
;                         else { *(unsigned long long*)sb = (unsigned long long)cvt_pk_bf16(acc[ai][0][0][n][0], acc[ai][0][0][n][1]) | ((unsigned long long)cvt_pk_bf16(acc[ai][0][0][n][2], acc[ai][0][0][n][3]) << 32);
;                                *(unsigned long long*)(sb + FFc) = (unsigned long long)cvt_pk_bf16(acc[ai][1][0][n][0], acc[ai][1][0][n][1]) | ((unsigned long long)cvt_pk_bf16(acc[ai][1][0][n][2], acc[ai][1][0][n][3]) << 32); }
;                     } else *(unsigned long long*)gp = w;
;                     if (m == 3 && fr >= 14) {
;                         *(unsigned long long*)hb = (unsigned long long)cvt_pk_bf16(acc[ai][0][3][n][0], acc[ai][0][3][n][1]) | ((unsigned long long)cvt_pk_bf16(acc[ai][0][3][n][2], acc[ai][0][3][n][3]) << 32);
;                         *(unsigned long long*)(hb + FFc) = (unsigned long long)cvt_pk_bf16(acc[ai][1][3][n][0], acc[ai][1][3][n][1]) | ((unsigned long long)cvt_pk_bf16(acc[ai][1][3][n][2], acc[ai][1][3][n][3]) << 32); }
;                     gp += (size_t)16 * FFc; asm volatile("" : "+v"(gp) :: "memory"); }
	v_mov_b32_dpp v138, v130 row_ror:2 row_mask:0xf bank_mask:0xf
	v_lshl_add_u64 v[108:109], v[108:109], 0, 8
	v_mul_f32_e32 v107, v137, v107
	v_mul_f32_e32 v107, v136, v107
	v_cvt_pk_bf16_f32 v136, v91, v93
	v_cvt_pk_bf16_f32 v137, v95, v107
	global_store_dwordx2 v[134:135], v[136:137], off
	v_mov_b32_e32 v137, v1
	v_mov_b32_e32 v136, v1
	v_mov_b32_dpp v139, v124 row_shr:2 row_mask:0xf bank_mask:0xf
	v_mov_b32_dpp v137, v132 row_ror:1 row_mask:0xf bank_mask:0xf
	v_mov_b32_dpp v136, v130 row_ror:1 row_mask:0xf bank_mask:0xf
	v_mov_b32_dpp v138, v122 row_shr:2 row_mask:0xf bank_mask:0xf
	v_mov_b32_dpp v137, v124 row_shr:1 row_mask:0xf bank_mask:0xf
	v_mov_b32_dpp v136, v122 row_shr:1 row_mask:0xf bank_mask:0xf
	v_pk_fma_f32 v[138:139], v[34:35], v[138:139], v[36:37]
	v_mov_b32_e32 v132, v123
	v_pk_fma_f32 v[136:137], v[38:39], v[136:137], v[138:139]
	v_mov_b32_e32 v138, v122
	v_mov_b32_e32 v139, v124
	v_pk_fma_f32 v[136:137], v[138:139], v[40:41], v[136:137]
	v_mov_b32_e32 v139, v1
	v_mul_f32_e32 v91, 0xbfb8aa3b, v137
	v_exp_f32_e32 v91, v91
	v_mov_b32_e32 v138, v1
	v_mov_b32_dpp v139, v133 row_ror:2 row_mask:0xf bank_mask:0xf
	v_lshl_add_u64 v[134:135], v[134:135], 0, s[50:51]
	v_add_f32_e32 v91, 1.0, v91
	v_rcp_f32_e32 v91, v91
	v_mov_b32_dpp v138, v131 row_ror:2 row_mask:0xf bank_mask:0xf
	v_mov_b32_dpp v139, v125 row_shr:2 row_mask:0xf bank_mask:0xf
	v_mul_f32_e32 v91, v137, v91
	v_mul_f32_e32 v91, v136, v91
	v_mov_b32_e32 v137, v1
	v_mov_b32_e32 v136, v1
	v_mov_b32_dpp v138, v123 row_shr:2 row_mask:0xf bank_mask:0xf
	v_mov_b32_dpp v137, v133 row_ror:1 row_mask:0xf bank_mask:0xf
	v_mov_b32_dpp v136, v131 row_ror:1 row_mask:0xf bank_mask:0xf
	v_pk_fma_f32 v[130:131], v[42:43], v[138:139], v[44:45]
	v_mov_b32_dpp v137, v125 row_shr:1 row_mask:0xf bank_mask:0xf
	v_mov_b32_dpp v136, v123 row_shr:1 row_mask:0xf bank_mask:0xf
	v_pk_fma_f32 v[130:131], v[46:47], v[136:137], v[130:131]
	v_mov_b32_e32 v133, v125
	v_pk_fma_f32 v[130:131], v[132:133], v[48:49], v[130:131]
	v_mov_b32_e32 v133, v1
	v_mul_f32_e32 v93, 0xbfb8aa3b, v131
	v_exp_f32_e32 v93, v93
	v_mov_b32_e32 v132, v1
	v_mov_b32_dpp v133, v128 row_ror:2 row_mask:0xf bank_mask:0xf
	v_add_f32_e32 v93, 1.0, v93
	v_rcp_f32_e32 v93, v93
	v_mov_b32_dpp v132, v126 row_ror:2 row_mask:0xf bank_mask:0xf
	v_mov_b32_dpp v133, v120 row_shr:2 row_mask:0xf bank_mask:0xf
	v_mul_f32_e32 v93, v131, v93
	v_mul_f32_e32 v93, v130, v93
	v_mov_b32_e32 v131, v1
	v_mov_b32_e32 v130, v1
	v_mov_b32_dpp v132, v118 row_shr:2 row_mask:0xf bank_mask:0xf
	v_mov_b32_dpp v131, v128 row_ror:1 row_mask:0xf bank_mask:0xf
	v_mov_b32_dpp v130, v126 row_ror:1 row_mask:0xf bank_mask:0xf
	v_pk_fma_f32 v[132:133], v[50:51], v[132:133], v[52:53]
	v_mov_b32_dpp v131, v120 row_shr:1 row_mask:0xf bank_mask:0xf
	v_mov_b32_dpp v130, v118 row_shr:1 row_mask:0xf bank_mask:0xf
	v_pk_fma_f32 v[130:131], v[54:55], v[130:131], v[132:133]
	v_mov_b32_e32 v132, v118
	v_mov_b32_e32 v133, v120
	v_pk_fma_f32 v[130:131], v[132:133], v[56:57], v[130:131]
	v_mov_b32_e32 v133, v1
	v_mul_f32_e32 v95, 0xbfb8aa3b, v131
	v_exp_f32_e32 v95, v95
	v_mov_b32_e32 v132, v1
	v_mov_b32_dpp v133, v129 row_ror:2 row_mask:0xf bank_mask:0xf
	v_mov_b32_e32 v128, v119
	v_add_f32_e32 v95, 1.0, v95
	v_rcp_f32_e32 v95, v95
	v_mov_b32_dpp v132, v127 row_ror:2 row_mask:0xf bank_mask:0xf
	v_mov_b32_dpp v133, v121 row_shr:2 row_mask:0xf bank_mask:0xf
	v_mul_f32_e32 v95, v131, v95
	v_mul_f32_e32 v95, v130, v95
	v_mov_b32_e32 v131, v1
	v_mov_b32_e32 v130, v1
	v_mov_b32_dpp v132, v119 row_shr:2 row_mask:0xf bank_mask:0xf
	v_mov_b32_dpp v131, v129 row_ror:1 row_mask:0xf bank_mask:0xf
	v_mov_b32_dpp v130, v127 row_ror:1 row_mask:0xf bank_mask:0xf
	v_pk_fma_f32 v[126:127], v[98:99], v[132:133], v[100:101]
	v_mov_b32_dpp v131, v121 row_shr:1 row_mask:0xf bank_mask:0xf
	v_mov_b32_dpp v130, v119 row_shr:1 row_mask:0xf bank_mask:0xf
	v_pk_fma_f32 v[126:127], v[102:103], v[130:131], v[126:127]
	v_mov_b32_e32 v129, v121
	v_pk_fma_f32 v[126:127], v[128:129], v[104:105], v[126:127]
	v_mov_b32_e32 v131, v1
	v_mul_f32_e32 v107, 0xbfb8aa3b, v127
	v_exp_f32_e32 v107, v107
	v_mov_b32_e32 v130, v1
	v_mov_b32_e32 v129, v1
	v_mov_b32_dpp v131, v124 row_ror:2 row_mask:0xf bank_mask:0xf
	v_add_f32_e32 v107, 1.0, v107
	v_rcp_f32_e32 v107, v107
	v_mov_b32_e32 v128, v1
	v_mov_b32_dpp v130, v122 row_ror:2 row_mask:0xf bank_mask:0xf
	v_mov_b32_dpp v129, v124 row_ror:1 row_mask:0xf bank_mask:0xf
	v_mov_b32_dpp v131, v116 row_shr:2 row_mask:0xf bank_mask:0xf
	v_mov_b32_dpp v128, v122 row_ror:1 row_mask:0xf bank_mask:0xf
	v_mov_b32_dpp v130, v112 row_shr:2 row_mask:0xf bank_mask:0xf
	v_mov_b32_dpp v129, v116 row_shr:1 row_mask:0xf bank_mask:0xf
	v_mov_b32_dpp v128, v112 row_shr:1 row_mask:0xf bank_mask:0xf
	v_pk_fma_f32 v[130:131], v[34:35], v[130:131], v[36:37]
	v_mul_f32_e32 v107, v127, v107
	v_pk_fma_f32 v[128:129], v[38:39], v[128:129], v[130:131]
	v_mov_b32_e32 v130, v112
	v_mov_b32_e32 v131, v116
	v_pk_fma_f32 v[128:129], v[130:131], v[40:41], v[128:129]
	v_mul_f32_e32 v107, v126, v107
	v_cvt_pk_bf16_f32 v126, v91, v93
	v_mul_f32_e32 v91, 0xbfb8aa3b, v129
	v_exp_f32_e32 v91, v91
	v_mov_b32_e32 v131, v1
	v_mov_b32_e32 v130, v1
	v_mov_b32_e32 v124, v113
	v_add_f32_e32 v91, 1.0, v91
	v_rcp_f32_e32 v91, v91
	v_mov_b32_dpp v131, v125 row_ror:2 row_mask:0xf bank_mask:0xf
	v_mov_b32_dpp v130, v123 row_ror:2 row_mask:0xf bank_mask:0xf
	v_cvt_pk_bf16_f32 v127, v95, v107
	v_mul_f32_e32 v91, v129, v91
	v_mul_f32_e32 v91, v128, v91
	v_mov_b32_e32 v129, v1
	v_mov_b32_e32 v128, v1
	v_mov_b32_dpp v131, v117 row_shr:2 row_mask:0xf bank_mask:0xf
	v_mov_b32_dpp v129, v125 row_ror:1 row_mask:0xf bank_mask:0xf
;     __device__ __forceinline__ void operator()(f32x4 (&acc)[2][2][4][2], const Unit& u, int wr, int wc, int fr, int fq) const {
;     ...
;                 for (int m = 0; m < 4; ++m) {
;                     float og[4];
; #pragma unroll
;                     for (int j = 0; j < 4; ++j) {
;                         const float vg = acc[ai][0][m][n][j], vv = acc[ai][1][m][n][j];
;                         const float pg = (m > 0) ? acc[ai][0][m - 1][n][j] : 0.f, pv = (m > 0) ? acc[ai][1][m - 1][n][j] : 0.f;
;                         const float g1 = dppf(dppf(0.f, pg, 2), vg, 0), g2 = dppf(dppf(0.f, pg, 3), vg, 1);
;                         const float v1 = dppf(dppf(0.f, pv, 2), vv, 0), v2 = dppf(dppf(0.f, pv, 3), vv, 1);
;                         const float cgate = bg[j] + wg0[j] * g2 + wg1[j] * g1 + wg2[j] * vg;
;                         const float cval = bv[j] + wv0[j] * v2 + wv1[j] * v1 + wv2[j] * vv;
;                         og[j] = cgate * __builtin_amdgcn_rcpf(1.0f + __builtin_amdgcn_exp2f(-1.4426950408889634f * cgate)) * cval; }
;                     const unsigned long long w = (unsigned long long)cvt_pk_bf16(og[0], og[1]) | ((unsigned long long)cvt_pk_bf16(og[2], og[3]) << 32);
;                     if (m == 0) {
;                         if (fr >= 2) *(unsigned long long*)gp = w;
;                         else { *(unsigned long long*)sb = (unsigned long long)cvt_pk_bf16(acc[ai][0][0][n][0], acc[ai][0][0][n][1]) | ((unsigned long long)cvt_pk_bf16(acc[ai][0][0][n][2], acc[ai][0][0][n][3]) << 32);
;                                *(unsigned long long*)(sb + FFc) = (unsigned long long)cvt_pk_bf16(acc[ai][1][0][n][0], acc[ai][1][0][n][1]) | ((unsigned long long)cvt_pk_bf16(acc[ai][1][0][n][2], acc[ai][1][0][n][3]) << 32); }
;                     } else *(unsigned long long*)gp = w;
;                     if (m == 3 && fr >= 14) {
;                         *(unsigned long long*)hb = (unsigned long long)cvt_pk_bf16(acc[ai][0][3][n][0], acc[ai][0][3][n][1]) | ((unsigned long long)cvt_pk_bf16(acc[ai][0][3][n][2], acc[ai][0][3][n][3]) << 32);
;                         *(unsigned long long*)(hb + FFc) = (unsigned long long)cvt_pk_bf16(acc[ai][1][3][n][0], acc[ai][1][3][n][1]) | ((unsigned long long)cvt_pk_bf16(acc[ai][1][3][n][2], acc[ai][1][3][n][3]) << 32); }
;                     gp += (size_t)16 * FFc; asm volatile("" : "+v"(gp) :: "memory"); }
	v_mov_b32_dpp v128, v123 row_ror:1 row_mask:0xf bank_mask:0xf
	v_mov_b32_dpp v130, v113 row_shr:2 row_mask:0xf bank_mask:0xf
	v_mov_b32_dpp v129, v117 row_shr:1 row_mask:0xf bank_mask:0xf
	v_mov_b32_dpp v128, v113 row_shr:1 row_mask:0xf bank_mask:0xf
	v_pk_fma_f32 v[122:123], v[42:43], v[130:131], v[44:45]
	v_mov_b32_e32 v125, v117
	v_pk_fma_f32 v[122:123], v[46:47], v[128:129], v[122:123]
	global_store_dwordx2 v[134:135], v[126:127], off
	v_pk_fma_f32 v[122:123], v[124:125], v[48:49], v[122:123]
	v_mov_b32_e32 v125, v1
	v_mul_f32_e32 v93, 0xbfb8aa3b, v123
	v_exp_f32_e32 v93, v93
	v_mov_b32_e32 v124, v1
	v_mov_b32_dpp v125, v120 row_ror:2 row_mask:0xf bank_mask:0xf
	v_lshl_add_u64 v[126:127], v[134:135], 0, s[50:51]
	v_add_f32_e32 v93, 1.0, v93
	v_rcp_f32_e32 v93, v93
	v_mov_b32_dpp v124, v118 row_ror:2 row_mask:0xf bank_mask:0xf
	v_mov_b32_dpp v125, v114 row_shr:2 row_mask:0xf bank_mask:0xf
	v_mul_f32_e32 v93, v123, v93
	v_mul_f32_e32 v93, v122, v93
	v_mov_b32_e32 v123, v1
	v_mov_b32_e32 v122, v1
	v_mov_b32_dpp v124, v110 row_shr:2 row_mask:0xf bank_mask:0xf
	v_mov_b32_dpp v123, v120 row_ror:1 row_mask:0xf bank_mask:0xf
	v_mov_b32_dpp v122, v118 row_ror:1 row_mask:0xf bank_mask:0xf
	v_pk_fma_f32 v[124:125], v[50:51], v[124:125], v[52:53]
	v_mov_b32_dpp v123, v114 row_shr:1 row_mask:0xf bank_mask:0xf
	v_mov_b32_dpp v122, v110 row_shr:1 row_mask:0xf bank_mask:0xf
	v_pk_fma_f32 v[122:123], v[54:55], v[122:123], v[124:125]
	v_mov_b32_e32 v124, v110
	v_mov_b32_e32 v125, v114
	v_pk_fma_f32 v[122:123], v[124:125], v[56:57], v[122:123]
	v_mov_b32_e32 v125, v1
	v_mul_f32_e32 v95, 0xbfb8aa3b, v123
	v_exp_f32_e32 v95, v95
	v_mov_b32_e32 v124, v1
	v_mov_b32_dpp v125, v121 row_ror:2 row_mask:0xf bank_mask:0xf
	v_mov_b32_e32 v120, v111
	v_add_f32_e32 v95, 1.0, v95
	v_rcp_f32_e32 v95, v95
	v_mov_b32_dpp v124, v119 row_ror:2 row_mask:0xf bank_mask:0xf
	v_mov_b32_dpp v125, v115 row_shr:2 row_mask:0xf bank_mask:0xf
	v_mul_f32_e32 v95, v123, v95
	v_mul_f32_e32 v95, v122, v95
	v_mov_b32_e32 v123, v1
	v_mov_b32_e32 v122, v1
	v_mov_b32_dpp v124, v111 row_shr:2 row_mask:0xf bank_mask:0xf
	v_mov_b32_dpp v123, v121 row_ror:1 row_mask:0xf bank_mask:0xf
	v_mov_b32_dpp v122, v119 row_ror:1 row_mask:0xf bank_mask:0xf
	v_pk_fma_f32 v[118:119], v[98:99], v[124:125], v[100:101]
	v_mov_b32_dpp v123, v115 row_shr:1 row_mask:0xf bank_mask:0xf
	v_mov_b32_dpp v122, v111 row_shr:1 row_mask:0xf bank_mask:0xf
	v_pk_fma_f32 v[118:119], v[102:103], v[122:123], v[118:119]
	v_mov_b32_e32 v121, v115
	v_pk_fma_f32 v[118:119], v[120:121], v[104:105], v[118:119]
	s_nop 0
	v_mul_f32_e32 v107, 0xbfb8aa3b, v119
	v_exp_f32_e32 v107, v107
	s_nop 0
	v_add_f32_e32 v107, 1.0, v107
	v_rcp_f32_e32 v107, v107
	s_nop 0
	v_mul_f32_e32 v107, v119, v107
	v_mul_f32_e32 v107, v118, v107
	v_cvt_pk_bf16_f32 v118, v91, v93
	v_cvt_pk_bf16_f32 v119, v95, v107
	global_store_dwordx2 v[126:127], v[118:119], off
	s_and_saveexec_b64 s[0:1], s[8:9]
	s_cbranch_execz .LBB0_1368
	v_cvt_pk_bf16_f32 v116, v116, v117
	v_cvt_pk_bf16_f32 v117, v114, v115
	global_store_dwordx2 v[108:109], v[116:117], off
	v_cvt_pk_bf16_f32 v112, v112, v113
	v_cvt_pk_bf16_f32 v113, v110, v111
	v_add_co_u32_e32 v110, vcc, 0x1000, v108
	s_nop 1
	v_addc_co_u32_e32 v111, vcc, 0, v109, vcc
	global_store_dwordx2 v[110:111], v[112:113], off offset:1536
.LBB0_1368:
	s_or_b64 exec, exec, s[0:1]
	v_mov_b32_e32 v107, v106
	v_mov_b32_e32 v112, v106
	v_mov_b32_e32 v113, v106
	v_pk_mul_f32 v[110:111], v[30:31], v[106:107]
	v_pk_mul_f32 v[106:107], v[26:27], v[106:107]
	v_lshl_add_u64 v[26:27], v[126:127], 0, s[50:51]
	v_mov_b32_e32 v95, v1
	v_mov_b32_e32 v91, v1
	v_pk_mul_f32 v[32:33], v[32:33], v[112:113]
	v_mov_b32_dpp v95, v95 row_ror:2 row_mask:0xf bank_mask:0xf
	v_pk_mul_f32 v[30:31], v[28:29], v[112:113]
	v_lshl_add_u64 v[112:113], v[26:27], 0, s[52:53]
	v_lshl_add_u64 v[26:27], v[96:97], 0, s[54:55]
	v_mov_b32_dpp v91, v91 row_ror:1 row_mask:0xf bank_mask:0xf
	v_mov_b32_e32 v96, v95
	v_mov_b32_e32 v93, v91
	v_mov_b32_e32 v97, v91
	v_mov_b32_dpp v96, v110 row_shr:2 row_mask:0xf bank_mask:0xf
	v_mov_b32_dpp v93, v110 row_shr:1 row_mask:0xf bank_mask:0xf
	v_fma_f32 v58, v58, v96, v82
	v_fmac_f32_e32 v58, v66, v93
	v_fmac_f32_e32 v58, v110, v74
	v_mul_f32_e32 v66, 0xbfb8aa3b, v58
	v_exp_f32_e32 v66, v66
	v_mov_b32_e32 v74, v95
	v_mov_b32_dpp v97, v106 row_shr:1 row_mask:0xf bank_mask:0xf
	v_lshl_add_u64 v[28:29], v[108:109], 0, s[54:55]
	v_add_f32_e32 v66, 1.0, v66
	v_rcp_f32_e32 v66, v66
	v_mov_b32_dpp v74, v106 row_shr:2 row_mask:0xf bank_mask:0xf
	v_fma_f32 v62, v62, v74, v86
	v_fmac_f32_e32 v62, v70, v97
	v_fmac_f32_e32 v62, v106, v78
	v_mul_f32_e32 v58, v58, v66
	v_mov_b32_e32 v66, v95
	v_mul_f32_e32 v58, v62, v58
	v_mov_b32_e32 v62, v91
	v_mov_b32_dpp v66, v111 row_shr:2 row_mask:0xf bank_mask:0xf
	v_fma_f32 v59, v59, v66, v83
	v_mov_b32_dpp v62, v111 row_shr:1 row_mask:0xf bank_mask:0xf
	v_fmac_f32_e32 v59, v67, v62
	v_fmac_f32_e32 v59, v111, v75
	v_mul_f32_e32 v62, 0xbfb8aa3b, v59
	v_exp_f32_e32 v62, v62
	v_mov_b32_e32 v66, v95
	v_mov_b32_e32 v70, v91
	v_add_f32_e32 v62, 1.0, v62
	v_rcp_f32_e32 v62, v62
	v_mov_b32_dpp v66, v107 row_shr:2 row_mask:0xf bank_mask:0xf
	v_mov_b32_dpp v70, v107 row_shr:1 row_mask:0xf bank_mask:0xf
	v_fma_f32 v63, v63, v66, v87
	v_fmac_f32_e32 v63, v71, v70
	v_fmac_f32_e32 v63, v107, v79
	v_mul_f32_e32 v59, v59, v62
	v_mul_f32_e32 v59, v63, v59
	v_mov_b32_e32 v63, v95
	v_mov_b32_e32 v62, v91
	v_mov_b32_e32 v66, v91
	v_mov_b32_dpp v63, v32 row_shr:2 row_mask:0xf bank_mask:0xf
	v_mov_b32_dpp v62, v32 row_shr:1 row_mask:0xf bank_mask:0xf
	v_fma_f32 v60, v60, v63, v84
	v_fmac_f32_e32 v60, v68, v62
	v_fmac_f32_e32 v60, v32, v76
	v_mul_f32_e32 v62, 0xbfb8aa3b, v60
	v_exp_f32_e32 v62, v62
	v_mov_b32_e32 v63, v95
	v_mov_b32_dpp v66, v30 row_shr:1 row_mask:0xf bank_mask:0xf
	v_cvt_pk_bf16_f32 v58, v58, v59
	v_add_f32_e32 v62, 1.0, v62
	v_rcp_f32_e32 v62, v62
	v_mov_b32_dpp v63, v30 row_shr:2 row_mask:0xf bank_mask:0xf
	v_fma_f32 v63, v64, v63, v88
	v_mov_b32_e32 v64, v95
	v_mul_f32_e32 v60, v60, v62
	v_mov_b32_e32 v62, v91
	v_mov_b32_dpp v64, v33 row_shr:2 row_mask:0xf bank_mask:0xf
	v_fmac_f32_e32 v85, v61, v64
	v_mov_b32_dpp v62, v33 row_shr:1 row_mask:0xf bank_mask:0xf
	v_fmac_f32_e32 v85, v69, v62
	v_fmac_f32_e32 v85, v33, v77
	v_mul_f32_e32 v61, 0xbfb8aa3b, v85
	v_exp_f32_e32 v61, v61
	v_mov_b32_dpp v95, v31 row_shr:2 row_mask:0xf bank_mask:0xf
	v_mov_b32_dpp v91, v31 row_shr:1 row_mask:0xf bank_mask:0xf
	v_fmac_f32_e32 v89, v65, v95
	v_add_f32_e32 v61, 1.0, v61
	v_rcp_f32_e32 v61, v61
	v_fmac_f32_e32 v63, v72, v66
	v_fmac_f32_e32 v89, v73, v91
	v_fmac_f32_e32 v63, v30, v80
	v_fmac_f32_e32 v89, v31, v81
	v_mul_f32_e32 v61, v85, v61
	v_mul_f32_e32 v60, v63, v60
	v_mul_f32_e32 v61, v89, v61
	v_cvt_pk_bf16_f32 v59, v60, v61
	s_and_saveexec_b64 s[0:1], s[6:7]
	s_xor_b64 s[0:1], exec, s[0:1]
	s_cbranch_execz .LBB0_1370
; __device__ __forceinline__ unsigned cvt_pk_bf16(float lo, float hi) { unsigned r; asm volatile("v_cvt_pk_bf16_f32 %0, %1, %2" : "=v"(r) : "v"(lo), "v"(hi)); return r; }
;     __device__ __forceinline__ void operator()(f32x4 (&acc)[2][2][4][2], const Unit& u, int wr, int wc, int fr, int fq) const {
;     ...
;                     if (m == 0) {
;                         if (fr >= 2) *(unsigned long long*)gp = w;
;                         else { *(unsigned long long*)sb = (unsigned long long)cvt_pk_bf16(acc[ai][0][0][n][0], acc[ai][0][0][n][1]) | ((unsigned long long)cvt_pk_bf16(acc[ai][0][0][n][2], acc[ai][0][0][n][3]) << 32);
;                                *(unsigned long long*)(sb + FFc) = (unsigned long long)cvt_pk_bf16(acc[ai][1][0][n][0], acc[ai][1][0][n][1]) | ((unsigned long long)cvt_pk_bf16(acc[ai][1][0][n][2], acc[ai][1][0][n][3]) << 32); }
;                     } else *(unsigned long long*)gp = w;
;                     if (m == 3 && fr >= 14) {
;                         *(unsigned long long*)hb = (unsigned long long)cvt_pk_bf16(acc[ai][0][3][n][0], acc[ai][0][3][n][1]) | ((unsigned long long)cvt_pk_bf16(acc[ai][0][3][n][2], acc[ai][0][3][n][3]) << 32);
;                         *(unsigned long long*)(hb + FFc) = (unsigned long long)cvt_pk_bf16(acc[ai][1][3][n][0], acc[ai][1][3][n][1]) | ((unsigned long long)cvt_pk_bf16(acc[ai][1][3][n][2], acc[ai][1][3][n][3]) << 32); }
;                     gp += (size_t)16 * FFc; asm volatile("" : "+v"(gp) :: "memory"); }
	v_cvt_pk_bf16_f32 v58, v110, v111
	v_cvt_pk_bf16_f32 v59, v32, v33
	v_add_co_u32_e32 v60, vcc, 0x1000, v26
	global_store_dwordx2 v[26:27], v[58:59], off
	v_cvt_pk_bf16_f32 v58, v106, v107
	v_cvt_pk_bf16_f32 v59, v30, v31
	s_nop 0
	v_addc_co_u32_e32 v61, vcc, 0, v27, vcc
	global_store_dwordx2 v[60:61], v[58:59], off offset:1536
.LBB0_1370:
	s_andn2_saveexec_b64 s[0:1], s[0:1]
	s_cbranch_execz .LBB0_1372
	global_store_dwordx2 v[112:113], v[58:59], off
.LBB0_1372:
	s_or_b64 exec, exec, s[0:1]
	v_mov_b32_e32 v91, v90
	v_mov_b32_e32 v58, v90
	v_mov_b32_e32 v59, v90
	v_mov_b32_e32 v93, v92
	v_pk_mul_f32 v[24:25], v[24:25], v[58:59]
	v_pk_mul_f32 v[60:61], v[22:23], v[90:91]
	v_pk_mul_f32 v[22:23], v[16:17], v[58:59]
	v_pk_mul_f32 v[58:59], v[14:15], v[90:91]
	v_mov_b32_e32 v14, v92
	v_mov_b32_e32 v15, v92
	v_mov_b32_e32 v62, v94
	v_mov_b32_e32 v63, v94
	v_mov_b32_e32 v95, v94
	v_pk_mul_f32 v[16:17], v[20:21], v[14:15]
	v_pk_mul_f32 v[20:21], v[18:19], v[92:93]
	v_pk_mul_f32 v[18:19], v[6:7], v[92:93]
	v_pk_mul_f32 v[6:7], v[12:13], v[62:63]
	v_mov_b32_e32 v13, v1
	v_mov_b32_e32 v12, v1
	v_pk_mul_f32 v[14:15], v[8:9], v[14:15]
	v_pk_mul_f32 v[8:9], v[10:11], v[94:95]
	v_mov_b32_e32 v11, v1
	v_mov_b32_dpp v13, v110 row_ror:2 row_mask:0xf bank_mask:0xf
	v_mov_b32_e32 v10, v1
	v_mov_b32_dpp v12, v106 row_ror:2 row_mask:0xf bank_mask:0xf
	v_mov_b32_dpp v11, v110 row_ror:1 row_mask:0xf bank_mask:0xf
	v_mov_b32_dpp v13, v60 row_shr:2 row_mask:0xf bank_mask:0xf
	v_mov_b32_dpp v10, v106 row_ror:1 row_mask:0xf bank_mask:0xf
	v_mov_b32_dpp v12, v58 row_shr:2 row_mask:0xf bank_mask:0xf
	v_mov_b32_dpp v11, v60 row_shr:1 row_mask:0xf bank_mask:0xf
	v_mov_b32_dpp v10, v58 row_shr:1 row_mask:0xf bank_mask:0xf
	v_pk_fma_f32 v[12:13], v[34:35], v[12:13], v[36:37]
	v_pk_mul_f32 v[4:5], v[4:5], v[62:63]
	v_pk_fma_f32 v[10:11], v[38:39], v[10:11], v[12:13]
	v_mov_b32_e32 v12, v58
	v_mov_b32_e32 v13, v60
	v_pk_fma_f32 v[10:11], v[12:13], v[40:41], v[10:11]
	v_mov_b32_e32 v65, v1
	v_mul_f32_e32 v12, 0xbfb8aa3b, v11
	v_exp_f32_e32 v64, v12
	v_mov_b32_e32 v63, v1
	v_mov_b32_dpp v65, v111 row_ror:2 row_mask:0xf bank_mask:0xf
	v_mov_b32_e32 v67, v1
	v_add_f32_e32 v62, 1.0, v64
	v_mov_b32_e32 v64, v1
	v_rcp_f32_e32 v66, v62
	v_mov_b32_e32 v62, v1
	v_mov_b32_dpp v64, v107 row_ror:2 row_mask:0xf bank_mask:0xf
	v_mov_b32_dpp v63, v111 row_ror:1 row_mask:0xf bank_mask:0xf
	v_mov_b32_dpp v65, v61 row_shr:2 row_mask:0xf bank_mask:0xf
	v_mov_b32_dpp v62, v107 row_ror:1 row_mask:0xf bank_mask:0xf
	v_mov_b32_dpp v64, v59 row_shr:2 row_mask:0xf bank_mask:0xf
	v_mov_b32_dpp v63, v61 row_shr:1 row_mask:0xf bank_mask:0xf
	v_mov_b32_dpp v62, v59 row_shr:1 row_mask:0xf bank_mask:0xf
	v_pk_fma_f32 v[64:65], v[42:43], v[64:65], v[44:45]
	v_mul_f32_e32 v11, v11, v66
	v_pk_fma_f32 v[62:63], v[46:47], v[62:63], v[64:65]
	v_mov_b32_e32 v64, v59
	v_mov_b32_e32 v65, v61
	v_pk_fma_f32 v[62:63], v[64:65], v[48:49], v[62:63]
	v_mul_f32_e32 v68, v10, v11
	v_mul_f32_e32 v64, 0xbfb8aa3b, v63
	v_exp_f32_e32 v64, v64
	v_mov_b32_e32 v65, v1
	v_mov_b32_e32 v11, v1
	v_mov_b32_e32 v66, v1
	v_add_f32_e32 v10, 1.0, v64
	v_mov_b32_e32 v64, v1
	v_rcp_f32_e32 v69, v10
	v_mov_b32_dpp v65, v32 row_ror:2 row_mask:0xf bank_mask:0xf
	v_mov_b32_e32 v10, v1
	v_mov_b32_dpp v64, v30 row_ror:2 row_mask:0xf bank_mask:0xf
	v_mov_b32_dpp v11, v32 row_ror:1 row_mask:0xf bank_mask:0xf
	v_mov_b32_dpp v65, v24 row_shr:2 row_mask:0xf bank_mask:0xf
	v_mov_b32_dpp v10, v30 row_ror:1 row_mask:0xf bank_mask:0xf
	v_mov_b32_dpp v64, v22 row_shr:2 row_mask:0xf bank_mask:0xf
	v_mov_b32_dpp v11, v24 row_shr:1 row_mask:0xf bank_mask:0xf
	v_mov_b32_dpp v10, v22 row_shr:1 row_mask:0xf bank_mask:0xf
	v_pk_fma_f32 v[64:65], v[50:51], v[64:65], v[52:53]
	v_mov_b32_dpp v67, v33 row_ror:2 row_mask:0xf bank_mask:0xf
	v_pk_fma_f32 v[10:11], v[54:55], v[10:11], v[64:65]
	v_mov_b32_e32 v64, v22
	v_mov_b32_e32 v65, v24
	v_pk_fma_f32 v[10:11], v[64:65], v[56:57], v[10:11]
	v_mov_b32_e32 v65, v1
	v_mov_b32_e32 v64, v1
	v_mov_b32_dpp v66, v31 row_ror:2 row_mask:0xf bank_mask:0xf
	v_mul_f32_e32 v30, 0xbfb8aa3b, v11
	v_mov_b32_dpp v65, v33 row_ror:1 row_mask:0xf bank_mask:0xf
	v_mov_b32_dpp v67, v25 row_shr:2 row_mask:0xf bank_mask:0xf
	v_mov_b32_dpp v64, v31 row_ror:1 row_mask:0xf bank_mask:0xf
	v_mov_b32_dpp v66, v23 row_shr:2 row_mask:0xf bank_mask:0xf
	v_exp_f32_e32 v70, v30
	v_mov_b32_dpp v65, v25 row_shr:1 row_mask:0xf bank_mask:0xf
	v_mov_b32_dpp v64, v23 row_shr:1 row_mask:0xf bank_mask:0xf
	v_pk_fma_f32 v[30:31], v[98:99], v[66:67], v[100:101]
	v_mov_b32_e32 v32, v23
	v_pk_fma_f32 v[30:31], v[102:103], v[64:65], v[30:31]
	v_mov_b32_e32 v33, v25
	v_pk_fma_f32 v[30:31], v[32:33], v[104:105], v[30:31]
	v_mul_f32_e32 v33, v63, v69
	v_mul_f32_e32 v32, 0xbfb8aa3b, v31
	v_exp_f32_e32 v32, v32
	v_add_f32_e32 v63, 1.0, v70
	v_rcp_f32_e32 v63, v63
	v_lshl_add_u64 v[12:13], v[112:113], 0, s[50:51]
	v_add_f32_e32 v32, 1.0, v32
	v_rcp_f32_e32 v32, v32
	v_mul_f32_e32 v11, v11, v63
	v_mul_f32_e32 v33, v62, v33
	v_mul_f32_e32 v11, v10, v11
	v_mul_f32_e32 v10, v31, v32
	v_mul_f32_e32 v62, v30, v10
	v_cvt_pk_bf16_f32 v10, v68, v33
	v_mov_b32_e32 v33, v1
	v_mov_b32_e32 v32, v1
	v_mov_b32_e32 v31, v1
	v_mov_b32_dpp v33, v60 row_ror:2 row_mask:0xf bank_mask:0xf
	v_mov_b32_e32 v30, v1
	v_mov_b32_dpp v32, v58 row_ror:2 row_mask:0xf bank_mask:0xf
	v_mov_b32_dpp v31, v60 row_ror:1 row_mask:0xf bank_mask:0xf
	v_mov_b32_dpp v33, v20 row_shr:2 row_mask:0xf bank_mask:0xf
	v_mov_b32_dpp v30, v58 row_ror:1 row_mask:0xf bank_mask:0xf
	v_mov_b32_dpp v32, v18 row_shr:2 row_mask:0xf bank_mask:0xf
	v_mov_b32_dpp v31, v20 row_shr:1 row_mask:0xf bank_mask:0xf
;     __device__ __forceinline__ void operator()(f32x4 (&acc)[2][2][4][2], const Unit& u, int wr, int wc, int fr, int fq) const {
;     ...
;                 for (int m = 0; m < 4; ++m) {
;                     float og[4];
; #pragma unroll
;                     for (int j = 0; j < 4; ++j) {
;                         const float vg = acc[ai][0][m][n][j], vv = acc[ai][1][m][n][j];
;                         const float pg = (m > 0) ? acc[ai][0][m - 1][n][j] : 0.f, pv = (m > 0) ? acc[ai][1][m - 1][n][j] : 0.f;
;                         const float g1 = dppf(dppf(0.f, pg, 2), vg, 0), g2 = dppf(dppf(0.f, pg, 3), vg, 1);
;                         const float v1 = dppf(dppf(0.f, pv, 2), vv, 0), v2 = dppf(dppf(0.f, pv, 3), vv, 1);
;                         const float cgate = bg[j] + wg0[j] * g2 + wg1[j] * g1 + wg2[j] * vg;
;                         const float cval = bv[j] + wv0[j] * v2 + wv1[j] * v1 + wv2[j] * vv;
;                         og[j] = cgate * __builtin_amdgcn_rcpf(1.0f + __builtin_amdgcn_exp2f(-1.4426950408889634f * cgate)) * cval; }
;                     const unsigned long long w = (unsigned long long)cvt_pk_bf16(og[0], og[1]) | ((unsigned long long)cvt_pk_bf16(og[2], og[3]) << 32);
;                     if (m == 0) {
;                         if (fr >= 2) *(unsigned long long*)gp = w;
;                         else { *(unsigned long long*)sb = (unsigned long long)cvt_pk_bf16(acc[ai][0][0][n][0], acc[ai][0][0][n][1]) | ((unsigned long long)cvt_pk_bf16(acc[ai][0][0][n][2], acc[ai][0][0][n][3]) << 32);
;                                *(unsigned long long*)(sb + FFc) = (unsigned long long)cvt_pk_bf16(acc[ai][1][0][n][0], acc[ai][1][0][n][1]) | ((unsigned long long)cvt_pk_bf16(acc[ai][1][0][n][2], acc[ai][1][0][n][3]) << 32); }
;                     } else *(unsigned long long*)gp = w;
;                     if (m == 3 && fr >= 14) {
;                         *(unsigned long long*)hb = (unsigned long long)cvt_pk_bf16(acc[ai][0][3][n][0], acc[ai][0][3][n][1]) | ((unsigned long long)cvt_pk_bf16(acc[ai][0][3][n][2], acc[ai][0][3][n][3]) << 32);
;                         *(unsigned long long*)(hb + FFc) = (unsigned long long)cvt_pk_bf16(acc[ai][1][3][n][0], acc[ai][1][3][n][1]) | ((unsigned long long)cvt_pk_bf16(acc[ai][1][3][n][2], acc[ai][1][3][n][3]) << 32); }
;                     gp += (size_t)16 * FFc; asm volatile("" : "+v"(gp) :: "memory"); }
	v_mov_b32_dpp v30, v18 row_shr:1 row_mask:0xf bank_mask:0xf
	v_pk_fma_f32 v[32:33], v[34:35], v[32:33], v[36:37]
	v_cvt_pk_bf16_f32 v11, v11, v62
	global_store_dwordx2 v[12:13], v[10:11], off
	v_pk_fma_f32 v[30:31], v[38:39], v[30:31], v[32:33]
	v_mov_b32_e32 v32, v18
	v_mov_b32_e32 v33, v20
	v_pk_fma_f32 v[30:31], v[32:33], v[40:41], v[30:31]
	v_lshl_add_u64 v[10:11], v[12:13], 0, s[50:51]
	v_mul_f32_e32 v32, 0xbfb8aa3b, v31
	v_exp_f32_e32 v32, v32
	v_mov_b32_e32 v33, v1
	v_mov_b32_e32 v13, v1
	v_pk_mul_f32 v[2:3], v[2:3], v[94:95]
	v_add_f32_e32 v12, 1.0, v32
	v_mov_b32_e32 v32, v1
	v_rcp_f32_e32 v58, v12
	v_mov_b32_dpp v33, v61 row_ror:2 row_mask:0xf bank_mask:0xf
	v_mov_b32_e32 v12, v1
	v_mov_b32_dpp v32, v59 row_ror:2 row_mask:0xf bank_mask:0xf
	v_mov_b32_dpp v13, v61 row_ror:1 row_mask:0xf bank_mask:0xf
	v_mov_b32_dpp v33, v21 row_shr:2 row_mask:0xf bank_mask:0xf
	v_mov_b32_dpp v12, v59 row_ror:1 row_mask:0xf bank_mask:0xf
	v_mov_b32_dpp v32, v19 row_shr:2 row_mask:0xf bank_mask:0xf
	v_mov_b32_dpp v13, v21 row_shr:1 row_mask:0xf bank_mask:0xf
	v_mov_b32_dpp v12, v19 row_shr:1 row_mask:0xf bank_mask:0xf
	v_pk_fma_f32 v[32:33], v[42:43], v[32:33], v[44:45]
	v_mul_f32_e32 v31, v31, v58
	v_pk_fma_f32 v[12:13], v[46:47], v[12:13], v[32:33]
	v_mov_b32_e32 v32, v19
	v_mov_b32_e32 v33, v21
	v_pk_fma_f32 v[12:13], v[32:33], v[48:49], v[12:13]
	v_mul_f32_e32 v60, v30, v31
	v_mul_f32_e32 v32, 0xbfb8aa3b, v13
	v_exp_f32_e32 v32, v32
	v_mov_b32_e32 v33, v1
	v_mov_b32_e32 v31, v1
	v_mov_b32_e32 v59, v1
	v_add_f32_e32 v30, 1.0, v32
	v_mov_b32_e32 v32, v1
	v_rcp_f32_e32 v61, v30
	v_mov_b32_dpp v33, v24 row_ror:2 row_mask:0xf bank_mask:0xf
	v_mov_b32_e32 v30, v1
	v_mov_b32_dpp v32, v22 row_ror:2 row_mask:0xf bank_mask:0xf
	v_mov_b32_dpp v31, v24 row_ror:1 row_mask:0xf bank_mask:0xf
	v_mov_b32_dpp v33, v16 row_shr:2 row_mask:0xf bank_mask:0xf
	v_mov_b32_dpp v30, v22 row_ror:1 row_mask:0xf bank_mask:0xf
	v_mov_b32_dpp v32, v14 row_shr:2 row_mask:0xf bank_mask:0xf
	v_mov_b32_dpp v31, v16 row_shr:1 row_mask:0xf bank_mask:0xf
	v_mov_b32_dpp v30, v14 row_shr:1 row_mask:0xf bank_mask:0xf
	v_pk_fma_f32 v[32:33], v[50:51], v[32:33], v[52:53]
	v_mov_b32_e32 v58, v1
	v_pk_fma_f32 v[30:31], v[54:55], v[30:31], v[32:33]
	v_mov_b32_e32 v32, v14
	v_mov_b32_e32 v33, v16
	v_pk_fma_f32 v[30:31], v[32:33], v[56:57], v[30:31]
	v_mov_b32_e32 v33, v1
	v_mov_b32_dpp v59, v25 row_ror:2 row_mask:0xf bank_mask:0xf
	v_mov_b32_e32 v32, v1
	v_mov_b32_dpp v58, v23 row_ror:2 row_mask:0xf bank_mask:0xf
	v_mul_f32_e32 v22, 0xbfb8aa3b, v31
	v_mov_b32_dpp v33, v25 row_ror:1 row_mask:0xf bank_mask:0xf
	v_mov_b32_dpp v59, v17 row_shr:2 row_mask:0xf bank_mask:0xf
	v_mov_b32_dpp v32, v23 row_ror:1 row_mask:0xf bank_mask:0xf
	v_mov_b32_dpp v58, v15 row_shr:2 row_mask:0xf bank_mask:0xf
	v_exp_f32_e32 v62, v22
	v_mov_b32_dpp v33, v17 row_shr:1 row_mask:0xf bank_mask:0xf
	v_mov_b32_dpp v32, v15 row_shr:1 row_mask:0xf bank_mask:0xf
	v_pk_fma_f32 v[22:23], v[98:99], v[58:59], v[100:101]
	v_mov_b32_e32 v24, v15
	v_pk_fma_f32 v[22:23], v[102:103], v[32:33], v[22:23]
	v_mov_b32_e32 v25, v17
	v_pk_fma_f32 v[22:23], v[24:25], v[104:105], v[22:23]
	v_add_f32_e32 v25, 1.0, v62
	v_mul_f32_e32 v24, 0xbfb8aa3b, v23
	v_exp_f32_e32 v24, v24
	v_rcp_f32_e32 v25, v25
	v_mul_f32_e32 v13, v13, v61
	v_mul_f32_e32 v12, v12, v13
	v_add_f32_e32 v24, 1.0, v24
	v_rcp_f32_e32 v24, v24
	v_mul_f32_e32 v13, v31, v25
	v_mov_b32_e32 v25, v1
	v_mul_f32_e32 v13, v30, v13
	v_mul_f32_e32 v23, v23, v24
	v_mov_b32_e32 v24, v1
	v_mul_f32_e32 v30, v22, v23
	v_mov_b32_e32 v23, v1
	v_mov_b32_dpp v25, v20 row_ror:2 row_mask:0xf bank_mask:0xf
	v_mov_b32_e32 v22, v1
	v_mov_b32_dpp v24, v18 row_ror:2 row_mask:0xf bank_mask:0xf
	v_mov_b32_dpp v23, v20 row_ror:1 row_mask:0xf bank_mask:0xf
	v_mov_b32_dpp v25, v8 row_shr:2 row_mask:0xf bank_mask:0xf
	v_mov_b32_dpp v22, v18 row_ror:1 row_mask:0xf bank_mask:0xf
	v_mov_b32_dpp v24, v2 row_shr:2 row_mask:0xf bank_mask:0xf
;     __device__ __forceinline__ void operator()(f32x4 (&acc)[2][2][4][2], const Unit& u, int wr, int wc, int fr, int fq) const {
;     ...
;                 for (int m = 0; m < 4; ++m) {
;                     float og[4];
; #pragma unroll
;                     for (int j = 0; j < 4; ++j) {
;                         const float vg = acc[ai][0][m][n][j], vv = acc[ai][1][m][n][j];
;                         const float pg = (m > 0) ? acc[ai][0][m - 1][n][j] : 0.f, pv = (m > 0) ? acc[ai][1][m - 1][n][j] : 0.f;
;                         const float g1 = dppf(dppf(0.f, pg, 2), vg, 0), g2 = dppf(dppf(0.f, pg, 3), vg, 1);
;                         const float v1 = dppf(dppf(0.f, pv, 2), vv, 0), v2 = dppf(dppf(0.f, pv, 3), vv, 1);
;                         const float cgate = bg[j] + wg0[j] * g2 + wg1[j] * g1 + wg2[j] * vg;
;                         const float cval = bv[j] + wv0[j] * v2 + wv1[j] * v1 + wv2[j] * vv;
;                         og[j] = cgate * __builtin_amdgcn_rcpf(1.0f + __builtin_amdgcn_exp2f(-1.4426950408889634f * cgate)) * cval; }
;                     const unsigned long long w = (unsigned long long)cvt_pk_bf16(og[0], og[1]) | ((unsigned long long)cvt_pk_bf16(og[2], og[3]) << 32);
;                     if (m == 0) {
;                         if (fr >= 2) *(unsigned long long*)gp = w;
;                         else { *(unsigned long long*)sb = (unsigned long long)cvt_pk_bf16(acc[ai][0][0][n][0], acc[ai][0][0][n][1]) | ((unsigned long long)cvt_pk_bf16(acc[ai][0][0][n][2], acc[ai][0][0][n][3]) << 32);
;                                *(unsigned long long*)(sb + FFc) = (unsigned long long)cvt_pk_bf16(acc[ai][1][0][n][0], acc[ai][1][0][n][1]) | ((unsigned long long)cvt_pk_bf16(acc[ai][1][0][n][2], acc[ai][1][0][n][3]) << 32); }
;                     } else *(unsigned long long*)gp = w;
;                     if (m == 3 && fr >= 14) {
;                         *(unsigned long long*)hb = (unsigned long long)cvt_pk_bf16(acc[ai][0][3][n][0], acc[ai][0][3][n][1]) | ((unsigned long long)cvt_pk_bf16(acc[ai][0][3][n][2], acc[ai][0][3][n][3]) << 32);
;                         *(unsigned long long*)(hb + FFc) = (unsigned long long)cvt_pk_bf16(acc[ai][1][3][n][0], acc[ai][1][3][n][1]) | ((unsigned long long)cvt_pk_bf16(acc[ai][1][3][n][2], acc[ai][1][3][n][3]) << 32); }
;                     gp += (size_t)16 * FFc; asm volatile("" : "+v"(gp) :: "memory"); }
	v_mov_b32_dpp v23, v8 row_shr:1 row_mask:0xf bank_mask:0xf
	v_mov_b32_dpp v22, v2 row_shr:1 row_mask:0xf bank_mask:0xf
	v_pk_fma_f32 v[24:25], v[34:35], v[24:25], v[36:37]
	v_cvt_pk_bf16_f32 v12, v60, v12
	v_cvt_pk_bf16_f32 v13, v13, v30
	global_store_dwordx2 v[10:11], v[12:13], off
	v_pk_fma_f32 v[22:23], v[38:39], v[22:23], v[24:25]
	v_mov_b32_e32 v24, v2
	v_mov_b32_e32 v25, v8
	v_pk_fma_f32 v[22:23], v[24:25], v[40:41], v[22:23]
	v_mov_b32_e32 v25, v1
	v_mul_f32_e32 v18, 0xbfb8aa3b, v23
	v_exp_f32_e32 v18, v18
	v_mov_b32_e32 v24, v1
	v_mov_b32_e32 v13, v1
	v_mov_b32_dpp v25, v21 row_ror:2 row_mask:0xf bank_mask:0xf
	v_add_f32_e32 v12, 1.0, v18
	v_rcp_f32_e32 v20, v12
	v_mov_b32_e32 v12, v1
	v_mov_b32_dpp v24, v19 row_ror:2 row_mask:0xf bank_mask:0xf
	v_mov_b32_dpp v13, v21 row_ror:1 row_mask:0xf bank_mask:0xf
	v_mov_b32_dpp v25, v9 row_shr:2 row_mask:0xf bank_mask:0xf
	v_mov_b32_dpp v12, v19 row_ror:1 row_mask:0xf bank_mask:0xf
	v_mov_b32_dpp v24, v3 row_shr:2 row_mask:0xf bank_mask:0xf
	v_mov_b32_dpp v13, v9 row_shr:1 row_mask:0xf bank_mask:0xf
	v_mov_b32_dpp v12, v3 row_shr:1 row_mask:0xf bank_mask:0xf
	v_pk_fma_f32 v[18:19], v[42:43], v[24:25], v[44:45]
	v_mov_b32_e32 v21, v1
	v_pk_fma_f32 v[12:13], v[46:47], v[12:13], v[18:19]
	v_mov_b32_e32 v18, v3
	v_mov_b32_e32 v19, v9
	v_pk_fma_f32 v[12:13], v[18:19], v[48:49], v[12:13]
	v_mul_f32_e32 v19, v23, v20
	v_mul_f32_e32 v18, 0xbfb8aa3b, v13
	v_exp_f32_e32 v18, v18
	v_mov_b32_e32 v20, v1
	v_mul_f32_e32 v24, v22, v19
	v_mov_b32_e32 v19, v1
	v_add_f32_e32 v18, 1.0, v18
	v_rcp_f32_e32 v25, v18
	v_mov_b32_dpp v21, v16 row_ror:2 row_mask:0xf bank_mask:0xf
	v_mov_b32_e32 v18, v1
	v_mov_b32_dpp v20, v14 row_ror:2 row_mask:0xf bank_mask:0xf
	v_mov_b32_dpp v19, v16 row_ror:1 row_mask:0xf bank_mask:0xf
	v_mov_b32_dpp v21, v6 row_shr:2 row_mask:0xf bank_mask:0xf
	v_mov_b32_dpp v18, v14 row_ror:1 row_mask:0xf bank_mask:0xf
	v_mov_b32_dpp v20, v4 row_shr:2 row_mask:0xf bank_mask:0xf
	v_mov_b32_dpp v19, v6 row_shr:1 row_mask:0xf bank_mask:0xf
	v_mov_b32_dpp v18, v4 row_shr:1 row_mask:0xf bank_mask:0xf
	v_pk_fma_f32 v[20:21], v[50:51], v[20:21], v[52:53]
	v_mov_b32_e32 v23, v1
	v_pk_fma_f32 v[18:19], v[54:55], v[18:19], v[20:21]
	v_mov_b32_e32 v20, v4
	v_mov_b32_e32 v21, v6
	v_mov_b32_e32 v22, v1
	v_pk_fma_f32 v[18:19], v[20:21], v[56:57], v[18:19]
	v_mov_b32_e32 v21, v1
	v_mov_b32_dpp v23, v17 row_ror:2 row_mask:0xf bank_mask:0xf
	v_mov_b32_e32 v20, v1
	v_mov_b32_dpp v22, v15 row_ror:2 row_mask:0xf bank_mask:0xf
	v_mul_f32_e32 v14, 0xbfb8aa3b, v19
	v_mov_b32_dpp v21, v17 row_ror:1 row_mask:0xf bank_mask:0xf
	v_mov_b32_dpp v23, v7 row_shr:2 row_mask:0xf bank_mask:0xf
	v_mov_b32_dpp v20, v15 row_ror:1 row_mask:0xf bank_mask:0xf
	v_mov_b32_dpp v22, v5 row_shr:2 row_mask:0xf bank_mask:0xf
	v_exp_f32_e32 v30, v14
	v_mov_b32_dpp v21, v7 row_shr:1 row_mask:0xf bank_mask:0xf
	v_mov_b32_dpp v20, v5 row_shr:1 row_mask:0xf bank_mask:0xf
	v_pk_fma_f32 v[14:15], v[98:99], v[22:23], v[100:101]
	v_mov_b32_e32 v16, v5
	v_pk_fma_f32 v[14:15], v[102:103], v[20:21], v[14:15]
	v_mov_b32_e32 v17, v7
	v_pk_fma_f32 v[14:15], v[16:17], v[104:105], v[14:15]
	v_add_f32_e32 v17, 1.0, v30
	v_mul_f32_e32 v16, 0xbfb8aa3b, v15
	v_exp_f32_e32 v16, v16
	v_rcp_f32_e32 v17, v17
	v_mul_f32_e32 v13, v13, v25
	v_mul_f32_e32 v12, v12, v13
	v_add_f32_e32 v16, 1.0, v16
	v_rcp_f32_e32 v16, v16
	v_mul_f32_e32 v13, v19, v17
	v_lshl_add_u64 v[10:11], v[10:11], 0, s[50:51]
	v_mul_f32_e32 v13, v18, v13
	v_mul_f32_e32 v15, v15, v16
	v_mul_f32_e32 v14, v14, v15
	v_cvt_pk_bf16_f32 v12, v24, v12
	v_cvt_pk_bf16_f32 v13, v13, v14
	global_store_dwordx2 v[10:11], v[12:13], off
	s_and_saveexec_b64 s[0:1], s[8:9]
	s_cbranch_execz .LBB0_1374
	v_cvt_pk_bf16_f32 v8, v8, v9
	v_cvt_pk_bf16_f32 v9, v6, v7
	global_store_dwordx2 v[28:29], v[8:9], off
	v_cvt_pk_bf16_f32 v2, v2, v3
	v_cvt_pk_bf16_f32 v3, v4, v5
	v_add_co_u32_e32 v4, vcc, 0x1000, v28
	s_nop 1
	v_addc_co_u32_e32 v5, vcc, 0, v29, vcc
	global_store_dwordx2 v[4:5], v[2:3], off offset:1536

; template <class Epi, class Sched, bool ALIGN_EPI = false, bool SP2 = false>
; __device__ __forceinline__ void gemm_phase(PG8_LAS unsigned char* lds, const Gemm g, const Sched& S, const Epi& E) {
;     ...
;     const int tid = tid_o, wid = __builtin_amdgcn_readfirstlane(tid >> 6), lane = tid & 63, wr = wid >> 2, wc = wid & 3, fr = lane & 15, fq = lane >> 4;
;     const int K = g.K, nt = K / BK;
;     unsigned voffA[2], voffB[2];
; #pragma unroll
;     for (int i = 0; i < 2; ++i) { int R, C; stage_rc(tid * 16 + i * 8192, R, C); const int Rb = Epi::PERM ? ((R & ~31) + perm32(R & 31)) : R;
;         voffA[i] = (unsigned)(R * K + C) * 2u; voffB[i] = (unsigned)(Rb * K + C) * 2u; }
;     const size_t kstep = (size_t)(BK * 2);
;     const size_t hstep = (size_t)HALF * K * 2;
;     const size_t tstep = 2 * hstep;
;     const unsigned ldsw = (unsigned)wid * 1024u;
;     const int aoff = lds_byte(wr * 64 + fr, fq * 8), boff = lds_byte(wc * 32 + fr, fq * 8);
;     ...
;     Unit cur, nxt; int ui = 0;
;     if (!S.next(0, cur)) return;
;     f32x4 acc[2][2][4][2];
; #pragma unroll
;     for (int a = 0; a < 2; ++a)
; #pragma unroll
;         for (int b = 0; b < 2; ++b)
; #pragma unroll
;             for (int m = 0; m < 4; ++m)
; #pragma unroll
;                 for (int n = 0; n < 2; ++n) acc[a][b][m][n] = (f32x4){0.f, 0.f, 0.f, 0.f};
;     bf16x8 At[4][2], B0[2][2], B1[2][2];
;     const char* cA = (const char*)g.A + (size_t)cur.pm * tstep; const char* cB = (const char*)g.Bt + (size_t)cur.pn * tstep;
;     S.a_ready(cur);
;     if constexpr (SP2) {
;         PG8_STAGE(PG8_SB(0, 0), cB, voffB); PG8_STAGE(PG8_SB(0, 1), cB + hstep, voffB); PG8_STAGE(PG8_SA(0, 0), cA, voffA); PG8_STAGE(PG8_SA(0, 1), cA + hstep, voffA);
;         if (wr == 1) PG8_BAR;
;         PG8_WAIT_V(2); PG8_BAR;
;         PG8_STAGE(PG8_SB(1, 0), cB + kstep, voffB); PG8_STAGE(PG8_SA(1, 0), cA + kstep, voffA); PG8_STAGE(PG8_SB(1, 1), cB + hstep + kstep, voffB);
;         PG8_WAIT_V(6); PG8_BAR;
;     } else {
;         PG8_STAGE(PG8_SB(0, 0), cB, voffB); PG8_STAGE(PG8_SA(0, 0), cA, voffA); PG8_STAGE(PG8_SB(0, 1), cB + hstep, voffB); PG8_STAGE(PG8_SA(0, 1), cA + hstep, voffA);
;         if (wr == 1) PG8_BAR;
;         PG8_WAIT_V(4); PG8_BAR;
;         PG8_STAGE(PG8_SB(1, 0), cB + kstep, voffB); PG8_STAGE(PG8_SA(1, 0), cA + kstep, voffA); PG8_STAGE(PG8_SB(1, 1), cB + hstep + kstep, voffB);
;         PG8_WAIT_V(6); PG8_BAR;
.LBB0_1498:
	v_bfe_u32 v15, v14, 4, 2
	v_readlane_b32 s72, v255, 3
	v_and_b32_e32 v20, 15, v14
	v_lshlrev_b32_e32 v21, 4, v15
	v_lshlrev_b32_e32 v14, 2, v14
	v_readlane_b32 s73, v255, 4
	s_and_b32 s82, s6, 3
	v_lshl_or_b32 v172, s5, 6, v20
	v_lshl_or_b32 v20, v20, 6, v21
	s_lshl_b32 s5, s5, 13
	v_and_b32_e32 v14, 32, v14
	s_add_i32 m0, s62, 0x18000
	v_lshl_add_u64 v[2:3], v[2:3], 0, s[60:61]
	v_lshl_add_u64 v[16:17], s[72:73], 0, v[0:1]
	v_bitop3_b32 v21, v20, s5, v14 bitop3:0xde
	s_lshl_b32 s5, s82, 12
	s_waitcnt vmcnt(2)
	s_barrier
	global_load_lds_dwordx4 v[2:3], off
	v_lshl_add_u64 v[2:3], v[4:5], 0, s[60:61]
	s_add_i32 m0, s62, 0x1a000
	s_add_i32 s83, s62, 0x8000
	s_add_i32 s84, s62, 0xa000
	v_lshl_add_u64 v[18:19], s[72:73], 0, v[130:131]
	global_load_lds_dwordx4 v[2:3], off
	v_lshl_add_u64 v[2:3], v[16:17], 0, s[60:61]
	s_mov_b32 m0, s83
	s_add_u32 s6, s74, 0xb0080
	global_load_lds_dwordx4 v[2:3], off
	v_lshl_add_u64 v[2:3], v[18:19], 0, s[60:61]
	s_mov_b32 m0, s84
	s_addc_u32 s7, s75, 0
	global_load_lds_dwordx4 v[2:3], off
	s_add_i32 m0, s62, 0x1c000
	v_lshl_add_u64 v[2:3], s[6:7], 0, v[0:1]
	global_load_lds_dwordx4 v[2:3], off
	v_lshl_add_u64 v[2:3], s[6:7], 0, v[130:131]
	s_add_i32 m0, s62, 0x1e000
	s_movk_i32 s9, 0xb00
	global_load_lds_dwordx4 v[2:3], off
	v_lshlrev_b32_e32 v2, 2, v15
	v_lshl_or_b32 v174, s82, 5, v2
	v_lshrrev_b32_e32 v3, 1, v11
	v_mul_lo_u32 v2, v10, s9
	s_mov_b32 s8, 0xb000
	v_mad_u64_u32 v[2:3], s[6:7], v3, s8, v[2:3]
	v_or_b32_e32 v2, v2, v12
	v_add_lshl_u32 v2, v2, v13, 1
	v_mov_b32_e32 v3, v1
	s_mov_b64 s[12:13], 0xb0080
	v_lshl_add_u64 v[132:133], v[2:3], 0, s[12:13]
	v_lshrrev_b32_e32 v3, 1, v6
	v_mul_lo_u32 v2, v7, s9
	v_mad_u64_u32 v[2:3], s[6:7], v3, s8, v[2:3]
	s_waitcnt vmcnt(6)
	s_mov_b32 s100, 0
	v_or_b32_e32 v2, v2, v8
	s_cmpk_lt_u32 s4, 0x100
	v_add_lshl_u32 v2, v2, v9, 1
	v_mov_b32_e32 v3, v1
	v_readlane_b32 s6, v255, 1
	v_bitop3_b32 v173, v20, s5, v14 bitop3:0xde
	s_cselect_b64 s[10:11], -1, 0
	s_mov_b32 s85, 0
	v_cmp_eq_u32_e64 s[4:5], 0, v15
	v_lshl_add_u64 v[134:135], v[2:3], 0, s[12:13]
	v_add_u32_e32 v175, 0, v21
	v_readlane_b32 s12, v254, 46
	s_mov_b32 s13, s6
	s_barrier
	v_readlane_b32 s7, v255, 2
	s_branch .LBB0_1501

; #define PG8_STAGE(bufoff, gbase, voff) do { _Pragma("unroll") for (int _i = 0; _i < 2; ++_i) \
;         __builtin_amdgcn_global_load_lds((const unsigned*)((const char*)(gbase) + (voff)[_i]), (PG8_LAS unsigned*)(lds + (bufoff) + ldsw + _i * 8192), 16, 0, 0); } while (0)
; #define PG8_LDA(dst, b, h) do { _Pragma("unroll") for (int m = 0; m < 4; ++m) _Pragma("unroll") for (int k = 0; k < 2; ++k) dst[m][k] = *(const PG8_LAS bf16x8*)(lds + PG8_SA(b, h) + aoff + m * 2048 + k * 1024); } while (0)
; #define PG8_LDB(dst, b, h) do { _Pragma("unroll") for (int n = 0; n < 2; ++n) _Pragma("unroll") for (int k = 0; k < 2; ++k) dst[n][k] = *(const PG8_LAS bf16x8*)(lds + PG8_SB(b, h) + boff + n * 2048 + k * 1024); } while (0)
; template <class Epi, class Sched, bool ALIGN_EPI = false, bool SP2 = false>
; __device__ __forceinline__ void gemm_phase(PG8_LAS unsigned char* lds, const Gemm g, const Sched& S, const Epi& E) {
;     ...
;         for (int t = 0; t < nt; t += 2) {
;             const bool last = (t == nt - 2);
;             const char* a1 = cA + (size_t)(t + 1) * kstep;
;             const char* a2 = last ? nA : cA + (size_t)(t + 2) * kstep; const char* b2 = last ? nB : cB + (size_t)(t + 2) * kstep;
;             const char* a3 = a2 + kstep; const char* b3 = b2 + kstep;
;             if (last && has_next) S.a_ready(nxt);
;             if constexpr (SP2) {
;             PG8_LDB(B0, 0, 0); PG8_LDB(B1, 0, 1); PG8_SCHED; PG8_LDA(At, 0, 0); PG8_STAGE(PG8_SA(1, 1), a1 + hstep, voffA);
;             PG8_WAIT_V(8); PG8_WAIT_L(0); PG8_BAR; PG8_MMA(0, 0, At, B0); PG8_MMA(0, 1, At, B1); PG8_BAR; PG8_SCHED;
;             PG8_LDA(At, 0, 1); PG8_STAGE(PG8_SB(0, 0), b2, voffB); PG8_STAGE(PG8_SB(0, 1), b2 + hstep, voffB); PG8_STAGE(PG8_SA(0, 0), a2, voffA);
;             PG8_WAIT_V(8); PG8_WAIT_L(0); PG8_BAR; PG8_MMA(1, 0, At, B0); PG8_MMA(1, 1, At, B1); PG8_BAR; PG8_SCHED;
;             PG8_LDB(B0, 1, 0); PG8_LDB(B1, 1, 1); PG8_SCHED; PG8_LDA(At, 1, 0); PG8_STAGE(PG8_SA(0, 1), a2 + hstep, voffA);
;             PG8_WAIT_V(8); PG8_WAIT_L(0); PG8_BAR; PG8_MMA(0, 0, At, B0); PG8_MMA(0, 1, At, B1); PG8_BAR; PG8_SCHED;
;             PG8_LDA(At, 1, 1); PG8_STAGE(PG8_SB(1, 0), b3, voffB); PG8_STAGE(PG8_SB(1, 1), b3 + hstep, voffB); PG8_STAGE(PG8_SA(1, 0), a3, voffA);
;             PG8_WAIT_V(8); PG8_WAIT_L(0); PG8_BAR; PG8_MMA(1, 0, At, B0); PG8_MMA(1, 1, At, B1); PG8_BAR; PG8_SCHED;
.LBB0_1512:
	s_add_u32 s74, s72, 0x100
	s_addc_u32 s75, s73, 0
	s_add_i32 s50, 0, 0x10000
	s_cmp_eq_u32 s54, 40
	s_cselect_b32 s79, s9, s75
	s_cselect_b32 s78, s8, s74
	s_cselect_b32 s77, s71, s53
	s_cselect_b32 s76, s70, s52
	s_add_i32 s55, 0, 0x14000
	v_add_u32_e32 v148, s50, v173
	v_add_u32_e32 v164, s55, v173
	ds_read_b128 v[136:139], v148
	ds_read_b128 v[140:143], v148 offset:1024
	ds_read_b128 v[144:147], v148 offset:2048
	ds_read_b128 v[148:151], v148 offset:3072
	ds_read_b128 v[152:155], v164
	ds_read_b128 v[156:159], v164 offset:1024
	ds_read_b128 v[160:163], v164 offset:2048
	ds_read_b128 v[164:167], v164 offset:3072
	v_lshl_add_u64 v[184:185], s[72:73], 0, v[132:133]
	s_add_i32 m0, s62, 0xc000
	ds_read_b128 v[168:171], v175
	ds_read_b128 v[176:179], v175 offset:1024
	ds_read_b128 v[180:183], v175 offset:2048
	ds_read_b128 v[192:195], v175 offset:3072
	ds_read_b128 v[196:199], v175 offset:4096
	ds_read_b128 v[200:203], v175 offset:5120
	ds_read_b128 v[204:207], v175 offset:6144
	ds_read_b128 v[208:211], v175 offset:7168
	global_load_lds_dwordx4 v[184:185], off
	v_lshl_add_u64 v[184:185], s[72:73], 0, v[134:135]
	s_add_i32 m0, s62, 0xe000
	s_nop 0
	global_load_lds_dwordx4 v[184:185], off
	s_cmp_lg_u32 s100, 0
	s_cbranch_scc1 .Lpe_skip_dn_0
	s_waitcnt vmcnt(8)
.Lpe_skip_dn_0:
	s_waitcnt lgkmcnt(0)
	s_barrier
	s_setprio 1
	s_waitcnt lgkmcnt(0)
	v_mfma_f32_16x16x32_bf16 v[126:129], v[136:139], v[168:171], v[126:129]
	v_mfma_f32_16x16x32_bf16 v[122:125], v[144:147], v[168:171], v[122:125]
	v_mfma_f32_16x16x32_bf16 v[110:113], v[136:139], v[180:183], v[110:113]
	v_mfma_f32_16x16x32_bf16 v[106:109], v[144:147], v[180:183], v[106:109]
	v_mfma_f32_16x16x32_bf16 v[94:97], v[136:139], v[196:199], v[94:97]
	v_mfma_f32_16x16x32_bf16 v[90:93], v[144:147], v[196:199], v[90:93]
	v_mfma_f32_16x16x32_bf16 v[78:81], v[136:139], v[204:207], v[78:81]
	v_mfma_f32_16x16x32_bf16 v[74:77], v[144:147], v[204:207], v[74:77]
	v_mfma_f32_16x16x32_bf16 v[126:129], v[140:143], v[176:179], v[126:129]
	v_mfma_f32_16x16x32_bf16 v[122:125], v[148:151], v[176:179], v[122:125]
	v_mfma_f32_16x16x32_bf16 v[110:113], v[140:143], v[192:195], v[110:113]
	v_mfma_f32_16x16x32_bf16 v[106:109], v[148:151], v[192:195], v[106:109]
	v_mfma_f32_16x16x32_bf16 v[94:97], v[140:143], v[200:203], v[94:97]
	v_mfma_f32_16x16x32_bf16 v[90:93], v[148:151], v[200:203], v[90:93]
	v_mfma_f32_16x16x32_bf16 v[78:81], v[140:143], v[208:211], v[78:81]
	v_mfma_f32_16x16x32_bf16 v[74:77], v[148:151], v[208:211], v[74:77]
	s_setprio 0
	s_setprio 1
	v_mfma_f32_16x16x32_bf16 v[118:121], v[152:155], v[168:171], v[118:121]
	v_mfma_f32_16x16x32_bf16 v[114:117], v[160:163], v[168:171], v[114:117]
	v_mfma_f32_16x16x32_bf16 v[102:105], v[152:155], v[180:183], v[102:105]
	v_mfma_f32_16x16x32_bf16 v[98:101], v[160:163], v[180:183], v[98:101]
	v_mfma_f32_16x16x32_bf16 v[86:89], v[152:155], v[196:199], v[86:89]
	v_mfma_f32_16x16x32_bf16 v[82:85], v[160:163], v[196:199], v[82:85]
	v_mfma_f32_16x16x32_bf16 v[70:73], v[152:155], v[204:207], v[70:73]
	v_mfma_f32_16x16x32_bf16 v[66:69], v[160:163], v[204:207], v[66:69]
	v_mfma_f32_16x16x32_bf16 v[118:121], v[156:159], v[176:179], v[118:121]
	v_mfma_f32_16x16x32_bf16 v[114:117], v[164:167], v[176:179], v[114:117]
	v_mfma_f32_16x16x32_bf16 v[102:105], v[156:159], v[192:195], v[102:105]
	v_mfma_f32_16x16x32_bf16 v[98:101], v[164:167], v[192:195], v[98:101]
	v_mfma_f32_16x16x32_bf16 v[86:89], v[156:159], v[200:203], v[86:89]
	v_mfma_f32_16x16x32_bf16 v[82:85], v[164:167], v[200:203], v[82:85]
	v_mfma_f32_16x16x32_bf16 v[70:73], v[156:159], v[208:211], v[70:73]
	v_mfma_f32_16x16x32_bf16 v[66:69], v[164:167], v[208:211], v[66:69]
	s_setprio 0
	s_barrier
	s_add_i32 s50, s50, s35
	v_lshl_add_u64 v[184:185], s[76:77], 0, v[0:1]
	s_mov_b32 m0, s50
	ds_read_b128 v[168:171], v175 offset:16384
	ds_read_b128 v[176:179], v175 offset:17408
	ds_read_b128 v[180:183], v175 offset:18432
	ds_read_b128 v[192:195], v175 offset:19456
	ds_read_b128 v[196:199], v175 offset:20480
	ds_read_b128 v[200:203], v175 offset:21504
	ds_read_b128 v[204:207], v175 offset:22528
	ds_read_b128 v[208:211], v175 offset:23552
	global_load_lds_dwordx4 v[184:185], off
	s_add_i32 m0, s50, 0x2000
	s_add_u32 s50, s76, 0xb0000
	v_lshl_add_u64 v[188:189], s[76:77], 0, v[130:131]
	s_addc_u32 s51, s77, 0
	s_add_i32 s55, s55, s35
	global_load_lds_dwordx4 v[188:189], off
	v_lshl_add_u64 v[190:191], s[50:51], 0, v[0:1]
	s_mov_b32 m0, s55
	v_lshl_add_u64 v[212:213], s[78:79], 0, v[130:131]
	global_load_lds_dwordx4 v[190:191], off
	v_lshl_add_u64 v[190:191], s[50:51], 0, v[130:131]
	s_add_i32 m0, s55, 0x2000
	s_nop 0
	global_load_lds_dwordx4 v[190:191], off
	v_lshl_add_u64 v[190:191], s[78:79], 0, v[0:1]
	s_mov_b32 m0, s62
	s_nop 0
	global_load_lds_dwordx4 v[190:191], off
	s_mov_b32 m0, s63
	s_nop 0
	global_load_lds_dwordx4 v[212:213], off
	s_cmp_lg_u32 s100, 0
	s_cbranch_scc1 .Lpe_skip_dn_1
	s_waitcnt vmcnt(8)
; #define PG8_STAGE(bufoff, gbase, voff) do { _Pragma("unroll") for (int _i = 0; _i < 2; ++_i) \
;         __builtin_amdgcn_global_load_lds((const unsigned*)((const char*)(gbase) + (voff)[_i]), (PG8_LAS unsigned*)(lds + (bufoff) + ldsw + _i * 8192), 16, 0, 0); } while (0)
; #define PG8_LDA(dst, b, h) do { _Pragma("unroll") for (int m = 0; m < 4; ++m) _Pragma("unroll") for (int k = 0; k < 2; ++k) dst[m][k] = *(const PG8_LAS bf16x8*)(lds + PG8_SA(b, h) + aoff + m * 2048 + k * 1024); } while (0)
; #define PG8_LDB(dst, b, h) do { _Pragma("unroll") for (int n = 0; n < 2; ++n) _Pragma("unroll") for (int k = 0; k < 2; ++k) dst[n][k] = *(const PG8_LAS bf16x8*)(lds + PG8_SB(b, h) + boff + n * 2048 + k * 1024); } while (0)
; #define PG8_MMA(ai, bj, At, Bt) do { __builtin_amdgcn_s_setprio(1); _Pragma("unroll") for (int m = 0; m < 4; ++m) _Pragma("unroll") for (int n = 0; n < 2; ++n) _Pragma("unroll") for (int k = 0; k < 2; ++k) \
;         acc[ai][bj][m][n] = __builtin_amdgcn_mfma_f32_16x16x32_bf16(Bt[n][k], At[m][k], acc[ai][bj][m][n], 0, 0, 0); __builtin_amdgcn_s_setprio(0); } while (0)
; #define PG8_WAIT_V(n) asm volatile("s_waitcnt vmcnt(" #n ")" ::: "memory")
; #define PG8_WAIT_L(n) asm volatile("s_waitcnt lgkmcnt(" #n ")" ::: "memory")
; #define PG8_BAR __builtin_amdgcn_s_barrier()
; template <class Epi, class Sched, bool ALIGN_EPI = false, bool SP2 = false>
; __device__ __forceinline__ void gemm_phase(PG8_LAS unsigned char* lds, const Gemm g, const Sched& S, const Epi& E) {
;     ...
;             PG8_WAIT_V(8); PG8_WAIT_L(0); PG8_BAR; PG8_MMA(0, 0, At, B0); PG8_MMA(0, 1, At, B1); PG8_BAR; PG8_SCHED;
;             PG8_LDA(At, 0, 1); PG8_STAGE(PG8_SB(0, 0), b2, voffB); PG8_STAGE(PG8_SB(0, 1), b2 + hstep, voffB); PG8_STAGE(PG8_SA(0, 0), a2, voffA);
;             PG8_WAIT_V(8); PG8_WAIT_L(0); PG8_BAR; PG8_MMA(1, 0, At, B0); PG8_MMA(1, 1, At, B1); PG8_BAR; PG8_SCHED;
;             PG8_LDB(B0, 1, 0); PG8_LDB(B1, 1, 1); PG8_SCHED; PG8_LDA(At, 1, 0); PG8_STAGE(PG8_SA(0, 1), a2 + hstep, voffA);
;             PG8_WAIT_V(8); PG8_WAIT_L(0); PG8_BAR; PG8_MMA(0, 0, At, B0); PG8_MMA(0, 1, At, B1); PG8_BAR; PG8_SCHED;
;             PG8_LDA(At, 1, 1); PG8_STAGE(PG8_SB(1, 0), b3, voffB); PG8_STAGE(PG8_SB(1, 1), b3 + hstep, voffB); PG8_STAGE(PG8_SA(1, 0), a3, voffA);
;             PG8_WAIT_V(8); PG8_WAIT_L(0); PG8_BAR; PG8_MMA(1, 0, At, B0); PG8_MMA(1, 1, At, B1); PG8_BAR; PG8_SCHED;
.Lpe_skip_dn_1:
	s_mov_b32 s100, 0
	s_waitcnt lgkmcnt(0)
	s_barrier
	s_setprio 1
	s_waitcnt lgkmcnt(0)
	v_mfma_f32_16x16x32_bf16 v[62:65], v[136:139], v[168:171], v[62:65]
	v_mfma_f32_16x16x32_bf16 v[58:61], v[144:147], v[168:171], v[58:61]
	v_mfma_f32_16x16x32_bf16 v[46:49], v[136:139], v[180:183], v[46:49]
	v_mfma_f32_16x16x32_bf16 v[42:45], v[144:147], v[180:183], v[42:45]
	v_mfma_f32_16x16x32_bf16 v[30:33], v[136:139], v[196:199], v[30:33]
	v_mfma_f32_16x16x32_bf16 v[26:29], v[144:147], v[196:199], v[26:29]
	v_mfma_f32_16x16x32_bf16 v[14:17], v[136:139], v[204:207], v[14:17]
	v_mfma_f32_16x16x32_bf16 v[10:13], v[144:147], v[204:207], v[10:13]
	v_mfma_f32_16x16x32_bf16 v[62:65], v[140:143], v[176:179], v[62:65]
	v_mfma_f32_16x16x32_bf16 v[58:61], v[148:151], v[176:179], v[58:61]
	v_mfma_f32_16x16x32_bf16 v[46:49], v[140:143], v[192:195], v[46:49]
	v_mfma_f32_16x16x32_bf16 v[42:45], v[148:151], v[192:195], v[42:45]
	v_mfma_f32_16x16x32_bf16 v[30:33], v[140:143], v[200:203], v[30:33]
	v_mfma_f32_16x16x32_bf16 v[26:29], v[148:151], v[200:203], v[26:29]
	v_mfma_f32_16x16x32_bf16 v[14:17], v[140:143], v[208:211], v[14:17]
	v_mfma_f32_16x16x32_bf16 v[10:13], v[148:151], v[208:211], v[10:13]
	s_setprio 0
	s_setprio 1
	v_mfma_f32_16x16x32_bf16 v[54:57], v[152:155], v[168:171], v[54:57]
	v_mfma_f32_16x16x32_bf16 v[50:53], v[160:163], v[168:171], v[50:53]
	v_mfma_f32_16x16x32_bf16 v[38:41], v[152:155], v[180:183], v[38:41]
	v_mfma_f32_16x16x32_bf16 v[34:37], v[160:163], v[180:183], v[34:37]
	v_mfma_f32_16x16x32_bf16 v[22:25], v[152:155], v[196:199], v[22:25]
	v_mfma_f32_16x16x32_bf16 v[18:21], v[160:163], v[196:199], v[18:21]
	v_mfma_f32_16x16x32_bf16 v[6:9], v[152:155], v[204:207], v[6:9]
	v_mfma_f32_16x16x32_bf16 v[2:5], v[160:163], v[204:207], v[2:5]
	v_mfma_f32_16x16x32_bf16 v[54:57], v[156:159], v[176:179], v[54:57]
	v_mfma_f32_16x16x32_bf16 v[50:53], v[164:167], v[176:179], v[50:53]
	v_mfma_f32_16x16x32_bf16 v[38:41], v[156:159], v[192:195], v[38:41]
	v_mfma_f32_16x16x32_bf16 v[34:37], v[164:167], v[192:195], v[34:37]
	v_mfma_f32_16x16x32_bf16 v[22:25], v[156:159], v[200:203], v[22:25]
	v_mfma_f32_16x16x32_bf16 v[18:21], v[164:167], v[200:203], v[18:21]
	v_mfma_f32_16x16x32_bf16 v[6:9], v[156:159], v[208:211], v[6:9]
	v_mfma_f32_16x16x32_bf16 v[2:5], v[164:167], v[208:211], v[2:5]
	s_setprio 0
	s_barrier
	s_add_i32 s55, 0, 0x18000
	s_add_i32 s56, 0, 0x1c000
	v_add_u32_e32 v148, s55, v173
	v_add_u32_e32 v164, s56, v173
	ds_read_b128 v[136:139], v148
	ds_read_b128 v[140:143], v148 offset:1024
	ds_read_b128 v[144:147], v148 offset:2048
	ds_read_b128 v[148:151], v148 offset:3072
	ds_read_b128 v[152:155], v164
	ds_read_b128 v[156:159], v164 offset:1024
	ds_read_b128 v[160:163], v164 offset:2048
	ds_read_b128 v[164:167], v164 offset:3072
	s_add_u32 s50, s78, 0xb0000
	s_addc_u32 s51, s79, 0
	s_mov_b32 m0, s80
	v_lshl_add_u64 v[214:215], s[50:51], 0, v[0:1]
	ds_read_b128 v[168:171], v175 offset:32768
	ds_read_b128 v[176:179], v175 offset:33792
	ds_read_b128 v[180:183], v175 offset:34816
	ds_read_b128 v[192:195], v175 offset:35840
	ds_read_b128 v[196:199], v175 offset:36864
	ds_read_b128 v[200:203], v175 offset:37888
	ds_read_b128 v[204:207], v175 offset:38912
	ds_read_b128 v[208:211], v175 offset:39936
	global_load_lds_dwordx4 v[214:215], off
	v_lshl_add_u64 v[214:215], s[50:51], 0, v[130:131]
	s_mov_b32 m0, s81
	s_nop 0
	global_load_lds_dwordx4 v[214:215], off
	s_waitcnt vmcnt(8)
	s_waitcnt lgkmcnt(0)
	s_barrier
	s_setprio 1
	s_waitcnt lgkmcnt(0)
	v_mfma_f32_16x16x32_bf16 v[126:129], v[136:139], v[168:171], v[126:129]
	v_mfma_f32_16x16x32_bf16 v[122:125], v[144:147], v[168:171], v[122:125]
	v_mfma_f32_16x16x32_bf16 v[110:113], v[136:139], v[180:183], v[110:113]
	v_mfma_f32_16x16x32_bf16 v[106:109], v[144:147], v[180:183], v[106:109]
	v_mfma_f32_16x16x32_bf16 v[94:97], v[136:139], v[196:199], v[94:97]
	v_mfma_f32_16x16x32_bf16 v[90:93], v[144:147], v[196:199], v[90:93]
	v_mfma_f32_16x16x32_bf16 v[78:81], v[136:139], v[204:207], v[78:81]
	v_mfma_f32_16x16x32_bf16 v[74:77], v[144:147], v[204:207], v[74:77]
	v_mfma_f32_16x16x32_bf16 v[126:129], v[140:143], v[176:179], v[126:129]
	v_mfma_f32_16x16x32_bf16 v[122:125], v[148:151], v[176:179], v[122:125]
	v_mfma_f32_16x16x32_bf16 v[110:113], v[140:143], v[192:195], v[110:113]
	v_mfma_f32_16x16x32_bf16 v[106:109], v[148:151], v[192:195], v[106:109]
	v_mfma_f32_16x16x32_bf16 v[94:97], v[140:143], v[200:203], v[94:97]
	v_mfma_f32_16x16x32_bf16 v[90:93], v[148:151], v[200:203], v[90:93]
	v_mfma_f32_16x16x32_bf16 v[78:81], v[140:143], v[208:211], v[78:81]
	v_mfma_f32_16x16x32_bf16 v[74:77], v[148:151], v[208:211], v[74:77]
	s_setprio 0
	s_setprio 1
	v_mfma_f32_16x16x32_bf16 v[118:121], v[152:155], v[168:171], v[118:121]
	v_mfma_f32_16x16x32_bf16 v[114:117], v[160:163], v[168:171], v[114:117]
	v_mfma_f32_16x16x32_bf16 v[102:105], v[152:155], v[180:183], v[102:105]
	v_mfma_f32_16x16x32_bf16 v[98:101], v[160:163], v[180:183], v[98:101]
	v_mfma_f32_16x16x32_bf16 v[86:89], v[152:155], v[196:199], v[86:89]
	v_mfma_f32_16x16x32_bf16 v[82:85], v[160:163], v[196:199], v[82:85]
	v_mfma_f32_16x16x32_bf16 v[70:73], v[152:155], v[204:207], v[70:73]
	v_mfma_f32_16x16x32_bf16 v[66:69], v[160:163], v[204:207], v[66:69]
	v_mfma_f32_16x16x32_bf16 v[118:121], v[156:159], v[176:179], v[118:121]
	v_mfma_f32_16x16x32_bf16 v[114:117], v[164:167], v[176:179], v[114:117]
	v_mfma_f32_16x16x32_bf16 v[102:105], v[156:159], v[192:195], v[102:105]
	v_mfma_f32_16x16x32_bf16 v[98:101], v[164:167], v[192:195], v[98:101]
	v_mfma_f32_16x16x32_bf16 v[86:89], v[156:159], v[200:203], v[86:89]
	v_mfma_f32_16x16x32_bf16 v[82:85], v[164:167], v[200:203], v[82:85]
	v_mfma_f32_16x16x32_bf16 v[70:73], v[156:159], v[208:211], v[70:73]
	v_mfma_f32_16x16x32_bf16 v[66:69], v[164:167], v[208:211], v[66:69]
	s_setprio 0
	s_barrier
; #define PG8_STAGE(bufoff, gbase, voff) do { _Pragma("unroll") for (int _i = 0; _i < 2; ++_i) \
;         __builtin_amdgcn_global_load_lds((const unsigned*)((const char*)(gbase) + (voff)[_i]), (PG8_LAS unsigned*)(lds + (bufoff) + ldsw + _i * 8192), 16, 0, 0); } while (0)
; #define PG8_LDA(dst, b, h) do { _Pragma("unroll") for (int m = 0; m < 4; ++m) _Pragma("unroll") for (int k = 0; k < 2; ++k) dst[m][k] = *(const PG8_LAS bf16x8*)(lds + PG8_SA(b, h) + aoff + m * 2048 + k * 1024); } while (0)
; #define PG8_LDB(dst, b, h) do { _Pragma("unroll") for (int n = 0; n < 2; ++n) _Pragma("unroll") for (int k = 0; k < 2; ++k) dst[n][k] = *(const PG8_LAS bf16x8*)(lds + PG8_SB(b, h) + boff + n * 2048 + k * 1024); } while (0)
; #define PG8_MMA(ai, bj, At, Bt) do { __builtin_amdgcn_s_setprio(1); _Pragma("unroll") for (int m = 0; m < 4; ++m) _Pragma("unroll") for (int n = 0; n < 2; ++n) _Pragma("unroll") for (int k = 0; k < 2; ++k) \
;         acc[ai][bj][m][n] = __builtin_amdgcn_mfma_f32_16x16x32_bf16(Bt[n][k], At[m][k], acc[ai][bj][m][n], 0, 0, 0); __builtin_amdgcn_s_setprio(0); } while (0)
; #define PG8_WAIT_V(n) asm volatile("s_waitcnt vmcnt(" #n ")" ::: "memory")
; #define PG8_WAIT_L(n) asm volatile("s_waitcnt lgkmcnt(" #n ")" ::: "memory")
; #define PG8_BAR __builtin_amdgcn_s_barrier()
; #define PG8_SCHED __builtin_amdgcn_sched_barrier(0)
; template <class Epi, class Sched, bool ALIGN_EPI = false, bool SP2 = false>
; __device__ __forceinline__ void gemm_phase(PG8_LAS unsigned char* lds, const Gemm g, const Sched& S, const Epi& E) {
;     ...
;         for (int t = 0; t < nt; t += 2) {
;     ...
;             PG8_LDB(B0, 1, 0); PG8_LDB(B1, 1, 1); PG8_SCHED; PG8_LDA(At, 1, 0); PG8_STAGE(PG8_SA(0, 1), a2 + hstep, voffA);
;             PG8_WAIT_V(8); PG8_WAIT_L(0); PG8_BAR; PG8_MMA(0, 0, At, B0); PG8_MMA(0, 1, At, B1); PG8_BAR; PG8_SCHED;
;             PG8_LDA(At, 1, 1); PG8_STAGE(PG8_SB(1, 0), b3, voffB); PG8_STAGE(PG8_SB(1, 1), b3 + hstep, voffB); PG8_STAGE(PG8_SA(1, 0), a3, voffA);
;             PG8_WAIT_V(8); PG8_WAIT_L(0); PG8_BAR; PG8_MMA(1, 0, At, B0); PG8_MMA(1, 1, At, B1); PG8_BAR; PG8_SCHED;
	s_add_i32 s50, s55, s35
	v_lshl_add_u64 v[184:185], v[184:185], 0, s[60:61]
	s_mov_b32 m0, s50
	ds_read_b128 v[168:171], v175 offset:49152
	ds_read_b128 v[176:179], v175 offset:50176
	ds_read_b128 v[180:183], v175 offset:51200
	ds_read_b128 v[192:195], v175 offset:52224
	ds_read_b128 v[196:199], v175 offset:53248
	ds_read_b128 v[200:203], v175 offset:54272
	ds_read_b128 v[204:207], v175 offset:55296
	ds_read_b128 v[208:211], v175 offset:56320
	global_load_lds_dwordx4 v[184:185], off
	s_add_i32 m0, s50, 0x2000
	s_add_u32 s50, s76, 0xb0080
	v_lshl_add_u64 v[184:185], v[188:189], 0, s[60:61]
	s_addc_u32 s51, s77, 0
	s_add_i32 s55, s56, s35
	global_load_lds_dwordx4 v[184:185], off
	v_lshl_add_u64 v[184:185], s[50:51], 0, v[0:1]
	s_mov_b32 m0, s55
	s_nop 0
	global_load_lds_dwordx4 v[184:185], off
	v_lshl_add_u64 v[184:185], s[50:51], 0, v[130:131]
	s_add_i32 m0, s55, 0x2000
	s_nop 0
	global_load_lds_dwordx4 v[184:185], off
	v_lshl_add_u64 v[184:185], v[190:191], 0, s[60:61]
	s_mov_b32 m0, s83
	s_nop 0
	global_load_lds_dwordx4 v[184:185], off
	v_lshl_add_u64 v[184:185], v[212:213], 0, s[60:61]
	s_mov_b32 m0, s84
	s_nop 0
	global_load_lds_dwordx4 v[184:185], off
	s_waitcnt vmcnt(8)
	s_waitcnt lgkmcnt(0)
	s_barrier
	s_setprio 1
	s_waitcnt lgkmcnt(0)
	v_mfma_f32_16x16x32_bf16 v[62:65], v[136:139], v[168:171], v[62:65]
	v_mfma_f32_16x16x32_bf16 v[58:61], v[144:147], v[168:171], v[58:61]
	v_mfma_f32_16x16x32_bf16 v[46:49], v[136:139], v[180:183], v[46:49]
	v_mfma_f32_16x16x32_bf16 v[42:45], v[144:147], v[180:183], v[42:45]
	v_mfma_f32_16x16x32_bf16 v[30:33], v[136:139], v[196:199], v[30:33]
	v_mfma_f32_16x16x32_bf16 v[26:29], v[144:147], v[196:199], v[26:29]
	v_mfma_f32_16x16x32_bf16 v[14:17], v[136:139], v[204:207], v[14:17]
	v_mfma_f32_16x16x32_bf16 v[10:13], v[144:147], v[204:207], v[10:13]
	v_mfma_f32_16x16x32_bf16 v[62:65], v[140:143], v[176:179], v[62:65]
	v_mfma_f32_16x16x32_bf16 v[58:61], v[148:151], v[176:179], v[58:61]
	v_mfma_f32_16x16x32_bf16 v[46:49], v[140:143], v[192:195], v[46:49]
	v_mfma_f32_16x16x32_bf16 v[42:45], v[148:151], v[192:195], v[42:45]
	v_mfma_f32_16x16x32_bf16 v[30:33], v[140:143], v[200:203], v[30:33]
	v_mfma_f32_16x16x32_bf16 v[26:29], v[148:151], v[200:203], v[26:29]
	v_mfma_f32_16x16x32_bf16 v[14:17], v[140:143], v[208:211], v[14:17]
	v_mfma_f32_16x16x32_bf16 v[10:13], v[148:151], v[208:211], v[10:13]
	s_setprio 0
	s_setprio 1
	v_mfma_f32_16x16x32_bf16 v[54:57], v[152:155], v[168:171], v[54:57]
	v_mfma_f32_16x16x32_bf16 v[50:53], v[160:163], v[168:171], v[50:53]
	v_mfma_f32_16x16x32_bf16 v[38:41], v[152:155], v[180:183], v[38:41]
	v_mfma_f32_16x16x32_bf16 v[34:37], v[160:163], v[180:183], v[34:37]
	v_mfma_f32_16x16x32_bf16 v[22:25], v[152:155], v[196:199], v[22:25]
	v_mfma_f32_16x16x32_bf16 v[18:21], v[160:163], v[196:199], v[18:21]
	v_mfma_f32_16x16x32_bf16 v[6:9], v[152:155], v[204:207], v[6:9]
	v_mfma_f32_16x16x32_bf16 v[2:5], v[160:163], v[204:207], v[2:5]
	v_mfma_f32_16x16x32_bf16 v[54:57], v[156:159], v[176:179], v[54:57]
	v_mfma_f32_16x16x32_bf16 v[50:53], v[164:167], v[176:179], v[50:53]
	v_mfma_f32_16x16x32_bf16 v[38:41], v[156:159], v[192:195], v[38:41]
	v_mfma_f32_16x16x32_bf16 v[34:37], v[164:167], v[192:195], v[34:37]
	v_mfma_f32_16x16x32_bf16 v[22:25], v[156:159], v[200:203], v[22:25]
	v_mfma_f32_16x16x32_bf16 v[18:21], v[164:167], v[200:203], v[18:21]
	v_mfma_f32_16x16x32_bf16 v[6:9], v[156:159], v[208:211], v[6:9]
	v_mfma_f32_16x16x32_bf16 v[2:5], v[164:167], v[208:211], v[2:5]
	s_setprio 0
	s_barrier
	s_add_i32 s54, s54, 2
	s_add_u32 s52, s52, 0x100
	s_addc_u32 s53, s53, 0
	s_cmp_gt_u32 s54, 41
	s_mov_b64 s[72:73], s[74:75]
	s_cbranch_scc0 .LBB0_1512
	s_and_b64 vcc, exec, s[10:11]
	s_cbranch_vccz .LBB0_1515
	s_barrier
; __device__ __forceinline__ unsigned cvt_pk_bf16(float lo, float hi) { unsigned r; asm volatile("v_cvt_pk_bf16_f32 %0, %1, %2" : "=v"(r) : "v"(lo), "v"(hi)); return r; }
;     __device__ __forceinline__ void operator()(f32x4 (&acc)[2][2][4][2], const Unit& u, int wr, int wc, int fr, int fq) const {
;         const int col0 = u.pn * BM + wc * 32 + 4 * fq;
; #pragma unroll
;         for (int ai = 0; ai < 2; ++ai) {
;             unsigned long long old[4][2][2];
; #pragma unroll
;             for (int m = 0; m < 4; ++m) { const size_t off = (size_t)(u.pm * BM + ai * HALF + wr * 64 + m * 16 + fr) * ldc + col0;
; #pragma unroll
;                 for (int bj = 0; bj < 2; ++bj)
; #pragma unroll
;                     for (int n = 0; n < 2; ++n) old[m][bj][n] = *(const unsigned long long*)(xb + off + bj * HALF + n * 16); }
; #pragma unroll
;             for (int m = 0; m < 4; ++m) { const int row = u.pm * BM + ai * HALF + wr * 64 + m * 16 + fr; const size_t off = (size_t)row * ldc + col0; float sq = 0.f;
; #pragma unroll
;                 for (int bj = 0; bj < 2; ++bj)
; #pragma unroll
;                     for (int n = 0; n < 2; ++n) { const unsigned long long b = old[m][bj][n];
;                         const unsigned blo = (unsigned)b, bhi = (unsigned)(b >> 32);
;                         f32x4 v; v[0] = __builtin_bit_cast(float, blo << 16); v[1] = __builtin_bit_cast(float, blo & 0xffff0000u); v[2] = __builtin_bit_cast(float, bhi << 16); v[3] = __builtin_bit_cast(float, bhi & 0xffff0000u);
;                         v = v + acc[ai][bj][m][n];
;                         sq += (v[0] * v[0] + v[1] * v[1]) + (v[2] * v[2] + v[3] * v[3]);
;                         *(unsigned long long*)(xb + off + bj * HALF + n * 16) = (unsigned long long)cvt_pk_bf16(v[0], v[1]) | ((unsigned long long)cvt_pk_bf16(v[2], v[3]) << 32); }
;                 sq += __shfl_xor(sq, 16); sq += __shfl_xor(sq, 32);
;                 if (fq == 0) ssp[(size_t)row * 16 + 4 * u.pn + wc] = sq; }
.LBB0_1515:
	v_lshl_or_b32 v136, s12, 8, v174
	v_lshl_add_u32 v140, s13, 8, v172
	v_ashrrev_i32_e32 v137, 31, v136
	v_lshlrev_b64 v[176:177], 1, v[136:137]
	v_ashrrev_i32_e32 v141, 31, v140
	v_lshl_add_u64 v[138:139], s[42:43], 0, v[176:177]
	v_lshlrev_b64 v[178:179], 11, v[140:141]
	v_lshl_add_u64 v[142:143], v[138:139], 0, v[178:179]
	global_load_dwordx2 v[180:181], v[142:143], off
	global_load_dwordx2 v[182:183], v[142:143], off offset:32
	global_load_dwordx2 v[184:185], v[142:143], off offset:256
	global_load_dwordx2 v[188:189], v[142:143], off offset:288
	v_or_b32_e32 v160, 16, v140
	v_ashrrev_i32_e32 v161, 31, v160
	v_lshlrev_b64 v[142:143], 11, v[160:161]
	v_or_b32_e32 v146, 32, v140
	v_lshl_add_u64 v[142:143], v[138:139], 0, v[142:143]
	v_ashrrev_i32_e32 v147, 31, v146
	global_load_dwordx2 v[170:171], v[142:143], off
	global_load_dwordx2 v[168:169], v[142:143], off offset:32
	global_load_dwordx2 v[166:167], v[142:143], off offset:256
	global_load_dwordx2 v[164:165], v[142:143], off offset:288
	v_lshlrev_b64 v[142:143], 11, v[146:147]
	v_lshl_add_u64 v[142:143], v[138:139], 0, v[142:143]
	global_load_dwordx2 v[162:163], v[142:143], off
	global_load_dwordx2 v[158:159], v[142:143], off offset:32
	global_load_dwordx2 v[154:155], v[142:143], off offset:256
	global_load_dwordx2 v[150:151], v[142:143], off offset:288
	v_or_b32_e32 v142, 48, v140
	v_ashrrev_i32_e32 v143, 31, v142
	v_lshlrev_b64 v[144:145], 11, v[142:143]
	v_lshl_add_u64 v[144:145], v[138:139], 0, v[144:145]
	global_load_dwordx2 v[156:157], v[144:145], off
	global_load_dwordx2 v[152:153], v[144:145], off offset:32
	global_load_dwordx2 v[148:149], v[144:145], off offset:256
	s_nop 0
	global_load_dwordx2 v[144:145], v[144:145], off offset:288
	s_lshl_b32 s72, s12, 2
	s_ashr_i32 s73, s72, 31
	s_waitcnt vmcnt(0)
	s_mov_b32 s100, 1
	v_lshlrev_b32_e32 v190, 16, v180
	v_and_b32_e32 v191, 0xffff0000, v180
	v_lshlrev_b32_e32 v180, 16, v181
	v_and_b32_e32 v181, 0xffff0000, v181
	v_pk_add_f32 v[128:129], v[128:129], v[180:181]
	v_pk_add_f32 v[126:127], v[126:127], v[190:191]
	v_mul_f32_e32 v181, v129, v129
	v_mul_f32_e32 v180, v127, v127
	v_fmac_f32_e32 v180, v126, v126
	v_fmac_f32_e32 v181, v128, v128
	v_cvt_pk_bf16_f32 v126, v126, v127
	v_cvt_pk_bf16_f32 v127, v128, v129
	v_lshl_add_u64 v[128:129], s[42:43], 0, v[178:179]
	v_lshl_add_u64 v[128:129], v[128:129], 0, v[176:177]
	global_store_dwordx2 v[128:129], v[126:127], off
	v_lshlrev_b32_e32 v126, 16, v182
	v_and_b32_e32 v127, 0xffff0000, v182
	v_pk_add_f32 v[122:123], v[122:123], v[126:127]
	v_lshlrev_b32_e32 v176, 16, v183
	v_and_b32_e32 v177, 0xffff0000, v183
	v_mul_f32_e32 v126, v123, v123
	v_pk_add_f32 v[124:125], v[124:125], v[176:177]
	v_fmac_f32_e32 v126, v122, v122
	v_cvt_pk_bf16_f32 v122, v122, v123
	v_cvt_pk_bf16_f32 v123, v124, v125
	v_mul_f32_e32 v127, v125, v125
	global_store_dwordx2 v[128:129], v[122:123], off offset:32
	v_lshlrev_b32_e32 v122, 16, v184
	v_and_b32_e32 v123, 0xffff0000, v184
	v_fmac_f32_e32 v127, v124, v124
	v_lshlrev_b32_e32 v124, 16, v185
	v_and_b32_e32 v125, 0xffff0000, v185
	v_pk_add_f32 v[118:119], v[118:119], v[122:123]
	v_pk_add_f32 v[120:121], v[120:121], v[124:125]
	v_mul_f32_e32 v122, v119, v119
	v_fmac_f32_e32 v122, v118, v118
	v_mul_f32_e32 v123, v121, v121
	v_cvt_pk_bf16_f32 v118, v118, v119
	v_cvt_pk_bf16_f32 v119, v120, v121
	v_fmac_f32_e32 v123, v120, v120
	global_store_dwordx2 v[128:129], v[118:119], off offset:256
	v_lshlrev_b32_e32 v118, 16, v188
	v_and_b32_e32 v119, 0xffff0000, v188
	v_lshlrev_b32_e32 v120, 16, v189
	v_and_b32_e32 v121, 0xffff0000, v189
	v_pk_add_f32 v[116:117], v[116:117], v[120:121]
	v_pk_add_f32 v[118:119], v[114:115], v[118:119]
	v_add_f32_e32 v180, v180, v181
	v_add_f32_e32 v126, v126, v127
	v_mul_f32_e32 v114, v119, v119
	v_mul_f32_e32 v115, v117, v117
	v_add_f32_e32 v126, v180, v126
	v_add_f32_e32 v122, v122, v123
	v_fmac_f32_e32 v114, v118, v118
	v_fmac_f32_e32 v115, v116, v116
	v_add_f32_e32 v122, v126, v122
	v_add_f32_e32 v114, v114, v115
	v_cvt_pk_bf16_f32 v118, v118, v119
	v_cvt_pk_bf16_f32 v119, v116, v117
	v_and_b32_e32 v116, 64, v229
	v_add_f32_e32 v115, v122, v114
	v_xor_b32_e32 v114, 16, v229
	v_add_u32_e32 v117, 64, v116
	v_cmp_lt_i32_e32 vcc, v114, v117
	global_store_dwordx2 v[128:129], v[118:119], off offset:288
	s_nop 0
	v_cndmask_b32_e32 v114, v229, v114, vcc
	v_lshlrev_b32_e32 v114, 2, v114
	v_mov_b32_e32 v116, v115
	s_nop 1
	v_permlane16_swap_b32_e32 v116, v115
	s_waitcnt lgkmcnt(0)
	v_add_f32_e32 v116, v115, v116
	v_xor_b32_e32 v115, 32, v229
	v_cmp_lt_i32_e32 vcc, v115, v117
	s_nop 1
	v_cndmask_b32_e32 v115, v229, v115, vcc
	v_lshlrev_b32_e32 v115, 2, v115
	ds_bpermute_b32 v117, v115, v116
	s_and_saveexec_b64 s[74:75], s[4:5]
	s_cbranch_execz .LBB0_1517
	v_readlane_b32 s12, v253, 38
	v_lshlrev_b64 v[118:119], 6, v[140:141]
	v_readlane_b32 s13, v253, 39
	s_lshl_b32 s64, s82, 2
	s_waitcnt lgkmcnt(0)
	v_add_f32_e32 v116, v116, v117
	v_lshl_add_u64 v[118:119], s[12:13], 0, v[118:119]
	v_lshl_add_u64 v[118:119], s[72:73], 2, v[118:119]
	v_lshl_add_u64 v[118:119], v[118:119], 0, s[64:65]
	global_store_dword v[118:119], v116, off
